# v18 + GEMM MMA segments: mid-segment setprio 0/1 flip pairs and already-satisfied lgkmcnt waits removed (32 bare MFMAs per segment)
# baseline (speedup 1.0000x reference)
; #define LDA(dst, b, h) for (int m = 0; m < 4; ++m) for (int k = 0; k < 2; ++k) \
;     dst[m][k] = *reinterpret_cast<const bf16x8*>((char*)SA(b, h) + lds_byte(wr * 64 + m * 16 + fr, k * 32 + fq * 8))
; #define LDB(dst, b, h) for (int n = 0; n < 2; ++n) for (int k = 0; k < 2; ++k) \
;     dst[n][k] = *reinterpret_cast<const bf16x8*>((char*)SB(b, h) + lds_byte(wc * 32 + n * 16 + fr, k * 32 + fq * 8))
; #define MMA(ai, bj, At, Bt_) do { __builtin_amdgcn_s_setprio(1); \
;     for (int m = 0; m < 4; ++m) for (int n = 0; n < 2; ++n) for (int k = 0; k < 2; ++k) \
;       acc[ai][bj][m][n] = __builtin_amdgcn_mfma_f32_16x16x32_bf16(Bt_[n][k], At[m][k], acc[ai][bj][m][n], 0, 0, 0); \
;     __builtin_amdgcn_s_setprio(0); } while (0)
; #define WAIT_V(n) asm volatile("s_waitcnt vmcnt(" #n ")" ::: "memory")
; #define WAIT_L(n) asm volatile("s_waitcnt lgkmcnt(" #n ")" ::: "memory")
; #define BAR __builtin_amdgcn_s_barrier()
; #define SCHED __builtin_amdgcn_sched_barrier(0)
; template <int MODE>
; DI void gemm_phase(const bf16_t* __restrict__ A, const bf16_t* __restrict__ Bt, int M, int N, int K, const Epi& ep) {
;     ...
;             LDB(B0, 0, 0); LDB(B1, 0, 1); SCHED; LDA(At, 0, 0); STAGE(SA(1, 1), rsA, brow + HALF, t + 1);
;             WAIT_V(8); WAIT_L(0); BAR; MMA(0, 0, At, B0); MMA(0, 1, At, B1); BAR; SCHED;
;             LDA(At, 0, 1); STAGE(SB(0, 0), rsB, bcol, t + 2); STAGE(SB(0, 1), rsB, bcol + HALF, t + 2); STAGE(SA(0, 0), rsA, brow, t + 2);
;             WAIT_V(8); WAIT_L(0); BAR; MMA(1, 0, At, B0); MMA(1, 1, At, B1); BAR; SCHED;
.LBB0_91:
	ds_read_b128 v[156:159], v146
	ds_read_b128 v[160:163], v146 offset:1024
	ds_read_b128 v[164:167], v146 offset:2048
	ds_read_b128 v[168:171], v146 offset:3072
	ds_read_b128 v[172:175], v147
	ds_read_b128 v[176:179], v147 offset:1024
	ds_read_b128 v[180:183], v147 offset:2048
	ds_read_b128 v[184:187], v147 offset:3072
	s_add_i32 s41, s0, s40
	v_readfirstlane_b32 s7, v144
	s_add_i32 s6, s41, 0x40080
	s_mov_b32 m0, s7
	v_readfirstlane_b32 s7, v145
	ds_read_b128 v[188:191], v148
	ds_read_b128 v[192:195], v148 offset:1024
	ds_read_b128 v[196:199], v149
	ds_read_b128 v[200:203], v149 offset:1024
	ds_read_b128 v[204:207], v150
	ds_read_b128 v[208:211], v150 offset:1024
	ds_read_b128 v[214:217], v151
	ds_read_b128 v[218:221], v151 offset:1024
	buffer_load_dwordx4 v128, s[8:11], s6 offen lds
	s_mov_b32 m0, s7
	s_nop 0
	buffer_load_dwordx4 v129, s[8:11], s6 offen lds
	s_waitcnt vmcnt(8)
	s_waitcnt lgkmcnt(0)
	s_barrier
	s_setprio 1
	v_mfma_f32_16x16x32_bf16 v[124:127], v[156:159], v[188:191], v[124:127]
	v_mfma_f32_16x16x32_bf16 v[120:123], v[164:167], v[188:191], v[120:123]
	v_mfma_f32_16x16x32_bf16 v[116:119], v[156:159], v[196:199], v[116:119]
	v_mfma_f32_16x16x32_bf16 v[112:115], v[164:167], v[196:199], v[112:115]
	v_mfma_f32_16x16x32_bf16 v[108:111], v[156:159], v[204:207], v[108:111]
	v_mfma_f32_16x16x32_bf16 v[104:107], v[164:167], v[204:207], v[104:107]
	v_mfma_f32_16x16x32_bf16 v[100:103], v[156:159], v[214:217], v[100:103]
	v_mfma_f32_16x16x32_bf16 v[96:99], v[164:167], v[214:217], v[96:99]
	v_mfma_f32_16x16x32_bf16 v[124:127], v[160:163], v[192:195], v[124:127]
	v_mfma_f32_16x16x32_bf16 v[120:123], v[168:171], v[192:195], v[120:123]
	v_mfma_f32_16x16x32_bf16 v[116:119], v[160:163], v[200:203], v[116:119]
	v_mfma_f32_16x16x32_bf16 v[112:115], v[168:171], v[200:203], v[112:115]
	v_mfma_f32_16x16x32_bf16 v[108:111], v[160:163], v[208:211], v[108:111]
	v_mfma_f32_16x16x32_bf16 v[104:107], v[168:171], v[208:211], v[104:107]
	v_mfma_f32_16x16x32_bf16 v[100:103], v[160:163], v[218:221], v[100:103]
	v_mfma_f32_16x16x32_bf16 v[96:99], v[168:171], v[218:221], v[96:99]
	v_mfma_f32_16x16x32_bf16 v[92:95], v[172:175], v[188:191], v[92:95]
	v_mfma_f32_16x16x32_bf16 v[88:91], v[180:183], v[188:191], v[88:91]
	v_mfma_f32_16x16x32_bf16 v[84:87], v[172:175], v[196:199], v[84:87]
	v_mfma_f32_16x16x32_bf16 v[80:83], v[180:183], v[196:199], v[80:83]
	v_mfma_f32_16x16x32_bf16 v[76:79], v[172:175], v[204:207], v[76:79]
	v_mfma_f32_16x16x32_bf16 v[72:75], v[180:183], v[204:207], v[72:75]
	v_mfma_f32_16x16x32_bf16 v[68:71], v[172:175], v[214:217], v[68:71]
	v_mfma_f32_16x16x32_bf16 v[64:67], v[180:183], v[214:217], v[64:67]
	v_mfma_f32_16x16x32_bf16 v[92:95], v[176:179], v[192:195], v[92:95]
	v_mfma_f32_16x16x32_bf16 v[88:91], v[184:187], v[192:195], v[88:91]
	v_mfma_f32_16x16x32_bf16 v[84:87], v[176:179], v[200:203], v[84:87]
	v_mfma_f32_16x16x32_bf16 v[80:83], v[184:187], v[200:203], v[80:83]
	v_mfma_f32_16x16x32_bf16 v[76:79], v[176:179], v[208:211], v[76:79]
	v_mfma_f32_16x16x32_bf16 v[72:75], v[184:187], v[208:211], v[72:75]
	v_mfma_f32_16x16x32_bf16 v[68:71], v[176:179], v[218:221], v[68:71]
	v_mfma_f32_16x16x32_bf16 v[64:67], v[184:187], v[218:221], v[64:67]
	s_setprio 0
	s_barrier
	s_add_i32 s42, s1, s40
	v_readfirstlane_b32 s44, v130
	s_add_i32 s43, s42, 0x100
	s_mov_b32 s6, s10
	s_mov_b32 s7, s11
	s_mov_b32 m0, s44
	v_readfirstlane_b32 s44, v131
	ds_read_b128 v[188:191], v148 offset:16384
	ds_read_b128 v[192:195], v148 offset:17408
	ds_read_b128 v[196:199], v149 offset:16384
	ds_read_b128 v[200:203], v149 offset:17408
	ds_read_b128 v[204:207], v150 offset:16384
	ds_read_b128 v[208:211], v150 offset:17408
	ds_read_b128 v[214:217], v151 offset:16384
	ds_read_b128 v[218:221], v151 offset:17408
	buffer_load_dwordx4 v128, s[4:7], s43 offen lds
	s_mov_b32 m0, s44
	v_readfirstlane_b32 s44, v132
	buffer_load_dwordx4 v129, s[4:7], s43 offen lds
	s_add_i32 s43, s42, 0x40100
	s_mov_b32 m0, s44
	v_readfirstlane_b32 s44, v133
	buffer_load_dwordx4 v128, s[4:7], s43 offen lds
	s_mov_b32 m0, s44
	v_readfirstlane_b32 s44, v134
	buffer_load_dwordx4 v129, s[4:7], s43 offen lds
	s_add_i32 s43, s41, 0x100
	s_mov_b32 m0, s44
	v_readfirstlane_b32 s44, v135
	buffer_load_dwordx4 v128, s[8:11], s43 offen lds
	s_mov_b32 m0, s44
	s_nop 0
	buffer_load_dwordx4 v129, s[8:11], s43 offen lds
	s_waitcnt vmcnt(8)
	s_waitcnt lgkmcnt(0)
	s_barrier
	s_setprio 1
	v_mfma_f32_16x16x32_bf16 v[60:63], v[156:159], v[188:191], v[60:63]
	v_mfma_f32_16x16x32_bf16 v[56:59], v[164:167], v[188:191], v[56:59]
	v_mfma_f32_16x16x32_bf16 v[52:55], v[156:159], v[196:199], v[52:55]
	v_mfma_f32_16x16x32_bf16 v[48:51], v[164:167], v[196:199], v[48:51]
	v_mfma_f32_16x16x32_bf16 v[44:47], v[156:159], v[204:207], v[44:47]
	v_mfma_f32_16x16x32_bf16 v[40:43], v[164:167], v[204:207], v[40:43]
	v_mfma_f32_16x16x32_bf16 v[36:39], v[156:159], v[214:217], v[36:39]
	v_mfma_f32_16x16x32_bf16 v[32:35], v[164:167], v[214:217], v[32:35]
	v_mfma_f32_16x16x32_bf16 v[60:63], v[160:163], v[192:195], v[60:63]
	v_mfma_f32_16x16x32_bf16 v[56:59], v[168:171], v[192:195], v[56:59]
	v_mfma_f32_16x16x32_bf16 v[52:55], v[160:163], v[200:203], v[52:55]
	v_mfma_f32_16x16x32_bf16 v[48:51], v[168:171], v[200:203], v[48:51]
	v_mfma_f32_16x16x32_bf16 v[44:47], v[160:163], v[208:211], v[44:47]
	v_mfma_f32_16x16x32_bf16 v[40:43], v[168:171], v[208:211], v[40:43]
	v_mfma_f32_16x16x32_bf16 v[36:39], v[160:163], v[218:221], v[36:39]
	v_mfma_f32_16x16x32_bf16 v[32:35], v[168:171], v[218:221], v[32:35]
	v_mfma_f32_16x16x32_bf16 v[28:31], v[172:175], v[188:191], v[28:31]
	v_mfma_f32_16x16x32_bf16 v[24:27], v[180:183], v[188:191], v[24:27]
	v_mfma_f32_16x16x32_bf16 v[20:23], v[172:175], v[196:199], v[20:23]
	v_mfma_f32_16x16x32_bf16 v[16:19], v[180:183], v[196:199], v[16:19]
	v_mfma_f32_16x16x32_bf16 v[12:15], v[172:175], v[204:207], v[12:15]
	v_mfma_f32_16x16x32_bf16 v[8:11], v[180:183], v[204:207], v[8:11]
	v_mfma_f32_16x16x32_bf16 v[4:7], v[172:175], v[214:217], v[4:7]
	v_mfma_f32_16x16x32_bf16 v[0:3], v[180:183], v[214:217], v[0:3]
	v_mfma_f32_16x16x32_bf16 v[28:31], v[176:179], v[192:195], v[28:31]
	v_mfma_f32_16x16x32_bf16 v[24:27], v[184:187], v[192:195], v[24:27]
	v_mfma_f32_16x16x32_bf16 v[20:23], v[176:179], v[200:203], v[20:23]
	v_mfma_f32_16x16x32_bf16 v[16:19], v[184:187], v[200:203], v[16:19]
	v_mfma_f32_16x16x32_bf16 v[12:15], v[176:179], v[208:211], v[12:15]
	v_mfma_f32_16x16x32_bf16 v[8:11], v[184:187], v[208:211], v[8:11]
	v_mfma_f32_16x16x32_bf16 v[4:7], v[176:179], v[218:221], v[4:7]
	v_mfma_f32_16x16x32_bf16 v[0:3], v[184:187], v[218:221], v[0:3]
	s_setprio 0
	s_barrier
; #define LDA(dst, b, h) for (int m = 0; m < 4; ++m) for (int k = 0; k < 2; ++k) \
;     dst[m][k] = *reinterpret_cast<const bf16x8*>((char*)SA(b, h) + lds_byte(wr * 64 + m * 16 + fr, k * 32 + fq * 8))
; #define LDB(dst, b, h) for (int n = 0; n < 2; ++n) for (int k = 0; k < 2; ++k) \
;     dst[n][k] = *reinterpret_cast<const bf16x8*>((char*)SB(b, h) + lds_byte(wc * 32 + n * 16 + fr, k * 32 + fq * 8))
; #define MMA(ai, bj, At, Bt_) do { __builtin_amdgcn_s_setprio(1); \
;     for (int m = 0; m < 4; ++m) for (int n = 0; n < 2; ++n) for (int k = 0; k < 2; ++k) \
;       acc[ai][bj][m][n] = __builtin_amdgcn_mfma_f32_16x16x32_bf16(Bt_[n][k], At[m][k], acc[ai][bj][m][n], 0, 0, 0); \
;     __builtin_amdgcn_s_setprio(0); } while (0)
; #define WAIT_V(n) asm volatile("s_waitcnt vmcnt(" #n ")" ::: "memory")
; #define WAIT_L(n) asm volatile("s_waitcnt lgkmcnt(" #n ")" ::: "memory")
; #define BAR __builtin_amdgcn_s_barrier()
; #define SCHED __builtin_amdgcn_sched_barrier(0)
; template <int MODE>
; DI void gemm_phase(const bf16_t* __restrict__ A, const bf16_t* __restrict__ Bt, int M, int N, int K, const Epi& ep) {
;     ...
;             LDB(B0, 1, 0); LDB(B1, 1, 1); SCHED; LDA(At, 1, 0); STAGE(SA(0, 1), rsA, brow + HALF, t + 2);
;             WAIT_V(8); WAIT_L(0); BAR; MMA(0, 0, At, B0); MMA(0, 1, At, B1); BAR; SCHED;
;             LDA(At, 1, 1); STAGE(SB(1, 0), rsB, bcol, t + 3); STAGE(SB(1, 1), rsB, bcol + HALF, t + 3); STAGE(SA(1, 0), rsA, brow, t + 3);
;             WAIT_V(8); WAIT_L(0); BAR; MMA(1, 0, At, B0); MMA(1, 1, At, B1); BAR; SCHED;
	ds_read_b128 v[156:159], v152
	ds_read_b128 v[160:163], v152 offset:1024
	ds_read_b128 v[164:167], v152 offset:2048
	ds_read_b128 v[168:171], v152 offset:3072
	ds_read_b128 v[172:175], v153
	ds_read_b128 v[176:179], v153 offset:1024
	ds_read_b128 v[180:183], v153 offset:2048
	ds_read_b128 v[184:187], v153 offset:3072
	v_readfirstlane_b32 s44, v136
	s_add_i32 s43, s41, 0x40100
	s_mov_b32 m0, s44
	v_readfirstlane_b32 s44, v137
	ds_read_b128 v[188:191], v148 offset:32768
	ds_read_b128 v[192:195], v148 offset:33792
	ds_read_b128 v[196:199], v149 offset:32768
	ds_read_b128 v[200:203], v149 offset:33792
	ds_read_b128 v[204:207], v150 offset:32768
	ds_read_b128 v[208:211], v150 offset:33792
	ds_read_b128 v[214:217], v151 offset:32768
	ds_read_b128 v[218:221], v151 offset:33792
	buffer_load_dwordx4 v128, s[8:11], s43 offen lds
	s_mov_b32 m0, s44
	s_nop 0
	buffer_load_dwordx4 v129, s[8:11], s43 offen lds
	s_waitcnt vmcnt(8)
	s_waitcnt lgkmcnt(0)
	s_barrier
	s_setprio 1
	v_mfma_f32_16x16x32_bf16 v[124:127], v[156:159], v[188:191], v[124:127]
	v_mfma_f32_16x16x32_bf16 v[120:123], v[164:167], v[188:191], v[120:123]
	v_mfma_f32_16x16x32_bf16 v[116:119], v[156:159], v[196:199], v[116:119]
	v_mfma_f32_16x16x32_bf16 v[112:115], v[164:167], v[196:199], v[112:115]
	v_mfma_f32_16x16x32_bf16 v[108:111], v[156:159], v[204:207], v[108:111]
	v_mfma_f32_16x16x32_bf16 v[104:107], v[164:167], v[204:207], v[104:107]
	v_mfma_f32_16x16x32_bf16 v[100:103], v[156:159], v[214:217], v[100:103]
	v_mfma_f32_16x16x32_bf16 v[96:99], v[164:167], v[214:217], v[96:99]
	v_mfma_f32_16x16x32_bf16 v[124:127], v[160:163], v[192:195], v[124:127]
	v_mfma_f32_16x16x32_bf16 v[120:123], v[168:171], v[192:195], v[120:123]
	v_mfma_f32_16x16x32_bf16 v[116:119], v[160:163], v[200:203], v[116:119]
	v_mfma_f32_16x16x32_bf16 v[112:115], v[168:171], v[200:203], v[112:115]
	v_mfma_f32_16x16x32_bf16 v[108:111], v[160:163], v[208:211], v[108:111]
	v_mfma_f32_16x16x32_bf16 v[104:107], v[168:171], v[208:211], v[104:107]
	v_mfma_f32_16x16x32_bf16 v[100:103], v[160:163], v[218:221], v[100:103]
	v_mfma_f32_16x16x32_bf16 v[96:99], v[168:171], v[218:221], v[96:99]
	v_mfma_f32_16x16x32_bf16 v[92:95], v[172:175], v[188:191], v[92:95]
	v_mfma_f32_16x16x32_bf16 v[88:91], v[180:183], v[188:191], v[88:91]
	v_mfma_f32_16x16x32_bf16 v[84:87], v[172:175], v[196:199], v[84:87]
	v_mfma_f32_16x16x32_bf16 v[80:83], v[180:183], v[196:199], v[80:83]
	v_mfma_f32_16x16x32_bf16 v[76:79], v[172:175], v[204:207], v[76:79]
	v_mfma_f32_16x16x32_bf16 v[72:75], v[180:183], v[204:207], v[72:75]
	v_mfma_f32_16x16x32_bf16 v[68:71], v[172:175], v[214:217], v[68:71]
	v_mfma_f32_16x16x32_bf16 v[64:67], v[180:183], v[214:217], v[64:67]
	v_mfma_f32_16x16x32_bf16 v[92:95], v[176:179], v[192:195], v[92:95]
	v_mfma_f32_16x16x32_bf16 v[88:91], v[184:187], v[192:195], v[88:91]
	v_mfma_f32_16x16x32_bf16 v[84:87], v[176:179], v[200:203], v[84:87]
	v_mfma_f32_16x16x32_bf16 v[80:83], v[184:187], v[200:203], v[80:83]
	v_mfma_f32_16x16x32_bf16 v[76:79], v[176:179], v[208:211], v[76:79]
	v_mfma_f32_16x16x32_bf16 v[72:75], v[184:187], v[208:211], v[72:75]
	v_mfma_f32_16x16x32_bf16 v[68:71], v[176:179], v[218:221], v[68:71]
	v_mfma_f32_16x16x32_bf16 v[64:67], v[184:187], v[218:221], v[64:67]
	s_setprio 0
	s_barrier
	v_readfirstlane_b32 s44, v138
	s_add_i32 s43, s42, 0x180
	s_mov_b32 m0, s44
	v_readfirstlane_b32 s44, v139
	ds_read_b128 v[188:191], v148 offset:49152
	ds_read_b128 v[192:195], v148 offset:50176
	ds_read_b128 v[196:199], v149 offset:49152
	ds_read_b128 v[200:203], v149 offset:50176
	ds_read_b128 v[204:207], v150 offset:49152
	ds_read_b128 v[208:211], v150 offset:50176
	ds_read_b128 v[214:217], v151 offset:49152
	ds_read_b128 v[218:221], v151 offset:50176
	buffer_load_dwordx4 v128, s[4:7], s43 offen lds
	s_mov_b32 m0, s44
	s_add_i32 s42, s42, 0x40180
	buffer_load_dwordx4 v129, s[4:7], s43 offen lds
	v_readfirstlane_b32 s43, v142
	s_mov_b32 m0, s43
	v_readfirstlane_b32 s43, v143
	buffer_load_dwordx4 v128, s[4:7], s42 offen lds
	s_mov_b32 m0, s43
	s_addk_i32 s41, 0x180
	buffer_load_dwordx4 v129, s[4:7], s42 offen lds
	v_readfirstlane_b32 s6, v140
	s_mov_b32 m0, s6
	v_readfirstlane_b32 s6, v141
	buffer_load_dwordx4 v128, s[8:11], s41 offen lds
	s_mov_b32 m0, s6
	s_nop 0
	buffer_load_dwordx4 v129, s[8:11], s41 offen lds
	s_waitcnt vmcnt(8)
	s_waitcnt lgkmcnt(0)
	s_barrier
	s_setprio 1
	v_mfma_f32_16x16x32_bf16 v[60:63], v[156:159], v[188:191], v[60:63]
	v_mfma_f32_16x16x32_bf16 v[56:59], v[164:167], v[188:191], v[56:59]
	v_mfma_f32_16x16x32_bf16 v[52:55], v[156:159], v[196:199], v[52:55]
	v_mfma_f32_16x16x32_bf16 v[48:51], v[164:167], v[196:199], v[48:51]
	v_mfma_f32_16x16x32_bf16 v[44:47], v[156:159], v[204:207], v[44:47]
	v_mfma_f32_16x16x32_bf16 v[40:43], v[164:167], v[204:207], v[40:43]
	v_mfma_f32_16x16x32_bf16 v[36:39], v[156:159], v[214:217], v[36:39]
	v_mfma_f32_16x16x32_bf16 v[32:35], v[164:167], v[214:217], v[32:35]
	v_mfma_f32_16x16x32_bf16 v[60:63], v[160:163], v[192:195], v[60:63]
	v_mfma_f32_16x16x32_bf16 v[56:59], v[168:171], v[192:195], v[56:59]
	v_mfma_f32_16x16x32_bf16 v[52:55], v[160:163], v[200:203], v[52:55]
	v_mfma_f32_16x16x32_bf16 v[48:51], v[168:171], v[200:203], v[48:51]
	v_mfma_f32_16x16x32_bf16 v[44:47], v[160:163], v[208:211], v[44:47]
	v_mfma_f32_16x16x32_bf16 v[40:43], v[168:171], v[208:211], v[40:43]
	v_mfma_f32_16x16x32_bf16 v[36:39], v[160:163], v[218:221], v[36:39]
	v_mfma_f32_16x16x32_bf16 v[32:35], v[168:171], v[218:221], v[32:35]
	v_mfma_f32_16x16x32_bf16 v[28:31], v[172:175], v[188:191], v[28:31]
	v_mfma_f32_16x16x32_bf16 v[24:27], v[180:183], v[188:191], v[24:27]
	v_mfma_f32_16x16x32_bf16 v[20:23], v[172:175], v[196:199], v[20:23]
	v_mfma_f32_16x16x32_bf16 v[16:19], v[180:183], v[196:199], v[16:19]
	v_mfma_f32_16x16x32_bf16 v[12:15], v[172:175], v[204:207], v[12:15]
	v_mfma_f32_16x16x32_bf16 v[8:11], v[180:183], v[204:207], v[8:11]
	v_mfma_f32_16x16x32_bf16 v[4:7], v[172:175], v[214:217], v[4:7]
	v_mfma_f32_16x16x32_bf16 v[0:3], v[180:183], v[214:217], v[0:3]
	v_mfma_f32_16x16x32_bf16 v[28:31], v[176:179], v[192:195], v[28:31]
	v_mfma_f32_16x16x32_bf16 v[24:27], v[184:187], v[192:195], v[24:27]
	v_mfma_f32_16x16x32_bf16 v[20:23], v[176:179], v[200:203], v[20:23]
	v_mfma_f32_16x16x32_bf16 v[16:19], v[184:187], v[200:203], v[16:19]
	v_mfma_f32_16x16x32_bf16 v[12:15], v[176:179], v[208:211], v[12:15]
	v_mfma_f32_16x16x32_bf16 v[8:11], v[184:187], v[208:211], v[8:11]
	v_mfma_f32_16x16x32_bf16 v[4:7], v[176:179], v[218:221], v[4:7]
	v_mfma_f32_16x16x32_bf16 v[0:3], v[184:187], v[218:221], v[0:3]
	s_setprio 0
	s_barrier
; #define LDA(dst, b, h) for (int m = 0; m < 4; ++m) for (int k = 0; k < 2; ++k) \
;     dst[m][k] = *reinterpret_cast<const bf16x8*>((char*)SA(b, h) + lds_byte(wr * 64 + m * 16 + fr, k * 32 + fq * 8))
; #define LDB(dst, b, h) for (int n = 0; n < 2; ++n) for (int k = 0; k < 2; ++k) \
;     dst[n][k] = *reinterpret_cast<const bf16x8*>((char*)SB(b, h) + lds_byte(wc * 32 + n * 16 + fr, k * 32 + fq * 8))
; #define MMA(ai, bj, At, Bt_) do { __builtin_amdgcn_s_setprio(1); \
;     for (int m = 0; m < 4; ++m) for (int n = 0; n < 2; ++n) for (int k = 0; k < 2; ++k) \
;       acc[ai][bj][m][n] = __builtin_amdgcn_mfma_f32_16x16x32_bf16(Bt_[n][k], At[m][k], acc[ai][bj][m][n], 0, 0, 0); \
;     __builtin_amdgcn_s_setprio(0); } while (0)
; #define WAIT_V(n) asm volatile("s_waitcnt vmcnt(" #n ")" ::: "memory")
; #define WAIT_L(n) asm volatile("s_waitcnt lgkmcnt(" #n ")" ::: "memory")
; #define BAR __builtin_amdgcn_s_barrier()
; #define SCHED __builtin_amdgcn_sched_barrier(0)
; template <int MODE>
; DI void gemm_phase(const bf16_t* __restrict__ A, const bf16_t* __restrict__ Bt, int M, int N, int K, const Epi& ep) {
;     ...
;             LDB(B0, 0, 0); LDB(B1, 0, 1); SCHED; LDA(At, 0, 0); STAGE(SA(1, 1), rsA, brow + HALF, nt - 1);
;             WAIT_V(8); WAIT_L(0); BAR; MMA(0, 0, At, B0); MMA(0, 1, At, B1); BAR; SCHED;
;             LDA(At, 0, 1);
;             WAIT_V(2); WAIT_L(0); BAR; MMA(1, 0, At, B0); MMA(1, 1, At, B1); BAR; SCHED;
	s_add_i32 s31, s31, 2
	s_addk_i32 s40, 0x100
	s_cmp_lt_u32 s31, 12
	s_cbranch_scc1 .LBB0_91
	ds_read_b128 v[156:159], v146
	ds_read_b128 v[160:163], v146 offset:1024
	ds_read_b128 v[164:167], v146 offset:2048
	ds_read_b128 v[168:171], v146 offset:3072
	ds_read_b128 v[172:175], v147
	ds_read_b128 v[176:179], v147 offset:1024
	ds_read_b128 v[180:183], v147 offset:2048
	ds_read_b128 v[184:187], v147 offset:3072
	v_readfirstlane_b32 s1, v144
	s_or_b32 s0, s30, 0x40780
	s_mov_b32 m0, s1
	v_readfirstlane_b32 s1, v145
	ds_read_b128 v[188:191], v148
	ds_read_b128 v[192:195], v148 offset:1024
	ds_read_b128 v[196:199], v149
	ds_read_b128 v[200:203], v149 offset:1024
	ds_read_b128 v[204:207], v150
	ds_read_b128 v[208:211], v150 offset:1024
	ds_read_b128 v[214:217], v151
	ds_read_b128 v[218:221], v151 offset:1024
	buffer_load_dwordx4 v128, s[8:11], s0 offen lds
	s_mov_b32 m0, s1
	s_nop 0
	buffer_load_dwordx4 v129, s[8:11], s0 offen lds
	s_waitcnt vmcnt(8)
	s_waitcnt lgkmcnt(0)
	s_barrier
	s_setprio 1
	v_mfma_f32_16x16x32_bf16 v[124:127], v[156:159], v[188:191], v[124:127]
	v_mfma_f32_16x16x32_bf16 v[120:123], v[164:167], v[188:191], v[120:123]
	v_mfma_f32_16x16x32_bf16 v[116:119], v[156:159], v[196:199], v[116:119]
	v_mfma_f32_16x16x32_bf16 v[112:115], v[164:167], v[196:199], v[112:115]
	v_mfma_f32_16x16x32_bf16 v[108:111], v[156:159], v[204:207], v[108:111]
	v_mfma_f32_16x16x32_bf16 v[124:127], v[160:163], v[192:195], v[124:127]
	v_mfma_f32_16x16x32_bf16 v[120:123], v[168:171], v[192:195], v[120:123]
	v_mfma_f32_16x16x32_bf16 v[116:119], v[160:163], v[200:203], v[116:119]
	v_mfma_f32_16x16x32_bf16 v[112:115], v[168:171], v[200:203], v[112:115]
	v_mfma_f32_16x16x32_bf16 v[222:225], v[160:163], v[208:211], v[108:111]
	v_mfma_f32_16x16x32_bf16 v[104:107], v[164:167], v[204:207], v[104:107]
	v_mfma_f32_16x16x32_bf16 v[100:103], v[156:159], v[214:217], v[100:103]
	v_mfma_f32_16x16x32_bf16 v[96:99], v[164:167], v[214:217], v[96:99]
	v_mfma_f32_16x16x32_bf16 v[226:229], v[168:171], v[208:211], v[104:107]
	v_mfma_f32_16x16x32_bf16 v[230:233], v[160:163], v[218:221], v[100:103]
	v_mfma_f32_16x16x32_bf16 v[234:237], v[168:171], v[218:221], v[96:99]
	v_mfma_f32_16x16x32_bf16 v[92:95], v[172:175], v[188:191], v[92:95]
	v_mfma_f32_16x16x32_bf16 v[88:91], v[180:183], v[188:191], v[88:91]
	v_mfma_f32_16x16x32_bf16 v[84:87], v[172:175], v[196:199], v[84:87]
	v_mfma_f32_16x16x32_bf16 v[80:83], v[180:183], v[196:199], v[80:83]
	v_mfma_f32_16x16x32_bf16 v[92:95], v[176:179], v[192:195], v[92:95]
	v_mfma_f32_16x16x32_bf16 v[88:91], v[184:187], v[192:195], v[88:91]
	v_mfma_f32_16x16x32_bf16 v[84:87], v[176:179], v[200:203], v[84:87]
	v_mfma_f32_16x16x32_bf16 v[80:83], v[184:187], v[200:203], v[80:83]
	v_mfma_f32_16x16x32_bf16 v[76:79], v[172:175], v[204:207], v[76:79]
	v_mfma_f32_16x16x32_bf16 v[72:75], v[180:183], v[204:207], v[72:75]
	v_mfma_f32_16x16x32_bf16 v[68:71], v[172:175], v[214:217], v[68:71]
	v_mfma_f32_16x16x32_bf16 v[64:67], v[180:183], v[214:217], v[64:67]
	v_mfma_f32_16x16x32_bf16 v[188:191], v[176:179], v[208:211], v[76:79]
	v_mfma_f32_16x16x32_bf16 v[192:195], v[184:187], v[208:211], v[72:75]
	v_mfma_f32_16x16x32_bf16 v[196:199], v[176:179], v[218:221], v[68:71]
	v_mfma_f32_16x16x32_bf16 v[200:203], v[184:187], v[218:221], v[64:67]
	s_setprio 0
	s_barrier
	s_nop 1
	ds_read_b128 v[64:67], v148 offset:16384
	ds_read_b128 v[68:71], v148 offset:17408
	ds_read_b128 v[72:75], v149 offset:16384
	ds_read_b128 v[76:79], v149 offset:17408
	ds_read_b128 v[96:99], v150 offset:16384
	ds_read_b128 v[100:103], v150 offset:17408
	ds_read_b128 v[104:107], v151 offset:16384
	ds_read_b128 v[108:111], v151 offset:17408
	s_waitcnt vmcnt(2)
	s_waitcnt lgkmcnt(0)
	s_barrier
	s_setprio 1
	v_mfma_f32_16x16x32_bf16 v[60:63], v[156:159], v[64:67], v[60:63]
	v_mfma_f32_16x16x32_bf16 v[56:59], v[164:167], v[64:67], v[56:59]
	v_mfma_f32_16x16x32_bf16 v[52:55], v[156:159], v[72:75], v[52:55]
	v_mfma_f32_16x16x32_bf16 v[48:51], v[164:167], v[72:75], v[48:51]
	v_mfma_f32_16x16x32_bf16 v[60:63], v[160:163], v[68:71], v[60:63]
	v_mfma_f32_16x16x32_bf16 v[56:59], v[168:171], v[68:71], v[56:59]
	v_mfma_f32_16x16x32_bf16 v[52:55], v[160:163], v[76:79], v[52:55]
	v_mfma_f32_16x16x32_bf16 v[48:51], v[168:171], v[76:79], v[48:51]
	v_mfma_f32_16x16x32_bf16 v[44:47], v[156:159], v[96:99], v[44:47]
	v_mfma_f32_16x16x32_bf16 v[40:43], v[164:167], v[96:99], v[40:43]
	v_mfma_f32_16x16x32_bf16 v[36:39], v[156:159], v[104:107], v[36:39]
	v_mfma_f32_16x16x32_bf16 v[32:35], v[164:167], v[104:107], v[32:35]
	v_mfma_f32_16x16x32_bf16 v[204:207], v[160:163], v[100:103], v[44:47]
	v_mfma_f32_16x16x32_bf16 v[208:211], v[168:171], v[100:103], v[40:43]
	v_mfma_f32_16x16x32_bf16 v[156:159], v[160:163], v[108:111], v[36:39]
	v_mfma_f32_16x16x32_bf16 v[160:163], v[168:171], v[108:111], v[32:35]
	v_mfma_f32_16x16x32_bf16 v[28:31], v[172:175], v[64:67], v[28:31]
	v_mfma_f32_16x16x32_bf16 v[24:27], v[180:183], v[64:67], v[24:27]
	v_mfma_f32_16x16x32_bf16 v[20:23], v[172:175], v[72:75], v[20:23]
	v_mfma_f32_16x16x32_bf16 v[16:19], v[180:183], v[72:75], v[16:19]
	v_mfma_f32_16x16x32_bf16 v[28:31], v[176:179], v[68:71], v[28:31]
	v_mfma_f32_16x16x32_bf16 v[24:27], v[184:187], v[68:71], v[24:27]
	v_mfma_f32_16x16x32_bf16 v[20:23], v[176:179], v[76:79], v[20:23]
	v_mfma_f32_16x16x32_bf16 v[16:19], v[184:187], v[76:79], v[16:19]
	v_mfma_f32_16x16x32_bf16 v[12:15], v[172:175], v[96:99], v[12:15]
	v_mfma_f32_16x16x32_bf16 v[8:11], v[180:183], v[96:99], v[8:11]
	v_mfma_f32_16x16x32_bf16 v[4:7], v[172:175], v[104:107], v[4:7]
	v_mfma_f32_16x16x32_bf16 v[0:3], v[180:183], v[104:107], v[0:3]
	v_mfma_f32_16x16x32_bf16 v[164:167], v[176:179], v[100:103], v[12:15]
	v_mfma_f32_16x16x32_bf16 v[168:171], v[184:187], v[100:103], v[8:11]
	v_mfma_f32_16x16x32_bf16 v[172:175], v[176:179], v[108:111], v[4:7]
	v_mfma_f32_16x16x32_bf16 v[176:179], v[184:187], v[108:111], v[0:3]
	s_setprio 0
	s_barrier
; #define LDA(dst, b, h) for (int m = 0; m < 4; ++m) for (int k = 0; k < 2; ++k) \
;     dst[m][k] = *reinterpret_cast<const bf16x8*>((char*)SA(b, h) + lds_byte(wr * 64 + m * 16 + fr, k * 32 + fq * 8))
; #define LDB(dst, b, h) for (int n = 0; n < 2; ++n) for (int k = 0; k < 2; ++k) \
;     dst[n][k] = *reinterpret_cast<const bf16x8*>((char*)SB(b, h) + lds_byte(wc * 32 + n * 16 + fr, k * 32 + fq * 8))
; #define MMA(ai, bj, At, Bt_) do { __builtin_amdgcn_s_setprio(1); \
;     for (int m = 0; m < 4; ++m) for (int n = 0; n < 2; ++n) for (int k = 0; k < 2; ++k) \
;       acc[ai][bj][m][n] = __builtin_amdgcn_mfma_f32_16x16x32_bf16(Bt_[n][k], At[m][k], acc[ai][bj][m][n], 0, 0, 0); \
;     __builtin_amdgcn_s_setprio(0); } while (0)
; #define WAIT_V(n) asm volatile("s_waitcnt vmcnt(" #n ")" ::: "memory")
; #define WAIT_L(n) asm volatile("s_waitcnt lgkmcnt(" #n ")" ::: "memory")
; #define BAR __builtin_amdgcn_s_barrier()
; #define SCHED __builtin_amdgcn_sched_barrier(0)
; template <int MODE>
; DI void gemm_phase(const bf16_t* __restrict__ A, const bf16_t* __restrict__ Bt, int M, int N, int K, const Epi& ep) {
;     ...
;             LDB(B0, 1, 0); LDB(B1, 1, 1); SCHED; LDA(At, 1, 0);
;             WAIT_V(0); WAIT_L(0); BAR; MMA(0, 0, At, B0); MMA(0, 1, At, B1); BAR; SCHED;
;             LDA(At, 1, 1);
;             WAIT_L(0); BAR; MMA(1, 0, At, B0); MMA(1, 1, At, B1); BAR; SCHED;
;         }
;         if (wr == 0) BAR;
	s_nop 1
	ds_read_b128 v[0:3], v152
	ds_read_b128 v[4:7], v152 offset:1024
	ds_read_b128 v[8:11], v152 offset:2048
	ds_read_b128 v[12:15], v152 offset:3072
	ds_read_b128 v[180:183], v153
	ds_read_b128 v[184:187], v153 offset:1024
	ds_read_b128 v[214:217], v153 offset:2048
	ds_read_b128 v[218:221], v153 offset:3072
	ds_read_b128 v[32:35], v148 offset:32768
	ds_read_b128 v[36:39], v148 offset:33792
	ds_read_b128 v[40:43], v149 offset:32768
	ds_read_b128 v[44:47], v149 offset:33792
	ds_read_b128 v[238:241], v150 offset:32768
	ds_read_b128 v[242:245], v150 offset:33792
	ds_read_b128 v[246:249], v151 offset:32768
	ds_read_b128 v[64:67], v151 offset:33792
	s_waitcnt vmcnt(0)
	s_waitcnt lgkmcnt(0)
	s_barrier
	s_setprio 1
	v_mfma_f32_16x16x32_bf16 v[68:71], v[0:3], v[32:35], v[124:127]
	v_mfma_f32_16x16x32_bf16 v[96:99], v[4:7], v[36:39], v[68:71]
	v_mfma_f32_16x16x32_bf16 v[68:71], v[8:11], v[32:35], v[120:123]
	v_mfma_f32_16x16x32_bf16 v[100:103], v[12:15], v[36:39], v[68:71]
	v_mfma_f32_16x16x32_bf16 v[68:71], v[0:3], v[40:43], v[116:119]
	v_mfma_f32_16x16x32_bf16 v[104:107], v[4:7], v[44:47], v[68:71]
	v_mfma_f32_16x16x32_bf16 v[68:71], v[8:11], v[40:43], v[112:115]
	v_mfma_f32_16x16x32_bf16 v[108:111], v[12:15], v[44:47], v[68:71]
	v_mfma_f32_16x16x32_bf16 v[68:71], v[0:3], v[238:241], v[222:225]
	v_mfma_f32_16x16x32_bf16 v[112:115], v[4:7], v[242:245], v[68:71]
	v_mfma_f32_16x16x32_bf16 v[68:71], v[8:11], v[238:241], v[226:229]
	v_mfma_f32_16x16x32_bf16 v[116:119], v[12:15], v[242:245], v[68:71]
	v_mfma_f32_16x16x32_bf16 v[68:71], v[0:3], v[246:249], v[230:233]
	v_mfma_f32_16x16x32_bf16 v[120:123], v[4:7], v[64:67], v[68:71]
	v_mfma_f32_16x16x32_bf16 v[68:71], v[8:11], v[246:249], v[234:237]
	v_mfma_f32_16x16x32_bf16 v[124:127], v[12:15], v[64:67], v[68:71]
	v_mfma_f32_16x16x32_bf16 v[68:71], v[180:183], v[32:35], v[92:95]
	v_mfma_f32_16x16x32_bf16 v[32:35], v[214:217], v[32:35], v[88:91]
	v_mfma_f32_16x16x32_bf16 v[222:225], v[184:187], v[36:39], v[68:71]
	v_mfma_f32_16x16x32_bf16 v[68:71], v[218:221], v[36:39], v[32:35]
	v_mfma_f32_16x16x32_bf16 v[32:35], v[180:183], v[40:43], v[84:87]
	v_mfma_f32_16x16x32_bf16 v[72:75], v[184:187], v[44:47], v[32:35]
	v_mfma_f32_16x16x32_bf16 v[32:35], v[214:217], v[40:43], v[80:83]
	v_mfma_f32_16x16x32_bf16 v[76:79], v[218:221], v[44:47], v[32:35]
	v_mfma_f32_16x16x32_bf16 v[32:35], v[180:183], v[238:241], v[188:191]
	v_mfma_f32_16x16x32_bf16 v[80:83], v[184:187], v[242:245], v[32:35]
	v_mfma_f32_16x16x32_bf16 v[32:35], v[214:217], v[238:241], v[192:195]
	v_mfma_f32_16x16x32_bf16 v[84:87], v[218:221], v[242:245], v[32:35]
	v_mfma_f32_16x16x32_bf16 v[32:35], v[180:183], v[246:249], v[196:199]
	v_mfma_f32_16x16x32_bf16 v[88:91], v[184:187], v[64:67], v[32:35]
	v_mfma_f32_16x16x32_bf16 v[32:35], v[214:217], v[246:249], v[200:203]
	v_mfma_f32_16x16x32_bf16 v[92:95], v[218:221], v[64:67], v[32:35]
	s_setprio 0
	s_barrier
	ds_read_b128 v[64:67], v148 offset:49152
	ds_read_b128 v[188:191], v148 offset:50176
	ds_read_b128 v[192:195], v149 offset:49152
	ds_read_b128 v[196:199], v149 offset:50176
	ds_read_b128 v[200:203], v150 offset:49152
	ds_read_b128 v[226:229], v150 offset:50176
	ds_read_b128 v[230:233], v151 offset:49152
	ds_read_b128 v[234:237], v151 offset:50176
	s_waitcnt lgkmcnt(0)
	s_barrier
	s_setprio 1
	v_mfma_f32_16x16x32_bf16 v[32:35], v[0:3], v[64:67], v[60:63]
	v_mfma_f32_16x16x32_bf16 v[40:43], v[0:3], v[192:195], v[52:55]
	v_mfma_f32_16x16x32_bf16 v[44:47], v[8:11], v[192:195], v[48:51]
	v_mfma_f32_16x16x32_bf16 v[48:51], v[0:3], v[200:203], v[204:207]
	v_mfma_f32_16x16x32_bf16 v[0:3], v[0:3], v[230:233], v[156:159]
	v_mfma_f32_16x16x32_bf16 v[36:39], v[8:11], v[64:67], v[56:59]
	v_mfma_f32_16x16x32_bf16 v[52:55], v[8:11], v[200:203], v[208:211]
	v_mfma_f32_16x16x32_bf16 v[56:59], v[4:7], v[234:237], v[0:3]
	v_mfma_f32_16x16x32_bf16 v[0:3], v[8:11], v[230:233], v[160:163]
	v_mfma_f32_16x16x32_bf16 v[32:35], v[4:7], v[188:191], v[32:35]
	v_mfma_f32_16x16x32_bf16 v[36:39], v[12:15], v[188:191], v[36:39]
	v_mfma_f32_16x16x32_bf16 v[40:43], v[4:7], v[196:199], v[40:43]
	v_mfma_f32_16x16x32_bf16 v[44:47], v[12:15], v[196:199], v[44:47]
	v_mfma_f32_16x16x32_bf16 v[48:51], v[4:7], v[226:229], v[48:51]
	v_mfma_f32_16x16x32_bf16 v[52:55], v[12:15], v[226:229], v[52:55]
	v_mfma_f32_16x16x32_bf16 v[60:63], v[12:15], v[234:237], v[0:3]
	v_mfma_f32_16x16x32_bf16 v[0:3], v[180:183], v[64:67], v[28:31]
	v_mfma_f32_16x16x32_bf16 v[4:7], v[214:217], v[64:67], v[24:27]
	v_mfma_f32_16x16x32_bf16 v[8:11], v[180:183], v[192:195], v[20:23]
	v_mfma_f32_16x16x32_bf16 v[12:15], v[214:217], v[192:195], v[16:19]
	v_mfma_f32_16x16x32_bf16 v[16:19], v[180:183], v[200:203], v[164:167]
	v_mfma_f32_16x16x32_bf16 v[20:23], v[214:217], v[200:203], v[168:171]
	v_mfma_f32_16x16x32_bf16 v[24:27], v[180:183], v[230:233], v[172:175]
	v_mfma_f32_16x16x32_bf16 v[28:31], v[214:217], v[230:233], v[176:179]
	v_mfma_f32_16x16x32_bf16 v[0:3], v[184:187], v[188:191], v[0:3]
	v_mfma_f32_16x16x32_bf16 v[4:7], v[218:221], v[188:191], v[4:7]
	v_mfma_f32_16x16x32_bf16 v[8:11], v[184:187], v[196:199], v[8:11]
	v_mfma_f32_16x16x32_bf16 v[12:15], v[218:221], v[196:199], v[12:15]
	v_mfma_f32_16x16x32_bf16 v[16:19], v[184:187], v[226:229], v[16:19]
	v_mfma_f32_16x16x32_bf16 v[20:23], v[218:221], v[226:229], v[20:23]
	v_mfma_f32_16x16x32_bf16 v[24:27], v[184:187], v[234:237], v[24:27]
	v_mfma_f32_16x16x32_bf16 v[28:31], v[218:221], v[234:237], v[28:31]
	s_setprio 0
	s_barrier
	s_and_saveexec_b64 s[0:1], s[38:39]
	s_cbranch_execz .LBB0_94
	s_barrier

; #define LDA(dst, b, h) for (int m = 0; m < 4; ++m) for (int k = 0; k < 2; ++k) \
;     dst[m][k] = *reinterpret_cast<const bf16x8*>((char*)SA(b, h) + lds_byte(wr * 64 + m * 16 + fr, k * 32 + fq * 8))
; #define LDB(dst, b, h) for (int n = 0; n < 2; ++n) for (int k = 0; k < 2; ++k) \
;     dst[n][k] = *reinterpret_cast<const bf16x8*>((char*)SB(b, h) + lds_byte(wc * 32 + n * 16 + fr, k * 32 + fq * 8))
; #define MMA(ai, bj, At, Bt_) do { __builtin_amdgcn_s_setprio(1); \
;     for (int m = 0; m < 4; ++m) for (int n = 0; n < 2; ++n) for (int k = 0; k < 2; ++k) \
;       acc[ai][bj][m][n] = __builtin_amdgcn_mfma_f32_16x16x32_bf16(Bt_[n][k], At[m][k], acc[ai][bj][m][n], 0, 0, 0); \
;     __builtin_amdgcn_s_setprio(0); } while (0)
; #define WAIT_V(n) asm volatile("s_waitcnt vmcnt(" #n ")" ::: "memory")
; #define WAIT_L(n) asm volatile("s_waitcnt lgkmcnt(" #n ")" ::: "memory")
; #define BAR __builtin_amdgcn_s_barrier()
; #define SCHED __builtin_amdgcn_sched_barrier(0)
; template <int MODE>
; DI void gemm_phase(const bf16_t* __restrict__ A, const bf16_t* __restrict__ Bt, int M, int N, int K, const Epi& ep) {
;     ...
;             LDB(B0, 0, 0); LDB(B1, 0, 1); SCHED; LDA(At, 0, 0); STAGE(SA(1, 1), rsA, brow + HALF, t + 1);
;             WAIT_V(8); WAIT_L(0); BAR; MMA(0, 0, At, B0); MMA(0, 1, At, B1); BAR; SCHED;
;             LDA(At, 0, 1); STAGE(SB(0, 0), rsB, bcol, t + 2); STAGE(SB(0, 1), rsB, bcol + HALF, t + 2); STAGE(SA(0, 0), rsA, brow, t + 2);
;             WAIT_V(8); WAIT_L(0); BAR; MMA(1, 0, At, B0); MMA(1, 1, At, B1); BAR; SCHED;
.LBB0_488:
	ds_read_b128 v[156:159], v147
	ds_read_b128 v[160:163], v147 offset:1024
	ds_read_b128 v[164:167], v147 offset:2048
	ds_read_b128 v[168:171], v147 offset:3072
	ds_read_b128 v[172:175], v148
	ds_read_b128 v[176:179], v148 offset:1024
	ds_read_b128 v[180:183], v148 offset:2048
	ds_read_b128 v[184:187], v148 offset:3072
	s_add_i32 s42, s27, s41
	v_readfirstlane_b32 s15, v144
	s_add_i32 s14, s42, 0x40080
	s_mov_b32 s30, s10
	s_mov_b32 s31, s11
	s_mov_b32 m0, s15
	v_readfirstlane_b32 s15, v145
	ds_read_b128 v[188:191], v149
	ds_read_b128 v[192:195], v149 offset:1024
	ds_read_b128 v[196:199], v150
	ds_read_b128 v[200:203], v150 offset:1024
	ds_read_b128 v[204:207], v151
	ds_read_b128 v[208:211], v151 offset:1024
	ds_read_b128 v[214:217], v152
	ds_read_b128 v[218:221], v152 offset:1024
	buffer_load_dwordx4 v128, s[28:31], s14 offen lds
	s_mov_b32 m0, s15
	s_nop 0
	buffer_load_dwordx4 v129, s[28:31], s14 offen lds
	s_waitcnt vmcnt(8)
	s_waitcnt lgkmcnt(0)
	s_barrier
	s_setprio 1
	v_mfma_f32_16x16x32_bf16 v[124:127], v[156:159], v[188:191], v[124:127]
	v_mfma_f32_16x16x32_bf16 v[120:123], v[164:167], v[188:191], v[120:123]
	v_mfma_f32_16x16x32_bf16 v[116:119], v[156:159], v[196:199], v[116:119]
	v_mfma_f32_16x16x32_bf16 v[112:115], v[164:167], v[196:199], v[112:115]
	v_mfma_f32_16x16x32_bf16 v[108:111], v[156:159], v[204:207], v[108:111]
	v_mfma_f32_16x16x32_bf16 v[104:107], v[164:167], v[204:207], v[104:107]
	v_mfma_f32_16x16x32_bf16 v[100:103], v[156:159], v[214:217], v[100:103]
	v_mfma_f32_16x16x32_bf16 v[96:99], v[164:167], v[214:217], v[96:99]
	v_mfma_f32_16x16x32_bf16 v[124:127], v[160:163], v[192:195], v[124:127]
	v_mfma_f32_16x16x32_bf16 v[120:123], v[168:171], v[192:195], v[120:123]
	v_mfma_f32_16x16x32_bf16 v[116:119], v[160:163], v[200:203], v[116:119]
	v_mfma_f32_16x16x32_bf16 v[112:115], v[168:171], v[200:203], v[112:115]
	v_mfma_f32_16x16x32_bf16 v[108:111], v[160:163], v[208:211], v[108:111]
	v_mfma_f32_16x16x32_bf16 v[104:107], v[168:171], v[208:211], v[104:107]
	v_mfma_f32_16x16x32_bf16 v[100:103], v[160:163], v[218:221], v[100:103]
	v_mfma_f32_16x16x32_bf16 v[96:99], v[168:171], v[218:221], v[96:99]
	v_mfma_f32_16x16x32_bf16 v[92:95], v[172:175], v[188:191], v[92:95]
	v_mfma_f32_16x16x32_bf16 v[88:91], v[180:183], v[188:191], v[88:91]
	v_mfma_f32_16x16x32_bf16 v[84:87], v[172:175], v[196:199], v[84:87]
	v_mfma_f32_16x16x32_bf16 v[80:83], v[180:183], v[196:199], v[80:83]
	v_mfma_f32_16x16x32_bf16 v[76:79], v[172:175], v[204:207], v[76:79]
	v_mfma_f32_16x16x32_bf16 v[72:75], v[180:183], v[204:207], v[72:75]
	v_mfma_f32_16x16x32_bf16 v[68:71], v[172:175], v[214:217], v[68:71]
	v_mfma_f32_16x16x32_bf16 v[64:67], v[180:183], v[214:217], v[64:67]
	v_mfma_f32_16x16x32_bf16 v[92:95], v[176:179], v[192:195], v[92:95]
	v_mfma_f32_16x16x32_bf16 v[88:91], v[184:187], v[192:195], v[88:91]
	v_mfma_f32_16x16x32_bf16 v[84:87], v[176:179], v[200:203], v[84:87]
	v_mfma_f32_16x16x32_bf16 v[80:83], v[184:187], v[200:203], v[80:83]
	v_mfma_f32_16x16x32_bf16 v[76:79], v[176:179], v[208:211], v[76:79]
	v_mfma_f32_16x16x32_bf16 v[72:75], v[184:187], v[208:211], v[72:75]
	v_mfma_f32_16x16x32_bf16 v[68:71], v[176:179], v[218:221], v[68:71]
	v_mfma_f32_16x16x32_bf16 v[64:67], v[184:187], v[218:221], v[64:67]
	s_setprio 0
	s_barrier
	s_add_i32 s43, s6, s41
	v_readfirstlane_b32 s45, v130
	s_add_i32 s44, s43, 0x100
	s_mov_b32 s14, s10
	s_mov_b32 s15, s11
	s_mov_b32 m0, s45
	v_readfirstlane_b32 s45, v131
	ds_read_b128 v[188:191], v149 offset:16384
	ds_read_b128 v[192:195], v149 offset:17408
	ds_read_b128 v[196:199], v150 offset:16384
	ds_read_b128 v[200:203], v150 offset:17408
	ds_read_b128 v[204:207], v151 offset:16384
	ds_read_b128 v[208:211], v151 offset:17408
	ds_read_b128 v[214:217], v152 offset:16384
	ds_read_b128 v[218:221], v152 offset:17408
	buffer_load_dwordx4 v128, s[12:15], s44 offen lds
	s_mov_b32 m0, s45
	v_readfirstlane_b32 s45, v132
	buffer_load_dwordx4 v129, s[12:15], s44 offen lds
	s_add_i32 s44, s43, 0x40100
	s_mov_b32 m0, s45
	v_readfirstlane_b32 s45, v133
	buffer_load_dwordx4 v128, s[12:15], s44 offen lds
	s_mov_b32 m0, s45
	v_readfirstlane_b32 s45, v134
	buffer_load_dwordx4 v129, s[12:15], s44 offen lds
	s_add_i32 s44, s42, 0x100
	s_mov_b32 m0, s45
	v_readfirstlane_b32 s45, v135
	buffer_load_dwordx4 v128, s[28:31], s44 offen lds
	s_mov_b32 m0, s45
	s_nop 0
	buffer_load_dwordx4 v129, s[28:31], s44 offen lds
	s_waitcnt vmcnt(8)
	s_waitcnt lgkmcnt(0)
	s_barrier
	s_setprio 1
	v_mfma_f32_16x16x32_bf16 v[60:63], v[156:159], v[188:191], v[60:63]
	v_mfma_f32_16x16x32_bf16 v[56:59], v[164:167], v[188:191], v[56:59]
	v_mfma_f32_16x16x32_bf16 v[52:55], v[156:159], v[196:199], v[52:55]
	v_mfma_f32_16x16x32_bf16 v[48:51], v[164:167], v[196:199], v[48:51]
	v_mfma_f32_16x16x32_bf16 v[44:47], v[156:159], v[204:207], v[44:47]
	v_mfma_f32_16x16x32_bf16 v[40:43], v[164:167], v[204:207], v[40:43]
	v_mfma_f32_16x16x32_bf16 v[36:39], v[156:159], v[214:217], v[36:39]
	v_mfma_f32_16x16x32_bf16 v[32:35], v[164:167], v[214:217], v[32:35]
	v_mfma_f32_16x16x32_bf16 v[60:63], v[160:163], v[192:195], v[60:63]
	v_mfma_f32_16x16x32_bf16 v[56:59], v[168:171], v[192:195], v[56:59]
	v_mfma_f32_16x16x32_bf16 v[52:55], v[160:163], v[200:203], v[52:55]
	v_mfma_f32_16x16x32_bf16 v[48:51], v[168:171], v[200:203], v[48:51]
	v_mfma_f32_16x16x32_bf16 v[44:47], v[160:163], v[208:211], v[44:47]
	v_mfma_f32_16x16x32_bf16 v[40:43], v[168:171], v[208:211], v[40:43]
	v_mfma_f32_16x16x32_bf16 v[36:39], v[160:163], v[218:221], v[36:39]
	v_mfma_f32_16x16x32_bf16 v[32:35], v[168:171], v[218:221], v[32:35]
	v_mfma_f32_16x16x32_bf16 v[28:31], v[172:175], v[188:191], v[28:31]
	v_mfma_f32_16x16x32_bf16 v[24:27], v[180:183], v[188:191], v[24:27]
	v_mfma_f32_16x16x32_bf16 v[20:23], v[172:175], v[196:199], v[20:23]
	v_mfma_f32_16x16x32_bf16 v[16:19], v[180:183], v[196:199], v[16:19]
	v_mfma_f32_16x16x32_bf16 v[12:15], v[172:175], v[204:207], v[12:15]
	v_mfma_f32_16x16x32_bf16 v[8:11], v[180:183], v[204:207], v[8:11]
	v_mfma_f32_16x16x32_bf16 v[4:7], v[172:175], v[214:217], v[4:7]
	v_mfma_f32_16x16x32_bf16 v[0:3], v[180:183], v[214:217], v[0:3]
	v_mfma_f32_16x16x32_bf16 v[28:31], v[176:179], v[192:195], v[28:31]
	v_mfma_f32_16x16x32_bf16 v[24:27], v[184:187], v[192:195], v[24:27]
	v_mfma_f32_16x16x32_bf16 v[20:23], v[176:179], v[200:203], v[20:23]
	v_mfma_f32_16x16x32_bf16 v[16:19], v[184:187], v[200:203], v[16:19]
	v_mfma_f32_16x16x32_bf16 v[12:15], v[176:179], v[208:211], v[12:15]
	v_mfma_f32_16x16x32_bf16 v[8:11], v[184:187], v[208:211], v[8:11]
	v_mfma_f32_16x16x32_bf16 v[4:7], v[176:179], v[218:221], v[4:7]
	v_mfma_f32_16x16x32_bf16 v[0:3], v[184:187], v[218:221], v[0:3]
	s_setprio 0
	s_barrier
; #define LDA(dst, b, h) for (int m = 0; m < 4; ++m) for (int k = 0; k < 2; ++k) \
;     dst[m][k] = *reinterpret_cast<const bf16x8*>((char*)SA(b, h) + lds_byte(wr * 64 + m * 16 + fr, k * 32 + fq * 8))
; #define LDB(dst, b, h) for (int n = 0; n < 2; ++n) for (int k = 0; k < 2; ++k) \
;     dst[n][k] = *reinterpret_cast<const bf16x8*>((char*)SB(b, h) + lds_byte(wc * 32 + n * 16 + fr, k * 32 + fq * 8))
; #define MMA(ai, bj, At, Bt_) do { __builtin_amdgcn_s_setprio(1); \
;     for (int m = 0; m < 4; ++m) for (int n = 0; n < 2; ++n) for (int k = 0; k < 2; ++k) \
;       acc[ai][bj][m][n] = __builtin_amdgcn_mfma_f32_16x16x32_bf16(Bt_[n][k], At[m][k], acc[ai][bj][m][n], 0, 0, 0); \
;     __builtin_amdgcn_s_setprio(0); } while (0)
; #define WAIT_V(n) asm volatile("s_waitcnt vmcnt(" #n ")" ::: "memory")
; #define WAIT_L(n) asm volatile("s_waitcnt lgkmcnt(" #n ")" ::: "memory")
; #define BAR __builtin_amdgcn_s_barrier()
; #define SCHED __builtin_amdgcn_sched_barrier(0)
; template <int MODE>
; DI void gemm_phase(const bf16_t* __restrict__ A, const bf16_t* __restrict__ Bt, int M, int N, int K, const Epi& ep) {
;     ...
;             LDB(B0, 1, 0); LDB(B1, 1, 1); SCHED; LDA(At, 1, 0); STAGE(SA(0, 1), rsA, brow + HALF, t + 2);
;             WAIT_V(8); WAIT_L(0); BAR; MMA(0, 0, At, B0); MMA(0, 1, At, B1); BAR; SCHED;
;             LDA(At, 1, 1); STAGE(SB(1, 0), rsB, bcol, t + 3); STAGE(SB(1, 1), rsB, bcol + HALF, t + 3); STAGE(SA(1, 0), rsA, brow, t + 3);
;             WAIT_V(8); WAIT_L(0); BAR; MMA(1, 0, At, B0); MMA(1, 1, At, B1); BAR; SCHED;
	ds_read_b128 v[156:159], v153
	ds_read_b128 v[160:163], v153 offset:1024
	ds_read_b128 v[164:167], v153 offset:2048
	ds_read_b128 v[168:171], v153 offset:3072
	ds_read_b128 v[172:175], v154
	ds_read_b128 v[176:179], v154 offset:1024
	ds_read_b128 v[180:183], v154 offset:2048
	ds_read_b128 v[184:187], v154 offset:3072
	v_readfirstlane_b32 s45, v136
	s_add_i32 s44, s42, 0x40100
	s_mov_b32 m0, s45
	v_readfirstlane_b32 s45, v137
	ds_read_b128 v[188:191], v149 offset:32768
	ds_read_b128 v[192:195], v149 offset:33792
	ds_read_b128 v[196:199], v150 offset:32768
	ds_read_b128 v[200:203], v150 offset:33792
	ds_read_b128 v[204:207], v151 offset:32768
	ds_read_b128 v[208:211], v151 offset:33792
	ds_read_b128 v[214:217], v152 offset:32768
	ds_read_b128 v[218:221], v152 offset:33792
	buffer_load_dwordx4 v128, s[28:31], s44 offen lds
	s_mov_b32 m0, s45
	s_nop 0
	buffer_load_dwordx4 v129, s[28:31], s44 offen lds
	s_waitcnt vmcnt(8)
	s_waitcnt lgkmcnt(0)
	s_barrier
	s_setprio 1
	v_mfma_f32_16x16x32_bf16 v[124:127], v[156:159], v[188:191], v[124:127]
	v_mfma_f32_16x16x32_bf16 v[120:123], v[164:167], v[188:191], v[120:123]
	v_mfma_f32_16x16x32_bf16 v[116:119], v[156:159], v[196:199], v[116:119]
	v_mfma_f32_16x16x32_bf16 v[112:115], v[164:167], v[196:199], v[112:115]
	v_mfma_f32_16x16x32_bf16 v[108:111], v[156:159], v[204:207], v[108:111]
	v_mfma_f32_16x16x32_bf16 v[104:107], v[164:167], v[204:207], v[104:107]
	v_mfma_f32_16x16x32_bf16 v[100:103], v[156:159], v[214:217], v[100:103]
	v_mfma_f32_16x16x32_bf16 v[96:99], v[164:167], v[214:217], v[96:99]
	v_mfma_f32_16x16x32_bf16 v[124:127], v[160:163], v[192:195], v[124:127]
	v_mfma_f32_16x16x32_bf16 v[120:123], v[168:171], v[192:195], v[120:123]
	v_mfma_f32_16x16x32_bf16 v[116:119], v[160:163], v[200:203], v[116:119]
	v_mfma_f32_16x16x32_bf16 v[112:115], v[168:171], v[200:203], v[112:115]
	v_mfma_f32_16x16x32_bf16 v[108:111], v[160:163], v[208:211], v[108:111]
	v_mfma_f32_16x16x32_bf16 v[104:107], v[168:171], v[208:211], v[104:107]
	v_mfma_f32_16x16x32_bf16 v[100:103], v[160:163], v[218:221], v[100:103]
	v_mfma_f32_16x16x32_bf16 v[96:99], v[168:171], v[218:221], v[96:99]
	v_mfma_f32_16x16x32_bf16 v[92:95], v[172:175], v[188:191], v[92:95]
	v_mfma_f32_16x16x32_bf16 v[88:91], v[180:183], v[188:191], v[88:91]
	v_mfma_f32_16x16x32_bf16 v[84:87], v[172:175], v[196:199], v[84:87]
	v_mfma_f32_16x16x32_bf16 v[80:83], v[180:183], v[196:199], v[80:83]
	v_mfma_f32_16x16x32_bf16 v[76:79], v[172:175], v[204:207], v[76:79]
	v_mfma_f32_16x16x32_bf16 v[72:75], v[180:183], v[204:207], v[72:75]
	v_mfma_f32_16x16x32_bf16 v[68:71], v[172:175], v[214:217], v[68:71]
	v_mfma_f32_16x16x32_bf16 v[64:67], v[180:183], v[214:217], v[64:67]
	v_mfma_f32_16x16x32_bf16 v[92:95], v[176:179], v[192:195], v[92:95]
	v_mfma_f32_16x16x32_bf16 v[88:91], v[184:187], v[192:195], v[88:91]
	v_mfma_f32_16x16x32_bf16 v[84:87], v[176:179], v[200:203], v[84:87]
	v_mfma_f32_16x16x32_bf16 v[80:83], v[184:187], v[200:203], v[80:83]
	v_mfma_f32_16x16x32_bf16 v[76:79], v[176:179], v[208:211], v[76:79]
	v_mfma_f32_16x16x32_bf16 v[72:75], v[184:187], v[208:211], v[72:75]
	v_mfma_f32_16x16x32_bf16 v[68:71], v[176:179], v[218:221], v[68:71]
	v_mfma_f32_16x16x32_bf16 v[64:67], v[184:187], v[218:221], v[64:67]
	s_setprio 0
	s_barrier
	v_readfirstlane_b32 s45, v138
	s_add_i32 s44, s43, 0x180
	s_mov_b32 m0, s45
	v_readfirstlane_b32 s45, v139
	ds_read_b128 v[188:191], v149 offset:49152
	ds_read_b128 v[192:195], v149 offset:50176
	ds_read_b128 v[196:199], v150 offset:49152
	ds_read_b128 v[200:203], v150 offset:50176
	ds_read_b128 v[204:207], v151 offset:49152
	ds_read_b128 v[208:211], v151 offset:50176
	ds_read_b128 v[214:217], v152 offset:49152
	ds_read_b128 v[218:221], v152 offset:50176
	buffer_load_dwordx4 v128, s[12:15], s44 offen lds
	s_mov_b32 m0, s45
	s_add_i32 s43, s43, 0x40180
	buffer_load_dwordx4 v129, s[12:15], s44 offen lds
	v_readfirstlane_b32 s44, v142
	s_mov_b32 m0, s44
	v_readfirstlane_b32 s44, v143
	buffer_load_dwordx4 v128, s[12:15], s43 offen lds
	s_mov_b32 m0, s44
	s_addk_i32 s42, 0x180
	buffer_load_dwordx4 v129, s[12:15], s43 offen lds
	v_readfirstlane_b32 s14, v140
	s_mov_b32 m0, s14
	v_readfirstlane_b32 s14, v141
	buffer_load_dwordx4 v128, s[28:31], s42 offen lds
	s_mov_b32 m0, s14
	s_nop 0
	buffer_load_dwordx4 v129, s[28:31], s42 offen lds
	s_waitcnt vmcnt(8)
	s_waitcnt lgkmcnt(0)
	s_barrier
	s_setprio 1
	v_mfma_f32_16x16x32_bf16 v[60:63], v[156:159], v[188:191], v[60:63]
	v_mfma_f32_16x16x32_bf16 v[56:59], v[164:167], v[188:191], v[56:59]
	v_mfma_f32_16x16x32_bf16 v[52:55], v[156:159], v[196:199], v[52:55]
	v_mfma_f32_16x16x32_bf16 v[48:51], v[164:167], v[196:199], v[48:51]
	v_mfma_f32_16x16x32_bf16 v[44:47], v[156:159], v[204:207], v[44:47]
	v_mfma_f32_16x16x32_bf16 v[40:43], v[164:167], v[204:207], v[40:43]
	v_mfma_f32_16x16x32_bf16 v[36:39], v[156:159], v[214:217], v[36:39]
	v_mfma_f32_16x16x32_bf16 v[32:35], v[164:167], v[214:217], v[32:35]
	v_mfma_f32_16x16x32_bf16 v[60:63], v[160:163], v[192:195], v[60:63]
	v_mfma_f32_16x16x32_bf16 v[56:59], v[168:171], v[192:195], v[56:59]
	v_mfma_f32_16x16x32_bf16 v[52:55], v[160:163], v[200:203], v[52:55]
	v_mfma_f32_16x16x32_bf16 v[48:51], v[168:171], v[200:203], v[48:51]
	v_mfma_f32_16x16x32_bf16 v[44:47], v[160:163], v[208:211], v[44:47]
	v_mfma_f32_16x16x32_bf16 v[40:43], v[168:171], v[208:211], v[40:43]
	v_mfma_f32_16x16x32_bf16 v[36:39], v[160:163], v[218:221], v[36:39]
	v_mfma_f32_16x16x32_bf16 v[32:35], v[168:171], v[218:221], v[32:35]
	v_mfma_f32_16x16x32_bf16 v[28:31], v[172:175], v[188:191], v[28:31]
	v_mfma_f32_16x16x32_bf16 v[24:27], v[180:183], v[188:191], v[24:27]
	v_mfma_f32_16x16x32_bf16 v[20:23], v[172:175], v[196:199], v[20:23]
	v_mfma_f32_16x16x32_bf16 v[16:19], v[180:183], v[196:199], v[16:19]
	v_mfma_f32_16x16x32_bf16 v[12:15], v[172:175], v[204:207], v[12:15]
	v_mfma_f32_16x16x32_bf16 v[8:11], v[180:183], v[204:207], v[8:11]
	v_mfma_f32_16x16x32_bf16 v[4:7], v[172:175], v[214:217], v[4:7]
	v_mfma_f32_16x16x32_bf16 v[0:3], v[180:183], v[214:217], v[0:3]
	v_mfma_f32_16x16x32_bf16 v[28:31], v[176:179], v[192:195], v[28:31]
	v_mfma_f32_16x16x32_bf16 v[24:27], v[184:187], v[192:195], v[24:27]
	v_mfma_f32_16x16x32_bf16 v[20:23], v[176:179], v[200:203], v[20:23]
	v_mfma_f32_16x16x32_bf16 v[16:19], v[184:187], v[200:203], v[16:19]
	v_mfma_f32_16x16x32_bf16 v[12:15], v[176:179], v[208:211], v[12:15]
	v_mfma_f32_16x16x32_bf16 v[8:11], v[184:187], v[208:211], v[8:11]
	v_mfma_f32_16x16x32_bf16 v[4:7], v[176:179], v[218:221], v[4:7]
	v_mfma_f32_16x16x32_bf16 v[0:3], v[184:187], v[218:221], v[0:3]
	s_setprio 0
	s_barrier
; #define LDA(dst, b, h) for (int m = 0; m < 4; ++m) for (int k = 0; k < 2; ++k) \
;     dst[m][k] = *reinterpret_cast<const bf16x8*>((char*)SA(b, h) + lds_byte(wr * 64 + m * 16 + fr, k * 32 + fq * 8))
; #define LDB(dst, b, h) for (int n = 0; n < 2; ++n) for (int k = 0; k < 2; ++k) \
;     dst[n][k] = *reinterpret_cast<const bf16x8*>((char*)SB(b, h) + lds_byte(wc * 32 + n * 16 + fr, k * 32 + fq * 8))
; #define MMA(ai, bj, At, Bt_) do { __builtin_amdgcn_s_setprio(1); \
;     for (int m = 0; m < 4; ++m) for (int n = 0; n < 2; ++n) for (int k = 0; k < 2; ++k) \
;       acc[ai][bj][m][n] = __builtin_amdgcn_mfma_f32_16x16x32_bf16(Bt_[n][k], At[m][k], acc[ai][bj][m][n], 0, 0, 0); \
;     __builtin_amdgcn_s_setprio(0); } while (0)
; #define WAIT_V(n) asm volatile("s_waitcnt vmcnt(" #n ")" ::: "memory")
; #define WAIT_L(n) asm volatile("s_waitcnt lgkmcnt(" #n ")" ::: "memory")
; #define BAR __builtin_amdgcn_s_barrier()
; #define SCHED __builtin_amdgcn_sched_barrier(0)
; template <int MODE>
; DI void gemm_phase(const bf16_t* __restrict__ A, const bf16_t* __restrict__ Bt, int M, int N, int K, const Epi& ep) {
;     ...
;         for (int t = 0; t < nt - 2; t += 2) {
;             LDB(B0, 0, 0); LDB(B1, 0, 1); SCHED; LDA(At, 0, 0); STAGE(SA(1, 1), rsA, brow + HALF, t + 1);
;             WAIT_V(8); WAIT_L(0); BAR; MMA(0, 0, At, B0); MMA(0, 1, At, B1); BAR; SCHED;
;             LDA(At, 0, 1); STAGE(SB(0, 0), rsB, bcol, t + 2); STAGE(SB(0, 1), rsB, bcol + HALF, t + 2); STAGE(SA(0, 0), rsA, brow, t + 2);
;             WAIT_V(8); WAIT_L(0); BAR; MMA(1, 0, At, B0); MMA(1, 1, At, B1); BAR; SCHED;
;             LDB(B0, 1, 0); LDB(B1, 1, 1); SCHED; LDA(At, 1, 0); STAGE(SA(0, 1), rsA, brow + HALF, t + 2);
;             WAIT_V(8); WAIT_L(0); BAR; MMA(0, 0, At, B0); MMA(0, 1, At, B1); BAR; SCHED;
;             LDA(At, 1, 1); STAGE(SB(1, 0), rsB, bcol, t + 3); STAGE(SB(1, 1), rsB, bcol + HALF, t + 3); STAGE(SA(1, 0), rsA, brow, t + 3);
;             WAIT_V(8); WAIT_L(0); BAR; MMA(1, 0, At, B0); MMA(1, 1, At, B1); BAR; SCHED;
;         }
;         {
;             LDB(B0, 0, 0); LDB(B1, 0, 1); SCHED; LDA(At, 0, 0); STAGE(SA(1, 1), rsA, brow + HALF, nt - 1);
;             WAIT_V(8); WAIT_L(0); BAR; MMA(0, 0, At, B0); MMA(0, 1, At, B1); BAR; SCHED;
;             LDA(At, 0, 1);
;             WAIT_V(2); WAIT_L(0); BAR; MMA(1, 0, At, B0); MMA(1, 1, At, B1); BAR; SCHED;
	s_add_i32 s40, s40, 2
	s_addk_i32 s41, 0x100
	s_cmp_gt_u32 s40, 11
	s_cbranch_scc0 .LBB0_488
	ds_read_b128 v[156:159], v147
	ds_read_b128 v[160:163], v147 offset:1024
	ds_read_b128 v[164:167], v147 offset:2048
	ds_read_b128 v[168:171], v147 offset:3072
	ds_read_b128 v[172:175], v148
	ds_read_b128 v[176:179], v148 offset:1024
	ds_read_b128 v[180:183], v148 offset:2048
	ds_read_b128 v[184:187], v148 offset:3072
	s_or_b32 s6, s7, 0x780
	v_readfirstlane_b32 s7, v144
	s_mov_b32 m0, s7
	v_readfirstlane_b32 s7, v145
	ds_read_b128 v[188:191], v149
	ds_read_b128 v[192:195], v149 offset:1024
	ds_read_b128 v[196:199], v150
	ds_read_b128 v[200:203], v150 offset:1024
	ds_read_b128 v[204:207], v151
	ds_read_b128 v[208:211], v151 offset:1024
	ds_read_b128 v[214:217], v152
	ds_read_b128 v[218:221], v152 offset:1024
	buffer_load_dwordx4 v128, s[28:31], s6 offen lds
	s_mov_b32 m0, s7
	s_nop 0
	buffer_load_dwordx4 v129, s[28:31], s6 offen lds
	s_waitcnt vmcnt(8)
	s_waitcnt lgkmcnt(0)
	s_barrier
	s_setprio 1
	v_mfma_f32_16x16x32_bf16 v[124:127], v[156:159], v[188:191], v[124:127]
	v_mfma_f32_16x16x32_bf16 v[120:123], v[164:167], v[188:191], v[120:123]
	v_mfma_f32_16x16x32_bf16 v[116:119], v[156:159], v[196:199], v[116:119]
	v_mfma_f32_16x16x32_bf16 v[112:115], v[164:167], v[196:199], v[112:115]
	v_mfma_f32_16x16x32_bf16 v[108:111], v[156:159], v[204:207], v[108:111]
	v_mfma_f32_16x16x32_bf16 v[124:127], v[160:163], v[192:195], v[124:127]
	v_mfma_f32_16x16x32_bf16 v[120:123], v[168:171], v[192:195], v[120:123]
	v_mfma_f32_16x16x32_bf16 v[116:119], v[160:163], v[200:203], v[116:119]
	v_mfma_f32_16x16x32_bf16 v[112:115], v[168:171], v[200:203], v[112:115]
	v_mfma_f32_16x16x32_bf16 v[222:225], v[160:163], v[208:211], v[108:111]
	v_mfma_f32_16x16x32_bf16 v[104:107], v[164:167], v[204:207], v[104:107]
	v_mfma_f32_16x16x32_bf16 v[100:103], v[156:159], v[214:217], v[100:103]
	v_mfma_f32_16x16x32_bf16 v[96:99], v[164:167], v[214:217], v[96:99]
	v_mfma_f32_16x16x32_bf16 v[226:229], v[168:171], v[208:211], v[104:107]
	v_mfma_f32_16x16x32_bf16 v[230:233], v[160:163], v[218:221], v[100:103]
	v_mfma_f32_16x16x32_bf16 v[234:237], v[168:171], v[218:221], v[96:99]
	v_mfma_f32_16x16x32_bf16 v[92:95], v[172:175], v[188:191], v[92:95]
	v_mfma_f32_16x16x32_bf16 v[88:91], v[180:183], v[188:191], v[88:91]
	v_mfma_f32_16x16x32_bf16 v[84:87], v[172:175], v[196:199], v[84:87]
	v_mfma_f32_16x16x32_bf16 v[80:83], v[180:183], v[196:199], v[80:83]
	v_mfma_f32_16x16x32_bf16 v[92:95], v[176:179], v[192:195], v[92:95]
	v_mfma_f32_16x16x32_bf16 v[88:91], v[184:187], v[192:195], v[88:91]
	v_mfma_f32_16x16x32_bf16 v[84:87], v[176:179], v[200:203], v[84:87]
	v_mfma_f32_16x16x32_bf16 v[80:83], v[184:187], v[200:203], v[80:83]
	v_mfma_f32_16x16x32_bf16 v[76:79], v[172:175], v[204:207], v[76:79]
	v_mfma_f32_16x16x32_bf16 v[72:75], v[180:183], v[204:207], v[72:75]
	v_mfma_f32_16x16x32_bf16 v[68:71], v[172:175], v[214:217], v[68:71]
	v_mfma_f32_16x16x32_bf16 v[64:67], v[180:183], v[214:217], v[64:67]
	v_mfma_f32_16x16x32_bf16 v[188:191], v[176:179], v[208:211], v[76:79]
	v_mfma_f32_16x16x32_bf16 v[192:195], v[184:187], v[208:211], v[72:75]
	v_mfma_f32_16x16x32_bf16 v[196:199], v[176:179], v[218:221], v[68:71]
	v_mfma_f32_16x16x32_bf16 v[200:203], v[184:187], v[218:221], v[64:67]
	s_setprio 0
	s_barrier
	s_nop 1
	ds_read_b128 v[64:67], v149 offset:16384
	ds_read_b128 v[68:71], v149 offset:17408
	ds_read_b128 v[72:75], v150 offset:16384
	ds_read_b128 v[76:79], v150 offset:17408
	ds_read_b128 v[96:99], v151 offset:16384
	ds_read_b128 v[100:103], v151 offset:17408
	ds_read_b128 v[104:107], v152 offset:16384
	ds_read_b128 v[108:111], v152 offset:17408
	s_waitcnt vmcnt(2)
	s_waitcnt lgkmcnt(0)
	s_barrier
	s_setprio 1
	v_mfma_f32_16x16x32_bf16 v[60:63], v[156:159], v[64:67], v[60:63]
	v_mfma_f32_16x16x32_bf16 v[56:59], v[164:167], v[64:67], v[56:59]
	v_mfma_f32_16x16x32_bf16 v[52:55], v[156:159], v[72:75], v[52:55]
	v_mfma_f32_16x16x32_bf16 v[48:51], v[164:167], v[72:75], v[48:51]
	v_mfma_f32_16x16x32_bf16 v[60:63], v[160:163], v[68:71], v[60:63]
	v_mfma_f32_16x16x32_bf16 v[56:59], v[168:171], v[68:71], v[56:59]
	v_mfma_f32_16x16x32_bf16 v[52:55], v[160:163], v[76:79], v[52:55]
	v_mfma_f32_16x16x32_bf16 v[48:51], v[168:171], v[76:79], v[48:51]
	v_mfma_f32_16x16x32_bf16 v[44:47], v[156:159], v[96:99], v[44:47]
	v_mfma_f32_16x16x32_bf16 v[40:43], v[164:167], v[96:99], v[40:43]
	v_mfma_f32_16x16x32_bf16 v[36:39], v[156:159], v[104:107], v[36:39]
	v_mfma_f32_16x16x32_bf16 v[32:35], v[164:167], v[104:107], v[32:35]
	v_mfma_f32_16x16x32_bf16 v[204:207], v[160:163], v[100:103], v[44:47]
	v_mfma_f32_16x16x32_bf16 v[208:211], v[168:171], v[100:103], v[40:43]
	v_mfma_f32_16x16x32_bf16 v[156:159], v[160:163], v[108:111], v[36:39]
	v_mfma_f32_16x16x32_bf16 v[160:163], v[168:171], v[108:111], v[32:35]
	v_mfma_f32_16x16x32_bf16 v[28:31], v[172:175], v[64:67], v[28:31]
	v_mfma_f32_16x16x32_bf16 v[24:27], v[180:183], v[64:67], v[24:27]
	v_mfma_f32_16x16x32_bf16 v[20:23], v[172:175], v[72:75], v[20:23]
	v_mfma_f32_16x16x32_bf16 v[16:19], v[180:183], v[72:75], v[16:19]
	v_mfma_f32_16x16x32_bf16 v[28:31], v[176:179], v[68:71], v[28:31]
	v_mfma_f32_16x16x32_bf16 v[24:27], v[184:187], v[68:71], v[24:27]
	v_mfma_f32_16x16x32_bf16 v[20:23], v[176:179], v[76:79], v[20:23]
	v_mfma_f32_16x16x32_bf16 v[16:19], v[184:187], v[76:79], v[16:19]
	v_mfma_f32_16x16x32_bf16 v[12:15], v[172:175], v[96:99], v[12:15]
	v_mfma_f32_16x16x32_bf16 v[8:11], v[180:183], v[96:99], v[8:11]
	v_mfma_f32_16x16x32_bf16 v[4:7], v[172:175], v[104:107], v[4:7]
	v_mfma_f32_16x16x32_bf16 v[0:3], v[180:183], v[104:107], v[0:3]
	v_mfma_f32_16x16x32_bf16 v[164:167], v[176:179], v[100:103], v[12:15]
	v_mfma_f32_16x16x32_bf16 v[168:171], v[184:187], v[100:103], v[8:11]
	v_mfma_f32_16x16x32_bf16 v[172:175], v[176:179], v[108:111], v[4:7]
	v_mfma_f32_16x16x32_bf16 v[176:179], v[184:187], v[108:111], v[0:3]
	s_setprio 0
	s_barrier
; #define LDA(dst, b, h) for (int m = 0; m < 4; ++m) for (int k = 0; k < 2; ++k) \
;     dst[m][k] = *reinterpret_cast<const bf16x8*>((char*)SA(b, h) + lds_byte(wr * 64 + m * 16 + fr, k * 32 + fq * 8))
; #define LDB(dst, b, h) for (int n = 0; n < 2; ++n) for (int k = 0; k < 2; ++k) \
;     dst[n][k] = *reinterpret_cast<const bf16x8*>((char*)SB(b, h) + lds_byte(wc * 32 + n * 16 + fr, k * 32 + fq * 8))
; #define MMA(ai, bj, At, Bt_) do { __builtin_amdgcn_s_setprio(1); \
;     for (int m = 0; m < 4; ++m) for (int n = 0; n < 2; ++n) for (int k = 0; k < 2; ++k) \
;       acc[ai][bj][m][n] = __builtin_amdgcn_mfma_f32_16x16x32_bf16(Bt_[n][k], At[m][k], acc[ai][bj][m][n], 0, 0, 0); \
;     __builtin_amdgcn_s_setprio(0); } while (0)
; #define WAIT_V(n) asm volatile("s_waitcnt vmcnt(" #n ")" ::: "memory")
; #define WAIT_L(n) asm volatile("s_waitcnt lgkmcnt(" #n ")" ::: "memory")
; #define BAR __builtin_amdgcn_s_barrier()
; #define SCHED __builtin_amdgcn_sched_barrier(0)
; template <int MODE>
; DI void gemm_phase(const bf16_t* __restrict__ A, const bf16_t* __restrict__ Bt, int M, int N, int K, const Epi& ep) {
;     ...
;             LDB(B0, 1, 0); LDB(B1, 1, 1); SCHED; LDA(At, 1, 0);
;             WAIT_V(0); WAIT_L(0); BAR; MMA(0, 0, At, B0); MMA(0, 1, At, B1); BAR; SCHED;
;             LDA(At, 1, 1);
;             WAIT_L(0); BAR; MMA(1, 0, At, B0); MMA(1, 1, At, B1); BAR; SCHED;
;         }
;         if (wr == 0) BAR;
	s_nop 1
	ds_read_b128 v[0:3], v153
	ds_read_b128 v[4:7], v153 offset:1024
	ds_read_b128 v[8:11], v153 offset:2048
	ds_read_b128 v[12:15], v153 offset:3072
	ds_read_b128 v[180:183], v154
	ds_read_b128 v[184:187], v154 offset:1024
	ds_read_b128 v[214:217], v154 offset:2048
	ds_read_b128 v[218:221], v154 offset:3072
	ds_read_b128 v[32:35], v149 offset:32768
	ds_read_b128 v[36:39], v149 offset:33792
	ds_read_b128 v[40:43], v150 offset:32768
	ds_read_b128 v[44:47], v150 offset:33792
	ds_read_b128 v[238:241], v151 offset:32768
	ds_read_b128 v[242:245], v151 offset:33792
	ds_read_b128 v[246:249], v152 offset:32768
	ds_read_b128 v[64:67], v152 offset:33792
	s_waitcnt vmcnt(0)
	s_waitcnt lgkmcnt(0)
	s_barrier
	s_setprio 1
	v_mfma_f32_16x16x32_bf16 v[68:71], v[0:3], v[32:35], v[124:127]
	v_mfma_f32_16x16x32_bf16 v[96:99], v[4:7], v[36:39], v[68:71]
	v_mfma_f32_16x16x32_bf16 v[68:71], v[8:11], v[32:35], v[120:123]
	v_mfma_f32_16x16x32_bf16 v[100:103], v[12:15], v[36:39], v[68:71]
	v_mfma_f32_16x16x32_bf16 v[68:71], v[0:3], v[40:43], v[116:119]
	v_mfma_f32_16x16x32_bf16 v[104:107], v[4:7], v[44:47], v[68:71]
	v_mfma_f32_16x16x32_bf16 v[68:71], v[8:11], v[40:43], v[112:115]
	v_mfma_f32_16x16x32_bf16 v[108:111], v[12:15], v[44:47], v[68:71]
	v_mfma_f32_16x16x32_bf16 v[68:71], v[0:3], v[238:241], v[222:225]
	v_mfma_f32_16x16x32_bf16 v[112:115], v[4:7], v[242:245], v[68:71]
	v_mfma_f32_16x16x32_bf16 v[68:71], v[8:11], v[238:241], v[226:229]
	v_mfma_f32_16x16x32_bf16 v[116:119], v[12:15], v[242:245], v[68:71]
	v_mfma_f32_16x16x32_bf16 v[68:71], v[0:3], v[246:249], v[230:233]
	v_mfma_f32_16x16x32_bf16 v[120:123], v[4:7], v[64:67], v[68:71]
	v_mfma_f32_16x16x32_bf16 v[68:71], v[8:11], v[246:249], v[234:237]
	v_mfma_f32_16x16x32_bf16 v[124:127], v[12:15], v[64:67], v[68:71]
	v_mfma_f32_16x16x32_bf16 v[68:71], v[180:183], v[32:35], v[92:95]
	v_mfma_f32_16x16x32_bf16 v[32:35], v[214:217], v[32:35], v[88:91]
	v_mfma_f32_16x16x32_bf16 v[222:225], v[184:187], v[36:39], v[68:71]
	v_mfma_f32_16x16x32_bf16 v[68:71], v[218:221], v[36:39], v[32:35]
	v_mfma_f32_16x16x32_bf16 v[32:35], v[180:183], v[40:43], v[84:87]
	v_mfma_f32_16x16x32_bf16 v[72:75], v[184:187], v[44:47], v[32:35]
	v_mfma_f32_16x16x32_bf16 v[32:35], v[214:217], v[40:43], v[80:83]
	v_mfma_f32_16x16x32_bf16 v[76:79], v[218:221], v[44:47], v[32:35]
	v_mfma_f32_16x16x32_bf16 v[32:35], v[180:183], v[238:241], v[188:191]
	v_mfma_f32_16x16x32_bf16 v[80:83], v[184:187], v[242:245], v[32:35]
	v_mfma_f32_16x16x32_bf16 v[32:35], v[214:217], v[238:241], v[192:195]
	v_mfma_f32_16x16x32_bf16 v[84:87], v[218:221], v[242:245], v[32:35]
	v_mfma_f32_16x16x32_bf16 v[32:35], v[180:183], v[246:249], v[196:199]
	v_mfma_f32_16x16x32_bf16 v[88:91], v[184:187], v[64:67], v[32:35]
	v_mfma_f32_16x16x32_bf16 v[32:35], v[214:217], v[246:249], v[200:203]
	v_mfma_f32_16x16x32_bf16 v[92:95], v[218:221], v[64:67], v[32:35]
	s_setprio 0
	s_barrier
	ds_read_b128 v[64:67], v149 offset:49152
	ds_read_b128 v[188:191], v149 offset:50176
	ds_read_b128 v[192:195], v150 offset:49152
	ds_read_b128 v[196:199], v150 offset:50176
	ds_read_b128 v[200:203], v151 offset:49152
	ds_read_b128 v[226:229], v151 offset:50176
	ds_read_b128 v[230:233], v152 offset:49152
	ds_read_b128 v[234:237], v152 offset:50176
	s_waitcnt lgkmcnt(0)
	s_barrier
	s_setprio 1
	v_mfma_f32_16x16x32_bf16 v[32:35], v[0:3], v[64:67], v[60:63]
	v_mfma_f32_16x16x32_bf16 v[40:43], v[0:3], v[192:195], v[52:55]
	v_mfma_f32_16x16x32_bf16 v[44:47], v[8:11], v[192:195], v[48:51]
	v_mfma_f32_16x16x32_bf16 v[48:51], v[0:3], v[200:203], v[204:207]
	v_mfma_f32_16x16x32_bf16 v[0:3], v[0:3], v[230:233], v[156:159]
	v_mfma_f32_16x16x32_bf16 v[36:39], v[8:11], v[64:67], v[56:59]
	v_mfma_f32_16x16x32_bf16 v[52:55], v[8:11], v[200:203], v[208:211]
	v_mfma_f32_16x16x32_bf16 v[56:59], v[4:7], v[234:237], v[0:3]
	v_mfma_f32_16x16x32_bf16 v[0:3], v[8:11], v[230:233], v[160:163]
	v_mfma_f32_16x16x32_bf16 v[32:35], v[4:7], v[188:191], v[32:35]
	v_mfma_f32_16x16x32_bf16 v[36:39], v[12:15], v[188:191], v[36:39]
	v_mfma_f32_16x16x32_bf16 v[40:43], v[4:7], v[196:199], v[40:43]
	v_mfma_f32_16x16x32_bf16 v[44:47], v[12:15], v[196:199], v[44:47]
	v_mfma_f32_16x16x32_bf16 v[48:51], v[4:7], v[226:229], v[48:51]
	v_mfma_f32_16x16x32_bf16 v[52:55], v[12:15], v[226:229], v[52:55]
	v_mfma_f32_16x16x32_bf16 v[60:63], v[12:15], v[234:237], v[0:3]
	v_mfma_f32_16x16x32_bf16 v[0:3], v[180:183], v[64:67], v[28:31]
	v_mfma_f32_16x16x32_bf16 v[4:7], v[214:217], v[64:67], v[24:27]
	v_mfma_f32_16x16x32_bf16 v[8:11], v[180:183], v[192:195], v[20:23]
	v_mfma_f32_16x16x32_bf16 v[12:15], v[214:217], v[192:195], v[16:19]
	v_mfma_f32_16x16x32_bf16 v[16:19], v[180:183], v[200:203], v[164:167]
	v_mfma_f32_16x16x32_bf16 v[20:23], v[214:217], v[200:203], v[168:171]
	v_mfma_f32_16x16x32_bf16 v[24:27], v[180:183], v[230:233], v[172:175]
	v_mfma_f32_16x16x32_bf16 v[28:31], v[214:217], v[230:233], v[176:179]
	v_mfma_f32_16x16x32_bf16 v[0:3], v[184:187], v[188:191], v[0:3]
	v_mfma_f32_16x16x32_bf16 v[4:7], v[218:221], v[188:191], v[4:7]
	v_mfma_f32_16x16x32_bf16 v[8:11], v[184:187], v[196:199], v[8:11]
	v_mfma_f32_16x16x32_bf16 v[12:15], v[218:221], v[196:199], v[12:15]
	v_mfma_f32_16x16x32_bf16 v[16:19], v[184:187], v[226:229], v[16:19]
	v_mfma_f32_16x16x32_bf16 v[20:23], v[218:221], v[226:229], v[20:23]
	v_mfma_f32_16x16x32_bf16 v[24:27], v[184:187], v[234:237], v[24:27]
	v_mfma_f32_16x16x32_bf16 v[28:31], v[218:221], v[234:237], v[28:31]
	s_setprio 0
	s_barrier
	s_and_saveexec_b64 s[6:7], s[38:39]
	s_cbranch_execz .LBB0_480
	s_barrier
	s_branch .LBB0_480

; #define LDA(dst, b, h) for (int m = 0; m < 4; ++m) for (int k = 0; k < 2; ++k) \
;     dst[m][k] = *reinterpret_cast<const bf16x8*>((char*)SA(b, h) + lds_byte(wr * 64 + m * 16 + fr, k * 32 + fq * 8))
; #define LDB(dst, b, h) for (int n = 0; n < 2; ++n) for (int k = 0; k < 2; ++k) \
;     dst[n][k] = *reinterpret_cast<const bf16x8*>((char*)SB(b, h) + lds_byte(wc * 32 + n * 16 + fr, k * 32 + fq * 8))
; #define MMA(ai, bj, At, Bt_) do { __builtin_amdgcn_s_setprio(1); \
;     for (int m = 0; m < 4; ++m) for (int n = 0; n < 2; ++n) for (int k = 0; k < 2; ++k) \
;       acc[ai][bj][m][n] = __builtin_amdgcn_mfma_f32_16x16x32_bf16(Bt_[n][k], At[m][k], acc[ai][bj][m][n], 0, 0, 0); \
;     __builtin_amdgcn_s_setprio(0); } while (0)
; #define WAIT_V(n) asm volatile("s_waitcnt vmcnt(" #n ")" ::: "memory")
; #define WAIT_L(n) asm volatile("s_waitcnt lgkmcnt(" #n ")" ::: "memory")
; #define BAR __builtin_amdgcn_s_barrier()
; #define SCHED __builtin_amdgcn_sched_barrier(0)
; template <int MODE>
; DI void gemm_phase(const bf16_t* __restrict__ A, const bf16_t* __restrict__ Bt, int M, int N, int K, const Epi& ep) {
;     ...
;             LDB(B0, 0, 0); LDB(B1, 0, 1); SCHED; LDA(At, 0, 0); STAGE(SA(1, 1), rsA, brow + HALF, t + 1);
;             WAIT_V(8); WAIT_L(0); BAR; MMA(0, 0, At, B0); MMA(0, 1, At, B1); BAR; SCHED;
;             LDA(At, 0, 1); STAGE(SB(0, 0), rsB, bcol, t + 2); STAGE(SB(0, 1), rsB, bcol + HALF, t + 2); STAGE(SA(0, 0), rsA, brow, t + 2);
;             WAIT_V(8); WAIT_L(0); BAR; MMA(1, 0, At, B0); MMA(1, 1, At, B1); BAR; SCHED;
.LBB0_558:
	ds_read_b128 v[156:159], v147
	ds_read_b128 v[160:163], v147 offset:1024
	ds_read_b128 v[164:167], v147 offset:2048
	ds_read_b128 v[168:171], v147 offset:3072
	ds_read_b128 v[172:175], v148
	ds_read_b128 v[176:179], v148 offset:1024
	ds_read_b128 v[180:183], v148 offset:2048
	ds_read_b128 v[184:187], v148 offset:3072
	s_add_i32 s40, s27, s31
	v_readfirstlane_b32 s7, v144
	s_add_i32 s6, s40, 0x40080
	s_mov_b32 m0, s7
	v_readfirstlane_b32 s7, v145
	ds_read_b128 v[188:191], v149
	ds_read_b128 v[192:195], v149 offset:1024
	ds_read_b128 v[196:199], v150
	ds_read_b128 v[200:203], v150 offset:1024
	ds_read_b128 v[204:207], v151
	ds_read_b128 v[208:211], v151 offset:1024
	ds_read_b128 v[214:217], v152
	ds_read_b128 v[218:221], v152 offset:1024
	buffer_load_dwordx4 v128, s[8:11], s6 offen lds
	s_mov_b32 m0, s7
	s_nop 0
	buffer_load_dwordx4 v129, s[8:11], s6 offen lds
	s_waitcnt vmcnt(8)
	s_waitcnt lgkmcnt(0)
	s_barrier
	s_setprio 1
	v_mfma_f32_16x16x32_bf16 v[124:127], v[156:159], v[188:191], v[124:127]
	v_mfma_f32_16x16x32_bf16 v[120:123], v[164:167], v[188:191], v[120:123]
	v_mfma_f32_16x16x32_bf16 v[116:119], v[156:159], v[196:199], v[116:119]
	v_mfma_f32_16x16x32_bf16 v[112:115], v[164:167], v[196:199], v[112:115]
	v_mfma_f32_16x16x32_bf16 v[108:111], v[156:159], v[204:207], v[108:111]
	v_mfma_f32_16x16x32_bf16 v[104:107], v[164:167], v[204:207], v[104:107]
	v_mfma_f32_16x16x32_bf16 v[100:103], v[156:159], v[214:217], v[100:103]
	v_mfma_f32_16x16x32_bf16 v[96:99], v[164:167], v[214:217], v[96:99]
	v_mfma_f32_16x16x32_bf16 v[124:127], v[160:163], v[192:195], v[124:127]
	v_mfma_f32_16x16x32_bf16 v[120:123], v[168:171], v[192:195], v[120:123]
	v_mfma_f32_16x16x32_bf16 v[116:119], v[160:163], v[200:203], v[116:119]
	v_mfma_f32_16x16x32_bf16 v[112:115], v[168:171], v[200:203], v[112:115]
	v_mfma_f32_16x16x32_bf16 v[108:111], v[160:163], v[208:211], v[108:111]
	v_mfma_f32_16x16x32_bf16 v[104:107], v[168:171], v[208:211], v[104:107]
	v_mfma_f32_16x16x32_bf16 v[100:103], v[160:163], v[218:221], v[100:103]
	v_mfma_f32_16x16x32_bf16 v[96:99], v[168:171], v[218:221], v[96:99]
	v_mfma_f32_16x16x32_bf16 v[92:95], v[172:175], v[188:191], v[92:95]
	v_mfma_f32_16x16x32_bf16 v[88:91], v[180:183], v[188:191], v[88:91]
	v_mfma_f32_16x16x32_bf16 v[84:87], v[172:175], v[196:199], v[84:87]
	v_mfma_f32_16x16x32_bf16 v[80:83], v[180:183], v[196:199], v[80:83]
	v_mfma_f32_16x16x32_bf16 v[76:79], v[172:175], v[204:207], v[76:79]
	v_mfma_f32_16x16x32_bf16 v[72:75], v[180:183], v[204:207], v[72:75]
	v_mfma_f32_16x16x32_bf16 v[68:71], v[172:175], v[214:217], v[68:71]
	v_mfma_f32_16x16x32_bf16 v[64:67], v[180:183], v[214:217], v[64:67]
	v_mfma_f32_16x16x32_bf16 v[92:95], v[176:179], v[192:195], v[92:95]
	v_mfma_f32_16x16x32_bf16 v[88:91], v[184:187], v[192:195], v[88:91]
	v_mfma_f32_16x16x32_bf16 v[84:87], v[176:179], v[200:203], v[84:87]
	v_mfma_f32_16x16x32_bf16 v[80:83], v[184:187], v[200:203], v[80:83]
	v_mfma_f32_16x16x32_bf16 v[76:79], v[176:179], v[208:211], v[76:79]
	v_mfma_f32_16x16x32_bf16 v[72:75], v[184:187], v[208:211], v[72:75]
	v_mfma_f32_16x16x32_bf16 v[68:71], v[176:179], v[218:221], v[68:71]
	v_mfma_f32_16x16x32_bf16 v[64:67], v[184:187], v[218:221], v[64:67]
	s_setprio 0
	s_barrier
	s_add_i32 s41, s23, s31
	v_readfirstlane_b32 s43, v130
	s_add_i32 s42, s41, 0x100
	s_mov_b32 s6, s10
	s_mov_b32 s7, s11
	s_mov_b32 m0, s43
	v_readfirstlane_b32 s43, v131
	ds_read_b128 v[188:191], v149 offset:16384
	ds_read_b128 v[192:195], v149 offset:17408
	ds_read_b128 v[196:199], v150 offset:16384
	ds_read_b128 v[200:203], v150 offset:17408
	ds_read_b128 v[204:207], v151 offset:16384
	ds_read_b128 v[208:211], v151 offset:17408
	ds_read_b128 v[214:217], v152 offset:16384
	ds_read_b128 v[218:221], v152 offset:17408
	buffer_load_dwordx4 v128, s[4:7], s42 offen lds
	s_mov_b32 m0, s43
	v_readfirstlane_b32 s43, v132
	buffer_load_dwordx4 v129, s[4:7], s42 offen lds
	s_add_i32 s42, s41, 0x40100
	s_mov_b32 m0, s43
	v_readfirstlane_b32 s43, v133
	buffer_load_dwordx4 v128, s[4:7], s42 offen lds
	s_mov_b32 m0, s43
	v_readfirstlane_b32 s43, v134
	buffer_load_dwordx4 v129, s[4:7], s42 offen lds
	s_add_i32 s42, s40, 0x100
	s_mov_b32 m0, s43
	v_readfirstlane_b32 s43, v135
	buffer_load_dwordx4 v128, s[8:11], s42 offen lds
	s_mov_b32 m0, s43
	s_nop 0
	buffer_load_dwordx4 v129, s[8:11], s42 offen lds
	s_waitcnt vmcnt(8)
	s_waitcnt lgkmcnt(0)
	s_barrier
	s_setprio 1
	v_mfma_f32_16x16x32_bf16 v[60:63], v[156:159], v[188:191], v[60:63]
	v_mfma_f32_16x16x32_bf16 v[56:59], v[164:167], v[188:191], v[56:59]
	v_mfma_f32_16x16x32_bf16 v[52:55], v[156:159], v[196:199], v[52:55]
	v_mfma_f32_16x16x32_bf16 v[48:51], v[164:167], v[196:199], v[48:51]
	v_mfma_f32_16x16x32_bf16 v[44:47], v[156:159], v[204:207], v[44:47]
	v_mfma_f32_16x16x32_bf16 v[40:43], v[164:167], v[204:207], v[40:43]
	v_mfma_f32_16x16x32_bf16 v[36:39], v[156:159], v[214:217], v[36:39]
	v_mfma_f32_16x16x32_bf16 v[32:35], v[164:167], v[214:217], v[32:35]
	v_mfma_f32_16x16x32_bf16 v[60:63], v[160:163], v[192:195], v[60:63]
	v_mfma_f32_16x16x32_bf16 v[56:59], v[168:171], v[192:195], v[56:59]
	v_mfma_f32_16x16x32_bf16 v[52:55], v[160:163], v[200:203], v[52:55]
	v_mfma_f32_16x16x32_bf16 v[48:51], v[168:171], v[200:203], v[48:51]
	v_mfma_f32_16x16x32_bf16 v[44:47], v[160:163], v[208:211], v[44:47]
	v_mfma_f32_16x16x32_bf16 v[40:43], v[168:171], v[208:211], v[40:43]
	v_mfma_f32_16x16x32_bf16 v[36:39], v[160:163], v[218:221], v[36:39]
	v_mfma_f32_16x16x32_bf16 v[32:35], v[168:171], v[218:221], v[32:35]
	v_mfma_f32_16x16x32_bf16 v[28:31], v[172:175], v[188:191], v[28:31]
	v_mfma_f32_16x16x32_bf16 v[24:27], v[180:183], v[188:191], v[24:27]
	v_mfma_f32_16x16x32_bf16 v[20:23], v[172:175], v[196:199], v[20:23]
	v_mfma_f32_16x16x32_bf16 v[16:19], v[180:183], v[196:199], v[16:19]
	v_mfma_f32_16x16x32_bf16 v[12:15], v[172:175], v[204:207], v[12:15]
	v_mfma_f32_16x16x32_bf16 v[8:11], v[180:183], v[204:207], v[8:11]
	v_mfma_f32_16x16x32_bf16 v[4:7], v[172:175], v[214:217], v[4:7]
	v_mfma_f32_16x16x32_bf16 v[0:3], v[180:183], v[214:217], v[0:3]
	v_mfma_f32_16x16x32_bf16 v[28:31], v[176:179], v[192:195], v[28:31]
	v_mfma_f32_16x16x32_bf16 v[24:27], v[184:187], v[192:195], v[24:27]
	v_mfma_f32_16x16x32_bf16 v[20:23], v[176:179], v[200:203], v[20:23]
	v_mfma_f32_16x16x32_bf16 v[16:19], v[184:187], v[200:203], v[16:19]
	v_mfma_f32_16x16x32_bf16 v[12:15], v[176:179], v[208:211], v[12:15]
	v_mfma_f32_16x16x32_bf16 v[8:11], v[184:187], v[208:211], v[8:11]
	v_mfma_f32_16x16x32_bf16 v[4:7], v[176:179], v[218:221], v[4:7]
	v_mfma_f32_16x16x32_bf16 v[0:3], v[184:187], v[218:221], v[0:3]
	s_setprio 0
	s_barrier
; #define LDA(dst, b, h) for (int m = 0; m < 4; ++m) for (int k = 0; k < 2; ++k) \
;     dst[m][k] = *reinterpret_cast<const bf16x8*>((char*)SA(b, h) + lds_byte(wr * 64 + m * 16 + fr, k * 32 + fq * 8))
; #define LDB(dst, b, h) for (int n = 0; n < 2; ++n) for (int k = 0; k < 2; ++k) \
;     dst[n][k] = *reinterpret_cast<const bf16x8*>((char*)SB(b, h) + lds_byte(wc * 32 + n * 16 + fr, k * 32 + fq * 8))
; #define MMA(ai, bj, At, Bt_) do { __builtin_amdgcn_s_setprio(1); \
;     for (int m = 0; m < 4; ++m) for (int n = 0; n < 2; ++n) for (int k = 0; k < 2; ++k) \
;       acc[ai][bj][m][n] = __builtin_amdgcn_mfma_f32_16x16x32_bf16(Bt_[n][k], At[m][k], acc[ai][bj][m][n], 0, 0, 0); \
;     __builtin_amdgcn_s_setprio(0); } while (0)
; #define WAIT_V(n) asm volatile("s_waitcnt vmcnt(" #n ")" ::: "memory")
; #define WAIT_L(n) asm volatile("s_waitcnt lgkmcnt(" #n ")" ::: "memory")
; #define BAR __builtin_amdgcn_s_barrier()
; #define SCHED __builtin_amdgcn_sched_barrier(0)
; template <int MODE>
; DI void gemm_phase(const bf16_t* __restrict__ A, const bf16_t* __restrict__ Bt, int M, int N, int K, const Epi& ep) {
;     ...
;             LDB(B0, 1, 0); LDB(B1, 1, 1); SCHED; LDA(At, 1, 0); STAGE(SA(0, 1), rsA, brow + HALF, t + 2);
;             WAIT_V(8); WAIT_L(0); BAR; MMA(0, 0, At, B0); MMA(0, 1, At, B1); BAR; SCHED;
;             LDA(At, 1, 1); STAGE(SB(1, 0), rsB, bcol, t + 3); STAGE(SB(1, 1), rsB, bcol + HALF, t + 3); STAGE(SA(1, 0), rsA, brow, t + 3);
;             WAIT_V(8); WAIT_L(0); BAR; MMA(1, 0, At, B0); MMA(1, 1, At, B1); BAR; SCHED;
	ds_read_b128 v[156:159], v153
	ds_read_b128 v[160:163], v153 offset:1024
	ds_read_b128 v[164:167], v153 offset:2048
	ds_read_b128 v[168:171], v153 offset:3072
	ds_read_b128 v[172:175], v154
	ds_read_b128 v[176:179], v154 offset:1024
	ds_read_b128 v[180:183], v154 offset:2048
	ds_read_b128 v[184:187], v154 offset:3072
	v_readfirstlane_b32 s43, v136
	s_add_i32 s42, s40, 0x40100
	s_mov_b32 m0, s43
	v_readfirstlane_b32 s43, v137
	ds_read_b128 v[188:191], v149 offset:32768
	ds_read_b128 v[192:195], v149 offset:33792
	ds_read_b128 v[196:199], v150 offset:32768
	ds_read_b128 v[200:203], v150 offset:33792
	ds_read_b128 v[204:207], v151 offset:32768
	ds_read_b128 v[208:211], v151 offset:33792
	ds_read_b128 v[214:217], v152 offset:32768
	ds_read_b128 v[218:221], v152 offset:33792
	buffer_load_dwordx4 v128, s[8:11], s42 offen lds
	s_mov_b32 m0, s43
	s_nop 0
	buffer_load_dwordx4 v129, s[8:11], s42 offen lds
	s_waitcnt vmcnt(8)
	s_waitcnt lgkmcnt(0)
	s_barrier
	s_setprio 1
	v_mfma_f32_16x16x32_bf16 v[124:127], v[156:159], v[188:191], v[124:127]
	v_mfma_f32_16x16x32_bf16 v[120:123], v[164:167], v[188:191], v[120:123]
	v_mfma_f32_16x16x32_bf16 v[116:119], v[156:159], v[196:199], v[116:119]
	v_mfma_f32_16x16x32_bf16 v[112:115], v[164:167], v[196:199], v[112:115]
	v_mfma_f32_16x16x32_bf16 v[108:111], v[156:159], v[204:207], v[108:111]
	v_mfma_f32_16x16x32_bf16 v[104:107], v[164:167], v[204:207], v[104:107]
	v_mfma_f32_16x16x32_bf16 v[100:103], v[156:159], v[214:217], v[100:103]
	v_mfma_f32_16x16x32_bf16 v[96:99], v[164:167], v[214:217], v[96:99]
	v_mfma_f32_16x16x32_bf16 v[124:127], v[160:163], v[192:195], v[124:127]
	v_mfma_f32_16x16x32_bf16 v[120:123], v[168:171], v[192:195], v[120:123]
	v_mfma_f32_16x16x32_bf16 v[116:119], v[160:163], v[200:203], v[116:119]
	v_mfma_f32_16x16x32_bf16 v[112:115], v[168:171], v[200:203], v[112:115]
	v_mfma_f32_16x16x32_bf16 v[108:111], v[160:163], v[208:211], v[108:111]
	v_mfma_f32_16x16x32_bf16 v[104:107], v[168:171], v[208:211], v[104:107]
	v_mfma_f32_16x16x32_bf16 v[100:103], v[160:163], v[218:221], v[100:103]
	v_mfma_f32_16x16x32_bf16 v[96:99], v[168:171], v[218:221], v[96:99]
	v_mfma_f32_16x16x32_bf16 v[92:95], v[172:175], v[188:191], v[92:95]
	v_mfma_f32_16x16x32_bf16 v[88:91], v[180:183], v[188:191], v[88:91]
	v_mfma_f32_16x16x32_bf16 v[84:87], v[172:175], v[196:199], v[84:87]
	v_mfma_f32_16x16x32_bf16 v[80:83], v[180:183], v[196:199], v[80:83]
	v_mfma_f32_16x16x32_bf16 v[76:79], v[172:175], v[204:207], v[76:79]
	v_mfma_f32_16x16x32_bf16 v[72:75], v[180:183], v[204:207], v[72:75]
	v_mfma_f32_16x16x32_bf16 v[68:71], v[172:175], v[214:217], v[68:71]
	v_mfma_f32_16x16x32_bf16 v[64:67], v[180:183], v[214:217], v[64:67]
	v_mfma_f32_16x16x32_bf16 v[92:95], v[176:179], v[192:195], v[92:95]
	v_mfma_f32_16x16x32_bf16 v[88:91], v[184:187], v[192:195], v[88:91]
	v_mfma_f32_16x16x32_bf16 v[84:87], v[176:179], v[200:203], v[84:87]
	v_mfma_f32_16x16x32_bf16 v[80:83], v[184:187], v[200:203], v[80:83]
	v_mfma_f32_16x16x32_bf16 v[76:79], v[176:179], v[208:211], v[76:79]
	v_mfma_f32_16x16x32_bf16 v[72:75], v[184:187], v[208:211], v[72:75]
	v_mfma_f32_16x16x32_bf16 v[68:71], v[176:179], v[218:221], v[68:71]
	v_mfma_f32_16x16x32_bf16 v[64:67], v[184:187], v[218:221], v[64:67]
	s_setprio 0
	s_barrier
	v_readfirstlane_b32 s43, v138
	s_add_i32 s42, s41, 0x180
	s_mov_b32 m0, s43
	v_readfirstlane_b32 s43, v139
	ds_read_b128 v[188:191], v149 offset:49152
	ds_read_b128 v[192:195], v149 offset:50176
	ds_read_b128 v[196:199], v150 offset:49152
	ds_read_b128 v[200:203], v150 offset:50176
	ds_read_b128 v[204:207], v151 offset:49152
	ds_read_b128 v[208:211], v151 offset:50176
	ds_read_b128 v[214:217], v152 offset:49152
	ds_read_b128 v[218:221], v152 offset:50176
	buffer_load_dwordx4 v128, s[4:7], s42 offen lds
	s_mov_b32 m0, s43
	s_add_i32 s41, s41, 0x40180
	buffer_load_dwordx4 v129, s[4:7], s42 offen lds
	v_readfirstlane_b32 s42, v142
	s_mov_b32 m0, s42
	v_readfirstlane_b32 s42, v143
	buffer_load_dwordx4 v128, s[4:7], s41 offen lds
	s_mov_b32 m0, s42
	s_addk_i32 s40, 0x180
	buffer_load_dwordx4 v129, s[4:7], s41 offen lds
	v_readfirstlane_b32 s6, v140
	s_mov_b32 m0, s6
	v_readfirstlane_b32 s6, v141
	buffer_load_dwordx4 v128, s[8:11], s40 offen lds
	s_mov_b32 m0, s6
	s_nop 0
	buffer_load_dwordx4 v129, s[8:11], s40 offen lds
	s_waitcnt vmcnt(8)
	s_waitcnt lgkmcnt(0)
	s_barrier
	s_setprio 1
	v_mfma_f32_16x16x32_bf16 v[60:63], v[156:159], v[188:191], v[60:63]
	v_mfma_f32_16x16x32_bf16 v[56:59], v[164:167], v[188:191], v[56:59]
	v_mfma_f32_16x16x32_bf16 v[52:55], v[156:159], v[196:199], v[52:55]
	v_mfma_f32_16x16x32_bf16 v[48:51], v[164:167], v[196:199], v[48:51]
	v_mfma_f32_16x16x32_bf16 v[44:47], v[156:159], v[204:207], v[44:47]
	v_mfma_f32_16x16x32_bf16 v[40:43], v[164:167], v[204:207], v[40:43]
	v_mfma_f32_16x16x32_bf16 v[36:39], v[156:159], v[214:217], v[36:39]
	v_mfma_f32_16x16x32_bf16 v[32:35], v[164:167], v[214:217], v[32:35]
	v_mfma_f32_16x16x32_bf16 v[60:63], v[160:163], v[192:195], v[60:63]
	v_mfma_f32_16x16x32_bf16 v[56:59], v[168:171], v[192:195], v[56:59]
	v_mfma_f32_16x16x32_bf16 v[52:55], v[160:163], v[200:203], v[52:55]
	v_mfma_f32_16x16x32_bf16 v[48:51], v[168:171], v[200:203], v[48:51]
	v_mfma_f32_16x16x32_bf16 v[44:47], v[160:163], v[208:211], v[44:47]
	v_mfma_f32_16x16x32_bf16 v[40:43], v[168:171], v[208:211], v[40:43]
	v_mfma_f32_16x16x32_bf16 v[36:39], v[160:163], v[218:221], v[36:39]
	v_mfma_f32_16x16x32_bf16 v[32:35], v[168:171], v[218:221], v[32:35]
	v_mfma_f32_16x16x32_bf16 v[28:31], v[172:175], v[188:191], v[28:31]
	v_mfma_f32_16x16x32_bf16 v[24:27], v[180:183], v[188:191], v[24:27]
	v_mfma_f32_16x16x32_bf16 v[20:23], v[172:175], v[196:199], v[20:23]
	v_mfma_f32_16x16x32_bf16 v[16:19], v[180:183], v[196:199], v[16:19]
	v_mfma_f32_16x16x32_bf16 v[12:15], v[172:175], v[204:207], v[12:15]
	v_mfma_f32_16x16x32_bf16 v[8:11], v[180:183], v[204:207], v[8:11]
	v_mfma_f32_16x16x32_bf16 v[4:7], v[172:175], v[214:217], v[4:7]
	v_mfma_f32_16x16x32_bf16 v[0:3], v[180:183], v[214:217], v[0:3]
	v_mfma_f32_16x16x32_bf16 v[28:31], v[176:179], v[192:195], v[28:31]
	v_mfma_f32_16x16x32_bf16 v[24:27], v[184:187], v[192:195], v[24:27]
	v_mfma_f32_16x16x32_bf16 v[20:23], v[176:179], v[200:203], v[20:23]
	v_mfma_f32_16x16x32_bf16 v[16:19], v[184:187], v[200:203], v[16:19]
	v_mfma_f32_16x16x32_bf16 v[12:15], v[176:179], v[208:211], v[12:15]
	v_mfma_f32_16x16x32_bf16 v[8:11], v[184:187], v[208:211], v[8:11]
	v_mfma_f32_16x16x32_bf16 v[4:7], v[176:179], v[218:221], v[4:7]
	v_mfma_f32_16x16x32_bf16 v[0:3], v[184:187], v[218:221], v[0:3]
	s_setprio 0
	s_barrier
; #define LDA(dst, b, h) for (int m = 0; m < 4; ++m) for (int k = 0; k < 2; ++k) \
;     dst[m][k] = *reinterpret_cast<const bf16x8*>((char*)SA(b, h) + lds_byte(wr * 64 + m * 16 + fr, k * 32 + fq * 8))
; #define LDB(dst, b, h) for (int n = 0; n < 2; ++n) for (int k = 0; k < 2; ++k) \
;     dst[n][k] = *reinterpret_cast<const bf16x8*>((char*)SB(b, h) + lds_byte(wc * 32 + n * 16 + fr, k * 32 + fq * 8))
; #define MMA(ai, bj, At, Bt_) do { __builtin_amdgcn_s_setprio(1); \
;     for (int m = 0; m < 4; ++m) for (int n = 0; n < 2; ++n) for (int k = 0; k < 2; ++k) \
;       acc[ai][bj][m][n] = __builtin_amdgcn_mfma_f32_16x16x32_bf16(Bt_[n][k], At[m][k], acc[ai][bj][m][n], 0, 0, 0); \
;     __builtin_amdgcn_s_setprio(0); } while (0)
; #define WAIT_V(n) asm volatile("s_waitcnt vmcnt(" #n ")" ::: "memory")
; #define WAIT_L(n) asm volatile("s_waitcnt lgkmcnt(" #n ")" ::: "memory")
; #define BAR __builtin_amdgcn_s_barrier()
; #define SCHED __builtin_amdgcn_sched_barrier(0)
; template <int MODE>
; DI void gemm_phase(const bf16_t* __restrict__ A, const bf16_t* __restrict__ Bt, int M, int N, int K, const Epi& ep) {
;     ...
;         for (int t = 0; t < nt - 2; t += 2) {
;             LDB(B0, 0, 0); LDB(B1, 0, 1); SCHED; LDA(At, 0, 0); STAGE(SA(1, 1), rsA, brow + HALF, t + 1);
;             WAIT_V(8); WAIT_L(0); BAR; MMA(0, 0, At, B0); MMA(0, 1, At, B1); BAR; SCHED;
;             LDA(At, 0, 1); STAGE(SB(0, 0), rsB, bcol, t + 2); STAGE(SB(0, 1), rsB, bcol + HALF, t + 2); STAGE(SA(0, 0), rsA, brow, t + 2);
;             WAIT_V(8); WAIT_L(0); BAR; MMA(1, 0, At, B0); MMA(1, 1, At, B1); BAR; SCHED;
;             LDB(B0, 1, 0); LDB(B1, 1, 1); SCHED; LDA(At, 1, 0); STAGE(SA(0, 1), rsA, brow + HALF, t + 2);
;             WAIT_V(8); WAIT_L(0); BAR; MMA(0, 0, At, B0); MMA(0, 1, At, B1); BAR; SCHED;
;             LDA(At, 1, 1); STAGE(SB(1, 0), rsB, bcol, t + 3); STAGE(SB(1, 1), rsB, bcol + HALF, t + 3); STAGE(SA(1, 0), rsA, brow, t + 3);
;             WAIT_V(8); WAIT_L(0); BAR; MMA(1, 0, At, B0); MMA(1, 1, At, B1); BAR; SCHED;
;         }
;         {
;             LDB(B0, 0, 0); LDB(B1, 0, 1); SCHED; LDA(At, 0, 0); STAGE(SA(1, 1), rsA, brow + HALF, nt - 1);
;             WAIT_V(8); WAIT_L(0); BAR; MMA(0, 0, At, B0); MMA(0, 1, At, B1); BAR; SCHED;
;             LDA(At, 0, 1);
;             WAIT_V(2); WAIT_L(0); BAR; MMA(1, 0, At, B0); MMA(1, 1, At, B1); BAR; SCHED;
	s_add_i32 s30, s30, 2
	s_addk_i32 s31, 0x100
	s_cmp_gt_u32 s30, 11
	s_cbranch_scc0 .LBB0_558
	ds_read_b128 v[164:167], v147
	ds_read_b128 v[168:171], v147 offset:1024
	ds_read_b128 v[172:175], v147 offset:2048
	ds_read_b128 v[176:179], v147 offset:3072
	ds_read_b128 v[180:183], v148
	ds_read_b128 v[184:187], v148 offset:1024
	ds_read_b128 v[188:191], v148 offset:2048
	ds_read_b128 v[192:195], v148 offset:3072
	v_readfirstlane_b32 s7, v144
	s_or_b32 s6, s26, 0x780
	s_mov_b32 m0, s7
	v_readfirstlane_b32 s7, v145
	ds_read_b128 v[196:199], v149
	ds_read_b128 v[200:203], v149 offset:1024
	ds_read_b128 v[214:217], v150
	ds_read_b128 v[218:221], v150 offset:1024
	ds_read_b128 v[222:225], v151
	ds_read_b128 v[226:229], v151 offset:1024
	ds_read_b128 v[230:233], v152
	ds_read_b128 v[234:237], v152 offset:1024
	buffer_load_dwordx4 v128, s[8:11], s6 offen lds
	s_mov_b32 m0, s7
	s_nop 0
	buffer_load_dwordx4 v129, s[8:11], s6 offen lds
	s_waitcnt vmcnt(8)
	s_waitcnt lgkmcnt(0)
	s_barrier
	s_setprio 1
	v_mfma_f32_16x16x32_bf16 v[124:127], v[164:167], v[196:199], v[124:127]
	v_mfma_f32_16x16x32_bf16 v[120:123], v[172:175], v[196:199], v[120:123]
	v_mfma_f32_16x16x32_bf16 v[116:119], v[164:167], v[214:217], v[116:119]
	v_mfma_f32_16x16x32_bf16 v[112:115], v[172:175], v[214:217], v[112:115]
	v_mfma_f32_16x16x32_bf16 v[96:99], v[172:175], v[230:233], v[96:99]
	v_mfma_f32_16x16x32_bf16 v[124:127], v[168:171], v[200:203], v[124:127]
	v_mfma_f32_16x16x32_bf16 v[120:123], v[176:179], v[200:203], v[120:123]
	v_mfma_f32_16x16x32_bf16 v[116:119], v[168:171], v[218:221], v[116:119]
	v_mfma_f32_16x16x32_bf16 v[112:115], v[176:179], v[218:221], v[112:115]
	v_mfma_f32_16x16x32_bf16 v[108:111], v[164:167], v[222:225], v[108:111]
	v_mfma_f32_16x16x32_bf16 v[104:107], v[172:175], v[222:225], v[104:107]
	v_mfma_f32_16x16x32_bf16 v[100:103], v[164:167], v[230:233], v[100:103]
	v_mfma_f32_16x16x32_bf16 v[160:163], v[176:179], v[234:237], v[96:99]
	v_mfma_f32_16x16x32_bf16 v[238:241], v[168:171], v[226:229], v[108:111]
	v_mfma_f32_16x16x32_bf16 v[242:245], v[176:179], v[226:229], v[104:107]
	v_mfma_f32_16x16x32_bf16 v[246:249], v[168:171], v[234:237], v[100:103]
	v_mfma_f32_16x16x32_bf16 v[92:95], v[180:183], v[196:199], v[92:95]
	v_mfma_f32_16x16x32_bf16 v[88:91], v[188:191], v[196:199], v[88:91]
	v_mfma_f32_16x16x32_bf16 v[84:87], v[180:183], v[214:217], v[84:87]
	v_mfma_f32_16x16x32_bf16 v[80:83], v[188:191], v[214:217], v[80:83]
	v_mfma_f32_16x16x32_bf16 v[92:95], v[184:187], v[200:203], v[92:95]
	v_mfma_f32_16x16x32_bf16 v[88:91], v[192:195], v[200:203], v[88:91]
	v_mfma_f32_16x16x32_bf16 v[84:87], v[184:187], v[218:221], v[84:87]
	v_mfma_f32_16x16x32_bf16 v[80:83], v[192:195], v[218:221], v[80:83]
	v_mfma_f32_16x16x32_bf16 v[76:79], v[180:183], v[222:225], v[76:79]
	v_mfma_f32_16x16x32_bf16 v[72:75], v[188:191], v[222:225], v[72:75]
	v_mfma_f32_16x16x32_bf16 v[68:71], v[180:183], v[230:233], v[68:71]
	v_mfma_f32_16x16x32_bf16 v[64:67], v[188:191], v[230:233], v[64:67]
	v_mfma_f32_16x16x32_bf16 v[196:199], v[184:187], v[226:229], v[76:79]
	v_mfma_f32_16x16x32_bf16 v[200:203], v[192:195], v[226:229], v[72:75]
	v_mfma_f32_16x16x32_bf16 v[214:217], v[184:187], v[234:237], v[68:71]
	v_mfma_f32_16x16x32_bf16 v[218:221], v[192:195], v[234:237], v[64:67]
	s_setprio 0
	s_barrier
	s_nop 1
	ds_read_b128 v[64:67], v149 offset:16384
	ds_read_b128 v[68:71], v149 offset:17408
	ds_read_b128 v[72:75], v150 offset:16384
	ds_read_b128 v[76:79], v150 offset:17408
	ds_read_b128 v[96:99], v151 offset:16384
	ds_read_b128 v[100:103], v151 offset:17408
	ds_read_b128 v[104:107], v152 offset:16384
	ds_read_b128 v[108:111], v152 offset:17408
	s_waitcnt vmcnt(2)
	s_waitcnt lgkmcnt(0)
	s_barrier
	s_setprio 1
	v_mfma_f32_16x16x32_bf16 v[60:63], v[164:167], v[64:67], v[60:63]
	v_mfma_f32_16x16x32_bf16 v[56:59], v[172:175], v[64:67], v[56:59]
	v_mfma_f32_16x16x32_bf16 v[52:55], v[164:167], v[72:75], v[52:55]
	v_mfma_f32_16x16x32_bf16 v[48:51], v[172:175], v[72:75], v[48:51]
	v_mfma_f32_16x16x32_bf16 v[60:63], v[168:171], v[68:71], v[60:63]
	v_mfma_f32_16x16x32_bf16 v[56:59], v[176:179], v[68:71], v[56:59]
	v_mfma_f32_16x16x32_bf16 v[52:55], v[168:171], v[76:79], v[52:55]
	v_mfma_f32_16x16x32_bf16 v[48:51], v[176:179], v[76:79], v[48:51]
	v_mfma_f32_16x16x32_bf16 v[44:47], v[164:167], v[96:99], v[44:47]
	v_mfma_f32_16x16x32_bf16 v[40:43], v[172:175], v[96:99], v[40:43]
	v_mfma_f32_16x16x32_bf16 v[36:39], v[164:167], v[104:107], v[36:39]
	v_mfma_f32_16x16x32_bf16 v[32:35], v[172:175], v[104:107], v[32:35]
	v_mfma_f32_16x16x32_bf16 v[222:225], v[168:171], v[100:103], v[44:47]
	v_mfma_f32_16x16x32_bf16 v[226:229], v[176:179], v[100:103], v[40:43]
	v_mfma_f32_16x16x32_bf16 v[164:167], v[168:171], v[108:111], v[36:39]
	v_mfma_f32_16x16x32_bf16 v[168:171], v[176:179], v[108:111], v[32:35]
	v_mfma_f32_16x16x32_bf16 v[28:31], v[180:183], v[64:67], v[28:31]
	v_mfma_f32_16x16x32_bf16 v[24:27], v[188:191], v[64:67], v[24:27]
	v_mfma_f32_16x16x32_bf16 v[20:23], v[180:183], v[72:75], v[20:23]
	v_mfma_f32_16x16x32_bf16 v[16:19], v[188:191], v[72:75], v[16:19]
	v_mfma_f32_16x16x32_bf16 v[28:31], v[184:187], v[68:71], v[28:31]
	v_mfma_f32_16x16x32_bf16 v[24:27], v[192:195], v[68:71], v[24:27]
	v_mfma_f32_16x16x32_bf16 v[20:23], v[184:187], v[76:79], v[20:23]
	v_mfma_f32_16x16x32_bf16 v[16:19], v[192:195], v[76:79], v[16:19]
	v_mfma_f32_16x16x32_bf16 v[12:15], v[180:183], v[96:99], v[12:15]
	v_mfma_f32_16x16x32_bf16 v[8:11], v[188:191], v[96:99], v[8:11]
	v_mfma_f32_16x16x32_bf16 v[4:7], v[180:183], v[104:107], v[4:7]
	v_mfma_f32_16x16x32_bf16 v[0:3], v[188:191], v[104:107], v[0:3]
	v_mfma_f32_16x16x32_bf16 v[172:175], v[184:187], v[100:103], v[12:15]
	v_mfma_f32_16x16x32_bf16 v[176:179], v[192:195], v[100:103], v[8:11]
	v_mfma_f32_16x16x32_bf16 v[180:183], v[184:187], v[108:111], v[4:7]
	v_mfma_f32_16x16x32_bf16 v[184:187], v[192:195], v[108:111], v[0:3]
	s_setprio 0
	s_barrier
; #define LDA(dst, b, h) for (int m = 0; m < 4; ++m) for (int k = 0; k < 2; ++k) \
;     dst[m][k] = *reinterpret_cast<const bf16x8*>((char*)SA(b, h) + lds_byte(wr * 64 + m * 16 + fr, k * 32 + fq * 8))
; #define LDB(dst, b, h) for (int n = 0; n < 2; ++n) for (int k = 0; k < 2; ++k) \
;     dst[n][k] = *reinterpret_cast<const bf16x8*>((char*)SB(b, h) + lds_byte(wc * 32 + n * 16 + fr, k * 32 + fq * 8))
; #define MMA(ai, bj, At, Bt_) do { __builtin_amdgcn_s_setprio(1); \
;     for (int m = 0; m < 4; ++m) for (int n = 0; n < 2; ++n) for (int k = 0; k < 2; ++k) \
;       acc[ai][bj][m][n] = __builtin_amdgcn_mfma_f32_16x16x32_bf16(Bt_[n][k], At[m][k], acc[ai][bj][m][n], 0, 0, 0); \
;     __builtin_amdgcn_s_setprio(0); } while (0)
; #define WAIT_V(n) asm volatile("s_waitcnt vmcnt(" #n ")" ::: "memory")
; #define WAIT_L(n) asm volatile("s_waitcnt lgkmcnt(" #n ")" ::: "memory")
; #define BAR __builtin_amdgcn_s_barrier()
; #define SCHED __builtin_amdgcn_sched_barrier(0)
; template <int MODE>
; DI void gemm_phase(const bf16_t* __restrict__ A, const bf16_t* __restrict__ Bt, int M, int N, int K, const Epi& ep) {
;     ...
;             LDB(B0, 1, 0); LDB(B1, 1, 1); SCHED; LDA(At, 1, 0);
;             WAIT_V(0); WAIT_L(0); BAR; MMA(0, 0, At, B0); MMA(0, 1, At, B1); BAR; SCHED;
;             LDA(At, 1, 1);
;             WAIT_L(0); BAR; MMA(1, 0, At, B0); MMA(1, 1, At, B1); BAR; SCHED;
;         }
;         if (wr == 0) BAR;
	s_nop 1
	ds_read_b128 v[0:3], v153
	ds_read_b128 v[4:7], v153 offset:1024
	ds_read_b128 v[8:11], v153 offset:2048
	ds_read_b128 v[12:15], v153 offset:3072
	ds_read_b128 v[188:191], v154
	ds_read_b128 v[192:195], v154 offset:1024
	ds_read_b128 v[230:233], v154 offset:2048
	ds_read_b128 v[234:237], v154 offset:3072
	ds_read_b128 v[32:35], v149 offset:32768
	ds_read_b128 v[36:39], v149 offset:33792
	ds_read_b128 v[40:43], v150 offset:32768
	ds_read_b128 v[44:47], v150 offset:33792
	ds_read_b128 v[208:211], v151 offset:32768
	ds_read_b128 v[204:207], v151 offset:33792
	ds_read_b128 v[156:159], v152 offset:32768
	ds_read_b128 v[64:67], v152 offset:33792
	s_waitcnt vmcnt(0)
	s_waitcnt lgkmcnt(0)
	s_barrier
	s_setprio 1
	v_mfma_f32_16x16x32_bf16 v[68:71], v[0:3], v[32:35], v[124:127]
	v_mfma_f32_16x16x32_bf16 v[96:99], v[4:7], v[36:39], v[68:71]
	v_mfma_f32_16x16x32_bf16 v[68:71], v[8:11], v[32:35], v[120:123]
	v_mfma_f32_16x16x32_bf16 v[100:103], v[12:15], v[36:39], v[68:71]
	v_mfma_f32_16x16x32_bf16 v[68:71], v[0:3], v[40:43], v[116:119]
	v_mfma_f32_16x16x32_bf16 v[104:107], v[4:7], v[44:47], v[68:71]
	v_mfma_f32_16x16x32_bf16 v[68:71], v[8:11], v[40:43], v[112:115]
	v_mfma_f32_16x16x32_bf16 v[108:111], v[12:15], v[44:47], v[68:71]
	v_mfma_f32_16x16x32_bf16 v[68:71], v[0:3], v[208:211], v[238:241]
	v_mfma_f32_16x16x32_bf16 v[112:115], v[4:7], v[204:207], v[68:71]
	v_mfma_f32_16x16x32_bf16 v[68:71], v[8:11], v[208:211], v[242:245]
	v_mfma_f32_16x16x32_bf16 v[116:119], v[12:15], v[204:207], v[68:71]
	v_mfma_f32_16x16x32_bf16 v[68:71], v[0:3], v[156:159], v[246:249]
	v_mfma_f32_16x16x32_bf16 v[120:123], v[4:7], v[64:67], v[68:71]
	v_mfma_f32_16x16x32_bf16 v[68:71], v[8:11], v[156:159], v[160:163]
	v_mfma_f32_16x16x32_bf16 v[124:127], v[12:15], v[64:67], v[68:71]
	v_mfma_f32_16x16x32_bf16 v[68:71], v[188:191], v[32:35], v[92:95]
	v_mfma_f32_16x16x32_bf16 v[32:35], v[230:233], v[32:35], v[88:91]
	v_mfma_f32_16x16x32_bf16 v[160:163], v[192:195], v[36:39], v[68:71]
	v_mfma_f32_16x16x32_bf16 v[68:71], v[234:237], v[36:39], v[32:35]
	v_mfma_f32_16x16x32_bf16 v[32:35], v[188:191], v[40:43], v[84:87]
	v_mfma_f32_16x16x32_bf16 v[72:75], v[192:195], v[44:47], v[32:35]
	v_mfma_f32_16x16x32_bf16 v[32:35], v[230:233], v[40:43], v[80:83]
	v_mfma_f32_16x16x32_bf16 v[76:79], v[234:237], v[44:47], v[32:35]
	v_mfma_f32_16x16x32_bf16 v[32:35], v[188:191], v[208:211], v[196:199]
	v_mfma_f32_16x16x32_bf16 v[80:83], v[192:195], v[204:207], v[32:35]
	v_mfma_f32_16x16x32_bf16 v[32:35], v[230:233], v[208:211], v[200:203]
	v_mfma_f32_16x16x32_bf16 v[84:87], v[234:237], v[204:207], v[32:35]
	v_mfma_f32_16x16x32_bf16 v[32:35], v[188:191], v[156:159], v[214:217]
	v_mfma_f32_16x16x32_bf16 v[88:91], v[192:195], v[64:67], v[32:35]
	v_mfma_f32_16x16x32_bf16 v[32:35], v[230:233], v[156:159], v[218:221]
	v_mfma_f32_16x16x32_bf16 v[92:95], v[234:237], v[64:67], v[32:35]
	s_setprio 0
	s_barrier
	ds_read_b128 v[64:67], v149 offset:49152
	ds_read_b128 v[156:159], v149 offset:50176
	ds_read_b128 v[196:199], v150 offset:49152
	ds_read_b128 v[200:203], v150 offset:50176
	ds_read_b128 v[204:207], v151 offset:49152
	ds_read_b128 v[208:211], v151 offset:50176
	ds_read_b128 v[214:217], v152 offset:49152
	ds_read_b128 v[218:221], v152 offset:50176
	s_waitcnt lgkmcnt(0)
	s_barrier
	s_setprio 1
	v_mfma_f32_16x16x32_bf16 v[32:35], v[0:3], v[64:67], v[60:63]
	v_mfma_f32_16x16x32_bf16 v[40:43], v[0:3], v[196:199], v[52:55]
	v_mfma_f32_16x16x32_bf16 v[44:47], v[8:11], v[196:199], v[48:51]
	v_mfma_f32_16x16x32_bf16 v[48:51], v[0:3], v[204:207], v[222:225]
	v_mfma_f32_16x16x32_bf16 v[0:3], v[0:3], v[214:217], v[164:167]
	v_mfma_f32_16x16x32_bf16 v[36:39], v[8:11], v[64:67], v[56:59]
	v_mfma_f32_16x16x32_bf16 v[52:55], v[8:11], v[204:207], v[226:229]
	v_mfma_f32_16x16x32_bf16 v[56:59], v[4:7], v[218:221], v[0:3]
	v_mfma_f32_16x16x32_bf16 v[0:3], v[8:11], v[214:217], v[168:171]
	v_mfma_f32_16x16x32_bf16 v[32:35], v[4:7], v[156:159], v[32:35]
	v_mfma_f32_16x16x32_bf16 v[36:39], v[12:15], v[156:159], v[36:39]
	v_mfma_f32_16x16x32_bf16 v[40:43], v[4:7], v[200:203], v[40:43]
	v_mfma_f32_16x16x32_bf16 v[44:47], v[12:15], v[200:203], v[44:47]
	v_mfma_f32_16x16x32_bf16 v[48:51], v[4:7], v[208:211], v[48:51]
	v_mfma_f32_16x16x32_bf16 v[52:55], v[12:15], v[208:211], v[52:55]
	v_mfma_f32_16x16x32_bf16 v[60:63], v[12:15], v[218:221], v[0:3]
	v_mfma_f32_16x16x32_bf16 v[0:3], v[188:191], v[64:67], v[28:31]
	v_mfma_f32_16x16x32_bf16 v[4:7], v[230:233], v[64:67], v[24:27]
	v_mfma_f32_16x16x32_bf16 v[8:11], v[188:191], v[196:199], v[20:23]
	v_mfma_f32_16x16x32_bf16 v[12:15], v[230:233], v[196:199], v[16:19]
	v_mfma_f32_16x16x32_bf16 v[16:19], v[188:191], v[204:207], v[172:175]
	v_mfma_f32_16x16x32_bf16 v[20:23], v[230:233], v[204:207], v[176:179]
	v_mfma_f32_16x16x32_bf16 v[24:27], v[188:191], v[214:217], v[180:183]
	v_mfma_f32_16x16x32_bf16 v[28:31], v[230:233], v[214:217], v[184:187]
	v_mfma_f32_16x16x32_bf16 v[0:3], v[192:195], v[156:159], v[0:3]
	v_mfma_f32_16x16x32_bf16 v[4:7], v[234:237], v[156:159], v[4:7]
	v_mfma_f32_16x16x32_bf16 v[8:11], v[192:195], v[200:203], v[8:11]
	v_mfma_f32_16x16x32_bf16 v[12:15], v[234:237], v[200:203], v[12:15]
	v_mfma_f32_16x16x32_bf16 v[16:19], v[192:195], v[208:211], v[16:19]
	v_mfma_f32_16x16x32_bf16 v[20:23], v[234:237], v[208:211], v[20:23]
	v_mfma_f32_16x16x32_bf16 v[24:27], v[192:195], v[218:221], v[24:27]
	v_mfma_f32_16x16x32_bf16 v[28:31], v[234:237], v[218:221], v[28:31]
	s_setprio 0
	s_barrier
	s_and_saveexec_b64 s[6:7], s[38:39]
	s_cbranch_execz .LBB0_550
	s_barrier
	s_branch .LBB0_550

; #define LDA(dst, b, h) for (int m = 0; m < 4; ++m) for (int k = 0; k < 2; ++k) \
;     dst[m][k] = *reinterpret_cast<const bf16x8*>((char*)SA(b, h) + lds_byte(wr * 64 + m * 16 + fr, k * 32 + fq * 8))
; #define LDB(dst, b, h) for (int n = 0; n < 2; ++n) for (int k = 0; k < 2; ++k) \
;     dst[n][k] = *reinterpret_cast<const bf16x8*>((char*)SB(b, h) + lds_byte(wc * 32 + n * 16 + fr, k * 32 + fq * 8))
; #define MMA(ai, bj, At, Bt_) do { __builtin_amdgcn_s_setprio(1); \
;     for (int m = 0; m < 4; ++m) for (int n = 0; n < 2; ++n) for (int k = 0; k < 2; ++k) \
;       acc[ai][bj][m][n] = __builtin_amdgcn_mfma_f32_16x16x32_bf16(Bt_[n][k], At[m][k], acc[ai][bj][m][n], 0, 0, 0); \
;     __builtin_amdgcn_s_setprio(0); } while (0)
; #define WAIT_V(n) asm volatile("s_waitcnt vmcnt(" #n ")" ::: "memory")
; #define WAIT_L(n) asm volatile("s_waitcnt lgkmcnt(" #n ")" ::: "memory")
; #define BAR __builtin_amdgcn_s_barrier()
; #define SCHED __builtin_amdgcn_sched_barrier(0)
; template <int MODE>
; DI void gemm_phase(const bf16_t* __restrict__ A, const bf16_t* __restrict__ Bt, int M, int N, int K, const Epi& ep) {
;     ...
;         if (wr == 1) BAR;
;         WAIT_V(2); BAR;
;         STAGE(SB(1, 0), rsB, bcol, 1); STAGE(SA(1, 0), rsA, brow, 1); STAGE(SB(1, 1), rsB, bcol + HALF, 1);
;         WAIT_V(6); BAR;
;         for (int t = 0; t < nt - 2; t += 2) {
;             LDB(B0, 0, 0); LDB(B1, 0, 1); SCHED; LDA(At, 0, 0); STAGE(SA(1, 1), rsA, brow + HALF, t + 1);
;             WAIT_V(8); WAIT_L(0); BAR; MMA(0, 0, At, B0); MMA(0, 1, At, B1); BAR; SCHED;
.LBB0_745:
	s_or_b64 exec, exec, s[6:7]
	v_readfirstlane_b32 s45, v141
	v_add_u32_e32 v0, 0x2000, v141
	s_or_b32 s6, s31, 0x80
	s_mov_b32 m0, s45
	v_readfirstlane_b32 s42, v0
	s_waitcnt vmcnt(2)
	s_barrier
	buffer_load_dwordx4 v128, s[20:23], s6 offen lds
	s_mov_b32 m0, s42
	v_add_u32_e32 v0, 0x8000, v134
	buffer_load_dwordx4 v129, s[20:23], s6 offen lds
	v_readfirstlane_b32 s6, v0
	v_add_u32_e32 v0, 0xa000, v134
	s_or_b32 s43, s41, 0x80
	s_mov_b32 m0, s6
	v_readfirstlane_b32 s7, v0
	buffer_load_dwordx4 v128, s[16:19], s43 offen lds
	s_mov_b32 m0, s7
	s_or_b32 s46, s40, 0x80
	buffer_load_dwordx4 v129, s[16:19], s43 offen lds
	v_readfirstlane_b32 s43, v142
	s_mov_b32 m0, s43
	v_readfirstlane_b32 s44, v143
	buffer_load_dwordx4 v128, s[20:23], s46 offen lds
	s_mov_b32 m0, s44
	s_or_b32 s48, s1, 0x80
	buffer_load_dwordx4 v129, s[20:23], s46 offen lds
	s_waitcnt vmcnt(6)
	s_barrier
	ds_read_b128 v[0:3], v146
	ds_read_b128 v[4:7], v146 offset:1024
	ds_read_b128 v[8:11], v146 offset:2048
	ds_read_b128 v[12:15], v146 offset:3072
	ds_read_b128 v[16:19], v147
	s_waitcnt vmcnt(14)
	ds_read_b128 v[20:23], v147 offset:1024
	ds_read_b128 v[24:27], v147 offset:2048
	ds_read_b128 v[28:31], v147 offset:3072
	v_readfirstlane_b32 s46, v144
	s_mov_b32 m0, s46
	v_readfirstlane_b32 s47, v145
	s_waitcnt vmcnt(14)
	ds_read_b128 v[32:35], v148
	ds_read_b128 v[36:39], v148 offset:1024
	ds_read_b128 v[40:43], v149
	ds_read_b128 v[44:47], v149 offset:1024
	ds_read_b128 v[48:51], v150
	ds_read_b128 v[52:55], v150 offset:1024
	ds_read_b128 v[56:59], v151
	ds_read_b128 v[60:63], v151 offset:1024
	buffer_load_dwordx4 v128, s[16:19], s48 offen lds
	s_mov_b32 m0, s47
	s_nop 0
	buffer_load_dwordx4 v129, s[16:19], s48 offen lds
	s_waitcnt vmcnt(8)
	s_waitcnt lgkmcnt(0)
	s_barrier
	s_setprio 1
	v_mfma_f32_16x16x32_bf16 v[64:67], v[0:3], v[32:35], 0
	v_mfma_f32_16x16x32_bf16 v[68:71], v[8:11], v[32:35], 0
	v_mfma_f32_16x16x32_bf16 v[72:75], v[0:3], v[40:43], 0
	v_mfma_f32_16x16x32_bf16 v[76:79], v[8:11], v[40:43], 0
	v_mfma_f32_16x16x32_bf16 v[80:83], v[0:3], v[48:51], 0
	v_mfma_f32_16x16x32_bf16 v[84:87], v[8:11], v[48:51], 0
	v_mfma_f32_16x16x32_bf16 v[88:91], v[0:3], v[56:59], 0
	v_mfma_f32_16x16x32_bf16 v[92:95], v[8:11], v[56:59], 0
	v_mfma_f32_16x16x32_bf16 v[64:67], v[4:7], v[36:39], v[64:67]
	v_mfma_f32_16x16x32_bf16 v[68:71], v[12:15], v[36:39], v[68:71]
	v_mfma_f32_16x16x32_bf16 v[72:75], v[4:7], v[44:47], v[72:75]
	v_mfma_f32_16x16x32_bf16 v[76:79], v[12:15], v[44:47], v[76:79]
	v_mfma_f32_16x16x32_bf16 v[80:83], v[4:7], v[52:55], v[80:83]
	v_mfma_f32_16x16x32_bf16 v[84:87], v[12:15], v[52:55], v[84:87]
	v_mfma_f32_16x16x32_bf16 v[88:91], v[4:7], v[60:63], v[88:91]
	v_mfma_f32_16x16x32_bf16 v[92:95], v[12:15], v[60:63], v[92:95]
	v_mfma_f32_16x16x32_bf16 v[96:99], v[16:19], v[32:35], 0
	v_mfma_f32_16x16x32_bf16 v[32:35], v[24:27], v[32:35], 0
	v_mfma_f32_16x16x32_bf16 v[96:99], v[20:23], v[36:39], v[96:99]
	v_mfma_f32_16x16x32_bf16 v[32:35], v[28:31], v[36:39], v[32:35]
	v_mfma_f32_16x16x32_bf16 v[36:39], v[16:19], v[40:43], 0
	v_mfma_f32_16x16x32_bf16 v[40:43], v[24:27], v[40:43], 0
	v_mfma_f32_16x16x32_bf16 v[36:39], v[20:23], v[44:47], v[36:39]
	v_mfma_f32_16x16x32_bf16 v[40:43], v[28:31], v[44:47], v[40:43]
	v_mfma_f32_16x16x32_bf16 v[44:47], v[16:19], v[48:51], 0
	v_mfma_f32_16x16x32_bf16 v[48:51], v[24:27], v[48:51], 0
	v_mfma_f32_16x16x32_bf16 v[44:47], v[20:23], v[52:55], v[44:47]
	v_mfma_f32_16x16x32_bf16 v[48:51], v[28:31], v[52:55], v[48:51]
	v_mfma_f32_16x16x32_bf16 v[52:55], v[16:19], v[56:59], 0
	v_mfma_f32_16x16x32_bf16 v[56:59], v[24:27], v[56:59], 0
	v_mfma_f32_16x16x32_bf16 v[52:55], v[20:23], v[60:63], v[52:55]
	v_mfma_f32_16x16x32_bf16 v[56:59], v[28:31], v[60:63], v[56:59]
	s_setprio 0
	s_barrier
	v_readfirstlane_b32 s66, v130
	s_or_b32 s49, s31, 0x100
	s_mov_b32 m0, s66
	v_readfirstlane_b32 s48, v131
	ds_read_b128 v[60:63], v148 offset:16384
	ds_read_b128 v[100:103], v148 offset:17408
	ds_read_b128 v[104:107], v149 offset:16384
	ds_read_b128 v[108:111], v149 offset:17408
	ds_read_b128 v[112:115], v150 offset:16384
	ds_read_b128 v[116:119], v150 offset:17408
	ds_read_b128 v[120:123], v151 offset:16384
	ds_read_b128 v[124:127], v151 offset:17408
	buffer_load_dwordx4 v128, s[20:23], s49 offen lds
	s_mov_b32 m0, s48
	s_or_b32 s54, s40, 0x100
	buffer_load_dwordx4 v129, s[20:23], s49 offen lds
	v_readfirstlane_b32 s49, v132
	s_mov_b32 m0, s49
	v_readfirstlane_b32 s50, v133
	buffer_load_dwordx4 v128, s[20:23], s54 offen lds
	s_mov_b32 m0, s50
	s_or_b32 s58, s41, 0x100
	buffer_load_dwordx4 v129, s[20:23], s54 offen lds
	v_readfirstlane_b32 s54, v134
	s_mov_b32 m0, s54
	v_readfirstlane_b32 s55, v135
	buffer_load_dwordx4 v128, s[16:19], s58 offen lds
	s_mov_b32 m0, s55
	s_nop 0
	buffer_load_dwordx4 v129, s[16:19], s58 offen lds
	s_waitcnt vmcnt(8)
	s_waitcnt lgkmcnt(0)
	s_barrier
; #define LDA(dst, b, h) for (int m = 0; m < 4; ++m) for (int k = 0; k < 2; ++k) \
;     dst[m][k] = *reinterpret_cast<const bf16x8*>((char*)SA(b, h) + lds_byte(wr * 64 + m * 16 + fr, k * 32 + fq * 8))
; #define LDB(dst, b, h) for (int n = 0; n < 2; ++n) for (int k = 0; k < 2; ++k) \
;     dst[n][k] = *reinterpret_cast<const bf16x8*>((char*)SB(b, h) + lds_byte(wc * 32 + n * 16 + fr, k * 32 + fq * 8))
; #define MMA(ai, bj, At, Bt_) do { __builtin_amdgcn_s_setprio(1); \
;     for (int m = 0; m < 4; ++m) for (int n = 0; n < 2; ++n) for (int k = 0; k < 2; ++k) \
;       acc[ai][bj][m][n] = __builtin_amdgcn_mfma_f32_16x16x32_bf16(Bt_[n][k], At[m][k], acc[ai][bj][m][n], 0, 0, 0); \
;     __builtin_amdgcn_s_setprio(0); } while (0)
; #define WAIT_V(n) asm volatile("s_waitcnt vmcnt(" #n ")" ::: "memory")
; #define WAIT_L(n) asm volatile("s_waitcnt lgkmcnt(" #n ")" ::: "memory")
; #define BAR __builtin_amdgcn_s_barrier()
; #define SCHED __builtin_amdgcn_sched_barrier(0)
; template <int MODE>
; DI void gemm_phase(const bf16_t* __restrict__ A, const bf16_t* __restrict__ Bt, int M, int N, int K, const Epi& ep) {
;     ...
;             LDA(At, 0, 1); STAGE(SB(0, 0), rsB, bcol, t + 2); STAGE(SB(0, 1), rsB, bcol + HALF, t + 2); STAGE(SA(0, 0), rsA, brow, t + 2);
;             WAIT_V(8); WAIT_L(0); BAR; MMA(1, 0, At, B0); MMA(1, 1, At, B1); BAR; SCHED;
;             LDB(B0, 1, 0); LDB(B1, 1, 1); SCHED; LDA(At, 1, 0); STAGE(SA(0, 1), rsA, brow + HALF, t + 2);
;             WAIT_V(8); WAIT_L(0); BAR; MMA(0, 0, At, B0); MMA(0, 1, At, B1); BAR; SCHED;
	s_setprio 1
	v_mfma_f32_16x16x32_bf16 v[156:159], v[0:3], v[60:63], 0
	v_mfma_f32_16x16x32_bf16 v[164:167], v[0:3], v[104:107], 0
	v_mfma_f32_16x16x32_bf16 v[172:175], v[0:3], v[112:115], 0
	v_mfma_f32_16x16x32_bf16 v[0:3], v[0:3], v[120:123], 0
	v_mfma_f32_16x16x32_bf16 v[156:159], v[4:7], v[100:103], v[156:159]
	v_mfma_f32_16x16x32_bf16 v[164:167], v[4:7], v[108:111], v[164:167]
	v_mfma_f32_16x16x32_bf16 v[172:175], v[4:7], v[116:119], v[172:175]
	v_mfma_f32_16x16x32_bf16 v[0:3], v[4:7], v[124:127], v[0:3]
	v_mfma_f32_16x16x32_bf16 v[4:7], v[8:11], v[120:123], 0
	v_mfma_f32_16x16x32_bf16 v[160:163], v[8:11], v[60:63], 0
	v_mfma_f32_16x16x32_bf16 v[168:171], v[8:11], v[104:107], 0
	v_mfma_f32_16x16x32_bf16 v[176:179], v[8:11], v[112:115], 0
	v_mfma_f32_16x16x32_bf16 v[4:7], v[12:15], v[124:127], v[4:7]
	v_mfma_f32_16x16x32_bf16 v[160:163], v[12:15], v[100:103], v[160:163]
	v_mfma_f32_16x16x32_bf16 v[168:171], v[12:15], v[108:111], v[168:171]
	v_mfma_f32_16x16x32_bf16 v[176:179], v[12:15], v[116:119], v[176:179]
	v_mfma_f32_16x16x32_bf16 v[8:11], v[16:19], v[60:63], 0
	v_mfma_f32_16x16x32_bf16 v[12:15], v[24:27], v[60:63], 0
	v_mfma_f32_16x16x32_bf16 v[8:11], v[20:23], v[100:103], v[8:11]
	v_mfma_f32_16x16x32_bf16 v[12:15], v[28:31], v[100:103], v[12:15]
	v_mfma_f32_16x16x32_bf16 v[60:63], v[16:19], v[104:107], 0
	v_mfma_f32_16x16x32_bf16 v[100:103], v[24:27], v[104:107], 0
	v_mfma_f32_16x16x32_bf16 v[104:107], v[16:19], v[112:115], 0
	v_mfma_f32_16x16x32_bf16 v[16:19], v[16:19], v[120:123], 0
	v_mfma_f32_16x16x32_bf16 v[60:63], v[20:23], v[108:111], v[60:63]
	v_mfma_f32_16x16x32_bf16 v[100:103], v[28:31], v[108:111], v[100:103]
	v_mfma_f32_16x16x32_bf16 v[104:107], v[20:23], v[116:119], v[104:107]
	v_mfma_f32_16x16x32_bf16 v[108:111], v[24:27], v[112:115], 0
	v_mfma_f32_16x16x32_bf16 v[16:19], v[20:23], v[124:127], v[16:19]
	v_mfma_f32_16x16x32_bf16 v[20:23], v[24:27], v[120:123], 0
	v_mfma_f32_16x16x32_bf16 v[108:111], v[28:31], v[116:119], v[108:111]
	v_mfma_f32_16x16x32_bf16 v[20:23], v[28:31], v[124:127], v[20:23]
	s_setprio 0
	s_barrier
	ds_read_b128 v[24:27], v152
	ds_read_b128 v[28:31], v152 offset:1024
	ds_read_b128 v[112:115], v152 offset:2048
	ds_read_b128 v[116:119], v152 offset:3072
	ds_read_b128 v[120:123], v153
	ds_read_b128 v[124:127], v153 offset:1024
	ds_read_b128 v[180:183], v153 offset:2048
	ds_read_b128 v[184:187], v153 offset:3072
	v_readfirstlane_b32 s58, v155
	s_or_b32 s67, s1, 0x100
	s_mov_b32 m0, s58
	v_readfirstlane_b32 s59, v140
	ds_read_b128 v[188:191], v148 offset:32768
	ds_read_b128 v[192:195], v148 offset:33792
	ds_read_b128 v[196:199], v149 offset:32768
	ds_read_b128 v[200:203], v149 offset:33792
	ds_read_b128 v[204:207], v150 offset:32768
	ds_read_b128 v[208:211], v150 offset:33792
	ds_read_b128 v[214:217], v151 offset:32768
	ds_read_b128 v[218:221], v151 offset:33792
	buffer_load_dwordx4 v128, s[16:19], s67 offen lds
	s_mov_b32 m0, s59
	s_nop 0
	buffer_load_dwordx4 v129, s[16:19], s67 offen lds
	s_waitcnt vmcnt(8)
	s_waitcnt lgkmcnt(0)
	s_barrier
	s_setprio 1
	v_mfma_f32_16x16x32_bf16 v[64:67], v[24:27], v[188:191], v[64:67]
	v_mfma_f32_16x16x32_bf16 v[68:71], v[112:115], v[188:191], v[68:71]
	v_mfma_f32_16x16x32_bf16 v[72:75], v[24:27], v[196:199], v[72:75]
	v_mfma_f32_16x16x32_bf16 v[76:79], v[112:115], v[196:199], v[76:79]
	v_mfma_f32_16x16x32_bf16 v[80:83], v[24:27], v[204:207], v[80:83]
	v_mfma_f32_16x16x32_bf16 v[84:87], v[112:115], v[204:207], v[84:87]
	v_mfma_f32_16x16x32_bf16 v[88:91], v[24:27], v[214:217], v[88:91]
	v_mfma_f32_16x16x32_bf16 v[92:95], v[112:115], v[214:217], v[92:95]
	v_mfma_f32_16x16x32_bf16 v[64:67], v[28:31], v[192:195], v[64:67]
	v_mfma_f32_16x16x32_bf16 v[68:71], v[116:119], v[192:195], v[68:71]
	v_mfma_f32_16x16x32_bf16 v[72:75], v[28:31], v[200:203], v[72:75]
	v_mfma_f32_16x16x32_bf16 v[76:79], v[116:119], v[200:203], v[76:79]
	v_mfma_f32_16x16x32_bf16 v[80:83], v[28:31], v[208:211], v[80:83]
	v_mfma_f32_16x16x32_bf16 v[84:87], v[116:119], v[208:211], v[84:87]
	v_mfma_f32_16x16x32_bf16 v[88:91], v[28:31], v[218:221], v[88:91]
	v_mfma_f32_16x16x32_bf16 v[92:95], v[116:119], v[218:221], v[92:95]
	v_mfma_f32_16x16x32_bf16 v[96:99], v[120:123], v[188:191], v[96:99]
	v_mfma_f32_16x16x32_bf16 v[32:35], v[180:183], v[188:191], v[32:35]
	v_mfma_f32_16x16x32_bf16 v[36:39], v[120:123], v[196:199], v[36:39]
	v_mfma_f32_16x16x32_bf16 v[40:43], v[180:183], v[196:199], v[40:43]
	v_mfma_f32_16x16x32_bf16 v[44:47], v[120:123], v[204:207], v[44:47]
	v_mfma_f32_16x16x32_bf16 v[48:51], v[180:183], v[204:207], v[48:51]
	v_mfma_f32_16x16x32_bf16 v[52:55], v[120:123], v[214:217], v[52:55]
	v_mfma_f32_16x16x32_bf16 v[56:59], v[180:183], v[214:217], v[56:59]
	v_mfma_f32_16x16x32_bf16 v[96:99], v[124:127], v[192:195], v[96:99]
	v_mfma_f32_16x16x32_bf16 v[32:35], v[184:187], v[192:195], v[32:35]
	v_mfma_f32_16x16x32_bf16 v[36:39], v[124:127], v[200:203], v[36:39]
	v_mfma_f32_16x16x32_bf16 v[40:43], v[184:187], v[200:203], v[40:43]
	v_mfma_f32_16x16x32_bf16 v[44:47], v[124:127], v[208:211], v[44:47]
	v_mfma_f32_16x16x32_bf16 v[48:51], v[184:187], v[208:211], v[48:51]
	v_mfma_f32_16x16x32_bf16 v[52:55], v[124:127], v[218:221], v[52:55]
	v_mfma_f32_16x16x32_bf16 v[56:59], v[184:187], v[218:221], v[56:59]
	s_setprio 0
	s_barrier
; #define LDA(dst, b, h) for (int m = 0; m < 4; ++m) for (int k = 0; k < 2; ++k) \
;     dst[m][k] = *reinterpret_cast<const bf16x8*>((char*)SA(b, h) + lds_byte(wr * 64 + m * 16 + fr, k * 32 + fq * 8))
; #define LDB(dst, b, h) for (int n = 0; n < 2; ++n) for (int k = 0; k < 2; ++k) \
;     dst[n][k] = *reinterpret_cast<const bf16x8*>((char*)SB(b, h) + lds_byte(wc * 32 + n * 16 + fr, k * 32 + fq * 8))
; #define MMA(ai, bj, At, Bt_) do { __builtin_amdgcn_s_setprio(1); \
;     for (int m = 0; m < 4; ++m) for (int n = 0; n < 2; ++n) for (int k = 0; k < 2; ++k) \
;       acc[ai][bj][m][n] = __builtin_amdgcn_mfma_f32_16x16x32_bf16(Bt_[n][k], At[m][k], acc[ai][bj][m][n], 0, 0, 0); \
;     __builtin_amdgcn_s_setprio(0); } while (0)
; #define WAIT_V(n) asm volatile("s_waitcnt vmcnt(" #n ")" ::: "memory")
; #define WAIT_L(n) asm volatile("s_waitcnt lgkmcnt(" #n ")" ::: "memory")
; #define BAR __builtin_amdgcn_s_barrier()
; #define SCHED __builtin_amdgcn_sched_barrier(0)
; template <int MODE>
; DI void gemm_phase(const bf16_t* __restrict__ A, const bf16_t* __restrict__ Bt, int M, int N, int K, const Epi& ep) {
;     ...
;             LDB(B0, 0, 0); LDB(B1, 0, 1); SCHED; LDA(At, 0, 0); STAGE(SA(1, 1), rsA, brow + HALF, t + 1);
;             WAIT_V(8); WAIT_L(0); BAR; MMA(0, 0, At, B0); MMA(0, 1, At, B1); BAR; SCHED;
;             LDA(At, 0, 1); STAGE(SB(0, 0), rsB, bcol, t + 2); STAGE(SB(0, 1), rsB, bcol + HALF, t + 2); STAGE(SA(0, 0), rsA, brow, t + 2);
;             WAIT_V(8); WAIT_L(0); BAR; MMA(1, 0, At, B0); MMA(1, 1, At, B1); BAR; SCHED;
;             LDB(B0, 1, 0); LDB(B1, 1, 1); SCHED; LDA(At, 1, 0); STAGE(SA(0, 1), rsA, brow + HALF, t + 2);
;             WAIT_V(8); WAIT_L(0); BAR; MMA(0, 0, At, B0); MMA(0, 1, At, B1); BAR; SCHED;
;             LDA(At, 1, 1); STAGE(SB(1, 0), rsB, bcol, t + 3); STAGE(SB(1, 1), rsB, bcol + HALF, t + 3); STAGE(SA(1, 0), rsA, brow, t + 3);
;             WAIT_V(8); WAIT_L(0); BAR; MMA(1, 0, At, B0); MMA(1, 1, At, B1); BAR; SCHED;
	s_mov_b32 m0, s45
	s_or_b32 s67, s31, 0x180
	ds_read_b128 v[188:191], v148 offset:49152
	ds_read_b128 v[192:195], v148 offset:50176
	ds_read_b128 v[196:199], v149 offset:49152
	ds_read_b128 v[200:203], v149 offset:50176
	ds_read_b128 v[204:207], v150 offset:49152
	ds_read_b128 v[208:211], v150 offset:50176
	ds_read_b128 v[214:217], v151 offset:49152
	ds_read_b128 v[218:221], v151 offset:50176
	buffer_load_dwordx4 v128, s[20:23], s67 offen lds
	s_mov_b32 m0, s42
	s_nop 0
	buffer_load_dwordx4 v129, s[20:23], s67 offen lds
	s_or_b32 s67, s40, 0x180
	s_mov_b32 m0, s43
	s_nop 0
	buffer_load_dwordx4 v128, s[20:23], s67 offen lds
	s_mov_b32 m0, s44
	s_nop 0
	buffer_load_dwordx4 v129, s[20:23], s67 offen lds
	s_or_b32 s67, s41, 0x180
	s_mov_b32 m0, s6
	s_nop 0
	buffer_load_dwordx4 v128, s[16:19], s67 offen lds
	s_mov_b32 m0, s7
	s_nop 0
	buffer_load_dwordx4 v129, s[16:19], s67 offen lds
	s_waitcnt vmcnt(8)
	s_waitcnt lgkmcnt(0)
	s_barrier
	s_setprio 1
	v_mfma_f32_16x16x32_bf16 v[0:3], v[24:27], v[214:217], v[0:3]
	v_mfma_f32_16x16x32_bf16 v[4:7], v[112:115], v[214:217], v[4:7]
	v_mfma_f32_16x16x32_bf16 v[156:159], v[24:27], v[188:191], v[156:159]
	v_mfma_f32_16x16x32_bf16 v[160:163], v[112:115], v[188:191], v[160:163]
	v_mfma_f32_16x16x32_bf16 v[164:167], v[24:27], v[196:199], v[164:167]
	v_mfma_f32_16x16x32_bf16 v[168:171], v[112:115], v[196:199], v[168:171]
	v_mfma_f32_16x16x32_bf16 v[172:175], v[24:27], v[204:207], v[172:175]
	v_mfma_f32_16x16x32_bf16 v[176:179], v[112:115], v[204:207], v[176:179]
	v_mfma_f32_16x16x32_bf16 v[0:3], v[28:31], v[218:221], v[0:3]
	v_mfma_f32_16x16x32_bf16 v[4:7], v[116:119], v[218:221], v[4:7]
	v_mfma_f32_16x16x32_bf16 v[156:159], v[28:31], v[192:195], v[156:159]
	v_mfma_f32_16x16x32_bf16 v[160:163], v[116:119], v[192:195], v[160:163]
	v_mfma_f32_16x16x32_bf16 v[164:167], v[28:31], v[200:203], v[164:167]
	v_mfma_f32_16x16x32_bf16 v[168:171], v[116:119], v[200:203], v[168:171]
	v_mfma_f32_16x16x32_bf16 v[172:175], v[28:31], v[208:211], v[172:175]
	v_mfma_f32_16x16x32_bf16 v[176:179], v[116:119], v[208:211], v[176:179]
	v_mfma_f32_16x16x32_bf16 v[8:11], v[120:123], v[188:191], v[8:11]
	v_mfma_f32_16x16x32_bf16 v[12:15], v[180:183], v[188:191], v[12:15]
	v_mfma_f32_16x16x32_bf16 v[24:27], v[120:123], v[196:199], v[60:63]
	v_mfma_f32_16x16x32_bf16 v[28:31], v[180:183], v[196:199], v[100:103]
	v_mfma_f32_16x16x32_bf16 v[60:63], v[120:123], v[204:207], v[104:107]
	v_mfma_f32_16x16x32_bf16 v[100:103], v[180:183], v[204:207], v[108:111]
	v_mfma_f32_16x16x32_bf16 v[16:19], v[120:123], v[214:217], v[16:19]
	v_mfma_f32_16x16x32_bf16 v[20:23], v[180:183], v[214:217], v[20:23]
	v_mfma_f32_16x16x32_bf16 v[8:11], v[124:127], v[192:195], v[8:11]
	v_mfma_f32_16x16x32_bf16 v[12:15], v[184:187], v[192:195], v[12:15]
	v_mfma_f32_16x16x32_bf16 v[24:27], v[124:127], v[200:203], v[24:27]
	v_mfma_f32_16x16x32_bf16 v[28:31], v[184:187], v[200:203], v[28:31]
	v_mfma_f32_16x16x32_bf16 v[60:63], v[124:127], v[208:211], v[60:63]
	v_mfma_f32_16x16x32_bf16 v[100:103], v[184:187], v[208:211], v[100:103]
	v_mfma_f32_16x16x32_bf16 v[16:19], v[124:127], v[218:221], v[16:19]
	v_mfma_f32_16x16x32_bf16 v[20:23], v[184:187], v[218:221], v[20:23]
	s_setprio 0
	s_barrier
	ds_read_b128 v[104:107], v146
	ds_read_b128 v[108:111], v146 offset:1024
	ds_read_b128 v[112:115], v146 offset:2048
	ds_read_b128 v[116:119], v146 offset:3072
	ds_read_b128 v[120:123], v147
	ds_read_b128 v[124:127], v147 offset:1024
	ds_read_b128 v[180:183], v147 offset:2048
	ds_read_b128 v[184:187], v147 offset:3072
	s_or_b32 s67, s1, 0x180
	s_mov_b32 m0, s46
	ds_read_b128 v[188:191], v148
	ds_read_b128 v[192:195], v148 offset:1024
	ds_read_b128 v[196:199], v149
	ds_read_b128 v[200:203], v149 offset:1024
	ds_read_b128 v[204:207], v150
	ds_read_b128 v[208:211], v150 offset:1024
	ds_read_b128 v[214:217], v151
	ds_read_b128 v[218:221], v151 offset:1024
	buffer_load_dwordx4 v128, s[16:19], s67 offen lds
	s_mov_b32 m0, s47
	s_nop 0
	buffer_load_dwordx4 v129, s[16:19], s67 offen lds
	s_waitcnt vmcnt(8)
	s_waitcnt lgkmcnt(0)
	s_barrier
	s_setprio 1
	v_mfma_f32_16x16x32_bf16 v[64:67], v[104:107], v[188:191], v[64:67]
	v_mfma_f32_16x16x32_bf16 v[68:71], v[112:115], v[188:191], v[68:71]
	v_mfma_f32_16x16x32_bf16 v[72:75], v[104:107], v[196:199], v[72:75]
	v_mfma_f32_16x16x32_bf16 v[76:79], v[112:115], v[196:199], v[76:79]
	v_mfma_f32_16x16x32_bf16 v[80:83], v[104:107], v[204:207], v[80:83]
	v_mfma_f32_16x16x32_bf16 v[84:87], v[112:115], v[204:207], v[84:87]
	v_mfma_f32_16x16x32_bf16 v[88:91], v[104:107], v[214:217], v[88:91]
	v_mfma_f32_16x16x32_bf16 v[92:95], v[112:115], v[214:217], v[92:95]
	v_mfma_f32_16x16x32_bf16 v[64:67], v[108:111], v[192:195], v[64:67]
	v_mfma_f32_16x16x32_bf16 v[68:71], v[116:119], v[192:195], v[68:71]
	v_mfma_f32_16x16x32_bf16 v[72:75], v[108:111], v[200:203], v[72:75]
	v_mfma_f32_16x16x32_bf16 v[76:79], v[116:119], v[200:203], v[76:79]
	v_mfma_f32_16x16x32_bf16 v[80:83], v[108:111], v[208:211], v[80:83]
	v_mfma_f32_16x16x32_bf16 v[84:87], v[116:119], v[208:211], v[84:87]
	v_mfma_f32_16x16x32_bf16 v[88:91], v[108:111], v[218:221], v[88:91]
	v_mfma_f32_16x16x32_bf16 v[92:95], v[116:119], v[218:221], v[92:95]
	v_mfma_f32_16x16x32_bf16 v[96:99], v[120:123], v[188:191], v[96:99]
	v_mfma_f32_16x16x32_bf16 v[32:35], v[180:183], v[188:191], v[32:35]
	v_mfma_f32_16x16x32_bf16 v[36:39], v[120:123], v[196:199], v[36:39]
	v_mfma_f32_16x16x32_bf16 v[40:43], v[180:183], v[196:199], v[40:43]
	v_mfma_f32_16x16x32_bf16 v[44:47], v[120:123], v[204:207], v[44:47]
	v_mfma_f32_16x16x32_bf16 v[48:51], v[180:183], v[204:207], v[48:51]
	v_mfma_f32_16x16x32_bf16 v[52:55], v[120:123], v[214:217], v[52:55]
	v_mfma_f32_16x16x32_bf16 v[56:59], v[180:183], v[214:217], v[56:59]
	v_mfma_f32_16x16x32_bf16 v[96:99], v[124:127], v[192:195], v[96:99]
	v_mfma_f32_16x16x32_bf16 v[32:35], v[184:187], v[192:195], v[32:35]
	v_mfma_f32_16x16x32_bf16 v[36:39], v[124:127], v[200:203], v[36:39]
	v_mfma_f32_16x16x32_bf16 v[40:43], v[184:187], v[200:203], v[40:43]
	v_mfma_f32_16x16x32_bf16 v[44:47], v[124:127], v[208:211], v[44:47]
	v_mfma_f32_16x16x32_bf16 v[48:51], v[184:187], v[208:211], v[48:51]
	v_mfma_f32_16x16x32_bf16 v[52:55], v[124:127], v[218:221], v[52:55]
	v_mfma_f32_16x16x32_bf16 v[56:59], v[184:187], v[218:221], v[56:59]
	s_setprio 0
	s_barrier
; #define LDA(dst, b, h) for (int m = 0; m < 4; ++m) for (int k = 0; k < 2; ++k) \
;     dst[m][k] = *reinterpret_cast<const bf16x8*>((char*)SA(b, h) + lds_byte(wr * 64 + m * 16 + fr, k * 32 + fq * 8))
; #define LDB(dst, b, h) for (int n = 0; n < 2; ++n) for (int k = 0; k < 2; ++k) \
;     dst[n][k] = *reinterpret_cast<const bf16x8*>((char*)SB(b, h) + lds_byte(wc * 32 + n * 16 + fr, k * 32 + fq * 8))
; #define MMA(ai, bj, At, Bt_) do { __builtin_amdgcn_s_setprio(1); \
;     for (int m = 0; m < 4; ++m) for (int n = 0; n < 2; ++n) for (int k = 0; k < 2; ++k) \
;       acc[ai][bj][m][n] = __builtin_amdgcn_mfma_f32_16x16x32_bf16(Bt_[n][k], At[m][k], acc[ai][bj][m][n], 0, 0, 0); \
;     __builtin_amdgcn_s_setprio(0); } while (0)
; #define WAIT_V(n) asm volatile("s_waitcnt vmcnt(" #n ")" ::: "memory")
; #define WAIT_L(n) asm volatile("s_waitcnt lgkmcnt(" #n ")" ::: "memory")
; #define BAR __builtin_amdgcn_s_barrier()
; #define SCHED __builtin_amdgcn_sched_barrier(0)
; template <int MODE>
; DI void gemm_phase(const bf16_t* __restrict__ A, const bf16_t* __restrict__ Bt, int M, int N, int K, const Epi& ep) {
;     ...
;             LDA(At, 0, 1); STAGE(SB(0, 0), rsB, bcol, t + 2); STAGE(SB(0, 1), rsB, bcol + HALF, t + 2); STAGE(SA(0, 0), rsA, brow, t + 2);
;             WAIT_V(8); WAIT_L(0); BAR; MMA(1, 0, At, B0); MMA(1, 1, At, B1); BAR; SCHED;
;             LDB(B0, 1, 0); LDB(B1, 1, 1); SCHED; LDA(At, 1, 0); STAGE(SA(0, 1), rsA, brow + HALF, t + 2);
;             WAIT_V(8); WAIT_L(0); BAR; MMA(0, 0, At, B0); MMA(0, 1, At, B1); BAR; SCHED;
	s_mov_b32 m0, s66
	s_or_b32 s46, s31, 0x200
	ds_read_b128 v[188:191], v148 offset:16384
	ds_read_b128 v[192:195], v148 offset:17408
	ds_read_b128 v[196:199], v149 offset:16384
	ds_read_b128 v[200:203], v149 offset:17408
	ds_read_b128 v[204:207], v150 offset:16384
	ds_read_b128 v[208:211], v150 offset:17408
	ds_read_b128 v[214:217], v151 offset:16384
	ds_read_b128 v[218:221], v151 offset:17408
	buffer_load_dwordx4 v128, s[20:23], s46 offen lds
	s_mov_b32 m0, s48
	s_nop 0
	buffer_load_dwordx4 v129, s[20:23], s46 offen lds
	s_or_b32 s46, s40, 0x200
	s_mov_b32 m0, s49
	s_nop 0
	buffer_load_dwordx4 v128, s[20:23], s46 offen lds
	s_mov_b32 m0, s50
	s_nop 0
	buffer_load_dwordx4 v129, s[20:23], s46 offen lds
	s_or_b32 s46, s41, 0x200
	s_mov_b32 m0, s54
	s_nop 0
	buffer_load_dwordx4 v128, s[16:19], s46 offen lds
	s_mov_b32 m0, s55
	s_nop 0
	buffer_load_dwordx4 v129, s[16:19], s46 offen lds
	s_waitcnt vmcnt(8)
	s_waitcnt lgkmcnt(0)
	s_barrier
	s_setprio 1
	v_mfma_f32_16x16x32_bf16 v[0:3], v[104:107], v[214:217], v[0:3]
	v_mfma_f32_16x16x32_bf16 v[4:7], v[112:115], v[214:217], v[4:7]
	v_mfma_f32_16x16x32_bf16 v[156:159], v[104:107], v[188:191], v[156:159]
	v_mfma_f32_16x16x32_bf16 v[160:163], v[112:115], v[188:191], v[160:163]
	v_mfma_f32_16x16x32_bf16 v[164:167], v[104:107], v[196:199], v[164:167]
	v_mfma_f32_16x16x32_bf16 v[168:171], v[112:115], v[196:199], v[168:171]
	v_mfma_f32_16x16x32_bf16 v[172:175], v[104:107], v[204:207], v[172:175]
	v_mfma_f32_16x16x32_bf16 v[176:179], v[112:115], v[204:207], v[176:179]
	v_mfma_f32_16x16x32_bf16 v[0:3], v[108:111], v[218:221], v[0:3]
	v_mfma_f32_16x16x32_bf16 v[4:7], v[116:119], v[218:221], v[4:7]
	v_mfma_f32_16x16x32_bf16 v[156:159], v[108:111], v[192:195], v[156:159]
	v_mfma_f32_16x16x32_bf16 v[160:163], v[116:119], v[192:195], v[160:163]
	v_mfma_f32_16x16x32_bf16 v[164:167], v[108:111], v[200:203], v[164:167]
	v_mfma_f32_16x16x32_bf16 v[168:171], v[116:119], v[200:203], v[168:171]
	v_mfma_f32_16x16x32_bf16 v[172:175], v[108:111], v[208:211], v[172:175]
	v_mfma_f32_16x16x32_bf16 v[176:179], v[116:119], v[208:211], v[176:179]
	v_mfma_f32_16x16x32_bf16 v[8:11], v[120:123], v[188:191], v[8:11]
	v_mfma_f32_16x16x32_bf16 v[12:15], v[180:183], v[188:191], v[12:15]
	v_mfma_f32_16x16x32_bf16 v[24:27], v[120:123], v[196:199], v[24:27]
	v_mfma_f32_16x16x32_bf16 v[28:31], v[180:183], v[196:199], v[28:31]
	v_mfma_f32_16x16x32_bf16 v[60:63], v[120:123], v[204:207], v[60:63]
	v_mfma_f32_16x16x32_bf16 v[100:103], v[180:183], v[204:207], v[100:103]
	v_mfma_f32_16x16x32_bf16 v[16:19], v[120:123], v[214:217], v[16:19]
	v_mfma_f32_16x16x32_bf16 v[20:23], v[180:183], v[214:217], v[20:23]
	v_mfma_f32_16x16x32_bf16 v[8:11], v[124:127], v[192:195], v[8:11]
	v_mfma_f32_16x16x32_bf16 v[12:15], v[184:187], v[192:195], v[12:15]
	v_mfma_f32_16x16x32_bf16 v[24:27], v[124:127], v[200:203], v[24:27]
	v_mfma_f32_16x16x32_bf16 v[28:31], v[184:187], v[200:203], v[28:31]
	v_mfma_f32_16x16x32_bf16 v[60:63], v[124:127], v[208:211], v[60:63]
	v_mfma_f32_16x16x32_bf16 v[100:103], v[184:187], v[208:211], v[100:103]
	v_mfma_f32_16x16x32_bf16 v[16:19], v[124:127], v[218:221], v[16:19]
	v_mfma_f32_16x16x32_bf16 v[20:23], v[184:187], v[218:221], v[20:23]
	s_setprio 0
	s_barrier
	ds_read_b128 v[104:107], v152
	ds_read_b128 v[108:111], v152 offset:1024
	ds_read_b128 v[112:115], v152 offset:2048
	ds_read_b128 v[116:119], v152 offset:3072
	ds_read_b128 v[120:123], v153
	ds_read_b128 v[124:127], v153 offset:1024
	ds_read_b128 v[180:183], v153 offset:2048
	ds_read_b128 v[184:187], v153 offset:3072
	s_or_b32 s46, s1, 0x200
	s_mov_b32 m0, s58
	ds_read_b128 v[188:191], v148 offset:32768
	ds_read_b128 v[192:195], v148 offset:33792
	ds_read_b128 v[196:199], v149 offset:32768
	ds_read_b128 v[200:203], v149 offset:33792
	ds_read_b128 v[204:207], v150 offset:32768
	ds_read_b128 v[208:211], v150 offset:33792
	ds_read_b128 v[214:217], v151 offset:32768
	ds_read_b128 v[218:221], v151 offset:33792
	buffer_load_dwordx4 v128, s[16:19], s46 offen lds
	s_mov_b32 m0, s59
	s_nop 0
	buffer_load_dwordx4 v129, s[16:19], s46 offen lds
	s_waitcnt vmcnt(8)
	s_waitcnt lgkmcnt(0)
	s_barrier
	s_setprio 1
	v_mfma_f32_16x16x32_bf16 v[64:67], v[104:107], v[188:191], v[64:67]
	v_mfma_f32_16x16x32_bf16 v[68:71], v[112:115], v[188:191], v[68:71]
	v_mfma_f32_16x16x32_bf16 v[72:75], v[104:107], v[196:199], v[72:75]
	v_mfma_f32_16x16x32_bf16 v[76:79], v[112:115], v[196:199], v[76:79]
	v_mfma_f32_16x16x32_bf16 v[80:83], v[104:107], v[204:207], v[80:83]
	v_mfma_f32_16x16x32_bf16 v[84:87], v[112:115], v[204:207], v[84:87]
	v_mfma_f32_16x16x32_bf16 v[88:91], v[104:107], v[214:217], v[88:91]
	v_mfma_f32_16x16x32_bf16 v[92:95], v[112:115], v[214:217], v[92:95]
	v_mfma_f32_16x16x32_bf16 v[64:67], v[108:111], v[192:195], v[64:67]
	v_mfma_f32_16x16x32_bf16 v[68:71], v[116:119], v[192:195], v[68:71]
	v_mfma_f32_16x16x32_bf16 v[72:75], v[108:111], v[200:203], v[72:75]
	v_mfma_f32_16x16x32_bf16 v[76:79], v[116:119], v[200:203], v[76:79]
	v_mfma_f32_16x16x32_bf16 v[80:83], v[108:111], v[208:211], v[80:83]
	v_mfma_f32_16x16x32_bf16 v[84:87], v[116:119], v[208:211], v[84:87]
	v_mfma_f32_16x16x32_bf16 v[88:91], v[108:111], v[218:221], v[88:91]
	v_mfma_f32_16x16x32_bf16 v[92:95], v[116:119], v[218:221], v[92:95]
	v_mfma_f32_16x16x32_bf16 v[96:99], v[120:123], v[188:191], v[96:99]
	v_mfma_f32_16x16x32_bf16 v[32:35], v[180:183], v[188:191], v[32:35]
	v_mfma_f32_16x16x32_bf16 v[36:39], v[120:123], v[196:199], v[36:39]
	v_mfma_f32_16x16x32_bf16 v[40:43], v[180:183], v[196:199], v[40:43]
	v_mfma_f32_16x16x32_bf16 v[44:47], v[120:123], v[204:207], v[44:47]
	v_mfma_f32_16x16x32_bf16 v[48:51], v[180:183], v[204:207], v[48:51]
	v_mfma_f32_16x16x32_bf16 v[52:55], v[120:123], v[214:217], v[52:55]
	v_mfma_f32_16x16x32_bf16 v[56:59], v[180:183], v[214:217], v[56:59]
	v_mfma_f32_16x16x32_bf16 v[96:99], v[124:127], v[192:195], v[96:99]
	v_mfma_f32_16x16x32_bf16 v[32:35], v[184:187], v[192:195], v[32:35]
	v_mfma_f32_16x16x32_bf16 v[36:39], v[124:127], v[200:203], v[36:39]
	v_mfma_f32_16x16x32_bf16 v[40:43], v[184:187], v[200:203], v[40:43]
	v_mfma_f32_16x16x32_bf16 v[44:47], v[124:127], v[208:211], v[44:47]
	v_mfma_f32_16x16x32_bf16 v[48:51], v[184:187], v[208:211], v[48:51]
	v_mfma_f32_16x16x32_bf16 v[52:55], v[124:127], v[218:221], v[52:55]
	v_mfma_f32_16x16x32_bf16 v[56:59], v[184:187], v[218:221], v[56:59]
	s_setprio 0
	s_barrier
; #define LDA(dst, b, h) for (int m = 0; m < 4; ++m) for (int k = 0; k < 2; ++k) \
;     dst[m][k] = *reinterpret_cast<const bf16x8*>((char*)SA(b, h) + lds_byte(wr * 64 + m * 16 + fr, k * 32 + fq * 8))
; #define LDB(dst, b, h) for (int n = 0; n < 2; ++n) for (int k = 0; k < 2; ++k) \
;     dst[n][k] = *reinterpret_cast<const bf16x8*>((char*)SB(b, h) + lds_byte(wc * 32 + n * 16 + fr, k * 32 + fq * 8))
; #define MMA(ai, bj, At, Bt_) do { __builtin_amdgcn_s_setprio(1); \
;     for (int m = 0; m < 4; ++m) for (int n = 0; n < 2; ++n) for (int k = 0; k < 2; ++k) \
;       acc[ai][bj][m][n] = __builtin_amdgcn_mfma_f32_16x16x32_bf16(Bt_[n][k], At[m][k], acc[ai][bj][m][n], 0, 0, 0); \
;     __builtin_amdgcn_s_setprio(0); } while (0)
; #define WAIT_V(n) asm volatile("s_waitcnt vmcnt(" #n ")" ::: "memory")
; #define WAIT_L(n) asm volatile("s_waitcnt lgkmcnt(" #n ")" ::: "memory")
; #define BAR __builtin_amdgcn_s_barrier()
; #define SCHED __builtin_amdgcn_sched_barrier(0)
; template <int MODE>
; DI void gemm_phase(const bf16_t* __restrict__ A, const bf16_t* __restrict__ Bt, int M, int N, int K, const Epi& ep) {
;     ...
;             LDA(At, 1, 1); STAGE(SB(1, 0), rsB, bcol, t + 3); STAGE(SB(1, 1), rsB, bcol + HALF, t + 3); STAGE(SA(1, 0), rsA, brow, t + 3);
;             WAIT_V(8); WAIT_L(0); BAR; MMA(1, 0, At, B0); MMA(1, 1, At, B1); BAR; SCHED;
;         }
;         {
;             LDB(B0, 0, 0); LDB(B1, 0, 1); SCHED; LDA(At, 0, 0); STAGE(SA(1, 1), rsA, brow + HALF, nt - 1);
;             WAIT_V(8); WAIT_L(0); BAR; MMA(0, 0, At, B0); MMA(0, 1, At, B1); BAR; SCHED;
	s_mov_b32 m0, s45
	s_or_b32 s31, s31, 0x280
	ds_read_b128 v[188:191], v148 offset:49152
	ds_read_b128 v[192:195], v148 offset:50176
	ds_read_b128 v[196:199], v149 offset:49152
	ds_read_b128 v[200:203], v149 offset:50176
	ds_read_b128 v[204:207], v150 offset:49152
	ds_read_b128 v[208:211], v150 offset:50176
	ds_read_b128 v[214:217], v151 offset:49152
	ds_read_b128 v[218:221], v151 offset:50176
	buffer_load_dwordx4 v128, s[20:23], s31 offen lds
	s_mov_b32 m0, s42
	s_nop 0
	buffer_load_dwordx4 v129, s[20:23], s31 offen lds
	s_or_b32 s31, s40, 0x280
	s_mov_b32 m0, s43
	s_nop 0
	buffer_load_dwordx4 v128, s[20:23], s31 offen lds
	s_mov_b32 m0, s44
	s_nop 0
	buffer_load_dwordx4 v129, s[20:23], s31 offen lds
	s_or_b32 s22, s41, 0x280
	s_mov_b32 m0, s6
	s_nop 0
	buffer_load_dwordx4 v128, s[16:19], s22 offen lds
	s_mov_b32 m0, s7
	s_nop 0
	buffer_load_dwordx4 v129, s[16:19], s22 offen lds
	s_waitcnt vmcnt(8)
	s_waitcnt lgkmcnt(0)
	s_barrier
	s_setprio 1
	v_mfma_f32_16x16x32_bf16 v[0:3], v[104:107], v[214:217], v[0:3]
	v_mfma_f32_16x16x32_bf16 v[4:7], v[112:115], v[214:217], v[4:7]
	v_mfma_f32_16x16x32_bf16 v[156:159], v[104:107], v[188:191], v[156:159]
	v_mfma_f32_16x16x32_bf16 v[160:163], v[112:115], v[188:191], v[160:163]
	v_mfma_f32_16x16x32_bf16 v[164:167], v[104:107], v[196:199], v[164:167]
	v_mfma_f32_16x16x32_bf16 v[168:171], v[112:115], v[196:199], v[168:171]
	v_mfma_f32_16x16x32_bf16 v[172:175], v[104:107], v[204:207], v[172:175]
	v_mfma_f32_16x16x32_bf16 v[176:179], v[112:115], v[204:207], v[176:179]
	v_mfma_f32_16x16x32_bf16 v[0:3], v[108:111], v[218:221], v[0:3]
	v_mfma_f32_16x16x32_bf16 v[4:7], v[116:119], v[218:221], v[4:7]
	v_mfma_f32_16x16x32_bf16 v[156:159], v[108:111], v[192:195], v[156:159]
	v_mfma_f32_16x16x32_bf16 v[160:163], v[116:119], v[192:195], v[160:163]
	v_mfma_f32_16x16x32_bf16 v[164:167], v[108:111], v[200:203], v[164:167]
	v_mfma_f32_16x16x32_bf16 v[168:171], v[116:119], v[200:203], v[168:171]
	v_mfma_f32_16x16x32_bf16 v[172:175], v[108:111], v[208:211], v[172:175]
	v_mfma_f32_16x16x32_bf16 v[176:179], v[116:119], v[208:211], v[176:179]
	v_mfma_f32_16x16x32_bf16 v[8:11], v[120:123], v[188:191], v[8:11]
	v_mfma_f32_16x16x32_bf16 v[12:15], v[180:183], v[188:191], v[12:15]
	v_mfma_f32_16x16x32_bf16 v[24:27], v[120:123], v[196:199], v[24:27]
	v_mfma_f32_16x16x32_bf16 v[28:31], v[180:183], v[196:199], v[28:31]
	v_mfma_f32_16x16x32_bf16 v[60:63], v[120:123], v[204:207], v[60:63]
	v_mfma_f32_16x16x32_bf16 v[100:103], v[180:183], v[204:207], v[100:103]
	v_mfma_f32_16x16x32_bf16 v[16:19], v[120:123], v[214:217], v[16:19]
	v_mfma_f32_16x16x32_bf16 v[20:23], v[180:183], v[214:217], v[20:23]
	v_mfma_f32_16x16x32_bf16 v[8:11], v[124:127], v[192:195], v[8:11]
	v_mfma_f32_16x16x32_bf16 v[12:15], v[184:187], v[192:195], v[12:15]
	v_mfma_f32_16x16x32_bf16 v[24:27], v[124:127], v[200:203], v[24:27]
	v_mfma_f32_16x16x32_bf16 v[28:31], v[184:187], v[200:203], v[28:31]
	v_mfma_f32_16x16x32_bf16 v[60:63], v[124:127], v[208:211], v[60:63]
	v_mfma_f32_16x16x32_bf16 v[100:103], v[184:187], v[208:211], v[100:103]
	v_mfma_f32_16x16x32_bf16 v[16:19], v[124:127], v[218:221], v[16:19]
	v_mfma_f32_16x16x32_bf16 v[20:23], v[184:187], v[218:221], v[20:23]
	s_setprio 0
	s_barrier
	ds_read_b128 v[104:107], v146
	ds_read_b128 v[108:111], v146 offset:1024
	ds_read_b128 v[112:115], v146 offset:2048
	ds_read_b128 v[116:119], v146 offset:3072
	ds_read_b128 v[120:123], v147
	ds_read_b128 v[124:127], v147 offset:1024
	ds_read_b128 v[180:183], v147 offset:2048
	ds_read_b128 v[184:187], v147 offset:3072
	v_readfirstlane_b32 s6, v144
	s_or_b32 s1, s1, 0x280
	s_mov_b32 m0, s6
	v_readfirstlane_b32 s6, v145
	ds_read_b128 v[188:191], v148
	ds_read_b128 v[192:195], v148 offset:1024
	ds_read_b128 v[196:199], v149
	ds_read_b128 v[200:203], v149 offset:1024
	ds_read_b128 v[204:207], v150
	ds_read_b128 v[208:211], v150 offset:1024
	ds_read_b128 v[214:217], v151
	ds_read_b128 v[218:221], v151 offset:1024
	buffer_load_dwordx4 v128, s[16:19], s1 offen lds
	s_mov_b32 m0, s6
	s_nop 0
	buffer_load_dwordx4 v129, s[16:19], s1 offen lds
	s_waitcnt vmcnt(8)
	s_waitcnt lgkmcnt(0)
	s_barrier
	s_setprio 1
	v_mfma_f32_16x16x32_bf16 v[64:67], v[104:107], v[188:191], v[64:67]
	v_mfma_f32_16x16x32_bf16 v[68:71], v[112:115], v[188:191], v[68:71]
	v_mfma_f32_16x16x32_bf16 v[72:75], v[104:107], v[196:199], v[72:75]
	v_mfma_f32_16x16x32_bf16 v[76:79], v[112:115], v[196:199], v[76:79]
	v_mfma_f32_16x16x32_bf16 v[80:83], v[104:107], v[204:207], v[80:83]
	v_mfma_f32_16x16x32_bf16 v[84:87], v[112:115], v[204:207], v[84:87]
	v_mfma_f32_16x16x32_bf16 v[88:91], v[104:107], v[214:217], v[88:91]
	v_mfma_f32_16x16x32_bf16 v[92:95], v[112:115], v[214:217], v[92:95]
	v_mfma_f32_16x16x32_bf16 v[64:67], v[108:111], v[192:195], v[64:67]
	v_mfma_f32_16x16x32_bf16 v[68:71], v[116:119], v[192:195], v[68:71]
	v_mfma_f32_16x16x32_bf16 v[72:75], v[108:111], v[200:203], v[72:75]
	v_mfma_f32_16x16x32_bf16 v[76:79], v[116:119], v[200:203], v[76:79]
	v_mfma_f32_16x16x32_bf16 v[80:83], v[108:111], v[208:211], v[80:83]
	v_mfma_f32_16x16x32_bf16 v[84:87], v[116:119], v[208:211], v[84:87]
	v_mfma_f32_16x16x32_bf16 v[88:91], v[108:111], v[218:221], v[88:91]
	v_mfma_f32_16x16x32_bf16 v[92:95], v[116:119], v[218:221], v[92:95]
	v_mfma_f32_16x16x32_bf16 v[32:35], v[180:183], v[188:191], v[32:35]
	v_mfma_f32_16x16x32_bf16 v[36:39], v[120:123], v[196:199], v[36:39]
	v_mfma_f32_16x16x32_bf16 v[40:43], v[180:183], v[196:199], v[40:43]
	v_mfma_f32_16x16x32_bf16 v[44:47], v[120:123], v[204:207], v[44:47]
	v_mfma_f32_16x16x32_bf16 v[48:51], v[180:183], v[204:207], v[48:51]
	v_mfma_f32_16x16x32_bf16 v[52:55], v[120:123], v[214:217], v[52:55]
	v_mfma_f32_16x16x32_bf16 v[56:59], v[180:183], v[214:217], v[56:59]
	v_mfma_f32_16x16x32_bf16 v[96:99], v[120:123], v[188:191], v[96:99]
	v_mfma_f32_16x16x32_bf16 v[32:35], v[184:187], v[192:195], v[32:35]
	v_mfma_f32_16x16x32_bf16 v[36:39], v[124:127], v[200:203], v[36:39]
	v_mfma_f32_16x16x32_bf16 v[40:43], v[184:187], v[200:203], v[40:43]
	v_mfma_f32_16x16x32_bf16 v[44:47], v[124:127], v[208:211], v[44:47]
	v_mfma_f32_16x16x32_bf16 v[48:51], v[184:187], v[208:211], v[48:51]
	v_mfma_f32_16x16x32_bf16 v[52:55], v[124:127], v[218:221], v[52:55]
	v_mfma_f32_16x16x32_bf16 v[56:59], v[184:187], v[218:221], v[56:59]
	v_mfma_f32_16x16x32_bf16 v[222:225], v[124:127], v[192:195], v[96:99]
	s_setprio 0
	s_barrier
; #define LDA(dst, b, h) for (int m = 0; m < 4; ++m) for (int k = 0; k < 2; ++k) \
;     dst[m][k] = *reinterpret_cast<const bf16x8*>((char*)SA(b, h) + lds_byte(wr * 64 + m * 16 + fr, k * 32 + fq * 8))
; #define LDB(dst, b, h) for (int n = 0; n < 2; ++n) for (int k = 0; k < 2; ++k) \
;     dst[n][k] = *reinterpret_cast<const bf16x8*>((char*)SB(b, h) + lds_byte(wc * 32 + n * 16 + fr, k * 32 + fq * 8))
; #define MMA(ai, bj, At, Bt_) do { __builtin_amdgcn_s_setprio(1); \
;     for (int m = 0; m < 4; ++m) for (int n = 0; n < 2; ++n) for (int k = 0; k < 2; ++k) \
;       acc[ai][bj][m][n] = __builtin_amdgcn_mfma_f32_16x16x32_bf16(Bt_[n][k], At[m][k], acc[ai][bj][m][n], 0, 0, 0); \
;     __builtin_amdgcn_s_setprio(0); } while (0)
; #define WAIT_V(n) asm volatile("s_waitcnt vmcnt(" #n ")" ::: "memory")
; #define WAIT_L(n) asm volatile("s_waitcnt lgkmcnt(" #n ")" ::: "memory")
; #define BAR __builtin_amdgcn_s_barrier()
; #define SCHED __builtin_amdgcn_sched_barrier(0)
; template <int MODE>
; DI void gemm_phase(const bf16_t* __restrict__ A, const bf16_t* __restrict__ Bt, int M, int N, int K, const Epi& ep) {
;     ...
;             LDA(At, 0, 1);
;             WAIT_V(2); WAIT_L(0); BAR; MMA(1, 0, At, B0); MMA(1, 1, At, B1); BAR; SCHED;
;             LDB(B0, 1, 0); LDB(B1, 1, 1); SCHED; LDA(At, 1, 0);
	s_nop 0
	ds_read_b128 v[96:99], v148 offset:16384
	ds_read_b128 v[188:191], v148 offset:17408
	ds_read_b128 v[192:195], v149 offset:16384
	ds_read_b128 v[196:199], v149 offset:17408
	ds_read_b128 v[200:203], v150 offset:16384
	ds_read_b128 v[204:207], v150 offset:17408
	ds_read_b128 v[208:211], v151 offset:16384
	ds_read_b128 v[214:217], v151 offset:17408
	s_waitcnt vmcnt(2)
	s_waitcnt lgkmcnt(0)
	s_barrier
	s_setprio 1
	v_mfma_f32_16x16x32_bf16 v[0:3], v[104:107], v[208:211], v[0:3]
	v_mfma_f32_16x16x32_bf16 v[4:7], v[112:115], v[208:211], v[4:7]
	v_mfma_f32_16x16x32_bf16 v[156:159], v[104:107], v[96:99], v[156:159]
	v_mfma_f32_16x16x32_bf16 v[160:163], v[112:115], v[96:99], v[160:163]
	v_mfma_f32_16x16x32_bf16 v[164:167], v[104:107], v[192:195], v[164:167]
	v_mfma_f32_16x16x32_bf16 v[168:171], v[112:115], v[192:195], v[168:171]
	v_mfma_f32_16x16x32_bf16 v[172:175], v[104:107], v[200:203], v[172:175]
	v_mfma_f32_16x16x32_bf16 v[176:179], v[112:115], v[200:203], v[176:179]
	v_mfma_f32_16x16x32_bf16 v[0:3], v[108:111], v[214:217], v[0:3]
	v_mfma_f32_16x16x32_bf16 v[4:7], v[116:119], v[214:217], v[4:7]
	v_mfma_f32_16x16x32_bf16 v[156:159], v[108:111], v[188:191], v[156:159]
	v_mfma_f32_16x16x32_bf16 v[160:163], v[116:119], v[188:191], v[160:163]
	v_mfma_f32_16x16x32_bf16 v[164:167], v[108:111], v[196:199], v[164:167]
	v_mfma_f32_16x16x32_bf16 v[168:171], v[116:119], v[196:199], v[168:171]
	v_mfma_f32_16x16x32_bf16 v[172:175], v[108:111], v[204:207], v[172:175]
	v_mfma_f32_16x16x32_bf16 v[176:179], v[116:119], v[204:207], v[176:179]
	v_mfma_f32_16x16x32_bf16 v[8:11], v[120:123], v[96:99], v[8:11]
	v_mfma_f32_16x16x32_bf16 v[12:15], v[180:183], v[96:99], v[12:15]
	v_mfma_f32_16x16x32_bf16 v[24:27], v[120:123], v[192:195], v[24:27]
	v_mfma_f32_16x16x32_bf16 v[28:31], v[180:183], v[192:195], v[28:31]
	v_mfma_f32_16x16x32_bf16 v[60:63], v[120:123], v[200:203], v[60:63]
	v_mfma_f32_16x16x32_bf16 v[16:19], v[120:123], v[208:211], v[16:19]
	v_mfma_f32_16x16x32_bf16 v[8:11], v[124:127], v[188:191], v[8:11]
	v_mfma_f32_16x16x32_bf16 v[12:15], v[184:187], v[188:191], v[12:15]
	v_mfma_f32_16x16x32_bf16 v[24:27], v[124:127], v[196:199], v[24:27]
	v_mfma_f32_16x16x32_bf16 v[28:31], v[184:187], v[196:199], v[28:31]
	v_mfma_f32_16x16x32_bf16 v[188:191], v[124:127], v[204:207], v[60:63]
	v_mfma_f32_16x16x32_bf16 v[60:63], v[180:183], v[200:203], v[100:103]
	v_mfma_f32_16x16x32_bf16 v[196:199], v[124:127], v[214:217], v[16:19]
	v_mfma_f32_16x16x32_bf16 v[16:19], v[180:183], v[208:211], v[20:23]
	v_mfma_f32_16x16x32_bf16 v[192:195], v[184:187], v[204:207], v[60:63]
	v_mfma_f32_16x16x32_bf16 v[180:183], v[184:187], v[214:217], v[16:19]
	s_setprio 0
	s_barrier
	s_nop 3
	ds_read_b128 v[16:19], v152
	ds_read_b128 v[20:23], v152 offset:1024
	ds_read_b128 v[60:63], v152 offset:2048
	ds_read_b128 v[184:187], v152 offset:3072
	ds_read_b128 v[200:203], v153
	ds_read_b128 v[204:207], v153 offset:1024
	ds_read_b128 v[208:211], v153 offset:2048
	ds_read_b128 v[214:217], v153 offset:3072
	ds_read_b128 v[218:221], v148 offset:32768
	ds_read_b128 v[226:229], v148 offset:33792
	ds_read_b128 v[230:233], v149 offset:32768
	ds_read_b128 v[234:237], v149 offset:33792
	ds_read_b128 v[238:241], v150 offset:32768
	ds_read_b128 v[242:245], v150 offset:33792
	ds_read_b128 v[246:249], v151 offset:32768
	ds_read_b128 v[136:139], v151 offset:33792
	s_waitcnt vmcnt(0)
	s_waitcnt lgkmcnt(0)
	s_barrier
; #define LDA(dst, b, h) for (int m = 0; m < 4; ++m) for (int k = 0; k < 2; ++k) \
;     dst[m][k] = *reinterpret_cast<const bf16x8*>((char*)SA(b, h) + lds_byte(wr * 64 + m * 16 + fr, k * 32 + fq * 8))
; #define MMA(ai, bj, At, Bt_) do { __builtin_amdgcn_s_setprio(1); \
;     for (int m = 0; m < 4; ++m) for (int n = 0; n < 2; ++n) for (int k = 0; k < 2; ++k) \
;       acc[ai][bj][m][n] = __builtin_amdgcn_mfma_f32_16x16x32_bf16(Bt_[n][k], At[m][k], acc[ai][bj][m][n], 0, 0, 0); \
;     __builtin_amdgcn_s_setprio(0); } while (0)
; #define WAIT_V(n) asm volatile("s_waitcnt vmcnt(" #n ")" ::: "memory")
; #define WAIT_L(n) asm volatile("s_waitcnt lgkmcnt(" #n ")" ::: "memory")
; #define BAR __builtin_amdgcn_s_barrier()
; #define SCHED __builtin_amdgcn_sched_barrier(0)
; template <int MODE>
; DI void gemm_phase(const bf16_t* __restrict__ A, const bf16_t* __restrict__ Bt, int M, int N, int K, const Epi& ep) {
;     ...
;             WAIT_V(0); WAIT_L(0); BAR; MMA(0, 0, At, B0); MMA(0, 1, At, B1); BAR; SCHED;
;             LDA(At, 1, 1);
;             WAIT_L(0); BAR; MMA(1, 0, At, B0); MMA(1, 1, At, B1); BAR; SCHED;
;         }
;         if (wr == 0) BAR;
	s_setprio 1
	v_mfma_f32_16x16x32_bf16 v[64:67], v[16:19], v[218:221], v[64:67]
	v_mfma_f32_16x16x32_bf16 v[96:99], v[20:23], v[226:229], v[64:67]
	v_mfma_f32_16x16x32_bf16 v[64:67], v[60:63], v[218:221], v[68:71]
	v_mfma_f32_16x16x32_bf16 v[100:103], v[184:187], v[226:229], v[64:67]
	v_mfma_f32_16x16x32_bf16 v[64:67], v[16:19], v[230:233], v[72:75]
	v_mfma_f32_16x16x32_bf16 v[104:107], v[20:23], v[234:237], v[64:67]
	v_mfma_f32_16x16x32_bf16 v[64:67], v[60:63], v[230:233], v[76:79]
	v_mfma_f32_16x16x32_bf16 v[108:111], v[184:187], v[234:237], v[64:67]
	v_mfma_f32_16x16x32_bf16 v[64:67], v[16:19], v[238:241], v[80:83]
	v_mfma_f32_16x16x32_bf16 v[112:115], v[20:23], v[242:245], v[64:67]
	v_mfma_f32_16x16x32_bf16 v[64:67], v[60:63], v[238:241], v[84:87]
	v_mfma_f32_16x16x32_bf16 v[116:119], v[184:187], v[242:245], v[64:67]
	v_mfma_f32_16x16x32_bf16 v[64:67], v[16:19], v[246:249], v[88:91]
	v_mfma_f32_16x16x32_bf16 v[120:123], v[20:23], v[136:139], v[64:67]
	v_mfma_f32_16x16x32_bf16 v[64:67], v[60:63], v[246:249], v[92:95]
	v_mfma_f32_16x16x32_bf16 v[124:127], v[184:187], v[136:139], v[64:67]
	v_mfma_f32_16x16x32_bf16 v[32:35], v[208:211], v[218:221], v[32:35]
	v_mfma_f32_16x16x32_bf16 v[68:71], v[214:217], v[226:229], v[32:35]
	v_mfma_f32_16x16x32_bf16 v[32:35], v[200:203], v[230:233], v[36:39]
	v_mfma_f32_16x16x32_bf16 v[72:75], v[204:207], v[234:237], v[32:35]
	v_mfma_f32_16x16x32_bf16 v[32:35], v[208:211], v[230:233], v[40:43]
	v_mfma_f32_16x16x32_bf16 v[76:79], v[214:217], v[234:237], v[32:35]
	v_mfma_f32_16x16x32_bf16 v[32:35], v[200:203], v[238:241], v[44:47]
	v_mfma_f32_16x16x32_bf16 v[80:83], v[204:207], v[242:245], v[32:35]
	v_mfma_f32_16x16x32_bf16 v[32:35], v[208:211], v[238:241], v[48:51]
	v_mfma_f32_16x16x32_bf16 v[84:87], v[214:217], v[242:245], v[32:35]
	v_mfma_f32_16x16x32_bf16 v[32:35], v[200:203], v[246:249], v[52:55]
	v_mfma_f32_16x16x32_bf16 v[64:67], v[200:203], v[218:221], v[222:225]
	v_mfma_f32_16x16x32_bf16 v[88:91], v[204:207], v[136:139], v[32:35]
	v_mfma_f32_16x16x32_bf16 v[32:35], v[208:211], v[246:249], v[56:59]
	v_mfma_f32_16x16x32_bf16 v[64:67], v[204:207], v[226:229], v[64:67]
	v_mfma_f32_16x16x32_bf16 v[92:95], v[214:217], v[136:139], v[32:35]
	s_setprio 0
	s_barrier
	ds_read_b128 v[136:139], v148 offset:49152
	ds_read_b128 v[218:221], v148 offset:50176
	ds_read_b128 v[222:225], v149 offset:49152
	ds_read_b128 v[226:229], v149 offset:50176
	ds_read_b128 v[230:233], v150 offset:49152
	ds_read_b128 v[234:237], v150 offset:50176
	ds_read_b128 v[238:241], v151 offset:49152
	ds_read_b128 v[242:245], v151 offset:50176
	s_waitcnt lgkmcnt(0)
	s_barrier
	s_setprio 1
	v_mfma_f32_16x16x32_bf16 v[0:3], v[16:19], v[238:241], v[0:3]
	v_mfma_f32_16x16x32_bf16 v[32:35], v[16:19], v[136:139], v[156:159]
	v_mfma_f32_16x16x32_bf16 v[36:39], v[60:63], v[136:139], v[160:163]
	v_mfma_f32_16x16x32_bf16 v[40:43], v[16:19], v[222:225], v[164:167]
	v_mfma_f32_16x16x32_bf16 v[44:47], v[60:63], v[222:225], v[168:171]
	v_mfma_f32_16x16x32_bf16 v[48:51], v[16:19], v[230:233], v[172:175]
	v_mfma_f32_16x16x32_bf16 v[52:55], v[60:63], v[230:233], v[176:179]
	v_mfma_f32_16x16x32_bf16 v[56:59], v[20:23], v[242:245], v[0:3]
	v_mfma_f32_16x16x32_bf16 v[0:3], v[60:63], v[238:241], v[4:7]
	v_mfma_f32_16x16x32_bf16 v[32:35], v[20:23], v[218:221], v[32:35]
	v_mfma_f32_16x16x32_bf16 v[36:39], v[184:187], v[218:221], v[36:39]
	v_mfma_f32_16x16x32_bf16 v[40:43], v[20:23], v[226:229], v[40:43]
	v_mfma_f32_16x16x32_bf16 v[44:47], v[184:187], v[226:229], v[44:47]
	v_mfma_f32_16x16x32_bf16 v[48:51], v[20:23], v[234:237], v[48:51]
	v_mfma_f32_16x16x32_bf16 v[52:55], v[184:187], v[234:237], v[52:55]
	v_mfma_f32_16x16x32_bf16 v[60:63], v[184:187], v[242:245], v[0:3]
	v_mfma_f32_16x16x32_bf16 v[0:3], v[200:203], v[136:139], v[8:11]
	v_mfma_f32_16x16x32_bf16 v[4:7], v[208:211], v[136:139], v[12:15]
	v_mfma_f32_16x16x32_bf16 v[8:11], v[200:203], v[222:225], v[24:27]
	v_mfma_f32_16x16x32_bf16 v[12:15], v[208:211], v[222:225], v[28:31]
	v_mfma_f32_16x16x32_bf16 v[16:19], v[200:203], v[230:233], v[188:191]
	v_mfma_f32_16x16x32_bf16 v[20:23], v[208:211], v[230:233], v[192:195]
	v_mfma_f32_16x16x32_bf16 v[24:27], v[200:203], v[238:241], v[196:199]
	v_mfma_f32_16x16x32_bf16 v[28:31], v[208:211], v[238:241], v[180:183]
	v_mfma_f32_16x16x32_bf16 v[0:3], v[204:207], v[218:221], v[0:3]
	v_mfma_f32_16x16x32_bf16 v[4:7], v[214:217], v[218:221], v[4:7]
	v_mfma_f32_16x16x32_bf16 v[8:11], v[204:207], v[226:229], v[8:11]
	v_mfma_f32_16x16x32_bf16 v[12:15], v[214:217], v[226:229], v[12:15]
	v_mfma_f32_16x16x32_bf16 v[16:19], v[204:207], v[234:237], v[16:19]
	v_mfma_f32_16x16x32_bf16 v[20:23], v[214:217], v[234:237], v[20:23]
	v_mfma_f32_16x16x32_bf16 v[24:27], v[204:207], v[242:245], v[24:27]
	v_mfma_f32_16x16x32_bf16 v[28:31], v[214:217], v[242:245], v[28:31]
	s_setprio 0
	s_barrier
	s_and_saveexec_b64 s[6:7], s[38:39]
	s_cbranch_execz .LBB0_747
	s_barrier

; #define LDA(dst, b, h) for (int m = 0; m < 4; ++m) for (int k = 0; k < 2; ++k) \
;     dst[m][k] = *reinterpret_cast<const bf16x8*>((char*)SA(b, h) + lds_byte(wr * 64 + m * 16 + fr, k * 32 + fq * 8))
; #define LDB(dst, b, h) for (int n = 0; n < 2; ++n) for (int k = 0; k < 2; ++k) \
;     dst[n][k] = *reinterpret_cast<const bf16x8*>((char*)SB(b, h) + lds_byte(wc * 32 + n * 16 + fr, k * 32 + fq * 8))
; #define MMA(ai, bj, At, Bt_) do { __builtin_amdgcn_s_setprio(1); \
;     for (int m = 0; m < 4; ++m) for (int n = 0; n < 2; ++n) for (int k = 0; k < 2; ++k) \
;       acc[ai][bj][m][n] = __builtin_amdgcn_mfma_f32_16x16x32_bf16(Bt_[n][k], At[m][k], acc[ai][bj][m][n], 0, 0, 0); \
;     __builtin_amdgcn_s_setprio(0); } while (0)
; #define WAIT_V(n) asm volatile("s_waitcnt vmcnt(" #n ")" ::: "memory")
; #define WAIT_L(n) asm volatile("s_waitcnt lgkmcnt(" #n ")" ::: "memory")
; #define BAR __builtin_amdgcn_s_barrier()
; #define SCHED __builtin_amdgcn_sched_barrier(0)
; template <int MODE>
; DI void gemm_phase(const bf16_t* __restrict__ A, const bf16_t* __restrict__ Bt, int M, int N, int K, const Epi& ep) {
;     ...
;         if (wr == 1) BAR;
;         WAIT_V(2); BAR;
;         STAGE(SB(1, 0), rsB, bcol, 1); STAGE(SA(1, 0), rsA, brow, 1); STAGE(SB(1, 1), rsB, bcol + HALF, 1);
;         WAIT_V(6); BAR;
;         for (int t = 0; t < nt - 2; t += 2) {
;             LDB(B0, 0, 0); LDB(B1, 0, 1); SCHED; LDA(At, 0, 0); STAGE(SA(1, 1), rsA, brow + HALF, t + 1);
;             WAIT_V(8); WAIT_L(0); BAR; MMA(0, 0, At, B0); MMA(0, 1, At, B1); BAR; SCHED;
.LBB0_816:
	s_or_b64 exec, exec, s[0:1]
	v_readfirstlane_b32 s27, v141
	v_readlane_b32 s88, v254, 38
	v_add_u32_e32 v0, 0x2000, v141
	s_or_b32 s0, s38, 0x80
	s_mov_b32 m0, s27
	v_readlane_b32 s89, v254, 39
	v_readlane_b32 s90, v254, 40
	v_readlane_b32 s91, v254, 41
	v_readfirstlane_b32 s15, v0
	v_add_u32_e32 v0, 0x8000, v134
	s_waitcnt vmcnt(2)
	s_barrier
	v_readfirstlane_b32 s7, v0
	s_nop 0
	buffer_load_dwordx4 v128, s[88:91], s0 offen lds
	s_mov_b32 m0, s15
	v_readlane_b32 s44, v254, 34
	v_add_u32_e32 v0, 0xa000, v134
	buffer_load_dwordx4 v129, s[88:91], s0 offen lds
	s_or_b32 s0, s6, 0x80
	s_mov_b32 m0, s7
	v_readlane_b32 s45, v254, 35
	v_readlane_b32 s46, v254, 36
	v_readlane_b32 s47, v254, 37
	v_readfirstlane_b32 s14, v0
	v_readfirstlane_b32 s26, v142
	v_readfirstlane_b32 s30, v143
	s_or_b32 s39, s6, 0x10080
	s_or_b32 s40, s38, 0x10100
	buffer_load_dwordx4 v128, s[44:47], s0 offen lds
	s_mov_b32 m0, s14
	s_or_b32 s41, s6, 0x10100
	buffer_load_dwordx4 v129, s[44:47], s0 offen lds
	s_or_b32 s0, s38, 0x10080
	s_mov_b32 m0, s26
	s_or_b32 s31, s38, 0x10180
	buffer_load_dwordx4 v128, s[88:91], s0 offen lds
	s_mov_b32 m0, s30
	s_or_b32 s42, s38, 0x100
	buffer_load_dwordx4 v129, s[88:91], s0 offen lds
	s_waitcnt vmcnt(6)
	s_barrier
	ds_read_b128 v[0:3], v146
	ds_read_b128 v[4:7], v146 offset:1024
	ds_read_b128 v[8:11], v146 offset:2048
	ds_read_b128 v[12:15], v146 offset:3072
	ds_read_b128 v[16:19], v147
	ds_read_b128 v[20:23], v147 offset:1024
	ds_read_b128 v[24:27], v147 offset:2048
	ds_read_b128 v[28:31], v147 offset:3072
	s_or_b32 s38, s38, 0x180
	s_or_b32 s43, s6, 0x100
	v_readfirstlane_b32 s0, v144
	s_mov_b32 m0, s0
	v_readfirstlane_b32 s1, v145
	ds_read_b128 v[32:35], v148
	ds_read_b128 v[36:39], v148 offset:1024
	ds_read_b128 v[40:43], v149
	ds_read_b128 v[44:47], v149 offset:1024
	ds_read_b128 v[48:51], v150
	ds_read_b128 v[52:55], v150 offset:1024
	ds_read_b128 v[56:59], v151
	ds_read_b128 v[60:63], v151 offset:1024
	buffer_load_dwordx4 v128, s[44:47], s39 offen lds
	s_mov_b32 m0, s1
	s_nop 0
	buffer_load_dwordx4 v129, s[44:47], s39 offen lds
	s_waitcnt vmcnt(8)
	s_waitcnt lgkmcnt(0)
	s_barrier
	s_setprio 1
	v_mfma_f32_16x16x32_bf16 v[64:67], v[0:3], v[32:35], 0
	v_mfma_f32_16x16x32_bf16 v[68:71], v[8:11], v[32:35], 0
	v_mfma_f32_16x16x32_bf16 v[72:75], v[0:3], v[40:43], 0
	v_mfma_f32_16x16x32_bf16 v[76:79], v[8:11], v[40:43], 0
	v_mfma_f32_16x16x32_bf16 v[80:83], v[0:3], v[48:51], 0
	v_mfma_f32_16x16x32_bf16 v[84:87], v[8:11], v[48:51], 0
	v_mfma_f32_16x16x32_bf16 v[88:91], v[0:3], v[56:59], 0
	v_mfma_f32_16x16x32_bf16 v[92:95], v[8:11], v[56:59], 0
	v_mfma_f32_16x16x32_bf16 v[64:67], v[4:7], v[36:39], v[64:67]
	v_mfma_f32_16x16x32_bf16 v[68:71], v[12:15], v[36:39], v[68:71]
	v_mfma_f32_16x16x32_bf16 v[72:75], v[4:7], v[44:47], v[72:75]
	v_mfma_f32_16x16x32_bf16 v[76:79], v[12:15], v[44:47], v[76:79]
	v_mfma_f32_16x16x32_bf16 v[80:83], v[4:7], v[52:55], v[80:83]
	v_mfma_f32_16x16x32_bf16 v[84:87], v[12:15], v[52:55], v[84:87]
	v_mfma_f32_16x16x32_bf16 v[88:91], v[4:7], v[60:63], v[88:91]
	v_mfma_f32_16x16x32_bf16 v[92:95], v[12:15], v[60:63], v[92:95]
	v_mfma_f32_16x16x32_bf16 v[96:99], v[16:19], v[32:35], 0
	v_mfma_f32_16x16x32_bf16 v[32:35], v[24:27], v[32:35], 0
	v_mfma_f32_16x16x32_bf16 v[96:99], v[20:23], v[36:39], v[96:99]
	v_mfma_f32_16x16x32_bf16 v[32:35], v[28:31], v[36:39], v[32:35]
	v_mfma_f32_16x16x32_bf16 v[36:39], v[16:19], v[40:43], 0
	v_mfma_f32_16x16x32_bf16 v[40:43], v[24:27], v[40:43], 0
	v_mfma_f32_16x16x32_bf16 v[36:39], v[20:23], v[44:47], v[36:39]
	v_mfma_f32_16x16x32_bf16 v[40:43], v[28:31], v[44:47], v[40:43]
	v_mfma_f32_16x16x32_bf16 v[44:47], v[16:19], v[48:51], 0
	v_mfma_f32_16x16x32_bf16 v[48:51], v[24:27], v[48:51], 0
	v_mfma_f32_16x16x32_bf16 v[44:47], v[20:23], v[52:55], v[44:47]
	v_mfma_f32_16x16x32_bf16 v[48:51], v[28:31], v[52:55], v[48:51]
	v_mfma_f32_16x16x32_bf16 v[52:55], v[16:19], v[56:59], 0
	v_mfma_f32_16x16x32_bf16 v[56:59], v[24:27], v[56:59], 0
	v_mfma_f32_16x16x32_bf16 v[52:55], v[20:23], v[60:63], v[52:55]
	v_mfma_f32_16x16x32_bf16 v[56:59], v[28:31], v[60:63], v[56:59]
	s_setprio 0
	s_barrier
	v_readfirstlane_b32 s39, v130
	s_mov_b32 m0, s39
	v_readfirstlane_b32 s39, v131
	ds_read_b128 v[60:63], v148 offset:16384
	ds_read_b128 v[100:103], v148 offset:17408
	ds_read_b128 v[104:107], v149 offset:16384
	ds_read_b128 v[108:111], v149 offset:17408
	ds_read_b128 v[112:115], v150 offset:16384
	ds_read_b128 v[116:119], v150 offset:17408
	ds_read_b128 v[120:123], v151 offset:16384
	ds_read_b128 v[124:127], v151 offset:17408
	buffer_load_dwordx4 v128, s[88:91], s42 offen lds
	s_mov_b32 m0, s39
	v_readfirstlane_b32 s39, v132
	buffer_load_dwordx4 v129, s[88:91], s42 offen lds
	s_mov_b32 m0, s39
	v_readfirstlane_b32 s39, v133
	buffer_load_dwordx4 v128, s[88:91], s40 offen lds
	s_mov_b32 m0, s39
	v_readfirstlane_b32 s39, v134
	buffer_load_dwordx4 v129, s[88:91], s40 offen lds
	s_mov_b32 m0, s39
	v_readfirstlane_b32 s39, v135
	buffer_load_dwordx4 v128, s[44:47], s43 offen lds
	s_mov_b32 m0, s39
	s_nop 0
	buffer_load_dwordx4 v129, s[44:47], s43 offen lds
	s_waitcnt vmcnt(8)
	s_waitcnt lgkmcnt(0)
	s_barrier
; #define LDA(dst, b, h) for (int m = 0; m < 4; ++m) for (int k = 0; k < 2; ++k) \
;     dst[m][k] = *reinterpret_cast<const bf16x8*>((char*)SA(b, h) + lds_byte(wr * 64 + m * 16 + fr, k * 32 + fq * 8))
; #define LDB(dst, b, h) for (int n = 0; n < 2; ++n) for (int k = 0; k < 2; ++k) \
;     dst[n][k] = *reinterpret_cast<const bf16x8*>((char*)SB(b, h) + lds_byte(wc * 32 + n * 16 + fr, k * 32 + fq * 8))
; #define MMA(ai, bj, At, Bt_) do { __builtin_amdgcn_s_setprio(1); \
;     for (int m = 0; m < 4; ++m) for (int n = 0; n < 2; ++n) for (int k = 0; k < 2; ++k) \
;       acc[ai][bj][m][n] = __builtin_amdgcn_mfma_f32_16x16x32_bf16(Bt_[n][k], At[m][k], acc[ai][bj][m][n], 0, 0, 0); \
;     __builtin_amdgcn_s_setprio(0); } while (0)
; #define WAIT_V(n) asm volatile("s_waitcnt vmcnt(" #n ")" ::: "memory")
; #define WAIT_L(n) asm volatile("s_waitcnt lgkmcnt(" #n ")" ::: "memory")
; #define BAR __builtin_amdgcn_s_barrier()
; #define SCHED __builtin_amdgcn_sched_barrier(0)
; template <int MODE>
; DI void gemm_phase(const bf16_t* __restrict__ A, const bf16_t* __restrict__ Bt, int M, int N, int K, const Epi& ep) {
;     ...
;             LDA(At, 0, 1); STAGE(SB(0, 0), rsB, bcol, t + 2); STAGE(SB(0, 1), rsB, bcol + HALF, t + 2); STAGE(SA(0, 0), rsA, brow, t + 2);
;             WAIT_V(8); WAIT_L(0); BAR; MMA(1, 0, At, B0); MMA(1, 1, At, B1); BAR; SCHED;
;             LDB(B0, 1, 0); LDB(B1, 1, 1); SCHED; LDA(At, 1, 0); STAGE(SA(0, 1), rsA, brow + HALF, t + 2);
;             WAIT_V(8); WAIT_L(0); BAR; MMA(0, 0, At, B0); MMA(0, 1, At, B1); BAR; SCHED;
	s_setprio 1
	v_mfma_f32_16x16x32_bf16 v[156:159], v[0:3], v[60:63], 0
	v_mfma_f32_16x16x32_bf16 v[164:167], v[0:3], v[104:107], 0
	v_mfma_f32_16x16x32_bf16 v[172:175], v[0:3], v[112:115], 0
	v_mfma_f32_16x16x32_bf16 v[0:3], v[0:3], v[120:123], 0
	v_mfma_f32_16x16x32_bf16 v[156:159], v[4:7], v[100:103], v[156:159]
	v_mfma_f32_16x16x32_bf16 v[164:167], v[4:7], v[108:111], v[164:167]
	v_mfma_f32_16x16x32_bf16 v[172:175], v[4:7], v[116:119], v[172:175]
	v_mfma_f32_16x16x32_bf16 v[0:3], v[4:7], v[124:127], v[0:3]
	v_mfma_f32_16x16x32_bf16 v[4:7], v[8:11], v[120:123], 0
	v_mfma_f32_16x16x32_bf16 v[160:163], v[8:11], v[60:63], 0
	v_mfma_f32_16x16x32_bf16 v[168:171], v[8:11], v[104:107], 0
	v_mfma_f32_16x16x32_bf16 v[176:179], v[8:11], v[112:115], 0
	v_mfma_f32_16x16x32_bf16 v[4:7], v[12:15], v[124:127], v[4:7]
	v_mfma_f32_16x16x32_bf16 v[160:163], v[12:15], v[100:103], v[160:163]
	v_mfma_f32_16x16x32_bf16 v[168:171], v[12:15], v[108:111], v[168:171]
	v_mfma_f32_16x16x32_bf16 v[176:179], v[12:15], v[116:119], v[176:179]
	v_mfma_f32_16x16x32_bf16 v[8:11], v[16:19], v[60:63], 0
	v_mfma_f32_16x16x32_bf16 v[12:15], v[24:27], v[60:63], 0
	v_mfma_f32_16x16x32_bf16 v[8:11], v[20:23], v[100:103], v[8:11]
	v_mfma_f32_16x16x32_bf16 v[12:15], v[28:31], v[100:103], v[12:15]
	v_mfma_f32_16x16x32_bf16 v[60:63], v[16:19], v[104:107], 0
	v_mfma_f32_16x16x32_bf16 v[100:103], v[24:27], v[104:107], 0
	v_mfma_f32_16x16x32_bf16 v[104:107], v[16:19], v[112:115], 0
	v_mfma_f32_16x16x32_bf16 v[16:19], v[16:19], v[120:123], 0
	v_mfma_f32_16x16x32_bf16 v[60:63], v[20:23], v[108:111], v[60:63]
	v_mfma_f32_16x16x32_bf16 v[100:103], v[28:31], v[108:111], v[100:103]
	v_mfma_f32_16x16x32_bf16 v[104:107], v[20:23], v[116:119], v[104:107]
	v_mfma_f32_16x16x32_bf16 v[108:111], v[24:27], v[112:115], 0
	v_mfma_f32_16x16x32_bf16 v[16:19], v[20:23], v[124:127], v[16:19]
	v_mfma_f32_16x16x32_bf16 v[20:23], v[24:27], v[120:123], 0
	v_mfma_f32_16x16x32_bf16 v[108:111], v[28:31], v[116:119], v[108:111]
	v_mfma_f32_16x16x32_bf16 v[20:23], v[28:31], v[124:127], v[20:23]
	s_setprio 0
	s_barrier
	ds_read_b128 v[24:27], v152
	ds_read_b128 v[28:31], v152 offset:1024
	ds_read_b128 v[112:115], v152 offset:2048
	ds_read_b128 v[116:119], v152 offset:3072
	ds_read_b128 v[120:123], v153
	ds_read_b128 v[124:127], v153 offset:1024
	ds_read_b128 v[180:183], v153 offset:2048
	ds_read_b128 v[184:187], v153 offset:3072
	v_readfirstlane_b32 s39, v155
	s_mov_b32 m0, s39
	v_readfirstlane_b32 s39, v140
	ds_read_b128 v[188:191], v148 offset:32768
	ds_read_b128 v[192:195], v148 offset:33792
	ds_read_b128 v[196:199], v149 offset:32768
	ds_read_b128 v[200:203], v149 offset:33792
	ds_read_b128 v[204:207], v150 offset:32768
	ds_read_b128 v[208:211], v150 offset:33792
	ds_read_b128 v[214:217], v151 offset:32768
	ds_read_b128 v[218:221], v151 offset:33792
	buffer_load_dwordx4 v128, s[44:47], s41 offen lds
	s_mov_b32 m0, s39
	s_nop 0
	buffer_load_dwordx4 v129, s[44:47], s41 offen lds
	s_waitcnt vmcnt(8)
	s_waitcnt lgkmcnt(0)
	s_barrier
	s_setprio 1
	v_mfma_f32_16x16x32_bf16 v[64:67], v[24:27], v[188:191], v[64:67]
	v_mfma_f32_16x16x32_bf16 v[68:71], v[112:115], v[188:191], v[68:71]
	v_mfma_f32_16x16x32_bf16 v[72:75], v[24:27], v[196:199], v[72:75]
	v_mfma_f32_16x16x32_bf16 v[76:79], v[112:115], v[196:199], v[76:79]
	v_mfma_f32_16x16x32_bf16 v[80:83], v[24:27], v[204:207], v[80:83]
	v_mfma_f32_16x16x32_bf16 v[84:87], v[112:115], v[204:207], v[84:87]
	v_mfma_f32_16x16x32_bf16 v[88:91], v[24:27], v[214:217], v[88:91]
	v_mfma_f32_16x16x32_bf16 v[92:95], v[112:115], v[214:217], v[92:95]
	v_mfma_f32_16x16x32_bf16 v[64:67], v[28:31], v[192:195], v[64:67]
	v_mfma_f32_16x16x32_bf16 v[68:71], v[116:119], v[192:195], v[68:71]
	v_mfma_f32_16x16x32_bf16 v[72:75], v[28:31], v[200:203], v[72:75]
	v_mfma_f32_16x16x32_bf16 v[76:79], v[116:119], v[200:203], v[76:79]
	v_mfma_f32_16x16x32_bf16 v[80:83], v[28:31], v[208:211], v[80:83]
	v_mfma_f32_16x16x32_bf16 v[84:87], v[116:119], v[208:211], v[84:87]
	v_mfma_f32_16x16x32_bf16 v[88:91], v[28:31], v[218:221], v[88:91]
	v_mfma_f32_16x16x32_bf16 v[92:95], v[116:119], v[218:221], v[92:95]
	v_mfma_f32_16x16x32_bf16 v[96:99], v[120:123], v[188:191], v[96:99]
	v_mfma_f32_16x16x32_bf16 v[32:35], v[180:183], v[188:191], v[32:35]
	v_mfma_f32_16x16x32_bf16 v[36:39], v[120:123], v[196:199], v[36:39]
	v_mfma_f32_16x16x32_bf16 v[40:43], v[180:183], v[196:199], v[40:43]
	v_mfma_f32_16x16x32_bf16 v[44:47], v[120:123], v[204:207], v[44:47]
	v_mfma_f32_16x16x32_bf16 v[48:51], v[180:183], v[204:207], v[48:51]
	v_mfma_f32_16x16x32_bf16 v[52:55], v[120:123], v[214:217], v[52:55]
	v_mfma_f32_16x16x32_bf16 v[56:59], v[180:183], v[214:217], v[56:59]
	v_mfma_f32_16x16x32_bf16 v[96:99], v[124:127], v[192:195], v[96:99]
	v_mfma_f32_16x16x32_bf16 v[32:35], v[184:187], v[192:195], v[32:35]
	v_mfma_f32_16x16x32_bf16 v[36:39], v[124:127], v[200:203], v[36:39]
	v_mfma_f32_16x16x32_bf16 v[40:43], v[184:187], v[200:203], v[40:43]
	v_mfma_f32_16x16x32_bf16 v[44:47], v[124:127], v[208:211], v[44:47]
	v_mfma_f32_16x16x32_bf16 v[48:51], v[184:187], v[208:211], v[48:51]
	v_mfma_f32_16x16x32_bf16 v[52:55], v[124:127], v[218:221], v[52:55]
	v_mfma_f32_16x16x32_bf16 v[56:59], v[184:187], v[218:221], v[56:59]
	s_setprio 0
	s_barrier
; #define LDA(dst, b, h) for (int m = 0; m < 4; ++m) for (int k = 0; k < 2; ++k) \
;     dst[m][k] = *reinterpret_cast<const bf16x8*>((char*)SA(b, h) + lds_byte(wr * 64 + m * 16 + fr, k * 32 + fq * 8))
; #define LDB(dst, b, h) for (int n = 0; n < 2; ++n) for (int k = 0; k < 2; ++k) \
;     dst[n][k] = *reinterpret_cast<const bf16x8*>((char*)SB(b, h) + lds_byte(wc * 32 + n * 16 + fr, k * 32 + fq * 8))
; #define MMA(ai, bj, At, Bt_) do { __builtin_amdgcn_s_setprio(1); \
;     for (int m = 0; m < 4; ++m) for (int n = 0; n < 2; ++n) for (int k = 0; k < 2; ++k) \
;       acc[ai][bj][m][n] = __builtin_amdgcn_mfma_f32_16x16x32_bf16(Bt_[n][k], At[m][k], acc[ai][bj][m][n], 0, 0, 0); \
;     __builtin_amdgcn_s_setprio(0); } while (0)
; #define WAIT_V(n) asm volatile("s_waitcnt vmcnt(" #n ")" ::: "memory")
; #define WAIT_L(n) asm volatile("s_waitcnt lgkmcnt(" #n ")" ::: "memory")
; #define BAR __builtin_amdgcn_s_barrier()
; #define SCHED __builtin_amdgcn_sched_barrier(0)
; template <int MODE>
; DI void gemm_phase(const bf16_t* __restrict__ A, const bf16_t* __restrict__ Bt, int M, int N, int K, const Epi& ep) {
;     ...
;             LDA(At, 1, 1); STAGE(SB(1, 0), rsB, bcol, t + 3); STAGE(SB(1, 1), rsB, bcol + HALF, t + 3); STAGE(SA(1, 0), rsA, brow, t + 3);
;             WAIT_V(8); WAIT_L(0); BAR; MMA(1, 0, At, B0); MMA(1, 1, At, B1); BAR; SCHED;
;         }
;         {
;             LDB(B0, 0, 0); LDB(B1, 0, 1); SCHED; LDA(At, 0, 0); STAGE(SA(1, 1), rsA, brow + HALF, nt - 1);
;             WAIT_V(8); WAIT_L(0); BAR; MMA(0, 0, At, B0); MMA(0, 1, At, B1); BAR; SCHED;
	s_mov_b32 m0, s27
	ds_read_b128 v[188:191], v148 offset:49152
	ds_read_b128 v[192:195], v148 offset:50176
	ds_read_b128 v[196:199], v149 offset:49152
	ds_read_b128 v[200:203], v149 offset:50176
	ds_read_b128 v[204:207], v150 offset:49152
	ds_read_b128 v[208:211], v150 offset:50176
	ds_read_b128 v[214:217], v151 offset:49152
	ds_read_b128 v[218:221], v151 offset:50176
	buffer_load_dwordx4 v128, s[88:91], s38 offen lds
	s_mov_b32 m0, s15
	s_or_b32 s27, s6, 0x180
	buffer_load_dwordx4 v129, s[88:91], s38 offen lds
	s_mov_b32 m0, s26
	s_nop 0
	buffer_load_dwordx4 v128, s[88:91], s31 offen lds
	s_mov_b32 m0, s30
	s_nop 0
	buffer_load_dwordx4 v129, s[88:91], s31 offen lds
	s_mov_b32 m0, s7
	s_nop 0
	buffer_load_dwordx4 v128, s[44:47], s27 offen lds
	s_mov_b32 m0, s14
	s_nop 0
	buffer_load_dwordx4 v129, s[44:47], s27 offen lds
	s_waitcnt vmcnt(8)
	s_waitcnt lgkmcnt(0)
	s_barrier
	s_setprio 1
	v_mfma_f32_16x16x32_bf16 v[0:3], v[24:27], v[214:217], v[0:3]
	v_mfma_f32_16x16x32_bf16 v[4:7], v[112:115], v[214:217], v[4:7]
	v_mfma_f32_16x16x32_bf16 v[156:159], v[24:27], v[188:191], v[156:159]
	v_mfma_f32_16x16x32_bf16 v[160:163], v[112:115], v[188:191], v[160:163]
	v_mfma_f32_16x16x32_bf16 v[164:167], v[24:27], v[196:199], v[164:167]
	v_mfma_f32_16x16x32_bf16 v[168:171], v[112:115], v[196:199], v[168:171]
	v_mfma_f32_16x16x32_bf16 v[172:175], v[24:27], v[204:207], v[172:175]
	v_mfma_f32_16x16x32_bf16 v[176:179], v[112:115], v[204:207], v[176:179]
	v_mfma_f32_16x16x32_bf16 v[0:3], v[28:31], v[218:221], v[0:3]
	v_mfma_f32_16x16x32_bf16 v[4:7], v[116:119], v[218:221], v[4:7]
	v_mfma_f32_16x16x32_bf16 v[156:159], v[28:31], v[192:195], v[156:159]
	v_mfma_f32_16x16x32_bf16 v[160:163], v[116:119], v[192:195], v[160:163]
	v_mfma_f32_16x16x32_bf16 v[164:167], v[28:31], v[200:203], v[164:167]
	v_mfma_f32_16x16x32_bf16 v[168:171], v[116:119], v[200:203], v[168:171]
	v_mfma_f32_16x16x32_bf16 v[172:175], v[28:31], v[208:211], v[172:175]
	v_mfma_f32_16x16x32_bf16 v[176:179], v[116:119], v[208:211], v[176:179]
	v_mfma_f32_16x16x32_bf16 v[8:11], v[120:123], v[188:191], v[8:11]
	v_mfma_f32_16x16x32_bf16 v[12:15], v[180:183], v[188:191], v[12:15]
	v_mfma_f32_16x16x32_bf16 v[24:27], v[120:123], v[196:199], v[60:63]
	v_mfma_f32_16x16x32_bf16 v[28:31], v[180:183], v[196:199], v[100:103]
	v_mfma_f32_16x16x32_bf16 v[60:63], v[120:123], v[204:207], v[104:107]
	v_mfma_f32_16x16x32_bf16 v[100:103], v[180:183], v[204:207], v[108:111]
	v_mfma_f32_16x16x32_bf16 v[16:19], v[120:123], v[214:217], v[16:19]
	v_mfma_f32_16x16x32_bf16 v[20:23], v[180:183], v[214:217], v[20:23]
	v_mfma_f32_16x16x32_bf16 v[8:11], v[124:127], v[192:195], v[8:11]
	v_mfma_f32_16x16x32_bf16 v[12:15], v[184:187], v[192:195], v[12:15]
	v_mfma_f32_16x16x32_bf16 v[24:27], v[124:127], v[200:203], v[24:27]
	v_mfma_f32_16x16x32_bf16 v[28:31], v[184:187], v[200:203], v[28:31]
	v_mfma_f32_16x16x32_bf16 v[60:63], v[124:127], v[208:211], v[60:63]
	v_mfma_f32_16x16x32_bf16 v[100:103], v[184:187], v[208:211], v[100:103]
	v_mfma_f32_16x16x32_bf16 v[16:19], v[124:127], v[218:221], v[16:19]
	v_mfma_f32_16x16x32_bf16 v[20:23], v[184:187], v[218:221], v[20:23]
	s_setprio 0
	s_barrier
	ds_read_b128 v[104:107], v146
	ds_read_b128 v[108:111], v146 offset:1024
	ds_read_b128 v[112:115], v146 offset:2048
	ds_read_b128 v[116:119], v146 offset:3072
	ds_read_b128 v[120:123], v147
	ds_read_b128 v[124:127], v147 offset:1024
	ds_read_b128 v[180:183], v147 offset:2048
	ds_read_b128 v[184:187], v147 offset:3072
	s_or_b32 s6, s6, 0x10180
	s_mov_b32 m0, s0
	ds_read_b128 v[188:191], v148
	ds_read_b128 v[192:195], v148 offset:1024
	ds_read_b128 v[196:199], v149
	ds_read_b128 v[200:203], v149 offset:1024
	ds_read_b128 v[204:207], v150
	ds_read_b128 v[208:211], v150 offset:1024
	ds_read_b128 v[214:217], v151
	ds_read_b128 v[218:221], v151 offset:1024
	buffer_load_dwordx4 v128, s[44:47], s6 offen lds
	s_mov_b32 m0, s1
	s_nop 0
	buffer_load_dwordx4 v129, s[44:47], s6 offen lds
	s_waitcnt vmcnt(8)
	s_waitcnt lgkmcnt(0)
	s_barrier
	s_setprio 1
	v_mfma_f32_16x16x32_bf16 v[64:67], v[104:107], v[188:191], v[64:67]
	v_mfma_f32_16x16x32_bf16 v[68:71], v[112:115], v[188:191], v[68:71]
	v_mfma_f32_16x16x32_bf16 v[72:75], v[104:107], v[196:199], v[72:75]
	v_mfma_f32_16x16x32_bf16 v[76:79], v[112:115], v[196:199], v[76:79]
	v_mfma_f32_16x16x32_bf16 v[80:83], v[104:107], v[204:207], v[80:83]
	v_mfma_f32_16x16x32_bf16 v[84:87], v[112:115], v[204:207], v[84:87]
	v_mfma_f32_16x16x32_bf16 v[88:91], v[104:107], v[214:217], v[88:91]
	v_mfma_f32_16x16x32_bf16 v[92:95], v[112:115], v[214:217], v[92:95]
	v_mfma_f32_16x16x32_bf16 v[64:67], v[108:111], v[192:195], v[64:67]
	v_mfma_f32_16x16x32_bf16 v[68:71], v[116:119], v[192:195], v[68:71]
	v_mfma_f32_16x16x32_bf16 v[72:75], v[108:111], v[200:203], v[72:75]
	v_mfma_f32_16x16x32_bf16 v[76:79], v[116:119], v[200:203], v[76:79]
	v_mfma_f32_16x16x32_bf16 v[80:83], v[108:111], v[208:211], v[80:83]
	v_mfma_f32_16x16x32_bf16 v[84:87], v[116:119], v[208:211], v[84:87]
	v_mfma_f32_16x16x32_bf16 v[88:91], v[108:111], v[218:221], v[88:91]
	v_mfma_f32_16x16x32_bf16 v[92:95], v[116:119], v[218:221], v[92:95]
	v_mfma_f32_16x16x32_bf16 v[32:35], v[180:183], v[188:191], v[32:35]
	v_mfma_f32_16x16x32_bf16 v[36:39], v[120:123], v[196:199], v[36:39]
	v_mfma_f32_16x16x32_bf16 v[40:43], v[180:183], v[196:199], v[40:43]
	v_mfma_f32_16x16x32_bf16 v[44:47], v[120:123], v[204:207], v[44:47]
	v_mfma_f32_16x16x32_bf16 v[48:51], v[180:183], v[204:207], v[48:51]
	v_mfma_f32_16x16x32_bf16 v[52:55], v[120:123], v[214:217], v[52:55]
	v_mfma_f32_16x16x32_bf16 v[56:59], v[180:183], v[214:217], v[56:59]
	v_mfma_f32_16x16x32_bf16 v[96:99], v[120:123], v[188:191], v[96:99]
	v_mfma_f32_16x16x32_bf16 v[32:35], v[184:187], v[192:195], v[32:35]
	v_mfma_f32_16x16x32_bf16 v[36:39], v[124:127], v[200:203], v[36:39]
	v_mfma_f32_16x16x32_bf16 v[40:43], v[184:187], v[200:203], v[40:43]
	v_mfma_f32_16x16x32_bf16 v[44:47], v[124:127], v[208:211], v[44:47]
	v_mfma_f32_16x16x32_bf16 v[48:51], v[184:187], v[208:211], v[48:51]
	v_mfma_f32_16x16x32_bf16 v[52:55], v[124:127], v[218:221], v[52:55]
	v_mfma_f32_16x16x32_bf16 v[56:59], v[184:187], v[218:221], v[56:59]
	v_mfma_f32_16x16x32_bf16 v[222:225], v[124:127], v[192:195], v[96:99]
	s_setprio 0
	s_barrier
; #define LDA(dst, b, h) for (int m = 0; m < 4; ++m) for (int k = 0; k < 2; ++k) \
;     dst[m][k] = *reinterpret_cast<const bf16x8*>((char*)SA(b, h) + lds_byte(wr * 64 + m * 16 + fr, k * 32 + fq * 8))
; #define LDB(dst, b, h) for (int n = 0; n < 2; ++n) for (int k = 0; k < 2; ++k) \
;     dst[n][k] = *reinterpret_cast<const bf16x8*>((char*)SB(b, h) + lds_byte(wc * 32 + n * 16 + fr, k * 32 + fq * 8))
; #define MMA(ai, bj, At, Bt_) do { __builtin_amdgcn_s_setprio(1); \
;     for (int m = 0; m < 4; ++m) for (int n = 0; n < 2; ++n) for (int k = 0; k < 2; ++k) \
;       acc[ai][bj][m][n] = __builtin_amdgcn_mfma_f32_16x16x32_bf16(Bt_[n][k], At[m][k], acc[ai][bj][m][n], 0, 0, 0); \
;     __builtin_amdgcn_s_setprio(0); } while (0)
; #define WAIT_V(n) asm volatile("s_waitcnt vmcnt(" #n ")" ::: "memory")
; #define WAIT_L(n) asm volatile("s_waitcnt lgkmcnt(" #n ")" ::: "memory")
; #define BAR __builtin_amdgcn_s_barrier()
; #define SCHED __builtin_amdgcn_sched_barrier(0)
; template <int MODE>
; DI void gemm_phase(const bf16_t* __restrict__ A, const bf16_t* __restrict__ Bt, int M, int N, int K, const Epi& ep) {
;     ...
;             LDA(At, 0, 1);
;             WAIT_V(2); WAIT_L(0); BAR; MMA(1, 0, At, B0); MMA(1, 1, At, B1); BAR; SCHED;
;             LDB(B0, 1, 0); LDB(B1, 1, 1); SCHED; LDA(At, 1, 0);
	s_nop 0
	ds_read_b128 v[96:99], v148 offset:16384
	ds_read_b128 v[188:191], v148 offset:17408
	ds_read_b128 v[192:195], v149 offset:16384
	ds_read_b128 v[196:199], v149 offset:17408
	ds_read_b128 v[200:203], v150 offset:16384
	ds_read_b128 v[204:207], v150 offset:17408
	ds_read_b128 v[208:211], v151 offset:16384
	ds_read_b128 v[214:217], v151 offset:17408
	s_waitcnt vmcnt(2)
	s_waitcnt lgkmcnt(0)
	s_barrier
	s_setprio 1
	v_mfma_f32_16x16x32_bf16 v[0:3], v[104:107], v[208:211], v[0:3]
	v_mfma_f32_16x16x32_bf16 v[4:7], v[112:115], v[208:211], v[4:7]
	v_mfma_f32_16x16x32_bf16 v[156:159], v[104:107], v[96:99], v[156:159]
	v_mfma_f32_16x16x32_bf16 v[160:163], v[112:115], v[96:99], v[160:163]
	v_mfma_f32_16x16x32_bf16 v[164:167], v[104:107], v[192:195], v[164:167]
	v_mfma_f32_16x16x32_bf16 v[168:171], v[112:115], v[192:195], v[168:171]
	v_mfma_f32_16x16x32_bf16 v[172:175], v[104:107], v[200:203], v[172:175]
	v_mfma_f32_16x16x32_bf16 v[176:179], v[112:115], v[200:203], v[176:179]
	v_mfma_f32_16x16x32_bf16 v[0:3], v[108:111], v[214:217], v[0:3]
	v_mfma_f32_16x16x32_bf16 v[4:7], v[116:119], v[214:217], v[4:7]
	v_mfma_f32_16x16x32_bf16 v[156:159], v[108:111], v[188:191], v[156:159]
	v_mfma_f32_16x16x32_bf16 v[160:163], v[116:119], v[188:191], v[160:163]
	v_mfma_f32_16x16x32_bf16 v[164:167], v[108:111], v[196:199], v[164:167]
	v_mfma_f32_16x16x32_bf16 v[168:171], v[116:119], v[196:199], v[168:171]
	v_mfma_f32_16x16x32_bf16 v[172:175], v[108:111], v[204:207], v[172:175]
	v_mfma_f32_16x16x32_bf16 v[176:179], v[116:119], v[204:207], v[176:179]
	v_mfma_f32_16x16x32_bf16 v[8:11], v[120:123], v[96:99], v[8:11]
	v_mfma_f32_16x16x32_bf16 v[12:15], v[180:183], v[96:99], v[12:15]
	v_mfma_f32_16x16x32_bf16 v[24:27], v[120:123], v[192:195], v[24:27]
	v_mfma_f32_16x16x32_bf16 v[28:31], v[180:183], v[192:195], v[28:31]
	v_mfma_f32_16x16x32_bf16 v[60:63], v[120:123], v[200:203], v[60:63]
	v_mfma_f32_16x16x32_bf16 v[16:19], v[120:123], v[208:211], v[16:19]
	v_mfma_f32_16x16x32_bf16 v[8:11], v[124:127], v[188:191], v[8:11]
	v_mfma_f32_16x16x32_bf16 v[12:15], v[184:187], v[188:191], v[12:15]
	v_mfma_f32_16x16x32_bf16 v[24:27], v[124:127], v[196:199], v[24:27]
	v_mfma_f32_16x16x32_bf16 v[28:31], v[184:187], v[196:199], v[28:31]
	v_mfma_f32_16x16x32_bf16 v[188:191], v[124:127], v[204:207], v[60:63]
	v_mfma_f32_16x16x32_bf16 v[60:63], v[180:183], v[200:203], v[100:103]
	v_mfma_f32_16x16x32_bf16 v[196:199], v[124:127], v[214:217], v[16:19]
	v_mfma_f32_16x16x32_bf16 v[16:19], v[180:183], v[208:211], v[20:23]
	v_mfma_f32_16x16x32_bf16 v[192:195], v[184:187], v[204:207], v[60:63]
	v_mfma_f32_16x16x32_bf16 v[180:183], v[184:187], v[214:217], v[16:19]
	s_setprio 0
	s_barrier
	s_nop 3
	ds_read_b128 v[16:19], v152
	ds_read_b128 v[20:23], v152 offset:1024
	ds_read_b128 v[60:63], v152 offset:2048
	ds_read_b128 v[184:187], v152 offset:3072
	ds_read_b128 v[200:203], v153
	ds_read_b128 v[204:207], v153 offset:1024
	ds_read_b128 v[208:211], v153 offset:2048
	ds_read_b128 v[214:217], v153 offset:3072
	ds_read_b128 v[218:221], v148 offset:32768
	ds_read_b128 v[226:229], v148 offset:33792
	ds_read_b128 v[230:233], v149 offset:32768
	ds_read_b128 v[234:237], v149 offset:33792
	ds_read_b128 v[238:241], v150 offset:32768
	ds_read_b128 v[242:245], v150 offset:33792
	ds_read_b128 v[246:249], v151 offset:32768
	ds_read_b128 v[136:139], v151 offset:33792
	s_waitcnt vmcnt(0)
	s_waitcnt lgkmcnt(0)
	s_barrier
; #define LDA(dst, b, h) for (int m = 0; m < 4; ++m) for (int k = 0; k < 2; ++k) \
;     dst[m][k] = *reinterpret_cast<const bf16x8*>((char*)SA(b, h) + lds_byte(wr * 64 + m * 16 + fr, k * 32 + fq * 8))
; #define LDB(dst, b, h) for (int n = 0; n < 2; ++n) for (int k = 0; k < 2; ++k) \
;     dst[n][k] = *reinterpret_cast<const bf16x8*>((char*)SB(b, h) + lds_byte(wc * 32 + n * 16 + fr, k * 32 + fq * 8))
; #define MMA(ai, bj, At, Bt_) do { __builtin_amdgcn_s_setprio(1); \
;     for (int m = 0; m < 4; ++m) for (int n = 0; n < 2; ++n) for (int k = 0; k < 2; ++k) \
;       acc[ai][bj][m][n] = __builtin_amdgcn_mfma_f32_16x16x32_bf16(Bt_[n][k], At[m][k], acc[ai][bj][m][n], 0, 0, 0); \
;     __builtin_amdgcn_s_setprio(0); } while (0)
; #define WAIT_V(n) asm volatile("s_waitcnt vmcnt(" #n ")" ::: "memory")
; #define WAIT_L(n) asm volatile("s_waitcnt lgkmcnt(" #n ")" ::: "memory")
; #define BAR __builtin_amdgcn_s_barrier()
; #define SCHED __builtin_amdgcn_sched_barrier(0)
; template <int MODE>
; DI void gemm_phase(const bf16_t* __restrict__ A, const bf16_t* __restrict__ Bt, int M, int N, int K, const Epi& ep) {
;     ...
;             LDB(B0, 1, 0); LDB(B1, 1, 1); SCHED; LDA(At, 1, 0);
;             WAIT_V(0); WAIT_L(0); BAR; MMA(0, 0, At, B0); MMA(0, 1, At, B1); BAR; SCHED;
;             LDA(At, 1, 1);
;             WAIT_L(0); BAR; MMA(1, 0, At, B0); MMA(1, 1, At, B1); BAR; SCHED;
;         }
;         if (wr == 0) BAR;
	s_setprio 1
	v_mfma_f32_16x16x32_bf16 v[64:67], v[16:19], v[218:221], v[64:67]
	v_mfma_f32_16x16x32_bf16 v[96:99], v[20:23], v[226:229], v[64:67]
	v_mfma_f32_16x16x32_bf16 v[64:67], v[60:63], v[218:221], v[68:71]
	v_mfma_f32_16x16x32_bf16 v[100:103], v[184:187], v[226:229], v[64:67]
	v_mfma_f32_16x16x32_bf16 v[64:67], v[16:19], v[230:233], v[72:75]
	v_mfma_f32_16x16x32_bf16 v[104:107], v[20:23], v[234:237], v[64:67]
	v_mfma_f32_16x16x32_bf16 v[64:67], v[60:63], v[230:233], v[76:79]
	v_mfma_f32_16x16x32_bf16 v[108:111], v[184:187], v[234:237], v[64:67]
	v_mfma_f32_16x16x32_bf16 v[64:67], v[16:19], v[238:241], v[80:83]
	v_mfma_f32_16x16x32_bf16 v[112:115], v[20:23], v[242:245], v[64:67]
	v_mfma_f32_16x16x32_bf16 v[64:67], v[60:63], v[238:241], v[84:87]
	v_mfma_f32_16x16x32_bf16 v[116:119], v[184:187], v[242:245], v[64:67]
	v_mfma_f32_16x16x32_bf16 v[64:67], v[16:19], v[246:249], v[88:91]
	v_mfma_f32_16x16x32_bf16 v[120:123], v[20:23], v[136:139], v[64:67]
	v_mfma_f32_16x16x32_bf16 v[64:67], v[60:63], v[246:249], v[92:95]
	v_mfma_f32_16x16x32_bf16 v[124:127], v[184:187], v[136:139], v[64:67]
	v_mfma_f32_16x16x32_bf16 v[32:35], v[208:211], v[218:221], v[32:35]
	v_mfma_f32_16x16x32_bf16 v[68:71], v[214:217], v[226:229], v[32:35]
	v_mfma_f32_16x16x32_bf16 v[32:35], v[200:203], v[230:233], v[36:39]
	v_mfma_f32_16x16x32_bf16 v[72:75], v[204:207], v[234:237], v[32:35]
	v_mfma_f32_16x16x32_bf16 v[32:35], v[208:211], v[230:233], v[40:43]
	v_mfma_f32_16x16x32_bf16 v[76:79], v[214:217], v[234:237], v[32:35]
	v_mfma_f32_16x16x32_bf16 v[32:35], v[200:203], v[238:241], v[44:47]
	v_mfma_f32_16x16x32_bf16 v[80:83], v[204:207], v[242:245], v[32:35]
	v_mfma_f32_16x16x32_bf16 v[32:35], v[208:211], v[238:241], v[48:51]
	v_mfma_f32_16x16x32_bf16 v[84:87], v[214:217], v[242:245], v[32:35]
	v_mfma_f32_16x16x32_bf16 v[32:35], v[200:203], v[246:249], v[52:55]
	v_mfma_f32_16x16x32_bf16 v[64:67], v[200:203], v[218:221], v[222:225]
	v_mfma_f32_16x16x32_bf16 v[88:91], v[204:207], v[136:139], v[32:35]
	v_mfma_f32_16x16x32_bf16 v[32:35], v[208:211], v[246:249], v[56:59]
	v_mfma_f32_16x16x32_bf16 v[64:67], v[204:207], v[226:229], v[64:67]
	v_mfma_f32_16x16x32_bf16 v[92:95], v[214:217], v[136:139], v[32:35]
	s_setprio 0
	s_barrier
	ds_read_b128 v[136:139], v148 offset:49152
	ds_read_b128 v[218:221], v148 offset:50176
	ds_read_b128 v[222:225], v149 offset:49152
	ds_read_b128 v[226:229], v149 offset:50176
	ds_read_b128 v[230:233], v150 offset:49152
	ds_read_b128 v[234:237], v150 offset:50176
	ds_read_b128 v[238:241], v151 offset:49152
	ds_read_b128 v[242:245], v151 offset:50176
	s_waitcnt lgkmcnt(0)
	s_barrier
	s_setprio 1
	v_mfma_f32_16x16x32_bf16 v[0:3], v[16:19], v[238:241], v[0:3]
	v_mfma_f32_16x16x32_bf16 v[32:35], v[16:19], v[136:139], v[156:159]
	v_mfma_f32_16x16x32_bf16 v[36:39], v[60:63], v[136:139], v[160:163]
	v_mfma_f32_16x16x32_bf16 v[40:43], v[16:19], v[222:225], v[164:167]
	v_mfma_f32_16x16x32_bf16 v[44:47], v[60:63], v[222:225], v[168:171]
	v_mfma_f32_16x16x32_bf16 v[48:51], v[16:19], v[230:233], v[172:175]
	v_mfma_f32_16x16x32_bf16 v[52:55], v[60:63], v[230:233], v[176:179]
	v_mfma_f32_16x16x32_bf16 v[56:59], v[20:23], v[242:245], v[0:3]
	v_mfma_f32_16x16x32_bf16 v[0:3], v[60:63], v[238:241], v[4:7]
	v_mfma_f32_16x16x32_bf16 v[32:35], v[20:23], v[218:221], v[32:35]
	v_mfma_f32_16x16x32_bf16 v[36:39], v[184:187], v[218:221], v[36:39]
	v_mfma_f32_16x16x32_bf16 v[40:43], v[20:23], v[226:229], v[40:43]
	v_mfma_f32_16x16x32_bf16 v[44:47], v[184:187], v[226:229], v[44:47]
	v_mfma_f32_16x16x32_bf16 v[48:51], v[20:23], v[234:237], v[48:51]
	v_mfma_f32_16x16x32_bf16 v[52:55], v[184:187], v[234:237], v[52:55]
	v_mfma_f32_16x16x32_bf16 v[60:63], v[184:187], v[242:245], v[0:3]
	v_mfma_f32_16x16x32_bf16 v[0:3], v[200:203], v[136:139], v[8:11]
	v_mfma_f32_16x16x32_bf16 v[4:7], v[208:211], v[136:139], v[12:15]
	v_mfma_f32_16x16x32_bf16 v[8:11], v[200:203], v[222:225], v[24:27]
	v_mfma_f32_16x16x32_bf16 v[12:15], v[208:211], v[222:225], v[28:31]
	v_mfma_f32_16x16x32_bf16 v[16:19], v[200:203], v[230:233], v[188:191]
	v_mfma_f32_16x16x32_bf16 v[20:23], v[208:211], v[230:233], v[192:195]
	v_mfma_f32_16x16x32_bf16 v[24:27], v[200:203], v[238:241], v[196:199]
	v_mfma_f32_16x16x32_bf16 v[28:31], v[208:211], v[238:241], v[180:183]
	v_mfma_f32_16x16x32_bf16 v[0:3], v[204:207], v[218:221], v[0:3]
	v_mfma_f32_16x16x32_bf16 v[4:7], v[214:217], v[218:221], v[4:7]
	v_mfma_f32_16x16x32_bf16 v[8:11], v[204:207], v[226:229], v[8:11]
	v_mfma_f32_16x16x32_bf16 v[12:15], v[214:217], v[226:229], v[12:15]
	v_mfma_f32_16x16x32_bf16 v[16:19], v[204:207], v[234:237], v[16:19]
	v_mfma_f32_16x16x32_bf16 v[20:23], v[214:217], v[234:237], v[20:23]
	v_mfma_f32_16x16x32_bf16 v[24:27], v[204:207], v[242:245], v[24:27]
	v_mfma_f32_16x16x32_bf16 v[28:31], v[214:217], v[242:245], v[28:31]
	s_setprio 0
	s_barrier
	s_and_saveexec_b64 s[0:1], s[36:37]
	s_cbranch_execz .LBB0_818
	s_barrier

; #define LDA(dst, b, h) for (int m = 0; m < 4; ++m) for (int k = 0; k < 2; ++k) \
;     dst[m][k] = *reinterpret_cast<const bf16x8*>((char*)SA(b, h) + lds_byte(wr * 64 + m * 16 + fr, k * 32 + fq * 8))
; #define LDB(dst, b, h) for (int n = 0; n < 2; ++n) for (int k = 0; k < 2; ++k) \
;     dst[n][k] = *reinterpret_cast<const bf16x8*>((char*)SB(b, h) + lds_byte(wc * 32 + n * 16 + fr, k * 32 + fq * 8))
; #define MMA(ai, bj, At, Bt_) do { __builtin_amdgcn_s_setprio(1); \
;     for (int m = 0; m < 4; ++m) for (int n = 0; n < 2; ++n) for (int k = 0; k < 2; ++k) \
;       acc[ai][bj][m][n] = __builtin_amdgcn_mfma_f32_16x16x32_bf16(Bt_[n][k], At[m][k], acc[ai][bj][m][n], 0, 0, 0); \
;     __builtin_amdgcn_s_setprio(0); } while (0)
; #define WAIT_V(n) asm volatile("s_waitcnt vmcnt(" #n ")" ::: "memory")
; #define WAIT_L(n) asm volatile("s_waitcnt lgkmcnt(" #n ")" ::: "memory")
; #define BAR __builtin_amdgcn_s_barrier()
; #define SCHED __builtin_amdgcn_sched_barrier(0)
; template <int MODE>
; DI void gemm_phase(const bf16_t* __restrict__ A, const bf16_t* __restrict__ Bt, int M, int N, int K, const Epi& ep) {
;     ...
;             LDB(B0, 0, 0); LDB(B1, 0, 1); SCHED; LDA(At, 0, 0); STAGE(SA(1, 1), rsA, brow + HALF, t + 1);
;             WAIT_V(8); WAIT_L(0); BAR; MMA(0, 0, At, B0); MMA(0, 1, At, B1); BAR; SCHED;
;             LDA(At, 0, 1); STAGE(SB(0, 0), rsB, bcol, t + 2); STAGE(SB(0, 1), rsB, bcol + HALF, t + 2); STAGE(SA(0, 0), rsA, brow, t + 2);
;             WAIT_V(8); WAIT_L(0); BAR; MMA(1, 0, At, B0); MMA(1, 1, At, B1); BAR; SCHED;
.LBB0_1023:
	ds_read_b128 v[156:159], v147
	ds_read_b128 v[160:163], v147 offset:1024
	ds_read_b128 v[164:167], v147 offset:2048
	ds_read_b128 v[168:171], v147 offset:3072
	ds_read_b128 v[172:175], v148
	ds_read_b128 v[176:179], v148 offset:1024
	ds_read_b128 v[180:183], v148 offset:2048
	ds_read_b128 v[184:187], v148 offset:3072
	s_add_i32 s42, s31, s41
	v_readfirstlane_b32 s15, v144
	s_add_i32 s14, s42, 0x40080
	s_mov_b32 s26, s10
	s_mov_b32 s27, s11
	s_mov_b32 m0, s15
	v_readfirstlane_b32 s15, v145
	ds_read_b128 v[188:191], v149
	ds_read_b128 v[192:195], v149 offset:1024
	ds_read_b128 v[196:199], v150
	ds_read_b128 v[200:203], v150 offset:1024
	ds_read_b128 v[204:207], v151
	ds_read_b128 v[208:211], v151 offset:1024
	ds_read_b128 v[214:217], v152
	ds_read_b128 v[218:221], v152 offset:1024
	buffer_load_dwordx4 v128, s[24:27], s14 offen lds
	s_mov_b32 m0, s15
	s_nop 0
	buffer_load_dwordx4 v129, s[24:27], s14 offen lds
	s_waitcnt vmcnt(8)
	s_waitcnt lgkmcnt(0)
	s_barrier
	s_setprio 1
	v_mfma_f32_16x16x32_bf16 v[124:127], v[156:159], v[188:191], v[124:127]
	v_mfma_f32_16x16x32_bf16 v[120:123], v[164:167], v[188:191], v[120:123]
	v_mfma_f32_16x16x32_bf16 v[116:119], v[156:159], v[196:199], v[116:119]
	v_mfma_f32_16x16x32_bf16 v[112:115], v[164:167], v[196:199], v[112:115]
	v_mfma_f32_16x16x32_bf16 v[108:111], v[156:159], v[204:207], v[108:111]
	v_mfma_f32_16x16x32_bf16 v[104:107], v[164:167], v[204:207], v[104:107]
	v_mfma_f32_16x16x32_bf16 v[100:103], v[156:159], v[214:217], v[100:103]
	v_mfma_f32_16x16x32_bf16 v[96:99], v[164:167], v[214:217], v[96:99]
	v_mfma_f32_16x16x32_bf16 v[124:127], v[160:163], v[192:195], v[124:127]
	v_mfma_f32_16x16x32_bf16 v[120:123], v[168:171], v[192:195], v[120:123]
	v_mfma_f32_16x16x32_bf16 v[116:119], v[160:163], v[200:203], v[116:119]
	v_mfma_f32_16x16x32_bf16 v[112:115], v[168:171], v[200:203], v[112:115]
	v_mfma_f32_16x16x32_bf16 v[108:111], v[160:163], v[208:211], v[108:111]
	v_mfma_f32_16x16x32_bf16 v[104:107], v[168:171], v[208:211], v[104:107]
	v_mfma_f32_16x16x32_bf16 v[100:103], v[160:163], v[218:221], v[100:103]
	v_mfma_f32_16x16x32_bf16 v[96:99], v[168:171], v[218:221], v[96:99]
	v_mfma_f32_16x16x32_bf16 v[92:95], v[172:175], v[188:191], v[92:95]
	v_mfma_f32_16x16x32_bf16 v[88:91], v[180:183], v[188:191], v[88:91]
	v_mfma_f32_16x16x32_bf16 v[84:87], v[172:175], v[196:199], v[84:87]
	v_mfma_f32_16x16x32_bf16 v[80:83], v[180:183], v[196:199], v[80:83]
	v_mfma_f32_16x16x32_bf16 v[76:79], v[172:175], v[204:207], v[76:79]
	v_mfma_f32_16x16x32_bf16 v[72:75], v[180:183], v[204:207], v[72:75]
	v_mfma_f32_16x16x32_bf16 v[68:71], v[172:175], v[214:217], v[68:71]
	v_mfma_f32_16x16x32_bf16 v[64:67], v[180:183], v[214:217], v[64:67]
	v_mfma_f32_16x16x32_bf16 v[92:95], v[176:179], v[192:195], v[92:95]
	v_mfma_f32_16x16x32_bf16 v[88:91], v[184:187], v[192:195], v[88:91]
	v_mfma_f32_16x16x32_bf16 v[84:87], v[176:179], v[200:203], v[84:87]
	v_mfma_f32_16x16x32_bf16 v[80:83], v[184:187], v[200:203], v[80:83]
	v_mfma_f32_16x16x32_bf16 v[76:79], v[176:179], v[208:211], v[76:79]
	v_mfma_f32_16x16x32_bf16 v[72:75], v[184:187], v[208:211], v[72:75]
	v_mfma_f32_16x16x32_bf16 v[68:71], v[176:179], v[218:221], v[68:71]
	v_mfma_f32_16x16x32_bf16 v[64:67], v[184:187], v[218:221], v[64:67]
	s_setprio 0
	s_barrier
	s_add_i32 s43, s6, s41
	v_readfirstlane_b32 s45, v130
	s_add_i32 s44, s43, 0x100
	s_mov_b32 s14, s10
	s_mov_b32 s15, s11
	s_mov_b32 m0, s45
	v_readfirstlane_b32 s45, v131
	ds_read_b128 v[188:191], v149 offset:16384
	ds_read_b128 v[192:195], v149 offset:17408
	ds_read_b128 v[196:199], v150 offset:16384
	ds_read_b128 v[200:203], v150 offset:17408
	ds_read_b128 v[204:207], v151 offset:16384
	ds_read_b128 v[208:211], v151 offset:17408
	ds_read_b128 v[214:217], v152 offset:16384
	ds_read_b128 v[218:221], v152 offset:17408
	buffer_load_dwordx4 v128, s[12:15], s44 offen lds
	s_mov_b32 m0, s45
	v_readfirstlane_b32 s45, v132
	buffer_load_dwordx4 v129, s[12:15], s44 offen lds
	s_add_i32 s44, s43, 0x40100
	s_mov_b32 m0, s45
	v_readfirstlane_b32 s45, v133
	buffer_load_dwordx4 v128, s[12:15], s44 offen lds
	s_mov_b32 m0, s45
	v_readfirstlane_b32 s45, v134
	buffer_load_dwordx4 v129, s[12:15], s44 offen lds
	s_add_i32 s44, s42, 0x100
	s_mov_b32 m0, s45
	v_readfirstlane_b32 s45, v135
	buffer_load_dwordx4 v128, s[24:27], s44 offen lds
	s_mov_b32 m0, s45
	s_nop 0
	buffer_load_dwordx4 v129, s[24:27], s44 offen lds
	s_waitcnt vmcnt(8)
	s_waitcnt lgkmcnt(0)
	s_barrier
	s_setprio 1
	v_mfma_f32_16x16x32_bf16 v[60:63], v[156:159], v[188:191], v[60:63]
	v_mfma_f32_16x16x32_bf16 v[56:59], v[164:167], v[188:191], v[56:59]
	v_mfma_f32_16x16x32_bf16 v[52:55], v[156:159], v[196:199], v[52:55]
	v_mfma_f32_16x16x32_bf16 v[48:51], v[164:167], v[196:199], v[48:51]
	v_mfma_f32_16x16x32_bf16 v[44:47], v[156:159], v[204:207], v[44:47]
	v_mfma_f32_16x16x32_bf16 v[40:43], v[164:167], v[204:207], v[40:43]
	v_mfma_f32_16x16x32_bf16 v[36:39], v[156:159], v[214:217], v[36:39]
	v_mfma_f32_16x16x32_bf16 v[32:35], v[164:167], v[214:217], v[32:35]
	v_mfma_f32_16x16x32_bf16 v[60:63], v[160:163], v[192:195], v[60:63]
	v_mfma_f32_16x16x32_bf16 v[56:59], v[168:171], v[192:195], v[56:59]
	v_mfma_f32_16x16x32_bf16 v[52:55], v[160:163], v[200:203], v[52:55]
	v_mfma_f32_16x16x32_bf16 v[48:51], v[168:171], v[200:203], v[48:51]
	v_mfma_f32_16x16x32_bf16 v[44:47], v[160:163], v[208:211], v[44:47]
	v_mfma_f32_16x16x32_bf16 v[40:43], v[168:171], v[208:211], v[40:43]
	v_mfma_f32_16x16x32_bf16 v[36:39], v[160:163], v[218:221], v[36:39]
	v_mfma_f32_16x16x32_bf16 v[32:35], v[168:171], v[218:221], v[32:35]
	v_mfma_f32_16x16x32_bf16 v[28:31], v[172:175], v[188:191], v[28:31]
	v_mfma_f32_16x16x32_bf16 v[24:27], v[180:183], v[188:191], v[24:27]
	v_mfma_f32_16x16x32_bf16 v[20:23], v[172:175], v[196:199], v[20:23]
	v_mfma_f32_16x16x32_bf16 v[16:19], v[180:183], v[196:199], v[16:19]
	v_mfma_f32_16x16x32_bf16 v[12:15], v[172:175], v[204:207], v[12:15]
	v_mfma_f32_16x16x32_bf16 v[8:11], v[180:183], v[204:207], v[8:11]
	v_mfma_f32_16x16x32_bf16 v[4:7], v[172:175], v[214:217], v[4:7]
	v_mfma_f32_16x16x32_bf16 v[0:3], v[180:183], v[214:217], v[0:3]
	v_mfma_f32_16x16x32_bf16 v[28:31], v[176:179], v[192:195], v[28:31]
	v_mfma_f32_16x16x32_bf16 v[24:27], v[184:187], v[192:195], v[24:27]
	v_mfma_f32_16x16x32_bf16 v[20:23], v[176:179], v[200:203], v[20:23]
	v_mfma_f32_16x16x32_bf16 v[16:19], v[184:187], v[200:203], v[16:19]
	v_mfma_f32_16x16x32_bf16 v[12:15], v[176:179], v[208:211], v[12:15]
	v_mfma_f32_16x16x32_bf16 v[8:11], v[184:187], v[208:211], v[8:11]
	v_mfma_f32_16x16x32_bf16 v[4:7], v[176:179], v[218:221], v[4:7]
	v_mfma_f32_16x16x32_bf16 v[0:3], v[184:187], v[218:221], v[0:3]
	s_setprio 0
	s_barrier
; #define LDA(dst, b, h) for (int m = 0; m < 4; ++m) for (int k = 0; k < 2; ++k) \
;     dst[m][k] = *reinterpret_cast<const bf16x8*>((char*)SA(b, h) + lds_byte(wr * 64 + m * 16 + fr, k * 32 + fq * 8))
; #define LDB(dst, b, h) for (int n = 0; n < 2; ++n) for (int k = 0; k < 2; ++k) \
;     dst[n][k] = *reinterpret_cast<const bf16x8*>((char*)SB(b, h) + lds_byte(wc * 32 + n * 16 + fr, k * 32 + fq * 8))
; #define MMA(ai, bj, At, Bt_) do { __builtin_amdgcn_s_setprio(1); \
;     for (int m = 0; m < 4; ++m) for (int n = 0; n < 2; ++n) for (int k = 0; k < 2; ++k) \
;       acc[ai][bj][m][n] = __builtin_amdgcn_mfma_f32_16x16x32_bf16(Bt_[n][k], At[m][k], acc[ai][bj][m][n], 0, 0, 0); \
;     __builtin_amdgcn_s_setprio(0); } while (0)
; #define WAIT_V(n) asm volatile("s_waitcnt vmcnt(" #n ")" ::: "memory")
; #define WAIT_L(n) asm volatile("s_waitcnt lgkmcnt(" #n ")" ::: "memory")
; #define BAR __builtin_amdgcn_s_barrier()
; #define SCHED __builtin_amdgcn_sched_barrier(0)
; template <int MODE>
; DI void gemm_phase(const bf16_t* __restrict__ A, const bf16_t* __restrict__ Bt, int M, int N, int K, const Epi& ep) {
;     ...
;             LDB(B0, 1, 0); LDB(B1, 1, 1); SCHED; LDA(At, 1, 0); STAGE(SA(0, 1), rsA, brow + HALF, t + 2);
;             WAIT_V(8); WAIT_L(0); BAR; MMA(0, 0, At, B0); MMA(0, 1, At, B1); BAR; SCHED;
;             LDA(At, 1, 1); STAGE(SB(1, 0), rsB, bcol, t + 3); STAGE(SB(1, 1), rsB, bcol + HALF, t + 3); STAGE(SA(1, 0), rsA, brow, t + 3);
;             WAIT_V(8); WAIT_L(0); BAR; MMA(1, 0, At, B0); MMA(1, 1, At, B1); BAR; SCHED;
	ds_read_b128 v[156:159], v153
	ds_read_b128 v[160:163], v153 offset:1024
	ds_read_b128 v[164:167], v153 offset:2048
	ds_read_b128 v[168:171], v153 offset:3072
	ds_read_b128 v[172:175], v154
	ds_read_b128 v[176:179], v154 offset:1024
	ds_read_b128 v[180:183], v154 offset:2048
	ds_read_b128 v[184:187], v154 offset:3072
	v_readfirstlane_b32 s45, v136
	s_add_i32 s44, s42, 0x40100
	s_mov_b32 m0, s45
	v_readfirstlane_b32 s45, v137
	ds_read_b128 v[188:191], v149 offset:32768
	ds_read_b128 v[192:195], v149 offset:33792
	ds_read_b128 v[196:199], v150 offset:32768
	ds_read_b128 v[200:203], v150 offset:33792
	ds_read_b128 v[204:207], v151 offset:32768
	ds_read_b128 v[208:211], v151 offset:33792
	ds_read_b128 v[214:217], v152 offset:32768
	ds_read_b128 v[218:221], v152 offset:33792
	buffer_load_dwordx4 v128, s[24:27], s44 offen lds
	s_mov_b32 m0, s45
	s_nop 0
	buffer_load_dwordx4 v129, s[24:27], s44 offen lds
	s_waitcnt vmcnt(8)
	s_waitcnt lgkmcnt(0)
	s_barrier
	s_setprio 1
	v_mfma_f32_16x16x32_bf16 v[124:127], v[156:159], v[188:191], v[124:127]
	v_mfma_f32_16x16x32_bf16 v[120:123], v[164:167], v[188:191], v[120:123]
	v_mfma_f32_16x16x32_bf16 v[116:119], v[156:159], v[196:199], v[116:119]
	v_mfma_f32_16x16x32_bf16 v[112:115], v[164:167], v[196:199], v[112:115]
	v_mfma_f32_16x16x32_bf16 v[108:111], v[156:159], v[204:207], v[108:111]
	v_mfma_f32_16x16x32_bf16 v[104:107], v[164:167], v[204:207], v[104:107]
	v_mfma_f32_16x16x32_bf16 v[100:103], v[156:159], v[214:217], v[100:103]
	v_mfma_f32_16x16x32_bf16 v[96:99], v[164:167], v[214:217], v[96:99]
	v_mfma_f32_16x16x32_bf16 v[124:127], v[160:163], v[192:195], v[124:127]
	v_mfma_f32_16x16x32_bf16 v[120:123], v[168:171], v[192:195], v[120:123]
	v_mfma_f32_16x16x32_bf16 v[116:119], v[160:163], v[200:203], v[116:119]
	v_mfma_f32_16x16x32_bf16 v[112:115], v[168:171], v[200:203], v[112:115]
	v_mfma_f32_16x16x32_bf16 v[108:111], v[160:163], v[208:211], v[108:111]
	v_mfma_f32_16x16x32_bf16 v[104:107], v[168:171], v[208:211], v[104:107]
	v_mfma_f32_16x16x32_bf16 v[100:103], v[160:163], v[218:221], v[100:103]
	v_mfma_f32_16x16x32_bf16 v[96:99], v[168:171], v[218:221], v[96:99]
	v_mfma_f32_16x16x32_bf16 v[92:95], v[172:175], v[188:191], v[92:95]
	v_mfma_f32_16x16x32_bf16 v[88:91], v[180:183], v[188:191], v[88:91]
	v_mfma_f32_16x16x32_bf16 v[84:87], v[172:175], v[196:199], v[84:87]
	v_mfma_f32_16x16x32_bf16 v[80:83], v[180:183], v[196:199], v[80:83]
	v_mfma_f32_16x16x32_bf16 v[76:79], v[172:175], v[204:207], v[76:79]
	v_mfma_f32_16x16x32_bf16 v[72:75], v[180:183], v[204:207], v[72:75]
	v_mfma_f32_16x16x32_bf16 v[68:71], v[172:175], v[214:217], v[68:71]
	v_mfma_f32_16x16x32_bf16 v[64:67], v[180:183], v[214:217], v[64:67]
	v_mfma_f32_16x16x32_bf16 v[92:95], v[176:179], v[192:195], v[92:95]
	v_mfma_f32_16x16x32_bf16 v[88:91], v[184:187], v[192:195], v[88:91]
	v_mfma_f32_16x16x32_bf16 v[84:87], v[176:179], v[200:203], v[84:87]
	v_mfma_f32_16x16x32_bf16 v[80:83], v[184:187], v[200:203], v[80:83]
	v_mfma_f32_16x16x32_bf16 v[76:79], v[176:179], v[208:211], v[76:79]
	v_mfma_f32_16x16x32_bf16 v[72:75], v[184:187], v[208:211], v[72:75]
	v_mfma_f32_16x16x32_bf16 v[68:71], v[176:179], v[218:221], v[68:71]
	v_mfma_f32_16x16x32_bf16 v[64:67], v[184:187], v[218:221], v[64:67]
	s_setprio 0
	s_barrier
	v_readfirstlane_b32 s45, v138
	s_add_i32 s44, s43, 0x180
	s_mov_b32 m0, s45
	v_readfirstlane_b32 s45, v139
	ds_read_b128 v[188:191], v149 offset:49152
	ds_read_b128 v[192:195], v149 offset:50176
	ds_read_b128 v[196:199], v150 offset:49152
	ds_read_b128 v[200:203], v150 offset:50176
	ds_read_b128 v[204:207], v151 offset:49152
	ds_read_b128 v[208:211], v151 offset:50176
	ds_read_b128 v[214:217], v152 offset:49152
	ds_read_b128 v[218:221], v152 offset:50176
	buffer_load_dwordx4 v128, s[12:15], s44 offen lds
	s_mov_b32 m0, s45
	s_add_i32 s43, s43, 0x40180
	buffer_load_dwordx4 v129, s[12:15], s44 offen lds
	v_readfirstlane_b32 s44, v142
	s_mov_b32 m0, s44
	v_readfirstlane_b32 s44, v143
	buffer_load_dwordx4 v128, s[12:15], s43 offen lds
	s_mov_b32 m0, s44
	s_addk_i32 s42, 0x180
	buffer_load_dwordx4 v129, s[12:15], s43 offen lds
	v_readfirstlane_b32 s14, v140
	s_mov_b32 m0, s14
	v_readfirstlane_b32 s14, v141
	buffer_load_dwordx4 v128, s[24:27], s42 offen lds
	s_mov_b32 m0, s14
	s_nop 0
	buffer_load_dwordx4 v129, s[24:27], s42 offen lds
	s_waitcnt vmcnt(8)
	s_waitcnt lgkmcnt(0)
	s_barrier
	s_setprio 1
	v_mfma_f32_16x16x32_bf16 v[60:63], v[156:159], v[188:191], v[60:63]
	v_mfma_f32_16x16x32_bf16 v[56:59], v[164:167], v[188:191], v[56:59]
	v_mfma_f32_16x16x32_bf16 v[52:55], v[156:159], v[196:199], v[52:55]
	v_mfma_f32_16x16x32_bf16 v[48:51], v[164:167], v[196:199], v[48:51]
	v_mfma_f32_16x16x32_bf16 v[44:47], v[156:159], v[204:207], v[44:47]
	v_mfma_f32_16x16x32_bf16 v[40:43], v[164:167], v[204:207], v[40:43]
	v_mfma_f32_16x16x32_bf16 v[36:39], v[156:159], v[214:217], v[36:39]
	v_mfma_f32_16x16x32_bf16 v[32:35], v[164:167], v[214:217], v[32:35]
	v_mfma_f32_16x16x32_bf16 v[60:63], v[160:163], v[192:195], v[60:63]
	v_mfma_f32_16x16x32_bf16 v[56:59], v[168:171], v[192:195], v[56:59]
	v_mfma_f32_16x16x32_bf16 v[52:55], v[160:163], v[200:203], v[52:55]
	v_mfma_f32_16x16x32_bf16 v[48:51], v[168:171], v[200:203], v[48:51]
	v_mfma_f32_16x16x32_bf16 v[44:47], v[160:163], v[208:211], v[44:47]
	v_mfma_f32_16x16x32_bf16 v[40:43], v[168:171], v[208:211], v[40:43]
	v_mfma_f32_16x16x32_bf16 v[36:39], v[160:163], v[218:221], v[36:39]
	v_mfma_f32_16x16x32_bf16 v[32:35], v[168:171], v[218:221], v[32:35]
	v_mfma_f32_16x16x32_bf16 v[28:31], v[172:175], v[188:191], v[28:31]
	v_mfma_f32_16x16x32_bf16 v[24:27], v[180:183], v[188:191], v[24:27]
	v_mfma_f32_16x16x32_bf16 v[20:23], v[172:175], v[196:199], v[20:23]
	v_mfma_f32_16x16x32_bf16 v[16:19], v[180:183], v[196:199], v[16:19]
	v_mfma_f32_16x16x32_bf16 v[12:15], v[172:175], v[204:207], v[12:15]
	v_mfma_f32_16x16x32_bf16 v[8:11], v[180:183], v[204:207], v[8:11]
	v_mfma_f32_16x16x32_bf16 v[4:7], v[172:175], v[214:217], v[4:7]
	v_mfma_f32_16x16x32_bf16 v[0:3], v[180:183], v[214:217], v[0:3]
	v_mfma_f32_16x16x32_bf16 v[28:31], v[176:179], v[192:195], v[28:31]
	v_mfma_f32_16x16x32_bf16 v[24:27], v[184:187], v[192:195], v[24:27]
	v_mfma_f32_16x16x32_bf16 v[20:23], v[176:179], v[200:203], v[20:23]
	v_mfma_f32_16x16x32_bf16 v[16:19], v[184:187], v[200:203], v[16:19]
	v_mfma_f32_16x16x32_bf16 v[12:15], v[176:179], v[208:211], v[12:15]
	v_mfma_f32_16x16x32_bf16 v[8:11], v[184:187], v[208:211], v[8:11]
	v_mfma_f32_16x16x32_bf16 v[4:7], v[176:179], v[218:221], v[4:7]
	v_mfma_f32_16x16x32_bf16 v[0:3], v[184:187], v[218:221], v[0:3]
	s_setprio 0
	s_barrier
; #define LDA(dst, b, h) for (int m = 0; m < 4; ++m) for (int k = 0; k < 2; ++k) \
;     dst[m][k] = *reinterpret_cast<const bf16x8*>((char*)SA(b, h) + lds_byte(wr * 64 + m * 16 + fr, k * 32 + fq * 8))
; #define LDB(dst, b, h) for (int n = 0; n < 2; ++n) for (int k = 0; k < 2; ++k) \
;     dst[n][k] = *reinterpret_cast<const bf16x8*>((char*)SB(b, h) + lds_byte(wc * 32 + n * 16 + fr, k * 32 + fq * 8))
; #define MMA(ai, bj, At, Bt_) do { __builtin_amdgcn_s_setprio(1); \
;     for (int m = 0; m < 4; ++m) for (int n = 0; n < 2; ++n) for (int k = 0; k < 2; ++k) \
;       acc[ai][bj][m][n] = __builtin_amdgcn_mfma_f32_16x16x32_bf16(Bt_[n][k], At[m][k], acc[ai][bj][m][n], 0, 0, 0); \
;     __builtin_amdgcn_s_setprio(0); } while (0)
; #define WAIT_V(n) asm volatile("s_waitcnt vmcnt(" #n ")" ::: "memory")
; #define WAIT_L(n) asm volatile("s_waitcnt lgkmcnt(" #n ")" ::: "memory")
; #define BAR __builtin_amdgcn_s_barrier()
; #define SCHED __builtin_amdgcn_sched_barrier(0)
; template <int MODE>
; DI void gemm_phase(const bf16_t* __restrict__ A, const bf16_t* __restrict__ Bt, int M, int N, int K, const Epi& ep) {
;     ...
;             LDB(B0, 0, 0); LDB(B1, 0, 1); SCHED; LDA(At, 0, 0); STAGE(SA(1, 1), rsA, brow + HALF, nt - 1);
;             WAIT_V(8); WAIT_L(0); BAR; MMA(0, 0, At, B0); MMA(0, 1, At, B1); BAR; SCHED;
;             LDA(At, 0, 1);
;             WAIT_V(2); WAIT_L(0); BAR; MMA(1, 0, At, B0); MMA(1, 1, At, B1); BAR; SCHED;
	s_add_i32 s40, s40, 2
	s_addk_i32 s41, 0x100
	s_cmp_gt_u32 s40, 11
	s_cbranch_scc0 .LBB0_1023
	ds_read_b128 v[156:159], v147
	ds_read_b128 v[160:163], v147 offset:1024
	ds_read_b128 v[164:167], v147 offset:2048
	ds_read_b128 v[168:171], v147 offset:3072
	ds_read_b128 v[172:175], v148
	ds_read_b128 v[176:179], v148 offset:1024
	ds_read_b128 v[180:183], v148 offset:2048
	ds_read_b128 v[184:187], v148 offset:3072
	s_or_b32 s6, s7, 0x780
	v_readfirstlane_b32 s7, v144
	s_mov_b32 m0, s7
	v_readfirstlane_b32 s7, v145
	ds_read_b128 v[188:191], v149
	ds_read_b128 v[192:195], v149 offset:1024
	ds_read_b128 v[196:199], v150
	ds_read_b128 v[200:203], v150 offset:1024
	ds_read_b128 v[204:207], v151
	ds_read_b128 v[208:211], v151 offset:1024
	ds_read_b128 v[214:217], v152
	ds_read_b128 v[218:221], v152 offset:1024
	buffer_load_dwordx4 v128, s[24:27], s6 offen lds
	s_mov_b32 m0, s7
	s_nop 0
	buffer_load_dwordx4 v129, s[24:27], s6 offen lds
	s_waitcnt vmcnt(8)
	s_waitcnt lgkmcnt(0)
	s_barrier
	s_setprio 1
	v_mfma_f32_16x16x32_bf16 v[124:127], v[156:159], v[188:191], v[124:127]
	v_mfma_f32_16x16x32_bf16 v[120:123], v[164:167], v[188:191], v[120:123]
	v_mfma_f32_16x16x32_bf16 v[116:119], v[156:159], v[196:199], v[116:119]
	v_mfma_f32_16x16x32_bf16 v[112:115], v[164:167], v[196:199], v[112:115]
	v_mfma_f32_16x16x32_bf16 v[108:111], v[156:159], v[204:207], v[108:111]
	v_mfma_f32_16x16x32_bf16 v[124:127], v[160:163], v[192:195], v[124:127]
	v_mfma_f32_16x16x32_bf16 v[120:123], v[168:171], v[192:195], v[120:123]
	v_mfma_f32_16x16x32_bf16 v[116:119], v[160:163], v[200:203], v[116:119]
	v_mfma_f32_16x16x32_bf16 v[112:115], v[168:171], v[200:203], v[112:115]
	v_mfma_f32_16x16x32_bf16 v[222:225], v[160:163], v[208:211], v[108:111]
	v_mfma_f32_16x16x32_bf16 v[104:107], v[164:167], v[204:207], v[104:107]
	v_mfma_f32_16x16x32_bf16 v[100:103], v[156:159], v[214:217], v[100:103]
	v_mfma_f32_16x16x32_bf16 v[96:99], v[164:167], v[214:217], v[96:99]
	v_mfma_f32_16x16x32_bf16 v[226:229], v[168:171], v[208:211], v[104:107]
	v_mfma_f32_16x16x32_bf16 v[230:233], v[160:163], v[218:221], v[100:103]
	v_mfma_f32_16x16x32_bf16 v[234:237], v[168:171], v[218:221], v[96:99]
	v_mfma_f32_16x16x32_bf16 v[92:95], v[172:175], v[188:191], v[92:95]
	v_mfma_f32_16x16x32_bf16 v[88:91], v[180:183], v[188:191], v[88:91]
	v_mfma_f32_16x16x32_bf16 v[84:87], v[172:175], v[196:199], v[84:87]
	v_mfma_f32_16x16x32_bf16 v[80:83], v[180:183], v[196:199], v[80:83]
	v_mfma_f32_16x16x32_bf16 v[92:95], v[176:179], v[192:195], v[92:95]
	v_mfma_f32_16x16x32_bf16 v[88:91], v[184:187], v[192:195], v[88:91]
	v_mfma_f32_16x16x32_bf16 v[84:87], v[176:179], v[200:203], v[84:87]
	v_mfma_f32_16x16x32_bf16 v[80:83], v[184:187], v[200:203], v[80:83]
	v_mfma_f32_16x16x32_bf16 v[76:79], v[172:175], v[204:207], v[76:79]
	v_mfma_f32_16x16x32_bf16 v[72:75], v[180:183], v[204:207], v[72:75]
	v_mfma_f32_16x16x32_bf16 v[68:71], v[172:175], v[214:217], v[68:71]
	v_mfma_f32_16x16x32_bf16 v[64:67], v[180:183], v[214:217], v[64:67]
	v_mfma_f32_16x16x32_bf16 v[188:191], v[176:179], v[208:211], v[76:79]
	v_mfma_f32_16x16x32_bf16 v[192:195], v[184:187], v[208:211], v[72:75]
	v_mfma_f32_16x16x32_bf16 v[196:199], v[176:179], v[218:221], v[68:71]
	v_mfma_f32_16x16x32_bf16 v[200:203], v[184:187], v[218:221], v[64:67]
	s_setprio 0
	s_barrier
	s_nop 1
	ds_read_b128 v[64:67], v149 offset:16384
	ds_read_b128 v[68:71], v149 offset:17408
	ds_read_b128 v[72:75], v150 offset:16384
	ds_read_b128 v[76:79], v150 offset:17408
	ds_read_b128 v[96:99], v151 offset:16384
	ds_read_b128 v[100:103], v151 offset:17408
	ds_read_b128 v[104:107], v152 offset:16384
	ds_read_b128 v[108:111], v152 offset:17408
	s_waitcnt vmcnt(2)
	s_waitcnt lgkmcnt(0)
	s_barrier
	s_setprio 1
	v_mfma_f32_16x16x32_bf16 v[60:63], v[156:159], v[64:67], v[60:63]
	v_mfma_f32_16x16x32_bf16 v[56:59], v[164:167], v[64:67], v[56:59]
	v_mfma_f32_16x16x32_bf16 v[52:55], v[156:159], v[72:75], v[52:55]
	v_mfma_f32_16x16x32_bf16 v[48:51], v[164:167], v[72:75], v[48:51]
	v_mfma_f32_16x16x32_bf16 v[60:63], v[160:163], v[68:71], v[60:63]
	v_mfma_f32_16x16x32_bf16 v[56:59], v[168:171], v[68:71], v[56:59]
	v_mfma_f32_16x16x32_bf16 v[52:55], v[160:163], v[76:79], v[52:55]
	v_mfma_f32_16x16x32_bf16 v[48:51], v[168:171], v[76:79], v[48:51]
	v_mfma_f32_16x16x32_bf16 v[44:47], v[156:159], v[96:99], v[44:47]
	v_mfma_f32_16x16x32_bf16 v[40:43], v[164:167], v[96:99], v[40:43]
	v_mfma_f32_16x16x32_bf16 v[36:39], v[156:159], v[104:107], v[36:39]
	v_mfma_f32_16x16x32_bf16 v[32:35], v[164:167], v[104:107], v[32:35]
	v_mfma_f32_16x16x32_bf16 v[204:207], v[160:163], v[100:103], v[44:47]
	v_mfma_f32_16x16x32_bf16 v[208:211], v[168:171], v[100:103], v[40:43]
	v_mfma_f32_16x16x32_bf16 v[156:159], v[160:163], v[108:111], v[36:39]
	v_mfma_f32_16x16x32_bf16 v[160:163], v[168:171], v[108:111], v[32:35]
	v_mfma_f32_16x16x32_bf16 v[28:31], v[172:175], v[64:67], v[28:31]
	v_mfma_f32_16x16x32_bf16 v[24:27], v[180:183], v[64:67], v[24:27]
	v_mfma_f32_16x16x32_bf16 v[20:23], v[172:175], v[72:75], v[20:23]
	v_mfma_f32_16x16x32_bf16 v[16:19], v[180:183], v[72:75], v[16:19]
	v_mfma_f32_16x16x32_bf16 v[28:31], v[176:179], v[68:71], v[28:31]
	v_mfma_f32_16x16x32_bf16 v[24:27], v[184:187], v[68:71], v[24:27]
	v_mfma_f32_16x16x32_bf16 v[20:23], v[176:179], v[76:79], v[20:23]
	v_mfma_f32_16x16x32_bf16 v[16:19], v[184:187], v[76:79], v[16:19]
	v_mfma_f32_16x16x32_bf16 v[12:15], v[172:175], v[96:99], v[12:15]
	v_mfma_f32_16x16x32_bf16 v[8:11], v[180:183], v[96:99], v[8:11]
	v_mfma_f32_16x16x32_bf16 v[4:7], v[172:175], v[104:107], v[4:7]
	v_mfma_f32_16x16x32_bf16 v[0:3], v[180:183], v[104:107], v[0:3]
	v_mfma_f32_16x16x32_bf16 v[164:167], v[176:179], v[100:103], v[12:15]
	v_mfma_f32_16x16x32_bf16 v[168:171], v[184:187], v[100:103], v[8:11]
	v_mfma_f32_16x16x32_bf16 v[172:175], v[176:179], v[108:111], v[4:7]
	v_mfma_f32_16x16x32_bf16 v[176:179], v[184:187], v[108:111], v[0:3]
	s_setprio 0
	s_barrier
; #define LDA(dst, b, h) for (int m = 0; m < 4; ++m) for (int k = 0; k < 2; ++k) \
;     dst[m][k] = *reinterpret_cast<const bf16x8*>((char*)SA(b, h) + lds_byte(wr * 64 + m * 16 + fr, k * 32 + fq * 8))
; #define LDB(dst, b, h) for (int n = 0; n < 2; ++n) for (int k = 0; k < 2; ++k) \
;     dst[n][k] = *reinterpret_cast<const bf16x8*>((char*)SB(b, h) + lds_byte(wc * 32 + n * 16 + fr, k * 32 + fq * 8))
; #define MMA(ai, bj, At, Bt_) do { __builtin_amdgcn_s_setprio(1); \
;     for (int m = 0; m < 4; ++m) for (int n = 0; n < 2; ++n) for (int k = 0; k < 2; ++k) \
;       acc[ai][bj][m][n] = __builtin_amdgcn_mfma_f32_16x16x32_bf16(Bt_[n][k], At[m][k], acc[ai][bj][m][n], 0, 0, 0); \
;     __builtin_amdgcn_s_setprio(0); } while (0)
; #define WAIT_V(n) asm volatile("s_waitcnt vmcnt(" #n ")" ::: "memory")
; #define WAIT_L(n) asm volatile("s_waitcnt lgkmcnt(" #n ")" ::: "memory")
; #define BAR __builtin_amdgcn_s_barrier()
; #define SCHED __builtin_amdgcn_sched_barrier(0)
; template <int MODE>
; DI void gemm_phase(const bf16_t* __restrict__ A, const bf16_t* __restrict__ Bt, int M, int N, int K, const Epi& ep) {
;     ...
;             LDB(B0, 1, 0); LDB(B1, 1, 1); SCHED; LDA(At, 1, 0);
;             WAIT_V(0); WAIT_L(0); BAR; MMA(0, 0, At, B0); MMA(0, 1, At, B1); BAR; SCHED;
;             LDA(At, 1, 1);
;             WAIT_L(0); BAR; MMA(1, 0, At, B0); MMA(1, 1, At, B1); BAR; SCHED;
;         }
;         if (wr == 0) BAR;
	s_nop 1
	ds_read_b128 v[0:3], v153
	ds_read_b128 v[4:7], v153 offset:1024
	ds_read_b128 v[8:11], v153 offset:2048
	ds_read_b128 v[12:15], v153 offset:3072
	ds_read_b128 v[180:183], v154
	ds_read_b128 v[184:187], v154 offset:1024
	ds_read_b128 v[214:217], v154 offset:2048
	ds_read_b128 v[218:221], v154 offset:3072
	ds_read_b128 v[32:35], v149 offset:32768
	ds_read_b128 v[36:39], v149 offset:33792
	ds_read_b128 v[40:43], v150 offset:32768
	ds_read_b128 v[44:47], v150 offset:33792
	ds_read_b128 v[238:241], v151 offset:32768
	ds_read_b128 v[242:245], v151 offset:33792
	ds_read_b128 v[246:249], v152 offset:32768
	ds_read_b128 v[64:67], v152 offset:33792
	s_waitcnt vmcnt(0)
	s_waitcnt lgkmcnt(0)
	s_barrier
	s_setprio 1
	v_mfma_f32_16x16x32_bf16 v[68:71], v[0:3], v[32:35], v[124:127]
	v_mfma_f32_16x16x32_bf16 v[96:99], v[4:7], v[36:39], v[68:71]
	v_mfma_f32_16x16x32_bf16 v[68:71], v[8:11], v[32:35], v[120:123]
	v_mfma_f32_16x16x32_bf16 v[100:103], v[12:15], v[36:39], v[68:71]
	v_mfma_f32_16x16x32_bf16 v[68:71], v[0:3], v[40:43], v[116:119]
	v_mfma_f32_16x16x32_bf16 v[104:107], v[4:7], v[44:47], v[68:71]
	v_mfma_f32_16x16x32_bf16 v[68:71], v[8:11], v[40:43], v[112:115]
	v_mfma_f32_16x16x32_bf16 v[108:111], v[12:15], v[44:47], v[68:71]
	v_mfma_f32_16x16x32_bf16 v[68:71], v[0:3], v[238:241], v[222:225]
	v_mfma_f32_16x16x32_bf16 v[112:115], v[4:7], v[242:245], v[68:71]
	v_mfma_f32_16x16x32_bf16 v[68:71], v[8:11], v[238:241], v[226:229]
	v_mfma_f32_16x16x32_bf16 v[116:119], v[12:15], v[242:245], v[68:71]
	v_mfma_f32_16x16x32_bf16 v[68:71], v[0:3], v[246:249], v[230:233]
	v_mfma_f32_16x16x32_bf16 v[120:123], v[4:7], v[64:67], v[68:71]
	v_mfma_f32_16x16x32_bf16 v[68:71], v[8:11], v[246:249], v[234:237]
	v_mfma_f32_16x16x32_bf16 v[124:127], v[12:15], v[64:67], v[68:71]
	v_mfma_f32_16x16x32_bf16 v[68:71], v[180:183], v[32:35], v[92:95]
	v_mfma_f32_16x16x32_bf16 v[32:35], v[214:217], v[32:35], v[88:91]
	v_mfma_f32_16x16x32_bf16 v[222:225], v[184:187], v[36:39], v[68:71]
	v_mfma_f32_16x16x32_bf16 v[68:71], v[218:221], v[36:39], v[32:35]
	v_mfma_f32_16x16x32_bf16 v[32:35], v[180:183], v[40:43], v[84:87]
	v_mfma_f32_16x16x32_bf16 v[72:75], v[184:187], v[44:47], v[32:35]
	v_mfma_f32_16x16x32_bf16 v[32:35], v[214:217], v[40:43], v[80:83]
	v_mfma_f32_16x16x32_bf16 v[76:79], v[218:221], v[44:47], v[32:35]
	v_mfma_f32_16x16x32_bf16 v[32:35], v[180:183], v[238:241], v[188:191]
	v_mfma_f32_16x16x32_bf16 v[80:83], v[184:187], v[242:245], v[32:35]
	v_mfma_f32_16x16x32_bf16 v[32:35], v[214:217], v[238:241], v[192:195]
	v_mfma_f32_16x16x32_bf16 v[84:87], v[218:221], v[242:245], v[32:35]
	v_mfma_f32_16x16x32_bf16 v[32:35], v[180:183], v[246:249], v[196:199]
	v_mfma_f32_16x16x32_bf16 v[88:91], v[184:187], v[64:67], v[32:35]
	v_mfma_f32_16x16x32_bf16 v[32:35], v[214:217], v[246:249], v[200:203]
	v_mfma_f32_16x16x32_bf16 v[92:95], v[218:221], v[64:67], v[32:35]
	s_setprio 0
	s_barrier
	ds_read_b128 v[64:67], v149 offset:49152
	ds_read_b128 v[188:191], v149 offset:50176
	ds_read_b128 v[192:195], v150 offset:49152
	ds_read_b128 v[196:199], v150 offset:50176
	ds_read_b128 v[200:203], v151 offset:49152
	ds_read_b128 v[226:229], v151 offset:50176
	ds_read_b128 v[230:233], v152 offset:49152
	ds_read_b128 v[234:237], v152 offset:50176
	s_waitcnt lgkmcnt(0)
	s_barrier
	s_setprio 1
	v_mfma_f32_16x16x32_bf16 v[32:35], v[0:3], v[64:67], v[60:63]
	v_mfma_f32_16x16x32_bf16 v[40:43], v[0:3], v[192:195], v[52:55]
	v_mfma_f32_16x16x32_bf16 v[44:47], v[8:11], v[192:195], v[48:51]
	v_mfma_f32_16x16x32_bf16 v[48:51], v[0:3], v[200:203], v[204:207]
	v_mfma_f32_16x16x32_bf16 v[0:3], v[0:3], v[230:233], v[156:159]
	v_mfma_f32_16x16x32_bf16 v[36:39], v[8:11], v[64:67], v[56:59]
	v_mfma_f32_16x16x32_bf16 v[52:55], v[8:11], v[200:203], v[208:211]
	v_mfma_f32_16x16x32_bf16 v[56:59], v[4:7], v[234:237], v[0:3]
	v_mfma_f32_16x16x32_bf16 v[0:3], v[8:11], v[230:233], v[160:163]
	v_mfma_f32_16x16x32_bf16 v[32:35], v[4:7], v[188:191], v[32:35]
	v_mfma_f32_16x16x32_bf16 v[36:39], v[12:15], v[188:191], v[36:39]
	v_mfma_f32_16x16x32_bf16 v[40:43], v[4:7], v[196:199], v[40:43]
	v_mfma_f32_16x16x32_bf16 v[44:47], v[12:15], v[196:199], v[44:47]
	v_mfma_f32_16x16x32_bf16 v[48:51], v[4:7], v[226:229], v[48:51]
	v_mfma_f32_16x16x32_bf16 v[52:55], v[12:15], v[226:229], v[52:55]
	v_mfma_f32_16x16x32_bf16 v[60:63], v[12:15], v[234:237], v[0:3]
	v_mfma_f32_16x16x32_bf16 v[0:3], v[180:183], v[64:67], v[28:31]
	v_mfma_f32_16x16x32_bf16 v[4:7], v[214:217], v[64:67], v[24:27]
	v_mfma_f32_16x16x32_bf16 v[8:11], v[180:183], v[192:195], v[20:23]
	v_mfma_f32_16x16x32_bf16 v[12:15], v[214:217], v[192:195], v[16:19]
	v_mfma_f32_16x16x32_bf16 v[16:19], v[180:183], v[200:203], v[164:167]
	v_mfma_f32_16x16x32_bf16 v[20:23], v[214:217], v[200:203], v[168:171]
	v_mfma_f32_16x16x32_bf16 v[24:27], v[180:183], v[230:233], v[172:175]
	v_mfma_f32_16x16x32_bf16 v[28:31], v[214:217], v[230:233], v[176:179]
	v_mfma_f32_16x16x32_bf16 v[0:3], v[184:187], v[188:191], v[0:3]
	v_mfma_f32_16x16x32_bf16 v[4:7], v[218:221], v[188:191], v[4:7]
	v_mfma_f32_16x16x32_bf16 v[8:11], v[184:187], v[196:199], v[8:11]
	v_mfma_f32_16x16x32_bf16 v[12:15], v[218:221], v[196:199], v[12:15]
	v_mfma_f32_16x16x32_bf16 v[16:19], v[184:187], v[226:229], v[16:19]
	v_mfma_f32_16x16x32_bf16 v[20:23], v[218:221], v[226:229], v[20:23]
	v_mfma_f32_16x16x32_bf16 v[24:27], v[184:187], v[234:237], v[24:27]
	v_mfma_f32_16x16x32_bf16 v[28:31], v[218:221], v[234:237], v[28:31]
	s_setprio 0
	s_barrier
	s_and_saveexec_b64 s[6:7], s[38:39]
	s_cbranch_execz .LBB0_1015
	s_barrier
	s_branch .LBB0_1015

; #define LDA(dst, b, h) for (int m = 0; m < 4; ++m) for (int k = 0; k < 2; ++k) \
;     dst[m][k] = *reinterpret_cast<const bf16x8*>((char*)SA(b, h) + lds_byte(wr * 64 + m * 16 + fr, k * 32 + fq * 8))
; #define LDB(dst, b, h) for (int n = 0; n < 2; ++n) for (int k = 0; k < 2; ++k) \
;     dst[n][k] = *reinterpret_cast<const bf16x8*>((char*)SB(b, h) + lds_byte(wc * 32 + n * 16 + fr, k * 32 + fq * 8))
; #define MMA(ai, bj, At, Bt_) do { __builtin_amdgcn_s_setprio(1); \
;     for (int m = 0; m < 4; ++m) for (int n = 0; n < 2; ++n) for (int k = 0; k < 2; ++k) \
;       acc[ai][bj][m][n] = __builtin_amdgcn_mfma_f32_16x16x32_bf16(Bt_[n][k], At[m][k], acc[ai][bj][m][n], 0, 0, 0); \
;     __builtin_amdgcn_s_setprio(0); } while (0)
; #define WAIT_V(n) asm volatile("s_waitcnt vmcnt(" #n ")" ::: "memory")
; #define WAIT_L(n) asm volatile("s_waitcnt lgkmcnt(" #n ")" ::: "memory")
; #define BAR __builtin_amdgcn_s_barrier()
; #define SCHED __builtin_amdgcn_sched_barrier(0)
; template <int MODE>
; DI void gemm_phase(const bf16_t* __restrict__ A, const bf16_t* __restrict__ Bt, int M, int N, int K, const Epi& ep) {
;     ...
;             LDB(B0, 0, 0); LDB(B1, 0, 1); SCHED; LDA(At, 0, 0); STAGE(SA(1, 1), rsA, brow + HALF, t + 1);
;             WAIT_V(8); WAIT_L(0); BAR; MMA(0, 0, At, B0); MMA(0, 1, At, B1); BAR; SCHED;
;             LDA(At, 0, 1); STAGE(SB(0, 0), rsB, bcol, t + 2); STAGE(SB(0, 1), rsB, bcol + HALF, t + 2); STAGE(SA(0, 0), rsA, brow, t + 2);
;             WAIT_V(8); WAIT_L(0); BAR; MMA(1, 0, At, B0); MMA(1, 1, At, B1); BAR; SCHED;
.LBB0_1150:
	ds_read_b128 v[128:131], v186
	ds_read_b128 v[132:135], v186 offset:1024
	ds_read_b128 v[136:139], v186 offset:2048
	ds_read_b128 v[140:143], v186 offset:3072
	ds_read_b128 v[144:147], v187
	ds_read_b128 v[148:151], v187 offset:1024
	ds_read_b128 v[152:155], v187 offset:2048
	ds_read_b128 v[156:159], v187 offset:3072
	s_add_i32 s41, s0, s40
	v_readfirstlane_b32 s43, v184
	s_add_i32 s42, s41, 0x40080
	s_mov_b32 m0, s43
	v_readfirstlane_b32 s43, v185
	ds_read_b128 v[160:163], v188
	ds_read_b128 v[164:167], v188 offset:1024
	ds_read_b128 v[196:199], v189
	ds_read_b128 v[200:203], v189 offset:1024
	ds_read_b128 v[204:207], v190
	ds_read_b128 v[208:211], v190 offset:1024
	ds_read_b128 v[214:217], v191
	ds_read_b128 v[218:221], v191 offset:1024
	buffer_load_dwordx4 v168, s[8:11], s42 offen lds
	s_mov_b32 m0, s43
	s_nop 0
	buffer_load_dwordx4 v169, s[8:11], s42 offen lds
	s_waitcnt vmcnt(8)
	s_waitcnt lgkmcnt(0)
	s_barrier
	s_setprio 1
	v_mfma_f32_16x16x32_bf16 v[124:127], v[128:131], v[160:163], v[124:127]
	v_mfma_f32_16x16x32_bf16 v[120:123], v[136:139], v[160:163], v[120:123]
	v_mfma_f32_16x16x32_bf16 v[116:119], v[128:131], v[196:199], v[116:119]
	v_mfma_f32_16x16x32_bf16 v[112:115], v[136:139], v[196:199], v[112:115]
	v_mfma_f32_16x16x32_bf16 v[108:111], v[128:131], v[204:207], v[108:111]
	v_mfma_f32_16x16x32_bf16 v[104:107], v[136:139], v[204:207], v[104:107]
	v_mfma_f32_16x16x32_bf16 v[100:103], v[128:131], v[214:217], v[100:103]
	v_mfma_f32_16x16x32_bf16 v[96:99], v[136:139], v[214:217], v[96:99]
	v_mfma_f32_16x16x32_bf16 v[124:127], v[132:135], v[164:167], v[124:127]
	v_mfma_f32_16x16x32_bf16 v[120:123], v[140:143], v[164:167], v[120:123]
	v_mfma_f32_16x16x32_bf16 v[116:119], v[132:135], v[200:203], v[116:119]
	v_mfma_f32_16x16x32_bf16 v[112:115], v[140:143], v[200:203], v[112:115]
	v_mfma_f32_16x16x32_bf16 v[108:111], v[132:135], v[208:211], v[108:111]
	v_mfma_f32_16x16x32_bf16 v[104:107], v[140:143], v[208:211], v[104:107]
	v_mfma_f32_16x16x32_bf16 v[100:103], v[132:135], v[218:221], v[100:103]
	v_mfma_f32_16x16x32_bf16 v[96:99], v[140:143], v[218:221], v[96:99]
	v_mfma_f32_16x16x32_bf16 v[92:95], v[144:147], v[160:163], v[92:95]
	v_mfma_f32_16x16x32_bf16 v[88:91], v[152:155], v[160:163], v[88:91]
	v_mfma_f32_16x16x32_bf16 v[84:87], v[144:147], v[196:199], v[84:87]
	v_mfma_f32_16x16x32_bf16 v[80:83], v[152:155], v[196:199], v[80:83]
	v_mfma_f32_16x16x32_bf16 v[76:79], v[144:147], v[204:207], v[76:79]
	v_mfma_f32_16x16x32_bf16 v[72:75], v[152:155], v[204:207], v[72:75]
	v_mfma_f32_16x16x32_bf16 v[68:71], v[144:147], v[214:217], v[68:71]
	v_mfma_f32_16x16x32_bf16 v[64:67], v[152:155], v[214:217], v[64:67]
	v_mfma_f32_16x16x32_bf16 v[92:95], v[148:151], v[164:167], v[92:95]
	v_mfma_f32_16x16x32_bf16 v[88:91], v[156:159], v[164:167], v[88:91]
	v_mfma_f32_16x16x32_bf16 v[84:87], v[148:151], v[200:203], v[84:87]
	v_mfma_f32_16x16x32_bf16 v[80:83], v[156:159], v[200:203], v[80:83]
	v_mfma_f32_16x16x32_bf16 v[76:79], v[148:151], v[208:211], v[76:79]
	v_mfma_f32_16x16x32_bf16 v[72:75], v[156:159], v[208:211], v[72:75]
	v_mfma_f32_16x16x32_bf16 v[68:71], v[148:151], v[218:221], v[68:71]
	v_mfma_f32_16x16x32_bf16 v[64:67], v[156:159], v[218:221], v[64:67]
	s_setprio 0
	s_barrier
	s_add_i32 s42, s1, s40
	v_readfirstlane_b32 s44, v170
	s_add_i32 s43, s42, 0x100
	s_mov_b32 s66, s10
	s_mov_b32 s67, s11
	s_mov_b32 m0, s44
	v_readfirstlane_b32 s44, v171
	ds_read_b128 v[160:163], v188 offset:16384
	ds_read_b128 v[164:167], v188 offset:17408
	ds_read_b128 v[196:199], v189 offset:16384
	ds_read_b128 v[200:203], v189 offset:17408
	ds_read_b128 v[204:207], v190 offset:16384
	ds_read_b128 v[208:211], v190 offset:17408
	ds_read_b128 v[214:217], v191 offset:16384
	ds_read_b128 v[218:221], v191 offset:17408
	buffer_load_dwordx4 v168, s[64:67], s43 offen lds
	s_mov_b32 m0, s44
	v_readfirstlane_b32 s44, v172
	buffer_load_dwordx4 v169, s[64:67], s43 offen lds
	s_add_i32 s43, s42, 0x40100
	s_mov_b32 m0, s44
	v_readfirstlane_b32 s44, v173
	buffer_load_dwordx4 v168, s[64:67], s43 offen lds
	s_mov_b32 m0, s44
	v_readfirstlane_b32 s44, v174
	buffer_load_dwordx4 v169, s[64:67], s43 offen lds
	s_add_i32 s43, s41, 0x100
	s_mov_b32 m0, s44
	v_readfirstlane_b32 s44, v175
	buffer_load_dwordx4 v168, s[8:11], s43 offen lds
	s_mov_b32 m0, s44
	s_nop 0
	buffer_load_dwordx4 v169, s[8:11], s43 offen lds
	s_waitcnt vmcnt(8)
	s_waitcnt lgkmcnt(0)
	s_barrier
	s_setprio 1
	v_mfma_f32_16x16x32_bf16 v[60:63], v[128:131], v[160:163], v[60:63]
	v_mfma_f32_16x16x32_bf16 v[56:59], v[136:139], v[160:163], v[56:59]
	v_mfma_f32_16x16x32_bf16 v[52:55], v[128:131], v[196:199], v[52:55]
	v_mfma_f32_16x16x32_bf16 v[48:51], v[136:139], v[196:199], v[48:51]
	v_mfma_f32_16x16x32_bf16 v[44:47], v[128:131], v[204:207], v[44:47]
	v_mfma_f32_16x16x32_bf16 v[40:43], v[136:139], v[204:207], v[40:43]
	v_mfma_f32_16x16x32_bf16 v[36:39], v[128:131], v[214:217], v[36:39]
	v_mfma_f32_16x16x32_bf16 v[32:35], v[136:139], v[214:217], v[32:35]
	v_mfma_f32_16x16x32_bf16 v[60:63], v[132:135], v[164:167], v[60:63]
	v_mfma_f32_16x16x32_bf16 v[56:59], v[140:143], v[164:167], v[56:59]
	v_mfma_f32_16x16x32_bf16 v[52:55], v[132:135], v[200:203], v[52:55]
	v_mfma_f32_16x16x32_bf16 v[48:51], v[140:143], v[200:203], v[48:51]
	v_mfma_f32_16x16x32_bf16 v[44:47], v[132:135], v[208:211], v[44:47]
	v_mfma_f32_16x16x32_bf16 v[40:43], v[140:143], v[208:211], v[40:43]
	v_mfma_f32_16x16x32_bf16 v[36:39], v[132:135], v[218:221], v[36:39]
	v_mfma_f32_16x16x32_bf16 v[32:35], v[140:143], v[218:221], v[32:35]
	v_mfma_f32_16x16x32_bf16 v[28:31], v[144:147], v[160:163], v[28:31]
	v_mfma_f32_16x16x32_bf16 v[24:27], v[152:155], v[160:163], v[24:27]
	v_mfma_f32_16x16x32_bf16 v[20:23], v[144:147], v[196:199], v[20:23]
	v_mfma_f32_16x16x32_bf16 v[16:19], v[152:155], v[196:199], v[16:19]
	v_mfma_f32_16x16x32_bf16 v[12:15], v[144:147], v[204:207], v[12:15]
	v_mfma_f32_16x16x32_bf16 v[8:11], v[152:155], v[204:207], v[8:11]
	v_mfma_f32_16x16x32_bf16 v[4:7], v[144:147], v[214:217], v[4:7]
	v_mfma_f32_16x16x32_bf16 v[0:3], v[152:155], v[214:217], v[0:3]
	v_mfma_f32_16x16x32_bf16 v[28:31], v[148:151], v[164:167], v[28:31]
	v_mfma_f32_16x16x32_bf16 v[24:27], v[156:159], v[164:167], v[24:27]
	v_mfma_f32_16x16x32_bf16 v[20:23], v[148:151], v[200:203], v[20:23]
	v_mfma_f32_16x16x32_bf16 v[16:19], v[156:159], v[200:203], v[16:19]
	v_mfma_f32_16x16x32_bf16 v[12:15], v[148:151], v[208:211], v[12:15]
	v_mfma_f32_16x16x32_bf16 v[8:11], v[156:159], v[208:211], v[8:11]
	v_mfma_f32_16x16x32_bf16 v[4:7], v[148:151], v[218:221], v[4:7]
	v_mfma_f32_16x16x32_bf16 v[0:3], v[156:159], v[218:221], v[0:3]
	s_setprio 0
	s_barrier
; #define LDA(dst, b, h) for (int m = 0; m < 4; ++m) for (int k = 0; k < 2; ++k) \
;     dst[m][k] = *reinterpret_cast<const bf16x8*>((char*)SA(b, h) + lds_byte(wr * 64 + m * 16 + fr, k * 32 + fq * 8))
; #define LDB(dst, b, h) for (int n = 0; n < 2; ++n) for (int k = 0; k < 2; ++k) \
;     dst[n][k] = *reinterpret_cast<const bf16x8*>((char*)SB(b, h) + lds_byte(wc * 32 + n * 16 + fr, k * 32 + fq * 8))
; #define MMA(ai, bj, At, Bt_) do { __builtin_amdgcn_s_setprio(1); \
;     for (int m = 0; m < 4; ++m) for (int n = 0; n < 2; ++n) for (int k = 0; k < 2; ++k) \
;       acc[ai][bj][m][n] = __builtin_amdgcn_mfma_f32_16x16x32_bf16(Bt_[n][k], At[m][k], acc[ai][bj][m][n], 0, 0, 0); \
;     __builtin_amdgcn_s_setprio(0); } while (0)
; #define WAIT_V(n) asm volatile("s_waitcnt vmcnt(" #n ")" ::: "memory")
; #define WAIT_L(n) asm volatile("s_waitcnt lgkmcnt(" #n ")" ::: "memory")
; #define BAR __builtin_amdgcn_s_barrier()
; #define SCHED __builtin_amdgcn_sched_barrier(0)
; template <int MODE>
; DI void gemm_phase(const bf16_t* __restrict__ A, const bf16_t* __restrict__ Bt, int M, int N, int K, const Epi& ep) {
;     ...
;             LDB(B0, 1, 0); LDB(B1, 1, 1); SCHED; LDA(At, 1, 0); STAGE(SA(0, 1), rsA, brow + HALF, t + 2);
;             WAIT_V(8); WAIT_L(0); BAR; MMA(0, 0, At, B0); MMA(0, 1, At, B1); BAR; SCHED;
;             LDA(At, 1, 1); STAGE(SB(1, 0), rsB, bcol, t + 3); STAGE(SB(1, 1), rsB, bcol + HALF, t + 3); STAGE(SA(1, 0), rsA, brow, t + 3);
;             WAIT_V(8); WAIT_L(0); BAR; MMA(1, 0, At, B0); MMA(1, 1, At, B1); BAR; SCHED;
	ds_read_b128 v[128:131], v192
	ds_read_b128 v[132:135], v192 offset:1024
	ds_read_b128 v[136:139], v192 offset:2048
	ds_read_b128 v[140:143], v192 offset:3072
	ds_read_b128 v[144:147], v193
	ds_read_b128 v[148:151], v193 offset:1024
	ds_read_b128 v[152:155], v193 offset:2048
	ds_read_b128 v[156:159], v193 offset:3072
	v_readfirstlane_b32 s44, v176
	s_add_i32 s43, s41, 0x40100
	s_mov_b32 m0, s44
	v_readfirstlane_b32 s44, v177
	ds_read_b128 v[160:163], v188 offset:32768
	ds_read_b128 v[164:167], v188 offset:33792
	ds_read_b128 v[196:199], v189 offset:32768
	ds_read_b128 v[200:203], v189 offset:33792
	ds_read_b128 v[204:207], v190 offset:32768
	ds_read_b128 v[208:211], v190 offset:33792
	ds_read_b128 v[214:217], v191 offset:32768
	ds_read_b128 v[218:221], v191 offset:33792
	buffer_load_dwordx4 v168, s[8:11], s43 offen lds
	s_mov_b32 m0, s44
	s_nop 0
	buffer_load_dwordx4 v169, s[8:11], s43 offen lds
	s_waitcnt vmcnt(8)
	s_waitcnt lgkmcnt(0)
	s_barrier
	s_setprio 1
	v_mfma_f32_16x16x32_bf16 v[124:127], v[128:131], v[160:163], v[124:127]
	v_mfma_f32_16x16x32_bf16 v[120:123], v[136:139], v[160:163], v[120:123]
	v_mfma_f32_16x16x32_bf16 v[116:119], v[128:131], v[196:199], v[116:119]
	v_mfma_f32_16x16x32_bf16 v[112:115], v[136:139], v[196:199], v[112:115]
	v_mfma_f32_16x16x32_bf16 v[108:111], v[128:131], v[204:207], v[108:111]
	v_mfma_f32_16x16x32_bf16 v[104:107], v[136:139], v[204:207], v[104:107]
	v_mfma_f32_16x16x32_bf16 v[100:103], v[128:131], v[214:217], v[100:103]
	v_mfma_f32_16x16x32_bf16 v[96:99], v[136:139], v[214:217], v[96:99]
	v_mfma_f32_16x16x32_bf16 v[124:127], v[132:135], v[164:167], v[124:127]
	v_mfma_f32_16x16x32_bf16 v[120:123], v[140:143], v[164:167], v[120:123]
	v_mfma_f32_16x16x32_bf16 v[116:119], v[132:135], v[200:203], v[116:119]
	v_mfma_f32_16x16x32_bf16 v[112:115], v[140:143], v[200:203], v[112:115]
	v_mfma_f32_16x16x32_bf16 v[108:111], v[132:135], v[208:211], v[108:111]
	v_mfma_f32_16x16x32_bf16 v[104:107], v[140:143], v[208:211], v[104:107]
	v_mfma_f32_16x16x32_bf16 v[100:103], v[132:135], v[218:221], v[100:103]
	v_mfma_f32_16x16x32_bf16 v[96:99], v[140:143], v[218:221], v[96:99]
	v_mfma_f32_16x16x32_bf16 v[92:95], v[144:147], v[160:163], v[92:95]
	v_mfma_f32_16x16x32_bf16 v[88:91], v[152:155], v[160:163], v[88:91]
	v_mfma_f32_16x16x32_bf16 v[84:87], v[144:147], v[196:199], v[84:87]
	v_mfma_f32_16x16x32_bf16 v[80:83], v[152:155], v[196:199], v[80:83]
	v_mfma_f32_16x16x32_bf16 v[76:79], v[144:147], v[204:207], v[76:79]
	v_mfma_f32_16x16x32_bf16 v[72:75], v[152:155], v[204:207], v[72:75]
	v_mfma_f32_16x16x32_bf16 v[68:71], v[144:147], v[214:217], v[68:71]
	v_mfma_f32_16x16x32_bf16 v[64:67], v[152:155], v[214:217], v[64:67]
	v_mfma_f32_16x16x32_bf16 v[92:95], v[148:151], v[164:167], v[92:95]
	v_mfma_f32_16x16x32_bf16 v[88:91], v[156:159], v[164:167], v[88:91]
	v_mfma_f32_16x16x32_bf16 v[84:87], v[148:151], v[200:203], v[84:87]
	v_mfma_f32_16x16x32_bf16 v[80:83], v[156:159], v[200:203], v[80:83]
	v_mfma_f32_16x16x32_bf16 v[76:79], v[148:151], v[208:211], v[76:79]
	v_mfma_f32_16x16x32_bf16 v[72:75], v[156:159], v[208:211], v[72:75]
	v_mfma_f32_16x16x32_bf16 v[68:71], v[148:151], v[218:221], v[68:71]
	v_mfma_f32_16x16x32_bf16 v[64:67], v[156:159], v[218:221], v[64:67]
	s_setprio 0
	s_barrier
	v_readfirstlane_b32 s44, v178
	s_add_i32 s43, s42, 0x180
	s_mov_b32 m0, s44
	v_readfirstlane_b32 s44, v179
	ds_read_b128 v[160:163], v188 offset:49152
	ds_read_b128 v[164:167], v188 offset:50176
	ds_read_b128 v[196:199], v189 offset:49152
	ds_read_b128 v[200:203], v189 offset:50176
	ds_read_b128 v[204:207], v190 offset:49152
	ds_read_b128 v[208:211], v190 offset:50176
	ds_read_b128 v[214:217], v191 offset:49152
	ds_read_b128 v[218:221], v191 offset:50176
	buffer_load_dwordx4 v168, s[64:67], s43 offen lds
	s_mov_b32 m0, s44
	s_add_i32 s42, s42, 0x40180
	buffer_load_dwordx4 v169, s[64:67], s43 offen lds
	v_readfirstlane_b32 s43, v182
	s_mov_b32 m0, s43
	v_readfirstlane_b32 s43, v183
	buffer_load_dwordx4 v168, s[64:67], s42 offen lds
	s_mov_b32 m0, s43
	s_addk_i32 s41, 0x180
	buffer_load_dwordx4 v169, s[64:67], s42 offen lds
	v_readfirstlane_b32 s42, v180
	s_mov_b32 m0, s42
	v_readfirstlane_b32 s42, v181
	buffer_load_dwordx4 v168, s[8:11], s41 offen lds
	s_mov_b32 m0, s42
	s_nop 0
	buffer_load_dwordx4 v169, s[8:11], s41 offen lds
	s_waitcnt vmcnt(8)
	s_waitcnt lgkmcnt(0)
	s_barrier
	s_setprio 1
	v_mfma_f32_16x16x32_bf16 v[60:63], v[128:131], v[160:163], v[60:63]
	v_mfma_f32_16x16x32_bf16 v[56:59], v[136:139], v[160:163], v[56:59]
	v_mfma_f32_16x16x32_bf16 v[52:55], v[128:131], v[196:199], v[52:55]
	v_mfma_f32_16x16x32_bf16 v[48:51], v[136:139], v[196:199], v[48:51]
	v_mfma_f32_16x16x32_bf16 v[44:47], v[128:131], v[204:207], v[44:47]
	v_mfma_f32_16x16x32_bf16 v[40:43], v[136:139], v[204:207], v[40:43]
	v_mfma_f32_16x16x32_bf16 v[36:39], v[128:131], v[214:217], v[36:39]
	v_mfma_f32_16x16x32_bf16 v[32:35], v[136:139], v[214:217], v[32:35]
	v_mfma_f32_16x16x32_bf16 v[60:63], v[132:135], v[164:167], v[60:63]
	v_mfma_f32_16x16x32_bf16 v[56:59], v[140:143], v[164:167], v[56:59]
	v_mfma_f32_16x16x32_bf16 v[52:55], v[132:135], v[200:203], v[52:55]
	v_mfma_f32_16x16x32_bf16 v[48:51], v[140:143], v[200:203], v[48:51]
	v_mfma_f32_16x16x32_bf16 v[44:47], v[132:135], v[208:211], v[44:47]
	v_mfma_f32_16x16x32_bf16 v[40:43], v[140:143], v[208:211], v[40:43]
	v_mfma_f32_16x16x32_bf16 v[36:39], v[132:135], v[218:221], v[36:39]
	v_mfma_f32_16x16x32_bf16 v[32:35], v[140:143], v[218:221], v[32:35]
	v_mfma_f32_16x16x32_bf16 v[28:31], v[144:147], v[160:163], v[28:31]
	v_mfma_f32_16x16x32_bf16 v[24:27], v[152:155], v[160:163], v[24:27]
	v_mfma_f32_16x16x32_bf16 v[20:23], v[144:147], v[196:199], v[20:23]
	v_mfma_f32_16x16x32_bf16 v[16:19], v[152:155], v[196:199], v[16:19]
	v_mfma_f32_16x16x32_bf16 v[12:15], v[144:147], v[204:207], v[12:15]
	v_mfma_f32_16x16x32_bf16 v[8:11], v[152:155], v[204:207], v[8:11]
	v_mfma_f32_16x16x32_bf16 v[4:7], v[144:147], v[214:217], v[4:7]
	v_mfma_f32_16x16x32_bf16 v[0:3], v[152:155], v[214:217], v[0:3]
	v_mfma_f32_16x16x32_bf16 v[28:31], v[148:151], v[164:167], v[28:31]
	v_mfma_f32_16x16x32_bf16 v[24:27], v[156:159], v[164:167], v[24:27]
	v_mfma_f32_16x16x32_bf16 v[20:23], v[148:151], v[200:203], v[20:23]
	v_mfma_f32_16x16x32_bf16 v[16:19], v[156:159], v[200:203], v[16:19]
	v_mfma_f32_16x16x32_bf16 v[12:15], v[148:151], v[208:211], v[12:15]
	v_mfma_f32_16x16x32_bf16 v[8:11], v[156:159], v[208:211], v[8:11]
	v_mfma_f32_16x16x32_bf16 v[4:7], v[148:151], v[218:221], v[4:7]
	v_mfma_f32_16x16x32_bf16 v[0:3], v[156:159], v[218:221], v[0:3]
	s_setprio 0
	s_barrier
; #define LDA(dst, b, h) for (int m = 0; m < 4; ++m) for (int k = 0; k < 2; ++k) \
;     dst[m][k] = *reinterpret_cast<const bf16x8*>((char*)SA(b, h) + lds_byte(wr * 64 + m * 16 + fr, k * 32 + fq * 8))
; #define LDB(dst, b, h) for (int n = 0; n < 2; ++n) for (int k = 0; k < 2; ++k) \
;     dst[n][k] = *reinterpret_cast<const bf16x8*>((char*)SB(b, h) + lds_byte(wc * 32 + n * 16 + fr, k * 32 + fq * 8))
; #define MMA(ai, bj, At, Bt_) do { __builtin_amdgcn_s_setprio(1); \
;     for (int m = 0; m < 4; ++m) for (int n = 0; n < 2; ++n) for (int k = 0; k < 2; ++k) \
;       acc[ai][bj][m][n] = __builtin_amdgcn_mfma_f32_16x16x32_bf16(Bt_[n][k], At[m][k], acc[ai][bj][m][n], 0, 0, 0); \
;     __builtin_amdgcn_s_setprio(0); } while (0)
; #define WAIT_V(n) asm volatile("s_waitcnt vmcnt(" #n ")" ::: "memory")
; #define WAIT_L(n) asm volatile("s_waitcnt lgkmcnt(" #n ")" ::: "memory")
; #define BAR __builtin_amdgcn_s_barrier()
; #define SCHED __builtin_amdgcn_sched_barrier(0)
; template <int MODE>
; DI void gemm_phase(const bf16_t* __restrict__ A, const bf16_t* __restrict__ Bt, int M, int N, int K, const Epi& ep) {
;     ...
;             LDB(B0, 0, 0); LDB(B1, 0, 1); SCHED; LDA(At, 0, 0); STAGE(SA(1, 1), rsA, brow + HALF, nt - 1);
;             WAIT_V(8); WAIT_L(0); BAR; MMA(0, 0, At, B0); MMA(0, 1, At, B1); BAR; SCHED;
;             LDA(At, 0, 1);
;             WAIT_V(2); WAIT_L(0); BAR; MMA(1, 0, At, B0); MMA(1, 1, At, B1); BAR; SCHED;
	s_add_i32 s31, s31, 2
	s_addk_i32 s40, 0x100
	s_cmp_lt_u32 s31, 12
	s_cbranch_scc1 .LBB0_1150
	ds_read_b128 v[128:131], v186
	ds_read_b128 v[132:135], v186 offset:1024
	ds_read_b128 v[136:139], v186 offset:2048
	ds_read_b128 v[140:143], v186 offset:3072
	ds_read_b128 v[144:147], v187
	ds_read_b128 v[148:151], v187 offset:1024
	ds_read_b128 v[152:155], v187 offset:2048
	ds_read_b128 v[156:159], v187 offset:3072
	v_readfirstlane_b32 s1, v184
	s_or_b32 s0, s30, 0x40780
	s_mov_b32 m0, s1
	v_readfirstlane_b32 s1, v185
	ds_read_b128 v[160:163], v188
	ds_read_b128 v[164:167], v188 offset:1024
	ds_read_b128 v[196:199], v189
	ds_read_b128 v[200:203], v189 offset:1024
	ds_read_b128 v[204:207], v190
	ds_read_b128 v[208:211], v190 offset:1024
	ds_read_b128 v[214:217], v191
	ds_read_b128 v[218:221], v191 offset:1024
	buffer_load_dwordx4 v168, s[8:11], s0 offen lds
	s_mov_b32 m0, s1
	s_nop 0
	buffer_load_dwordx4 v169, s[8:11], s0 offen lds
	s_waitcnt vmcnt(8)
	s_waitcnt lgkmcnt(0)
	s_barrier
	s_setprio 1
	v_mfma_f32_16x16x32_bf16 v[124:127], v[128:131], v[160:163], v[124:127]
	v_mfma_f32_16x16x32_bf16 v[120:123], v[136:139], v[160:163], v[120:123]
	v_mfma_f32_16x16x32_bf16 v[116:119], v[128:131], v[196:199], v[116:119]
	v_mfma_f32_16x16x32_bf16 v[112:115], v[136:139], v[196:199], v[112:115]
	v_mfma_f32_16x16x32_bf16 v[108:111], v[128:131], v[204:207], v[108:111]
	v_mfma_f32_16x16x32_bf16 v[124:127], v[132:135], v[164:167], v[124:127]
	v_mfma_f32_16x16x32_bf16 v[120:123], v[140:143], v[164:167], v[120:123]
	v_mfma_f32_16x16x32_bf16 v[116:119], v[132:135], v[200:203], v[116:119]
	v_mfma_f32_16x16x32_bf16 v[112:115], v[140:143], v[200:203], v[112:115]
	v_mfma_f32_16x16x32_bf16 v[222:225], v[132:135], v[208:211], v[108:111]
	v_mfma_f32_16x16x32_bf16 v[104:107], v[136:139], v[204:207], v[104:107]
	v_mfma_f32_16x16x32_bf16 v[100:103], v[128:131], v[214:217], v[100:103]
	v_mfma_f32_16x16x32_bf16 v[96:99], v[136:139], v[214:217], v[96:99]
	v_mfma_f32_16x16x32_bf16 v[226:229], v[140:143], v[208:211], v[104:107]
	v_mfma_f32_16x16x32_bf16 v[230:233], v[132:135], v[218:221], v[100:103]
	v_mfma_f32_16x16x32_bf16 v[234:237], v[140:143], v[218:221], v[96:99]
	v_mfma_f32_16x16x32_bf16 v[92:95], v[144:147], v[160:163], v[92:95]
	v_mfma_f32_16x16x32_bf16 v[88:91], v[152:155], v[160:163], v[88:91]
	v_mfma_f32_16x16x32_bf16 v[84:87], v[144:147], v[196:199], v[84:87]
	v_mfma_f32_16x16x32_bf16 v[80:83], v[152:155], v[196:199], v[80:83]
	v_mfma_f32_16x16x32_bf16 v[92:95], v[148:151], v[164:167], v[92:95]
	v_mfma_f32_16x16x32_bf16 v[88:91], v[156:159], v[164:167], v[88:91]
	v_mfma_f32_16x16x32_bf16 v[84:87], v[148:151], v[200:203], v[84:87]
	v_mfma_f32_16x16x32_bf16 v[80:83], v[156:159], v[200:203], v[80:83]
	v_mfma_f32_16x16x32_bf16 v[76:79], v[144:147], v[204:207], v[76:79]
	v_mfma_f32_16x16x32_bf16 v[72:75], v[152:155], v[204:207], v[72:75]
	v_mfma_f32_16x16x32_bf16 v[68:71], v[144:147], v[214:217], v[68:71]
	v_mfma_f32_16x16x32_bf16 v[64:67], v[152:155], v[214:217], v[64:67]
	v_mfma_f32_16x16x32_bf16 v[160:163], v[148:151], v[208:211], v[76:79]
	v_mfma_f32_16x16x32_bf16 v[164:167], v[156:159], v[208:211], v[72:75]
	v_mfma_f32_16x16x32_bf16 v[196:199], v[148:151], v[218:221], v[68:71]
	v_mfma_f32_16x16x32_bf16 v[200:203], v[156:159], v[218:221], v[64:67]
	s_setprio 0
	s_barrier
	s_nop 1
	ds_read_b128 v[64:67], v188 offset:16384
	ds_read_b128 v[68:71], v188 offset:17408
	ds_read_b128 v[72:75], v189 offset:16384
	ds_read_b128 v[76:79], v189 offset:17408
	ds_read_b128 v[96:99], v190 offset:16384
	ds_read_b128 v[100:103], v190 offset:17408
	ds_read_b128 v[104:107], v191 offset:16384
	ds_read_b128 v[108:111], v191 offset:17408
	s_waitcnt vmcnt(2)
	s_waitcnt lgkmcnt(0)
	s_barrier
	s_setprio 1
	v_mfma_f32_16x16x32_bf16 v[60:63], v[128:131], v[64:67], v[60:63]
	v_mfma_f32_16x16x32_bf16 v[56:59], v[136:139], v[64:67], v[56:59]
	v_mfma_f32_16x16x32_bf16 v[52:55], v[128:131], v[72:75], v[52:55]
	v_mfma_f32_16x16x32_bf16 v[48:51], v[136:139], v[72:75], v[48:51]
	v_mfma_f32_16x16x32_bf16 v[60:63], v[132:135], v[68:71], v[60:63]
	v_mfma_f32_16x16x32_bf16 v[56:59], v[140:143], v[68:71], v[56:59]
	v_mfma_f32_16x16x32_bf16 v[52:55], v[132:135], v[76:79], v[52:55]
	v_mfma_f32_16x16x32_bf16 v[48:51], v[140:143], v[76:79], v[48:51]
	v_mfma_f32_16x16x32_bf16 v[44:47], v[128:131], v[96:99], v[44:47]
	v_mfma_f32_16x16x32_bf16 v[40:43], v[136:139], v[96:99], v[40:43]
	v_mfma_f32_16x16x32_bf16 v[36:39], v[128:131], v[104:107], v[36:39]
	v_mfma_f32_16x16x32_bf16 v[32:35], v[136:139], v[104:107], v[32:35]
	v_mfma_f32_16x16x32_bf16 v[204:207], v[132:135], v[100:103], v[44:47]
	v_mfma_f32_16x16x32_bf16 v[208:211], v[140:143], v[100:103], v[40:43]
	v_mfma_f32_16x16x32_bf16 v[128:131], v[132:135], v[108:111], v[36:39]
	v_mfma_f32_16x16x32_bf16 v[132:135], v[140:143], v[108:111], v[32:35]
	v_mfma_f32_16x16x32_bf16 v[28:31], v[144:147], v[64:67], v[28:31]
	v_mfma_f32_16x16x32_bf16 v[24:27], v[152:155], v[64:67], v[24:27]
	v_mfma_f32_16x16x32_bf16 v[20:23], v[144:147], v[72:75], v[20:23]
	v_mfma_f32_16x16x32_bf16 v[16:19], v[152:155], v[72:75], v[16:19]
	v_mfma_f32_16x16x32_bf16 v[28:31], v[148:151], v[68:71], v[28:31]
	v_mfma_f32_16x16x32_bf16 v[24:27], v[156:159], v[68:71], v[24:27]
	v_mfma_f32_16x16x32_bf16 v[20:23], v[148:151], v[76:79], v[20:23]
	v_mfma_f32_16x16x32_bf16 v[16:19], v[156:159], v[76:79], v[16:19]
	v_mfma_f32_16x16x32_bf16 v[12:15], v[144:147], v[96:99], v[12:15]
	v_mfma_f32_16x16x32_bf16 v[8:11], v[152:155], v[96:99], v[8:11]
	v_mfma_f32_16x16x32_bf16 v[4:7], v[144:147], v[104:107], v[4:7]
	v_mfma_f32_16x16x32_bf16 v[0:3], v[152:155], v[104:107], v[0:3]
	v_mfma_f32_16x16x32_bf16 v[136:139], v[148:151], v[100:103], v[12:15]
	v_mfma_f32_16x16x32_bf16 v[140:143], v[156:159], v[100:103], v[8:11]
	v_mfma_f32_16x16x32_bf16 v[144:147], v[148:151], v[108:111], v[4:7]
	v_mfma_f32_16x16x32_bf16 v[148:151], v[156:159], v[108:111], v[0:3]
	s_setprio 0
	s_barrier
; #define LDA(dst, b, h) for (int m = 0; m < 4; ++m) for (int k = 0; k < 2; ++k) \
;     dst[m][k] = *reinterpret_cast<const bf16x8*>((char*)SA(b, h) + lds_byte(wr * 64 + m * 16 + fr, k * 32 + fq * 8))
; #define LDB(dst, b, h) for (int n = 0; n < 2; ++n) for (int k = 0; k < 2; ++k) \
;     dst[n][k] = *reinterpret_cast<const bf16x8*>((char*)SB(b, h) + lds_byte(wc * 32 + n * 16 + fr, k * 32 + fq * 8))
; #define MMA(ai, bj, At, Bt_) do { __builtin_amdgcn_s_setprio(1); \
;     for (int m = 0; m < 4; ++m) for (int n = 0; n < 2; ++n) for (int k = 0; k < 2; ++k) \
;       acc[ai][bj][m][n] = __builtin_amdgcn_mfma_f32_16x16x32_bf16(Bt_[n][k], At[m][k], acc[ai][bj][m][n], 0, 0, 0); \
;     __builtin_amdgcn_s_setprio(0); } while (0)
; #define WAIT_V(n) asm volatile("s_waitcnt vmcnt(" #n ")" ::: "memory")
; #define WAIT_L(n) asm volatile("s_waitcnt lgkmcnt(" #n ")" ::: "memory")
; #define BAR __builtin_amdgcn_s_barrier()
; #define SCHED __builtin_amdgcn_sched_barrier(0)
; template <int MODE>
; DI void gemm_phase(const bf16_t* __restrict__ A, const bf16_t* __restrict__ Bt, int M, int N, int K, const Epi& ep) {
;     ...
;             LDB(B0, 1, 0); LDB(B1, 1, 1); SCHED; LDA(At, 1, 0);
;             WAIT_V(0); WAIT_L(0); BAR; MMA(0, 0, At, B0); MMA(0, 1, At, B1); BAR; SCHED;
;             LDA(At, 1, 1);
;             WAIT_L(0); BAR; MMA(1, 0, At, B0); MMA(1, 1, At, B1); BAR; SCHED;
;         }
;         if (wr == 0) BAR;
	s_nop 1
	ds_read_b128 v[0:3], v192
	ds_read_b128 v[4:7], v192 offset:1024
	ds_read_b128 v[8:11], v192 offset:2048
	ds_read_b128 v[12:15], v192 offset:3072
	ds_read_b128 v[152:155], v193
	ds_read_b128 v[156:159], v193 offset:1024
	ds_read_b128 v[214:217], v193 offset:2048
	ds_read_b128 v[218:221], v193 offset:3072
	ds_read_b128 v[32:35], v188 offset:32768
	ds_read_b128 v[36:39], v188 offset:33792
	ds_read_b128 v[40:43], v189 offset:32768
	ds_read_b128 v[44:47], v189 offset:33792
	ds_read_b128 v[238:241], v190 offset:32768
	ds_read_b128 v[242:245], v190 offset:33792
	ds_read_b128 v[246:249], v191 offset:32768
	ds_read_b128 v[64:67], v191 offset:33792
	s_waitcnt vmcnt(0)
	s_waitcnt lgkmcnt(0)
	s_barrier
	s_setprio 1
	v_mfma_f32_16x16x32_bf16 v[68:71], v[0:3], v[32:35], v[124:127]
	v_mfma_f32_16x16x32_bf16 v[96:99], v[4:7], v[36:39], v[68:71]
	v_mfma_f32_16x16x32_bf16 v[68:71], v[8:11], v[32:35], v[120:123]
	v_mfma_f32_16x16x32_bf16 v[100:103], v[12:15], v[36:39], v[68:71]
	v_mfma_f32_16x16x32_bf16 v[68:71], v[0:3], v[40:43], v[116:119]
	v_mfma_f32_16x16x32_bf16 v[104:107], v[4:7], v[44:47], v[68:71]
	v_mfma_f32_16x16x32_bf16 v[68:71], v[8:11], v[40:43], v[112:115]
	v_mfma_f32_16x16x32_bf16 v[108:111], v[12:15], v[44:47], v[68:71]
	v_mfma_f32_16x16x32_bf16 v[68:71], v[0:3], v[238:241], v[222:225]
	v_mfma_f32_16x16x32_bf16 v[112:115], v[4:7], v[242:245], v[68:71]
	v_mfma_f32_16x16x32_bf16 v[68:71], v[8:11], v[238:241], v[226:229]
	v_mfma_f32_16x16x32_bf16 v[116:119], v[12:15], v[242:245], v[68:71]
	v_mfma_f32_16x16x32_bf16 v[68:71], v[0:3], v[246:249], v[230:233]
	v_mfma_f32_16x16x32_bf16 v[120:123], v[4:7], v[64:67], v[68:71]
	v_mfma_f32_16x16x32_bf16 v[68:71], v[8:11], v[246:249], v[234:237]
	v_mfma_f32_16x16x32_bf16 v[124:127], v[12:15], v[64:67], v[68:71]
	v_mfma_f32_16x16x32_bf16 v[68:71], v[152:155], v[32:35], v[92:95]
	v_mfma_f32_16x16x32_bf16 v[32:35], v[214:217], v[32:35], v[88:91]
	v_mfma_f32_16x16x32_bf16 v[222:225], v[156:159], v[36:39], v[68:71]
	v_mfma_f32_16x16x32_bf16 v[68:71], v[218:221], v[36:39], v[32:35]
	v_mfma_f32_16x16x32_bf16 v[32:35], v[152:155], v[40:43], v[84:87]
	v_mfma_f32_16x16x32_bf16 v[72:75], v[156:159], v[44:47], v[32:35]
	v_mfma_f32_16x16x32_bf16 v[32:35], v[214:217], v[40:43], v[80:83]
	v_mfma_f32_16x16x32_bf16 v[76:79], v[218:221], v[44:47], v[32:35]
	v_mfma_f32_16x16x32_bf16 v[32:35], v[152:155], v[238:241], v[160:163]
	v_mfma_f32_16x16x32_bf16 v[80:83], v[156:159], v[242:245], v[32:35]
	v_mfma_f32_16x16x32_bf16 v[32:35], v[214:217], v[238:241], v[164:167]
	v_mfma_f32_16x16x32_bf16 v[84:87], v[218:221], v[242:245], v[32:35]
	v_mfma_f32_16x16x32_bf16 v[32:35], v[152:155], v[246:249], v[196:199]
	v_mfma_f32_16x16x32_bf16 v[88:91], v[156:159], v[64:67], v[32:35]
	v_mfma_f32_16x16x32_bf16 v[32:35], v[214:217], v[246:249], v[200:203]
	v_mfma_f32_16x16x32_bf16 v[92:95], v[218:221], v[64:67], v[32:35]
	s_setprio 0
	s_barrier
	ds_read_b128 v[64:67], v188 offset:49152
	ds_read_b128 v[160:163], v188 offset:50176
	ds_read_b128 v[164:167], v189 offset:49152
	ds_read_b128 v[196:199], v189 offset:50176
	ds_read_b128 v[200:203], v190 offset:49152
	ds_read_b128 v[226:229], v190 offset:50176
	ds_read_b128 v[230:233], v191 offset:49152
	ds_read_b128 v[234:237], v191 offset:50176
	s_waitcnt lgkmcnt(0)
	s_barrier
	s_setprio 1
	v_mfma_f32_16x16x32_bf16 v[32:35], v[0:3], v[64:67], v[60:63]
	v_mfma_f32_16x16x32_bf16 v[40:43], v[0:3], v[164:167], v[52:55]
	v_mfma_f32_16x16x32_bf16 v[44:47], v[8:11], v[164:167], v[48:51]
	v_mfma_f32_16x16x32_bf16 v[48:51], v[0:3], v[200:203], v[204:207]
	v_mfma_f32_16x16x32_bf16 v[0:3], v[0:3], v[230:233], v[128:131]
	v_mfma_f32_16x16x32_bf16 v[36:39], v[8:11], v[64:67], v[56:59]
	v_mfma_f32_16x16x32_bf16 v[52:55], v[8:11], v[200:203], v[208:211]
	v_mfma_f32_16x16x32_bf16 v[56:59], v[4:7], v[234:237], v[0:3]
	v_mfma_f32_16x16x32_bf16 v[0:3], v[8:11], v[230:233], v[132:135]
	v_mfma_f32_16x16x32_bf16 v[32:35], v[4:7], v[160:163], v[32:35]
	v_mfma_f32_16x16x32_bf16 v[36:39], v[12:15], v[160:163], v[36:39]
	v_mfma_f32_16x16x32_bf16 v[40:43], v[4:7], v[196:199], v[40:43]
	v_mfma_f32_16x16x32_bf16 v[44:47], v[12:15], v[196:199], v[44:47]
	v_mfma_f32_16x16x32_bf16 v[48:51], v[4:7], v[226:229], v[48:51]
	v_mfma_f32_16x16x32_bf16 v[52:55], v[12:15], v[226:229], v[52:55]
	v_mfma_f32_16x16x32_bf16 v[60:63], v[12:15], v[234:237], v[0:3]
	v_mfma_f32_16x16x32_bf16 v[0:3], v[152:155], v[64:67], v[28:31]
	v_mfma_f32_16x16x32_bf16 v[4:7], v[214:217], v[64:67], v[24:27]
	v_mfma_f32_16x16x32_bf16 v[8:11], v[152:155], v[164:167], v[20:23]
	v_mfma_f32_16x16x32_bf16 v[12:15], v[214:217], v[164:167], v[16:19]
	v_mfma_f32_16x16x32_bf16 v[16:19], v[152:155], v[200:203], v[136:139]
	v_mfma_f32_16x16x32_bf16 v[20:23], v[214:217], v[200:203], v[140:143]
	v_mfma_f32_16x16x32_bf16 v[24:27], v[152:155], v[230:233], v[144:147]
	v_mfma_f32_16x16x32_bf16 v[28:31], v[214:217], v[230:233], v[148:151]
	v_mfma_f32_16x16x32_bf16 v[0:3], v[156:159], v[160:163], v[0:3]
	v_mfma_f32_16x16x32_bf16 v[4:7], v[218:221], v[160:163], v[4:7]
	v_mfma_f32_16x16x32_bf16 v[8:11], v[156:159], v[196:199], v[8:11]
	v_mfma_f32_16x16x32_bf16 v[12:15], v[218:221], v[196:199], v[12:15]
	v_mfma_f32_16x16x32_bf16 v[16:19], v[156:159], v[226:229], v[16:19]
	v_mfma_f32_16x16x32_bf16 v[20:23], v[218:221], v[226:229], v[20:23]
	v_mfma_f32_16x16x32_bf16 v[24:27], v[156:159], v[234:237], v[24:27]
	v_mfma_f32_16x16x32_bf16 v[28:31], v[218:221], v[234:237], v[28:31]
	s_setprio 0
	s_barrier
	s_and_saveexec_b64 s[0:1], s[38:39]
	s_cbranch_execz .LBB0_1153
	s_barrier

; #define LDA(dst, b, h) for (int m = 0; m < 4; ++m) for (int k = 0; k < 2; ++k) \
;     dst[m][k] = *reinterpret_cast<const bf16x8*>((char*)SA(b, h) + lds_byte(wr * 64 + m * 16 + fr, k * 32 + fq * 8))
; #define LDB(dst, b, h) for (int n = 0; n < 2; ++n) for (int k = 0; k < 2; ++k) \
;     dst[n][k] = *reinterpret_cast<const bf16x8*>((char*)SB(b, h) + lds_byte(wc * 32 + n * 16 + fr, k * 32 + fq * 8))
; #define MMA(ai, bj, At, Bt_) do { __builtin_amdgcn_s_setprio(1); \
;     for (int m = 0; m < 4; ++m) for (int n = 0; n < 2; ++n) for (int k = 0; k < 2; ++k) \
;       acc[ai][bj][m][n] = __builtin_amdgcn_mfma_f32_16x16x32_bf16(Bt_[n][k], At[m][k], acc[ai][bj][m][n], 0, 0, 0); \
;     __builtin_amdgcn_s_setprio(0); } while (0)
; #define WAIT_V(n) asm volatile("s_waitcnt vmcnt(" #n ")" ::: "memory")
; #define WAIT_L(n) asm volatile("s_waitcnt lgkmcnt(" #n ")" ::: "memory")
; #define BAR __builtin_amdgcn_s_barrier()
; #define SCHED __builtin_amdgcn_sched_barrier(0)
; template <int MODE>
; DI void gemm_phase(const bf16_t* __restrict__ A, const bf16_t* __restrict__ Bt, int M, int N, int K, const Epi& ep) {
;     ...
;             LDB(B0, 0, 0); LDB(B1, 0, 1); SCHED; LDA(At, 0, 0); STAGE(SA(1, 1), rsA, brow + HALF, t + 1);
;             WAIT_V(8); WAIT_L(0); BAR; MMA(0, 0, At, B0); MMA(0, 1, At, B1); BAR; SCHED;
;             LDA(At, 0, 1); STAGE(SB(0, 0), rsB, bcol, t + 2); STAGE(SB(0, 1), rsB, bcol + HALF, t + 2); STAGE(SA(0, 0), rsA, brow, t + 2);
;             WAIT_V(8); WAIT_L(0); BAR; MMA(1, 0, At, B0); MMA(1, 1, At, B1); BAR; SCHED;
.LBB0_1452:
	ds_read_b128 v[156:159], v147
	ds_read_b128 v[160:163], v147 offset:1024
	ds_read_b128 v[164:167], v147 offset:2048
	ds_read_b128 v[168:171], v147 offset:3072
	ds_read_b128 v[172:175], v148
	ds_read_b128 v[176:179], v148 offset:1024
	ds_read_b128 v[180:183], v148 offset:2048
	ds_read_b128 v[184:187], v148 offset:3072
	s_add_i32 s40, s6, s27
	v_readfirstlane_b32 s42, v144
	s_add_i32 s41, s40, 0xb0080
	s_mov_b32 s30, s10
	s_mov_b32 s31, s11
	s_mov_b32 m0, s42
	v_readfirstlane_b32 s42, v145
	ds_read_b128 v[188:191], v149
	ds_read_b128 v[192:195], v149 offset:1024
	ds_read_b128 v[196:199], v150
	ds_read_b128 v[200:203], v150 offset:1024
	ds_read_b128 v[204:207], v151
	ds_read_b128 v[208:211], v151 offset:1024
	ds_read_b128 v[214:217], v152
	ds_read_b128 v[218:221], v152 offset:1024
	buffer_load_dwordx4 v128, s[28:31], s41 offen lds
	s_mov_b32 m0, s42
	s_nop 0
	buffer_load_dwordx4 v129, s[28:31], s41 offen lds
	s_waitcnt vmcnt(8)
	s_waitcnt lgkmcnt(0)
	s_barrier
	s_setprio 1
	v_mfma_f32_16x16x32_bf16 v[124:127], v[156:159], v[188:191], v[124:127]
	v_mfma_f32_16x16x32_bf16 v[120:123], v[164:167], v[188:191], v[120:123]
	v_mfma_f32_16x16x32_bf16 v[116:119], v[156:159], v[196:199], v[116:119]
	v_mfma_f32_16x16x32_bf16 v[112:115], v[164:167], v[196:199], v[112:115]
	v_mfma_f32_16x16x32_bf16 v[108:111], v[156:159], v[204:207], v[108:111]
	v_mfma_f32_16x16x32_bf16 v[104:107], v[164:167], v[204:207], v[104:107]
	v_mfma_f32_16x16x32_bf16 v[100:103], v[156:159], v[214:217], v[100:103]
	v_mfma_f32_16x16x32_bf16 v[96:99], v[164:167], v[214:217], v[96:99]
	v_mfma_f32_16x16x32_bf16 v[124:127], v[160:163], v[192:195], v[124:127]
	v_mfma_f32_16x16x32_bf16 v[120:123], v[168:171], v[192:195], v[120:123]
	v_mfma_f32_16x16x32_bf16 v[116:119], v[160:163], v[200:203], v[116:119]
	v_mfma_f32_16x16x32_bf16 v[112:115], v[168:171], v[200:203], v[112:115]
	v_mfma_f32_16x16x32_bf16 v[108:111], v[160:163], v[208:211], v[108:111]
	v_mfma_f32_16x16x32_bf16 v[104:107], v[168:171], v[208:211], v[104:107]
	v_mfma_f32_16x16x32_bf16 v[100:103], v[160:163], v[218:221], v[100:103]
	v_mfma_f32_16x16x32_bf16 v[96:99], v[168:171], v[218:221], v[96:99]
	v_mfma_f32_16x16x32_bf16 v[92:95], v[172:175], v[188:191], v[92:95]
	v_mfma_f32_16x16x32_bf16 v[88:91], v[180:183], v[188:191], v[88:91]
	v_mfma_f32_16x16x32_bf16 v[84:87], v[172:175], v[196:199], v[84:87]
	v_mfma_f32_16x16x32_bf16 v[80:83], v[180:183], v[196:199], v[80:83]
	v_mfma_f32_16x16x32_bf16 v[76:79], v[172:175], v[204:207], v[76:79]
	v_mfma_f32_16x16x32_bf16 v[72:75], v[180:183], v[204:207], v[72:75]
	v_mfma_f32_16x16x32_bf16 v[68:71], v[172:175], v[214:217], v[68:71]
	v_mfma_f32_16x16x32_bf16 v[64:67], v[180:183], v[214:217], v[64:67]
	v_mfma_f32_16x16x32_bf16 v[92:95], v[176:179], v[192:195], v[92:95]
	v_mfma_f32_16x16x32_bf16 v[88:91], v[184:187], v[192:195], v[88:91]
	v_mfma_f32_16x16x32_bf16 v[84:87], v[176:179], v[200:203], v[84:87]
	v_mfma_f32_16x16x32_bf16 v[80:83], v[184:187], v[200:203], v[80:83]
	v_mfma_f32_16x16x32_bf16 v[76:79], v[176:179], v[208:211], v[76:79]
	v_mfma_f32_16x16x32_bf16 v[72:75], v[184:187], v[208:211], v[72:75]
	v_mfma_f32_16x16x32_bf16 v[68:71], v[176:179], v[218:221], v[68:71]
	v_mfma_f32_16x16x32_bf16 v[64:67], v[184:187], v[218:221], v[64:67]
	s_setprio 0
	s_barrier
	s_add_i32 s41, s23, s27
	v_readfirstlane_b32 s43, v130
	s_add_i32 s42, s41, 0x100
	s_mov_b32 s70, s10
	s_mov_b32 s71, s11
	s_mov_b32 m0, s43
	v_readfirstlane_b32 s43, v131
	ds_read_b128 v[188:191], v149 offset:16384
	ds_read_b128 v[192:195], v149 offset:17408
	ds_read_b128 v[196:199], v150 offset:16384
	ds_read_b128 v[200:203], v150 offset:17408
	ds_read_b128 v[204:207], v151 offset:16384
	ds_read_b128 v[208:211], v151 offset:17408
	ds_read_b128 v[214:217], v152 offset:16384
	ds_read_b128 v[218:221], v152 offset:17408
	buffer_load_dwordx4 v128, s[68:71], s42 offen lds
	s_mov_b32 m0, s43
	v_readfirstlane_b32 s43, v132
	buffer_load_dwordx4 v129, s[68:71], s42 offen lds
	s_add_i32 s42, s41, 0xb0100
	s_mov_b32 m0, s43
	v_readfirstlane_b32 s43, v133
	buffer_load_dwordx4 v128, s[68:71], s42 offen lds
	s_mov_b32 m0, s43
	v_readfirstlane_b32 s43, v134
	buffer_load_dwordx4 v129, s[68:71], s42 offen lds
	s_add_i32 s42, s40, 0x100
	s_mov_b32 m0, s43
	v_readfirstlane_b32 s43, v135
	buffer_load_dwordx4 v128, s[28:31], s42 offen lds
	s_mov_b32 m0, s43
	s_nop 0
	buffer_load_dwordx4 v129, s[28:31], s42 offen lds
	s_waitcnt vmcnt(8)
	s_waitcnt lgkmcnt(0)
	s_barrier
	s_setprio 1
	v_mfma_f32_16x16x32_bf16 v[60:63], v[156:159], v[188:191], v[60:63]
	v_mfma_f32_16x16x32_bf16 v[56:59], v[164:167], v[188:191], v[56:59]
	v_mfma_f32_16x16x32_bf16 v[52:55], v[156:159], v[196:199], v[52:55]
	v_mfma_f32_16x16x32_bf16 v[48:51], v[164:167], v[196:199], v[48:51]
	v_mfma_f32_16x16x32_bf16 v[44:47], v[156:159], v[204:207], v[44:47]
	v_mfma_f32_16x16x32_bf16 v[40:43], v[164:167], v[204:207], v[40:43]
	v_mfma_f32_16x16x32_bf16 v[36:39], v[156:159], v[214:217], v[36:39]
	v_mfma_f32_16x16x32_bf16 v[32:35], v[164:167], v[214:217], v[32:35]
	v_mfma_f32_16x16x32_bf16 v[60:63], v[160:163], v[192:195], v[60:63]
	v_mfma_f32_16x16x32_bf16 v[56:59], v[168:171], v[192:195], v[56:59]
	v_mfma_f32_16x16x32_bf16 v[52:55], v[160:163], v[200:203], v[52:55]
	v_mfma_f32_16x16x32_bf16 v[48:51], v[168:171], v[200:203], v[48:51]
	v_mfma_f32_16x16x32_bf16 v[44:47], v[160:163], v[208:211], v[44:47]
	v_mfma_f32_16x16x32_bf16 v[40:43], v[168:171], v[208:211], v[40:43]
	v_mfma_f32_16x16x32_bf16 v[36:39], v[160:163], v[218:221], v[36:39]
	v_mfma_f32_16x16x32_bf16 v[32:35], v[168:171], v[218:221], v[32:35]
	v_mfma_f32_16x16x32_bf16 v[28:31], v[172:175], v[188:191], v[28:31]
	v_mfma_f32_16x16x32_bf16 v[24:27], v[180:183], v[188:191], v[24:27]
	v_mfma_f32_16x16x32_bf16 v[20:23], v[172:175], v[196:199], v[20:23]
	v_mfma_f32_16x16x32_bf16 v[16:19], v[180:183], v[196:199], v[16:19]
	v_mfma_f32_16x16x32_bf16 v[12:15], v[172:175], v[204:207], v[12:15]
	v_mfma_f32_16x16x32_bf16 v[8:11], v[180:183], v[204:207], v[8:11]
	v_mfma_f32_16x16x32_bf16 v[4:7], v[172:175], v[214:217], v[4:7]
	v_mfma_f32_16x16x32_bf16 v[0:3], v[180:183], v[214:217], v[0:3]
	v_mfma_f32_16x16x32_bf16 v[28:31], v[176:179], v[192:195], v[28:31]
	v_mfma_f32_16x16x32_bf16 v[24:27], v[184:187], v[192:195], v[24:27]
	v_mfma_f32_16x16x32_bf16 v[20:23], v[176:179], v[200:203], v[20:23]
	v_mfma_f32_16x16x32_bf16 v[16:19], v[184:187], v[200:203], v[16:19]
	v_mfma_f32_16x16x32_bf16 v[12:15], v[176:179], v[208:211], v[12:15]
	v_mfma_f32_16x16x32_bf16 v[8:11], v[184:187], v[208:211], v[8:11]
	v_mfma_f32_16x16x32_bf16 v[4:7], v[176:179], v[218:221], v[4:7]
	v_mfma_f32_16x16x32_bf16 v[0:3], v[184:187], v[218:221], v[0:3]
	s_setprio 0
	s_barrier
; #define LDA(dst, b, h) for (int m = 0; m < 4; ++m) for (int k = 0; k < 2; ++k) \
;     dst[m][k] = *reinterpret_cast<const bf16x8*>((char*)SA(b, h) + lds_byte(wr * 64 + m * 16 + fr, k * 32 + fq * 8))
; #define LDB(dst, b, h) for (int n = 0; n < 2; ++n) for (int k = 0; k < 2; ++k) \
;     dst[n][k] = *reinterpret_cast<const bf16x8*>((char*)SB(b, h) + lds_byte(wc * 32 + n * 16 + fr, k * 32 + fq * 8))
; #define MMA(ai, bj, At, Bt_) do { __builtin_amdgcn_s_setprio(1); \
;     for (int m = 0; m < 4; ++m) for (int n = 0; n < 2; ++n) for (int k = 0; k < 2; ++k) \
;       acc[ai][bj][m][n] = __builtin_amdgcn_mfma_f32_16x16x32_bf16(Bt_[n][k], At[m][k], acc[ai][bj][m][n], 0, 0, 0); \
;     __builtin_amdgcn_s_setprio(0); } while (0)
; #define WAIT_V(n) asm volatile("s_waitcnt vmcnt(" #n ")" ::: "memory")
; #define WAIT_L(n) asm volatile("s_waitcnt lgkmcnt(" #n ")" ::: "memory")
; #define BAR __builtin_amdgcn_s_barrier()
; #define SCHED __builtin_amdgcn_sched_barrier(0)
; template <int MODE>
; DI void gemm_phase(const bf16_t* __restrict__ A, const bf16_t* __restrict__ Bt, int M, int N, int K, const Epi& ep) {
;     ...
;             LDB(B0, 1, 0); LDB(B1, 1, 1); SCHED; LDA(At, 1, 0); STAGE(SA(0, 1), rsA, brow + HALF, t + 2);
;             WAIT_V(8); WAIT_L(0); BAR; MMA(0, 0, At, B0); MMA(0, 1, At, B1); BAR; SCHED;
;             LDA(At, 1, 1); STAGE(SB(1, 0), rsB, bcol, t + 3); STAGE(SB(1, 1), rsB, bcol + HALF, t + 3); STAGE(SA(1, 0), rsA, brow, t + 3);
;             WAIT_V(8); WAIT_L(0); BAR; MMA(1, 0, At, B0); MMA(1, 1, At, B1); BAR; SCHED;
	ds_read_b128 v[156:159], v153
	ds_read_b128 v[160:163], v153 offset:1024
	ds_read_b128 v[164:167], v153 offset:2048
	ds_read_b128 v[168:171], v153 offset:3072
	ds_read_b128 v[172:175], v154
	ds_read_b128 v[176:179], v154 offset:1024
	ds_read_b128 v[180:183], v154 offset:2048
	ds_read_b128 v[184:187], v154 offset:3072
	v_readfirstlane_b32 s43, v136
	s_add_i32 s42, s40, 0xb0100
	s_mov_b32 m0, s43
	v_readfirstlane_b32 s43, v137
	ds_read_b128 v[188:191], v149 offset:32768
	ds_read_b128 v[192:195], v149 offset:33792
	ds_read_b128 v[196:199], v150 offset:32768
	ds_read_b128 v[200:203], v150 offset:33792
	ds_read_b128 v[204:207], v151 offset:32768
	ds_read_b128 v[208:211], v151 offset:33792
	ds_read_b128 v[214:217], v152 offset:32768
	ds_read_b128 v[218:221], v152 offset:33792
	buffer_load_dwordx4 v128, s[28:31], s42 offen lds
	s_mov_b32 m0, s43
	s_nop 0
	buffer_load_dwordx4 v129, s[28:31], s42 offen lds
	s_waitcnt vmcnt(8)
	s_waitcnt lgkmcnt(0)
	s_barrier
	s_setprio 1
	v_mfma_f32_16x16x32_bf16 v[124:127], v[156:159], v[188:191], v[124:127]
	v_mfma_f32_16x16x32_bf16 v[120:123], v[164:167], v[188:191], v[120:123]
	v_mfma_f32_16x16x32_bf16 v[116:119], v[156:159], v[196:199], v[116:119]
	v_mfma_f32_16x16x32_bf16 v[112:115], v[164:167], v[196:199], v[112:115]
	v_mfma_f32_16x16x32_bf16 v[108:111], v[156:159], v[204:207], v[108:111]
	v_mfma_f32_16x16x32_bf16 v[104:107], v[164:167], v[204:207], v[104:107]
	v_mfma_f32_16x16x32_bf16 v[100:103], v[156:159], v[214:217], v[100:103]
	v_mfma_f32_16x16x32_bf16 v[96:99], v[164:167], v[214:217], v[96:99]
	v_mfma_f32_16x16x32_bf16 v[124:127], v[160:163], v[192:195], v[124:127]
	v_mfma_f32_16x16x32_bf16 v[120:123], v[168:171], v[192:195], v[120:123]
	v_mfma_f32_16x16x32_bf16 v[116:119], v[160:163], v[200:203], v[116:119]
	v_mfma_f32_16x16x32_bf16 v[112:115], v[168:171], v[200:203], v[112:115]
	v_mfma_f32_16x16x32_bf16 v[108:111], v[160:163], v[208:211], v[108:111]
	v_mfma_f32_16x16x32_bf16 v[104:107], v[168:171], v[208:211], v[104:107]
	v_mfma_f32_16x16x32_bf16 v[100:103], v[160:163], v[218:221], v[100:103]
	v_mfma_f32_16x16x32_bf16 v[96:99], v[168:171], v[218:221], v[96:99]
	v_mfma_f32_16x16x32_bf16 v[92:95], v[172:175], v[188:191], v[92:95]
	v_mfma_f32_16x16x32_bf16 v[88:91], v[180:183], v[188:191], v[88:91]
	v_mfma_f32_16x16x32_bf16 v[84:87], v[172:175], v[196:199], v[84:87]
	v_mfma_f32_16x16x32_bf16 v[80:83], v[180:183], v[196:199], v[80:83]
	v_mfma_f32_16x16x32_bf16 v[76:79], v[172:175], v[204:207], v[76:79]
	v_mfma_f32_16x16x32_bf16 v[72:75], v[180:183], v[204:207], v[72:75]
	v_mfma_f32_16x16x32_bf16 v[68:71], v[172:175], v[214:217], v[68:71]
	v_mfma_f32_16x16x32_bf16 v[64:67], v[180:183], v[214:217], v[64:67]
	v_mfma_f32_16x16x32_bf16 v[92:95], v[176:179], v[192:195], v[92:95]
	v_mfma_f32_16x16x32_bf16 v[88:91], v[184:187], v[192:195], v[88:91]
	v_mfma_f32_16x16x32_bf16 v[84:87], v[176:179], v[200:203], v[84:87]
	v_mfma_f32_16x16x32_bf16 v[80:83], v[184:187], v[200:203], v[80:83]
	v_mfma_f32_16x16x32_bf16 v[76:79], v[176:179], v[208:211], v[76:79]
	v_mfma_f32_16x16x32_bf16 v[72:75], v[184:187], v[208:211], v[72:75]
	v_mfma_f32_16x16x32_bf16 v[68:71], v[176:179], v[218:221], v[68:71]
	v_mfma_f32_16x16x32_bf16 v[64:67], v[184:187], v[218:221], v[64:67]
	s_setprio 0
	s_barrier
	v_readfirstlane_b32 s43, v138
	s_add_i32 s42, s41, 0x180
	s_mov_b32 m0, s43
	v_readfirstlane_b32 s43, v139
	ds_read_b128 v[188:191], v149 offset:49152
	ds_read_b128 v[192:195], v149 offset:50176
	ds_read_b128 v[196:199], v150 offset:49152
	ds_read_b128 v[200:203], v150 offset:50176
	ds_read_b128 v[204:207], v151 offset:49152
	ds_read_b128 v[208:211], v151 offset:50176
	ds_read_b128 v[214:217], v152 offset:49152
	ds_read_b128 v[218:221], v152 offset:50176
	buffer_load_dwordx4 v128, s[68:71], s42 offen lds
	s_mov_b32 m0, s43
	s_add_i32 s41, s41, 0xb0180
	buffer_load_dwordx4 v129, s[68:71], s42 offen lds
	v_readfirstlane_b32 s42, v142
	s_mov_b32 m0, s42
	v_readfirstlane_b32 s42, v143
	buffer_load_dwordx4 v128, s[68:71], s41 offen lds
	s_mov_b32 m0, s42
	s_addk_i32 s40, 0x180
	buffer_load_dwordx4 v129, s[68:71], s41 offen lds
	v_readfirstlane_b32 s41, v140
	s_mov_b32 m0, s41
	v_readfirstlane_b32 s41, v141
	buffer_load_dwordx4 v128, s[28:31], s40 offen lds
	s_mov_b32 m0, s41
	s_nop 0
	buffer_load_dwordx4 v129, s[28:31], s40 offen lds
	s_waitcnt vmcnt(8)
	s_waitcnt lgkmcnt(0)
	s_barrier
	s_setprio 1
	v_mfma_f32_16x16x32_bf16 v[60:63], v[156:159], v[188:191], v[60:63]
	v_mfma_f32_16x16x32_bf16 v[56:59], v[164:167], v[188:191], v[56:59]
	v_mfma_f32_16x16x32_bf16 v[52:55], v[156:159], v[196:199], v[52:55]
	v_mfma_f32_16x16x32_bf16 v[48:51], v[164:167], v[196:199], v[48:51]
	v_mfma_f32_16x16x32_bf16 v[44:47], v[156:159], v[204:207], v[44:47]
	v_mfma_f32_16x16x32_bf16 v[40:43], v[164:167], v[204:207], v[40:43]
	v_mfma_f32_16x16x32_bf16 v[36:39], v[156:159], v[214:217], v[36:39]
	v_mfma_f32_16x16x32_bf16 v[32:35], v[164:167], v[214:217], v[32:35]
	v_mfma_f32_16x16x32_bf16 v[60:63], v[160:163], v[192:195], v[60:63]
	v_mfma_f32_16x16x32_bf16 v[56:59], v[168:171], v[192:195], v[56:59]
	v_mfma_f32_16x16x32_bf16 v[52:55], v[160:163], v[200:203], v[52:55]
	v_mfma_f32_16x16x32_bf16 v[48:51], v[168:171], v[200:203], v[48:51]
	v_mfma_f32_16x16x32_bf16 v[44:47], v[160:163], v[208:211], v[44:47]
	v_mfma_f32_16x16x32_bf16 v[40:43], v[168:171], v[208:211], v[40:43]
	v_mfma_f32_16x16x32_bf16 v[36:39], v[160:163], v[218:221], v[36:39]
	v_mfma_f32_16x16x32_bf16 v[32:35], v[168:171], v[218:221], v[32:35]
	v_mfma_f32_16x16x32_bf16 v[28:31], v[172:175], v[188:191], v[28:31]
	v_mfma_f32_16x16x32_bf16 v[24:27], v[180:183], v[188:191], v[24:27]
	v_mfma_f32_16x16x32_bf16 v[20:23], v[172:175], v[196:199], v[20:23]
	v_mfma_f32_16x16x32_bf16 v[16:19], v[180:183], v[196:199], v[16:19]
	v_mfma_f32_16x16x32_bf16 v[12:15], v[172:175], v[204:207], v[12:15]
	v_mfma_f32_16x16x32_bf16 v[8:11], v[180:183], v[204:207], v[8:11]
	v_mfma_f32_16x16x32_bf16 v[4:7], v[172:175], v[214:217], v[4:7]
	v_mfma_f32_16x16x32_bf16 v[0:3], v[180:183], v[214:217], v[0:3]
	v_mfma_f32_16x16x32_bf16 v[28:31], v[176:179], v[192:195], v[28:31]
	v_mfma_f32_16x16x32_bf16 v[24:27], v[184:187], v[192:195], v[24:27]
	v_mfma_f32_16x16x32_bf16 v[20:23], v[176:179], v[200:203], v[20:23]
	v_mfma_f32_16x16x32_bf16 v[16:19], v[184:187], v[200:203], v[16:19]
	v_mfma_f32_16x16x32_bf16 v[12:15], v[176:179], v[208:211], v[12:15]
	v_mfma_f32_16x16x32_bf16 v[8:11], v[184:187], v[208:211], v[8:11]
	v_mfma_f32_16x16x32_bf16 v[4:7], v[176:179], v[218:221], v[4:7]
	v_mfma_f32_16x16x32_bf16 v[0:3], v[184:187], v[218:221], v[0:3]
	s_setprio 0
	s_barrier
; #define LDA(dst, b, h) for (int m = 0; m < 4; ++m) for (int k = 0; k < 2; ++k) \
;     dst[m][k] = *reinterpret_cast<const bf16x8*>((char*)SA(b, h) + lds_byte(wr * 64 + m * 16 + fr, k * 32 + fq * 8))
; #define LDB(dst, b, h) for (int n = 0; n < 2; ++n) for (int k = 0; k < 2; ++k) \
;     dst[n][k] = *reinterpret_cast<const bf16x8*>((char*)SB(b, h) + lds_byte(wc * 32 + n * 16 + fr, k * 32 + fq * 8))
; #define MMA(ai, bj, At, Bt_) do { __builtin_amdgcn_s_setprio(1); \
;     for (int m = 0; m < 4; ++m) for (int n = 0; n < 2; ++n) for (int k = 0; k < 2; ++k) \
;       acc[ai][bj][m][n] = __builtin_amdgcn_mfma_f32_16x16x32_bf16(Bt_[n][k], At[m][k], acc[ai][bj][m][n], 0, 0, 0); \
;     __builtin_amdgcn_s_setprio(0); } while (0)
; #define WAIT_V(n) asm volatile("s_waitcnt vmcnt(" #n ")" ::: "memory")
; #define WAIT_L(n) asm volatile("s_waitcnt lgkmcnt(" #n ")" ::: "memory")
; #define BAR __builtin_amdgcn_s_barrier()
; #define SCHED __builtin_amdgcn_sched_barrier(0)
; template <int MODE>
; DI void gemm_phase(const bf16_t* __restrict__ A, const bf16_t* __restrict__ Bt, int M, int N, int K, const Epi& ep) {
;     ...
;             LDB(B0, 0, 0); LDB(B1, 0, 1); SCHED; LDA(At, 0, 0); STAGE(SA(1, 1), rsA, brow + HALF, nt - 1);
;             WAIT_V(8); WAIT_L(0); BAR; MMA(0, 0, At, B0); MMA(0, 1, At, B1); BAR; SCHED;
;             LDA(At, 0, 1);
;             WAIT_V(2); WAIT_L(0); BAR; MMA(1, 0, At, B0); MMA(1, 1, At, B1); BAR; SCHED;
	s_add_i32 s7, s7, 2
	s_addk_i32 s27, 0x100
	s_cmp_gt_u32 s7, 39
	s_cbranch_scc0 .LBB0_1452
	ds_read_b128 v[156:159], v147
	ds_read_b128 v[160:163], v147 offset:1024
	ds_read_b128 v[164:167], v147 offset:2048
	ds_read_b128 v[168:171], v147 offset:3072
	ds_read_b128 v[172:175], v148
	ds_read_b128 v[176:179], v148 offset:1024
	ds_read_b128 v[180:183], v148 offset:2048
	ds_read_b128 v[184:187], v148 offset:3072
	v_readfirstlane_b32 s7, v144
	s_or_b32 s6, s26, 0x1580
	s_mov_b32 m0, s7
	v_readfirstlane_b32 s7, v145
	ds_read_b128 v[188:191], v149
	ds_read_b128 v[192:195], v149 offset:1024
	ds_read_b128 v[196:199], v150
	ds_read_b128 v[200:203], v150 offset:1024
	ds_read_b128 v[204:207], v151
	ds_read_b128 v[208:211], v151 offset:1024
	ds_read_b128 v[214:217], v152
	ds_read_b128 v[218:221], v152 offset:1024
	buffer_load_dwordx4 v128, s[28:31], s6 offen lds
	s_mov_b32 m0, s7
	s_nop 0
	buffer_load_dwordx4 v129, s[28:31], s6 offen lds
	s_waitcnt vmcnt(8)
	s_waitcnt lgkmcnt(0)
	s_barrier
	s_setprio 1
	v_mfma_f32_16x16x32_bf16 v[124:127], v[156:159], v[188:191], v[124:127]
	v_mfma_f32_16x16x32_bf16 v[120:123], v[164:167], v[188:191], v[120:123]
	v_mfma_f32_16x16x32_bf16 v[116:119], v[156:159], v[196:199], v[116:119]
	v_mfma_f32_16x16x32_bf16 v[112:115], v[164:167], v[196:199], v[112:115]
	v_mfma_f32_16x16x32_bf16 v[108:111], v[156:159], v[204:207], v[108:111]
	v_mfma_f32_16x16x32_bf16 v[124:127], v[160:163], v[192:195], v[124:127]
	v_mfma_f32_16x16x32_bf16 v[120:123], v[168:171], v[192:195], v[120:123]
	v_mfma_f32_16x16x32_bf16 v[116:119], v[160:163], v[200:203], v[116:119]
	v_mfma_f32_16x16x32_bf16 v[112:115], v[168:171], v[200:203], v[112:115]
	v_mfma_f32_16x16x32_bf16 v[222:225], v[160:163], v[208:211], v[108:111]
	v_mfma_f32_16x16x32_bf16 v[104:107], v[164:167], v[204:207], v[104:107]
	v_mfma_f32_16x16x32_bf16 v[100:103], v[156:159], v[214:217], v[100:103]
	v_mfma_f32_16x16x32_bf16 v[96:99], v[164:167], v[214:217], v[96:99]
	v_mfma_f32_16x16x32_bf16 v[226:229], v[168:171], v[208:211], v[104:107]
	v_mfma_f32_16x16x32_bf16 v[230:233], v[160:163], v[218:221], v[100:103]
	v_mfma_f32_16x16x32_bf16 v[234:237], v[168:171], v[218:221], v[96:99]
	v_mfma_f32_16x16x32_bf16 v[92:95], v[172:175], v[188:191], v[92:95]
	v_mfma_f32_16x16x32_bf16 v[88:91], v[180:183], v[188:191], v[88:91]
	v_mfma_f32_16x16x32_bf16 v[84:87], v[172:175], v[196:199], v[84:87]
	v_mfma_f32_16x16x32_bf16 v[80:83], v[180:183], v[196:199], v[80:83]
	v_mfma_f32_16x16x32_bf16 v[92:95], v[176:179], v[192:195], v[92:95]
	v_mfma_f32_16x16x32_bf16 v[88:91], v[184:187], v[192:195], v[88:91]
	v_mfma_f32_16x16x32_bf16 v[84:87], v[176:179], v[200:203], v[84:87]
	v_mfma_f32_16x16x32_bf16 v[80:83], v[184:187], v[200:203], v[80:83]
	v_mfma_f32_16x16x32_bf16 v[76:79], v[172:175], v[204:207], v[76:79]
	v_mfma_f32_16x16x32_bf16 v[72:75], v[180:183], v[204:207], v[72:75]
	v_mfma_f32_16x16x32_bf16 v[68:71], v[172:175], v[214:217], v[68:71]
	v_mfma_f32_16x16x32_bf16 v[64:67], v[180:183], v[214:217], v[64:67]
	v_mfma_f32_16x16x32_bf16 v[188:191], v[176:179], v[208:211], v[76:79]
	v_mfma_f32_16x16x32_bf16 v[192:195], v[184:187], v[208:211], v[72:75]
	v_mfma_f32_16x16x32_bf16 v[196:199], v[176:179], v[218:221], v[68:71]
	v_mfma_f32_16x16x32_bf16 v[200:203], v[184:187], v[218:221], v[64:67]
	s_setprio 0
	s_barrier
	s_nop 1
	ds_read_b128 v[64:67], v149 offset:16384
	ds_read_b128 v[68:71], v149 offset:17408
	ds_read_b128 v[72:75], v150 offset:16384
	ds_read_b128 v[76:79], v150 offset:17408
	ds_read_b128 v[96:99], v151 offset:16384
	ds_read_b128 v[100:103], v151 offset:17408
	ds_read_b128 v[104:107], v152 offset:16384
	ds_read_b128 v[108:111], v152 offset:17408
	s_waitcnt vmcnt(2)
	s_waitcnt lgkmcnt(0)
	s_barrier
	s_setprio 1
	v_mfma_f32_16x16x32_bf16 v[60:63], v[156:159], v[64:67], v[60:63]
	v_mfma_f32_16x16x32_bf16 v[56:59], v[164:167], v[64:67], v[56:59]
	v_mfma_f32_16x16x32_bf16 v[52:55], v[156:159], v[72:75], v[52:55]
	v_mfma_f32_16x16x32_bf16 v[48:51], v[164:167], v[72:75], v[48:51]
	v_mfma_f32_16x16x32_bf16 v[60:63], v[160:163], v[68:71], v[60:63]
	v_mfma_f32_16x16x32_bf16 v[56:59], v[168:171], v[68:71], v[56:59]
	v_mfma_f32_16x16x32_bf16 v[52:55], v[160:163], v[76:79], v[52:55]
	v_mfma_f32_16x16x32_bf16 v[48:51], v[168:171], v[76:79], v[48:51]
	v_mfma_f32_16x16x32_bf16 v[44:47], v[156:159], v[96:99], v[44:47]
	v_mfma_f32_16x16x32_bf16 v[40:43], v[164:167], v[96:99], v[40:43]
	v_mfma_f32_16x16x32_bf16 v[36:39], v[156:159], v[104:107], v[36:39]
	v_mfma_f32_16x16x32_bf16 v[32:35], v[164:167], v[104:107], v[32:35]
	v_mfma_f32_16x16x32_bf16 v[204:207], v[160:163], v[100:103], v[44:47]
	v_mfma_f32_16x16x32_bf16 v[208:211], v[168:171], v[100:103], v[40:43]
	v_mfma_f32_16x16x32_bf16 v[156:159], v[160:163], v[108:111], v[36:39]
	v_mfma_f32_16x16x32_bf16 v[160:163], v[168:171], v[108:111], v[32:35]
	v_mfma_f32_16x16x32_bf16 v[28:31], v[172:175], v[64:67], v[28:31]
	v_mfma_f32_16x16x32_bf16 v[24:27], v[180:183], v[64:67], v[24:27]
	v_mfma_f32_16x16x32_bf16 v[20:23], v[172:175], v[72:75], v[20:23]
	v_mfma_f32_16x16x32_bf16 v[16:19], v[180:183], v[72:75], v[16:19]
	v_mfma_f32_16x16x32_bf16 v[28:31], v[176:179], v[68:71], v[28:31]
	v_mfma_f32_16x16x32_bf16 v[24:27], v[184:187], v[68:71], v[24:27]
	v_mfma_f32_16x16x32_bf16 v[20:23], v[176:179], v[76:79], v[20:23]
	v_mfma_f32_16x16x32_bf16 v[16:19], v[184:187], v[76:79], v[16:19]
	v_mfma_f32_16x16x32_bf16 v[12:15], v[172:175], v[96:99], v[12:15]
	v_mfma_f32_16x16x32_bf16 v[8:11], v[180:183], v[96:99], v[8:11]
	v_mfma_f32_16x16x32_bf16 v[4:7], v[172:175], v[104:107], v[4:7]
	v_mfma_f32_16x16x32_bf16 v[0:3], v[180:183], v[104:107], v[0:3]
	v_mfma_f32_16x16x32_bf16 v[164:167], v[176:179], v[100:103], v[12:15]
	v_mfma_f32_16x16x32_bf16 v[168:171], v[184:187], v[100:103], v[8:11]
	v_mfma_f32_16x16x32_bf16 v[172:175], v[176:179], v[108:111], v[4:7]
	v_mfma_f32_16x16x32_bf16 v[176:179], v[184:187], v[108:111], v[0:3]
	s_setprio 0
	s_barrier
; #define LDA(dst, b, h) for (int m = 0; m < 4; ++m) for (int k = 0; k < 2; ++k) \
;     dst[m][k] = *reinterpret_cast<const bf16x8*>((char*)SA(b, h) + lds_byte(wr * 64 + m * 16 + fr, k * 32 + fq * 8))
; #define LDB(dst, b, h) for (int n = 0; n < 2; ++n) for (int k = 0; k < 2; ++k) \
;     dst[n][k] = *reinterpret_cast<const bf16x8*>((char*)SB(b, h) + lds_byte(wc * 32 + n * 16 + fr, k * 32 + fq * 8))
; #define MMA(ai, bj, At, Bt_) do { __builtin_amdgcn_s_setprio(1); \
;     for (int m = 0; m < 4; ++m) for (int n = 0; n < 2; ++n) for (int k = 0; k < 2; ++k) \
;       acc[ai][bj][m][n] = __builtin_amdgcn_mfma_f32_16x16x32_bf16(Bt_[n][k], At[m][k], acc[ai][bj][m][n], 0, 0, 0); \
;     __builtin_amdgcn_s_setprio(0); } while (0)
; #define WAIT_V(n) asm volatile("s_waitcnt vmcnt(" #n ")" ::: "memory")
; #define WAIT_L(n) asm volatile("s_waitcnt lgkmcnt(" #n ")" ::: "memory")
; #define BAR __builtin_amdgcn_s_barrier()
; #define SCHED __builtin_amdgcn_sched_barrier(0)
; template <int MODE>
; DI void gemm_phase(const bf16_t* __restrict__ A, const bf16_t* __restrict__ Bt, int M, int N, int K, const Epi& ep) {
;     ...
;             LDB(B0, 1, 0); LDB(B1, 1, 1); SCHED; LDA(At, 1, 0);
;             WAIT_V(0); WAIT_L(0); BAR; MMA(0, 0, At, B0); MMA(0, 1, At, B1); BAR; SCHED;
;             LDA(At, 1, 1);
;             WAIT_L(0); BAR; MMA(1, 0, At, B0); MMA(1, 1, At, B1); BAR; SCHED;
;         }
;         if (wr == 0) BAR;
	s_nop 1
	ds_read_b128 v[0:3], v153
	ds_read_b128 v[4:7], v153 offset:1024
	ds_read_b128 v[8:11], v153 offset:2048
	ds_read_b128 v[12:15], v153 offset:3072
	ds_read_b128 v[180:183], v154
	ds_read_b128 v[184:187], v154 offset:1024
	ds_read_b128 v[214:217], v154 offset:2048
	ds_read_b128 v[218:221], v154 offset:3072
	ds_read_b128 v[32:35], v149 offset:32768
	ds_read_b128 v[36:39], v149 offset:33792
	ds_read_b128 v[40:43], v150 offset:32768
	ds_read_b128 v[44:47], v150 offset:33792
	ds_read_b128 v[238:241], v151 offset:32768
	ds_read_b128 v[242:245], v151 offset:33792
	ds_read_b128 v[246:249], v152 offset:32768
	ds_read_b128 v[64:67], v152 offset:33792
	s_waitcnt vmcnt(0)
	s_waitcnt lgkmcnt(0)
	s_barrier
	s_setprio 1
	v_mfma_f32_16x16x32_bf16 v[68:71], v[0:3], v[32:35], v[124:127]
	v_mfma_f32_16x16x32_bf16 v[96:99], v[4:7], v[36:39], v[68:71]
	v_mfma_f32_16x16x32_bf16 v[68:71], v[8:11], v[32:35], v[120:123]
	v_mfma_f32_16x16x32_bf16 v[100:103], v[12:15], v[36:39], v[68:71]
	v_mfma_f32_16x16x32_bf16 v[68:71], v[0:3], v[40:43], v[116:119]
	v_mfma_f32_16x16x32_bf16 v[104:107], v[4:7], v[44:47], v[68:71]
	v_mfma_f32_16x16x32_bf16 v[68:71], v[8:11], v[40:43], v[112:115]
	v_mfma_f32_16x16x32_bf16 v[108:111], v[12:15], v[44:47], v[68:71]
	v_mfma_f32_16x16x32_bf16 v[68:71], v[0:3], v[238:241], v[222:225]
	v_mfma_f32_16x16x32_bf16 v[112:115], v[4:7], v[242:245], v[68:71]
	v_mfma_f32_16x16x32_bf16 v[68:71], v[8:11], v[238:241], v[226:229]
	v_mfma_f32_16x16x32_bf16 v[116:119], v[12:15], v[242:245], v[68:71]
	v_mfma_f32_16x16x32_bf16 v[68:71], v[0:3], v[246:249], v[230:233]
	v_mfma_f32_16x16x32_bf16 v[120:123], v[4:7], v[64:67], v[68:71]
	v_mfma_f32_16x16x32_bf16 v[68:71], v[8:11], v[246:249], v[234:237]
	v_mfma_f32_16x16x32_bf16 v[124:127], v[12:15], v[64:67], v[68:71]
	v_mfma_f32_16x16x32_bf16 v[68:71], v[180:183], v[32:35], v[92:95]
	v_mfma_f32_16x16x32_bf16 v[32:35], v[214:217], v[32:35], v[88:91]
	v_mfma_f32_16x16x32_bf16 v[222:225], v[184:187], v[36:39], v[68:71]
	v_mfma_f32_16x16x32_bf16 v[68:71], v[218:221], v[36:39], v[32:35]
	v_mfma_f32_16x16x32_bf16 v[32:35], v[180:183], v[40:43], v[84:87]
	v_mfma_f32_16x16x32_bf16 v[72:75], v[184:187], v[44:47], v[32:35]
	v_mfma_f32_16x16x32_bf16 v[32:35], v[214:217], v[40:43], v[80:83]
	v_mfma_f32_16x16x32_bf16 v[76:79], v[218:221], v[44:47], v[32:35]
	v_mfma_f32_16x16x32_bf16 v[32:35], v[180:183], v[238:241], v[188:191]
	v_mfma_f32_16x16x32_bf16 v[80:83], v[184:187], v[242:245], v[32:35]
	v_mfma_f32_16x16x32_bf16 v[32:35], v[214:217], v[238:241], v[192:195]
	v_mfma_f32_16x16x32_bf16 v[84:87], v[218:221], v[242:245], v[32:35]
	v_mfma_f32_16x16x32_bf16 v[32:35], v[180:183], v[246:249], v[196:199]
	v_mfma_f32_16x16x32_bf16 v[88:91], v[184:187], v[64:67], v[32:35]
	v_mfma_f32_16x16x32_bf16 v[32:35], v[214:217], v[246:249], v[200:203]
	v_mfma_f32_16x16x32_bf16 v[92:95], v[218:221], v[64:67], v[32:35]
	s_setprio 0
	s_barrier
	ds_read_b128 v[64:67], v149 offset:49152
	ds_read_b128 v[188:191], v149 offset:50176
	ds_read_b128 v[192:195], v150 offset:49152
	ds_read_b128 v[196:199], v150 offset:50176
	ds_read_b128 v[200:203], v151 offset:49152
	ds_read_b128 v[226:229], v151 offset:50176
	ds_read_b128 v[230:233], v152 offset:49152
	ds_read_b128 v[234:237], v152 offset:50176
	s_waitcnt lgkmcnt(0)
	s_barrier
	s_setprio 1
	v_mfma_f32_16x16x32_bf16 v[32:35], v[0:3], v[64:67], v[60:63]
	v_mfma_f32_16x16x32_bf16 v[40:43], v[0:3], v[192:195], v[52:55]
	v_mfma_f32_16x16x32_bf16 v[44:47], v[8:11], v[192:195], v[48:51]
	v_mfma_f32_16x16x32_bf16 v[48:51], v[0:3], v[200:203], v[204:207]
	v_mfma_f32_16x16x32_bf16 v[0:3], v[0:3], v[230:233], v[156:159]
	v_mfma_f32_16x16x32_bf16 v[36:39], v[8:11], v[64:67], v[56:59]
	v_mfma_f32_16x16x32_bf16 v[52:55], v[8:11], v[200:203], v[208:211]
	v_mfma_f32_16x16x32_bf16 v[56:59], v[4:7], v[234:237], v[0:3]
	v_mfma_f32_16x16x32_bf16 v[0:3], v[8:11], v[230:233], v[160:163]
	v_mfma_f32_16x16x32_bf16 v[32:35], v[4:7], v[188:191], v[32:35]
	v_mfma_f32_16x16x32_bf16 v[36:39], v[12:15], v[188:191], v[36:39]
	v_mfma_f32_16x16x32_bf16 v[40:43], v[4:7], v[196:199], v[40:43]
	v_mfma_f32_16x16x32_bf16 v[44:47], v[12:15], v[196:199], v[44:47]
	v_mfma_f32_16x16x32_bf16 v[48:51], v[4:7], v[226:229], v[48:51]
	v_mfma_f32_16x16x32_bf16 v[52:55], v[12:15], v[226:229], v[52:55]
	v_mfma_f32_16x16x32_bf16 v[60:63], v[12:15], v[234:237], v[0:3]
	v_mfma_f32_16x16x32_bf16 v[0:3], v[180:183], v[64:67], v[28:31]
	v_mfma_f32_16x16x32_bf16 v[4:7], v[214:217], v[64:67], v[24:27]
	v_mfma_f32_16x16x32_bf16 v[8:11], v[180:183], v[192:195], v[20:23]
	v_mfma_f32_16x16x32_bf16 v[12:15], v[214:217], v[192:195], v[16:19]
	v_mfma_f32_16x16x32_bf16 v[16:19], v[180:183], v[200:203], v[164:167]
	v_mfma_f32_16x16x32_bf16 v[20:23], v[214:217], v[200:203], v[168:171]
	v_mfma_f32_16x16x32_bf16 v[24:27], v[180:183], v[230:233], v[172:175]
	v_mfma_f32_16x16x32_bf16 v[28:31], v[214:217], v[230:233], v[176:179]
	v_mfma_f32_16x16x32_bf16 v[0:3], v[184:187], v[188:191], v[0:3]
	v_mfma_f32_16x16x32_bf16 v[4:7], v[218:221], v[188:191], v[4:7]
	v_mfma_f32_16x16x32_bf16 v[8:11], v[184:187], v[196:199], v[8:11]
	v_mfma_f32_16x16x32_bf16 v[12:15], v[218:221], v[196:199], v[12:15]
	v_mfma_f32_16x16x32_bf16 v[16:19], v[184:187], v[226:229], v[16:19]
	v_mfma_f32_16x16x32_bf16 v[20:23], v[218:221], v[226:229], v[20:23]
	v_mfma_f32_16x16x32_bf16 v[24:27], v[184:187], v[234:237], v[24:27]
	v_mfma_f32_16x16x32_bf16 v[28:31], v[218:221], v[234:237], v[28:31]
	s_setprio 0
	s_barrier
	s_and_saveexec_b64 s[6:7], s[38:39]
	s_cbranch_execz .LBB0_1444
	s_barrier
	s_branch .LBB0_1444
